# MFMA reorder: two k-halves of each accumulator adjacent, snake operand order (98 safe groups)
# speedup vs baseline: 1.0110x; 1.0110x over previous
.LBB0_379:
	v_add_u32_e32 v14, s56, v140
	v_add_u32_e32 v30, s57, v140
	ds_read_b128 v[2:5], v14
	ds_read_b128 v[6:9], v14 offset:1024
	ds_read_b128 v[10:13], v14 offset:2048
	ds_read_b128 v[14:17], v14 offset:3072
	ds_read_b128 v[18:21], v30
	ds_read_b128 v[22:25], v30 offset:1024
	ds_read_b128 v[26:29], v30 offset:2048
	ds_read_b128 v[30:33], v30 offset:3072
	v_add_u32_e32 v141, 0, v1
	ds_read_b128 v[34:37], v141
	ds_read_b128 v[38:41], v141 offset:1024
	ds_read_b128 v[42:45], v141 offset:2048
	ds_read_b128 v[46:49], v141 offset:3072
	ds_read_b128 v[50:53], v141 offset:4096
	ds_read_b128 v[54:57], v141 offset:5120
	ds_read_b128 v[58:61], v141 offset:6144
	ds_read_b128 v[62:65], v141 offset:7168
	s_waitcnt vmcnt(8)
	s_waitcnt lgkmcnt(0)
	s_barrier
	s_setprio 1
	s_waitcnt lgkmcnt(0)
	v_mfma_f32_16x16x32_bf16 v[66:69], v[2:5], v[34:37], 0
	v_mfma_f32_16x16x32_bf16 v[66:69], v[6:9], v[38:41], v[66:69]
	v_mfma_f32_16x16x32_bf16 v[70:73], v[10:13], v[34:37], 0
	v_mfma_f32_16x16x32_bf16 v[70:73], v[14:17], v[38:41], v[70:73]
	v_mfma_f32_16x16x32_bf16 v[78:81], v[10:13], v[42:45], 0
	v_mfma_f32_16x16x32_bf16 v[78:81], v[14:17], v[46:49], v[78:81]
	v_mfma_f32_16x16x32_bf16 v[74:77], v[2:5], v[42:45], 0
	v_mfma_f32_16x16x32_bf16 v[74:77], v[6:9], v[46:49], v[74:77]
	v_mfma_f32_16x16x32_bf16 v[82:85], v[2:5], v[50:53], 0
	v_mfma_f32_16x16x32_bf16 v[82:85], v[6:9], v[54:57], v[82:85]
	v_mfma_f32_16x16x32_bf16 v[86:89], v[10:13], v[50:53], 0
	v_mfma_f32_16x16x32_bf16 v[86:89], v[14:17], v[54:57], v[86:89]
	v_mfma_f32_16x16x32_bf16 v[94:97], v[10:13], v[58:61], 0
	v_mfma_f32_16x16x32_bf16 v[94:97], v[14:17], v[62:65], v[94:97]
	v_mfma_f32_16x16x32_bf16 v[90:93], v[2:5], v[58:61], 0
	v_mfma_f32_16x16x32_bf16 v[90:93], v[6:9], v[62:65], v[90:93]
	s_setprio 0
	s_setprio 1
	v_mfma_f32_16x16x32_bf16 v[98:101], v[18:21], v[34:37], 0
	v_mfma_f32_16x16x32_bf16 v[34:37], v[26:29], v[34:37], 0
	v_mfma_f32_16x16x32_bf16 v[102:105], v[18:21], v[42:45], 0
	v_mfma_f32_16x16x32_bf16 v[42:45], v[26:29], v[42:45], 0
	v_mfma_f32_16x16x32_bf16 v[106:109], v[18:21], v[50:53], 0
	v_mfma_f32_16x16x32_bf16 v[50:53], v[26:29], v[50:53], 0
	v_mfma_f32_16x16x32_bf16 v[110:113], v[18:21], v[58:61], 0
	v_mfma_f32_16x16x32_bf16 v[58:61], v[26:29], v[58:61], 0
	v_mfma_f32_16x16x32_bf16 v[98:101], v[22:25], v[38:41], v[98:101]
	v_mfma_f32_16x16x32_bf16 v[38:41], v[30:33], v[38:41], v[34:37]
	v_mfma_f32_16x16x32_bf16 v[102:105], v[22:25], v[46:49], v[102:105]
	v_mfma_f32_16x16x32_bf16 v[46:49], v[30:33], v[46:49], v[42:45]
	v_mfma_f32_16x16x32_bf16 v[106:109], v[22:25], v[54:57], v[106:109]
	v_mfma_f32_16x16x32_bf16 v[54:57], v[30:33], v[54:57], v[50:53]
	v_mfma_f32_16x16x32_bf16 v[110:113], v[22:25], v[62:65], v[110:113]
	v_mfma_f32_16x16x32_bf16 v[62:65], v[30:33], v[62:65], v[58:61]
	s_setprio 0
	s_barrier
	v_lshl_add_u64 v[136:137], s[38:39], 0, v[130:131]
	s_add_i32 s60, s56, s21
	v_mov_b32_e32 v135, v131
	v_lshl_add_u64 v[142:143], v[136:137], 0, s[10:11]
	s_mov_b32 m0, s60
	v_lshl_add_u64 v[244:245], s[38:39], 0, v[134:135]
	ds_read_b128 v[34:37], v141 offset:16384
	ds_read_b128 v[42:45], v141 offset:17408
	ds_read_b128 v[50:53], v141 offset:18432
	ds_read_b128 v[58:61], v141 offset:19456
	ds_read_b128 v[114:117], v141 offset:20480
	ds_read_b128 v[118:121], v141 offset:21504
	ds_read_b128 v[122:125], v141 offset:22528
	ds_read_b128 v[126:129], v141 offset:23552
	global_load_lds_dwordx4 v[142:143], off
	v_lshl_add_u64 v[142:143], v[244:245], 0, s[10:11]
	s_add_i32 m0, s60, 0x2000
	s_add_i32 s60, s57, s21
	global_load_lds_dwordx4 v[142:143], off
	s_mov_b32 m0, s60
	v_mov_b32_e32 v139, v131
	global_load_lds_dwordx4 v130, s[40:41]
	s_add_i32 m0, s60, 0x2000
	v_lshl_add_u64 v[246:247], s[36:37], 0, v[138:139]
	v_mov_b32_e32 v133, v131
	global_load_lds_dwordx4 v134, s[40:41]
	v_lshl_add_u64 v[142:143], v[246:247], 0, s[10:11]
	s_mov_b32 m0, s33
	v_lshl_add_u64 v[248:249], s[36:37], 0, v[132:133]
	global_load_lds_dwordx4 v[142:143], off
	v_lshl_add_u64 v[142:143], v[248:249], 0, s[10:11]
	s_mov_b32 m0, s46
	s_nop 0
	global_load_lds_dwordx4 v[142:143], off
	s_waitcnt vmcnt(8)
	s_waitcnt lgkmcnt(0)
	s_barrier
	s_setprio 1
	s_waitcnt lgkmcnt(0)
	v_mfma_f32_16x16x32_bf16 v[142:145], v[2:5], v[34:37], 0
	v_mfma_f32_16x16x32_bf16 v[148:151], v[10:13], v[34:37], 0
	v_mfma_f32_16x16x32_bf16 v[152:155], v[2:5], v[50:53], 0
	v_mfma_f32_16x16x32_bf16 v[156:159], v[10:13], v[50:53], 0
	v_mfma_f32_16x16x32_bf16 v[160:163], v[2:5], v[114:117], 0
	v_mfma_f32_16x16x32_bf16 v[164:167], v[10:13], v[114:117], 0
	v_mfma_f32_16x16x32_bf16 v[2:5], v[2:5], v[122:125], 0
	v_mfma_f32_16x16x32_bf16 v[10:13], v[10:13], v[122:125], 0
	v_mfma_f32_16x16x32_bf16 v[142:145], v[6:9], v[42:45], v[142:145]
	v_mfma_f32_16x16x32_bf16 v[148:151], v[14:17], v[42:45], v[148:151]
	v_mfma_f32_16x16x32_bf16 v[152:155], v[6:9], v[58:61], v[152:155]
	v_mfma_f32_16x16x32_bf16 v[156:159], v[14:17], v[58:61], v[156:159]
	v_mfma_f32_16x16x32_bf16 v[160:163], v[6:9], v[118:121], v[160:163]
	v_mfma_f32_16x16x32_bf16 v[164:167], v[14:17], v[118:121], v[164:167]
	v_mfma_f32_16x16x32_bf16 v[168:171], v[6:9], v[126:129], v[2:5]
	v_mfma_f32_16x16x32_bf16 v[172:175], v[14:17], v[126:129], v[10:13]
	s_setprio 0
	s_setprio 1
	v_mfma_f32_16x16x32_bf16 v[2:5], v[18:21], v[34:37], 0
	v_mfma_f32_16x16x32_bf16 v[6:9], v[26:29], v[34:37], 0
	v_mfma_f32_16x16x32_bf16 v[10:13], v[18:21], v[50:53], 0
	v_mfma_f32_16x16x32_bf16 v[14:17], v[26:29], v[50:53], 0
	v_mfma_f32_16x16x32_bf16 v[34:37], v[18:21], v[114:117], 0
	v_mfma_f32_16x16x32_bf16 v[50:53], v[26:29], v[114:117], 0
	v_mfma_f32_16x16x32_bf16 v[18:21], v[18:21], v[122:125], 0
	v_mfma_f32_16x16x32_bf16 v[26:29], v[26:29], v[122:125], 0
	v_mfma_f32_16x16x32_bf16 v[114:117], v[22:25], v[42:45], v[2:5]
	v_mfma_f32_16x16x32_bf16 v[188:191], v[22:25], v[118:121], v[34:37]
	v_mfma_f32_16x16x32_bf16 v[118:121], v[30:33], v[118:121], v[50:53]
	v_mfma_f32_16x16x32_bf16 v[176:179], v[30:33], v[42:45], v[6:9]
	v_mfma_f32_16x16x32_bf16 v[180:183], v[22:25], v[58:61], v[10:13]
	v_mfma_f32_16x16x32_bf16 v[184:187], v[30:33], v[58:61], v[14:17]
	v_mfma_f32_16x16x32_bf16 v[192:195], v[22:25], v[126:129], v[18:21]
	v_mfma_f32_16x16x32_bf16 v[196:199], v[30:33], v[126:129], v[26:29]
	s_setprio 0
	s_barrier
	s_add_i32 s60, 0, 0x18000
	v_add_u32_e32 v2, s60, v140
	s_add_i32 s61, 0, 0x1c000
	ds_read_b128 v[200:203], v2
	ds_read_b128 v[204:207], v2 offset:1024
	ds_read_b128 v[208:211], v2 offset:2048
	ds_read_b128 v[212:215], v2 offset:3072
	v_add_u32_e32 v2, s61, v140
	ds_read_b128 v[216:219], v2
	ds_read_b128 v[220:223], v2 offset:1024
	ds_read_b128 v[224:227], v2 offset:2048
	ds_read_b128 v[228:231], v2 offset:3072
	s_mov_b32 m0, s47
	ds_read_b128 v[42:45], v141 offset:32768
	ds_read_b128 v[50:53], v141 offset:33792
	ds_read_b128 v[58:61], v141 offset:34816
	ds_read_b128 v[122:125], v141 offset:35840
	ds_read_b128 v[126:129], v141 offset:36864
	ds_read_b128 v[232:235], v141 offset:37888
	ds_read_b128 v[236:239], v141 offset:38912
	ds_read_b128 v[240:243], v141 offset:39936
	global_load_lds_dwordx4 v138, s[42:43]
	s_mov_b32 m0, s48
	s_nop 0
	global_load_lds_dwordx4 v132, s[42:43]
	s_waitcnt vmcnt(8)
	s_waitcnt lgkmcnt(0)
	s_barrier
	s_setprio 1
	s_waitcnt lgkmcnt(0)
	v_mfma_f32_16x16x32_bf16 v[2:5], v[200:203], v[42:45], v[66:69]
	v_mfma_f32_16x16x32_bf16 v[6:9], v[208:211], v[42:45], v[70:73]
	v_mfma_f32_16x16x32_bf16 v[10:13], v[200:203], v[58:61], v[74:77]
	v_mfma_f32_16x16x32_bf16 v[14:17], v[208:211], v[58:61], v[78:81]
	v_mfma_f32_16x16x32_bf16 v[18:21], v[200:203], v[126:129], v[82:85]
	v_mfma_f32_16x16x32_bf16 v[22:25], v[208:211], v[126:129], v[86:89]
	v_mfma_f32_16x16x32_bf16 v[26:29], v[200:203], v[236:239], v[90:93]
	v_mfma_f32_16x16x32_bf16 v[30:33], v[208:211], v[236:239], v[94:97]
	v_mfma_f32_16x16x32_bf16 v[2:5], v[204:207], v[50:53], v[2:5]
	v_mfma_f32_16x16x32_bf16 v[6:9], v[212:215], v[50:53], v[6:9]
	v_mfma_f32_16x16x32_bf16 v[10:13], v[204:207], v[122:125], v[10:13]
	v_mfma_f32_16x16x32_bf16 v[14:17], v[212:215], v[122:125], v[14:17]
	v_mfma_f32_16x16x32_bf16 v[18:21], v[204:207], v[232:235], v[18:21]
	v_mfma_f32_16x16x32_bf16 v[22:25], v[212:215], v[232:235], v[22:25]
	v_mfma_f32_16x16x32_bf16 v[26:29], v[204:207], v[240:243], v[26:29]
	v_mfma_f32_16x16x32_bf16 v[30:33], v[212:215], v[240:243], v[30:33]
	s_setprio 0
	s_setprio 1
	v_mfma_f32_16x16x32_bf16 v[34:37], v[216:219], v[42:45], v[98:101]
	v_mfma_f32_16x16x32_bf16 v[38:41], v[224:227], v[42:45], v[38:41]
	v_mfma_f32_16x16x32_bf16 v[34:37], v[220:223], v[50:53], v[34:37]
	v_mfma_f32_16x16x32_bf16 v[38:41], v[228:231], v[50:53], v[38:41]
	v_mfma_f32_16x16x32_bf16 v[42:45], v[216:219], v[58:61], v[102:105]
	v_mfma_f32_16x16x32_bf16 v[46:49], v[224:227], v[58:61], v[46:49]
	v_mfma_f32_16x16x32_bf16 v[50:53], v[216:219], v[126:129], v[106:109]
	v_mfma_f32_16x16x32_bf16 v[54:57], v[224:227], v[126:129], v[54:57]
	v_mfma_f32_16x16x32_bf16 v[58:61], v[216:219], v[236:239], v[110:113]
	v_mfma_f32_16x16x32_bf16 v[62:65], v[224:227], v[236:239], v[62:65]
	v_mfma_f32_16x16x32_bf16 v[42:45], v[220:223], v[122:125], v[42:45]
	v_mfma_f32_16x16x32_bf16 v[46:49], v[228:231], v[122:125], v[46:49]
	v_mfma_f32_16x16x32_bf16 v[50:53], v[220:223], v[232:235], v[50:53]
	v_mfma_f32_16x16x32_bf16 v[54:57], v[228:231], v[232:235], v[54:57]
	v_mfma_f32_16x16x32_bf16 v[58:61], v[220:223], v[240:243], v[58:61]
	v_mfma_f32_16x16x32_bf16 v[62:65], v[228:231], v[240:243], v[62:65]
	s_setprio 0
	s_barrier
	s_add_i32 s60, s60, s21
	v_lshl_add_u64 v[66:67], v[136:137], 0, s[12:13]
	s_mov_b32 m0, s60
	ds_read_b128 v[94:97], v141 offset:49152
	ds_read_b128 v[98:101], v141 offset:50176
	ds_read_b128 v[102:105], v141 offset:51200
	ds_read_b128 v[106:109], v141 offset:52224
	ds_read_b128 v[110:113], v141 offset:53248
	ds_read_b128 v[232:235], v141 offset:54272
	ds_read_b128 v[236:239], v141 offset:55296
	ds_read_b128 v[240:243], v141 offset:56320
	global_load_lds_dwordx4 v[66:67], off
	v_lshl_add_u64 v[66:67], v[244:245], 0, s[12:13]
	s_add_i32 m0, s60, 0x2000
	s_add_i32 s60, s61, s21
	global_load_lds_dwordx4 v[66:67], off
	s_mov_b32 m0, s60
	v_lshl_add_u64 v[66:67], v[246:247], 0, s[12:13]
	global_load_lds_dwordx4 v130, s[44:45]
	s_add_i32 m0, s60, 0x2000
	s_nop 0
	global_load_lds_dwordx4 v134, s[44:45]
	s_mov_b32 m0, s52
	s_nop 0
	global_load_lds_dwordx4 v[66:67], off
	v_lshl_add_u64 v[66:67], v[248:249], 0, s[12:13]
	s_mov_b32 m0, s53
	s_nop 0
	global_load_lds_dwordx4 v[66:67], off
	s_waitcnt vmcnt(8)
	s_waitcnt lgkmcnt(0)
	s_barrier
	s_setprio 1
	s_waitcnt lgkmcnt(0)
	v_mfma_f32_16x16x32_bf16 v[66:69], v[200:203], v[94:97], v[142:145]
	v_mfma_f32_16x16x32_bf16 v[122:125], v[204:207], v[98:101], v[66:69]
	v_mfma_f32_16x16x32_bf16 v[66:69], v[208:211], v[94:97], v[148:151]
	v_mfma_f32_16x16x32_bf16 v[126:129], v[212:215], v[98:101], v[66:69]
	v_mfma_f32_16x16x32_bf16 v[66:69], v[200:203], v[102:105], v[152:155]
	v_mfma_f32_16x16x32_bf16 v[70:73], v[208:211], v[102:105], v[156:159]
	v_mfma_f32_16x16x32_bf16 v[74:77], v[200:203], v[110:113], v[160:163]
	v_mfma_f32_16x16x32_bf16 v[78:81], v[208:211], v[110:113], v[164:167]
	v_mfma_f32_16x16x32_bf16 v[82:85], v[200:203], v[236:239], v[168:171]
	v_mfma_f32_16x16x32_bf16 v[86:89], v[208:211], v[236:239], v[172:175]
	v_mfma_f32_16x16x32_bf16 v[66:69], v[204:207], v[106:109], v[66:69]
	v_mfma_f32_16x16x32_bf16 v[70:73], v[212:215], v[106:109], v[70:73]
	v_mfma_f32_16x16x32_bf16 v[74:77], v[204:207], v[232:235], v[74:77]
	v_mfma_f32_16x16x32_bf16 v[78:81], v[212:215], v[232:235], v[78:81]
	v_mfma_f32_16x16x32_bf16 v[82:85], v[204:207], v[240:243], v[82:85]
	v_mfma_f32_16x16x32_bf16 v[86:89], v[212:215], v[240:243], v[86:89]
	s_setprio 0
	s_setprio 1
	v_mfma_f32_16x16x32_bf16 v[90:93], v[216:219], v[94:97], v[114:117]
	v_mfma_f32_16x16x32_bf16 v[94:97], v[224:227], v[94:97], v[176:179]
	v_mfma_f32_16x16x32_bf16 v[90:93], v[220:223], v[98:101], v[90:93]
	v_mfma_f32_16x16x32_bf16 v[94:97], v[228:231], v[98:101], v[94:97]
	v_mfma_f32_16x16x32_bf16 v[98:101], v[216:219], v[102:105], v[180:183]
	v_mfma_f32_16x16x32_bf16 v[102:105], v[224:227], v[102:105], v[184:187]
	v_mfma_f32_16x16x32_bf16 v[98:101], v[220:223], v[106:109], v[98:101]
	v_mfma_f32_16x16x32_bf16 v[102:105], v[228:231], v[106:109], v[102:105]
	v_mfma_f32_16x16x32_bf16 v[106:109], v[216:219], v[110:113], v[188:191]
	v_mfma_f32_16x16x32_bf16 v[110:113], v[224:227], v[110:113], v[118:121]
	v_mfma_f32_16x16x32_bf16 v[114:117], v[216:219], v[236:239], v[192:195]
	v_mfma_f32_16x16x32_bf16 v[118:121], v[224:227], v[236:239], v[196:199]
	v_mfma_f32_16x16x32_bf16 v[106:109], v[220:223], v[232:235], v[106:109]
	v_mfma_f32_16x16x32_bf16 v[110:113], v[228:231], v[232:235], v[110:113]
	v_mfma_f32_16x16x32_bf16 v[114:117], v[220:223], v[240:243], v[114:117]
	v_mfma_f32_16x16x32_bf16 v[118:121], v[228:231], v[240:243], v[118:121]
	s_setprio 0
	s_barrier
	s_add_i32 s59, s59, 2
	s_cmp_ge_i32 s59, s15
	s_cbranch_scc0 .LBB0_379
	v_mov_b32_e32 v136, v130
	s_branch .LBB0_382

.LBB0_383:
	v_add_u32_e32 v133, s56, v140
	ds_read_b128 v[142:145], v133
	ds_read_b128 v[148:151], v133 offset:1024
	ds_read_b128 v[152:155], v133 offset:2048
	ds_read_b128 v[156:159], v133 offset:3072
	v_add_u32_e32 v133, s57, v140
	ds_read_b128 v[160:163], v133
	ds_read_b128 v[164:167], v133 offset:1024
	ds_read_b128 v[168:171], v133 offset:2048
	ds_read_b128 v[172:175], v133 offset:3072
	s_add_u32 s38, s36, 0xfff80080
	s_addc_u32 s39, s37, -1
	s_cmp_eq_u32 s43, 28
	s_cselect_b32 s41, s31, s39
	s_cselect_b32 s40, s30, s38
	s_cselect_b32 s39, s35, s42
	s_cselect_b32 s38, s34, s15
	s_mov_b32 m0, s54
	v_add_u32_e32 v141, 0, v1
	ds_read_b128 v[176:179], v141
	ds_read_b128 v[180:183], v141 offset:1024
	ds_read_b128 v[184:187], v141 offset:2048
	ds_read_b128 v[188:191], v141 offset:3072
	ds_read_b128 v[192:195], v141 offset:4096
	ds_read_b128 v[196:199], v141 offset:5120
	ds_read_b128 v[200:203], v141 offset:6144
	ds_read_b128 v[204:207], v141 offset:7168
	global_load_lds_dwordx4 v130, s[36:37]
	s_mov_b32 m0, s55
	v_mov_b32_e32 v133, v131
	global_load_lds_dwordx4 v132, s[36:37]
	s_waitcnt vmcnt(8)
	s_waitcnt lgkmcnt(0)
	s_barrier
	s_setprio 1
	s_waitcnt lgkmcnt(0)
	v_mfma_f32_16x16x32_bf16 v[2:5], v[142:145], v[176:179], v[2:5]
	v_mfma_f32_16x16x32_bf16 v[2:5], v[148:151], v[180:183], v[2:5]
	v_mfma_f32_16x16x32_bf16 v[6:9], v[156:159], v[180:183], v[6:9]
	v_mfma_f32_16x16x32_bf16 v[6:9], v[152:155], v[176:179], v[6:9]
	v_mfma_f32_16x16x32_bf16 v[14:17], v[152:155], v[184:187], v[14:17]
	v_mfma_f32_16x16x32_bf16 v[14:17], v[156:159], v[188:191], v[14:17]
	v_mfma_f32_16x16x32_bf16 v[10:13], v[148:151], v[188:191], v[10:13]
	v_mfma_f32_16x16x32_bf16 v[10:13], v[142:145], v[184:187], v[10:13]
	v_mfma_f32_16x16x32_bf16 v[18:21], v[142:145], v[192:195], v[18:21]
	v_mfma_f32_16x16x32_bf16 v[18:21], v[148:151], v[196:199], v[18:21]
	v_mfma_f32_16x16x32_bf16 v[22:25], v[156:159], v[196:199], v[22:25]
	v_mfma_f32_16x16x32_bf16 v[22:25], v[152:155], v[192:195], v[22:25]
	v_mfma_f32_16x16x32_bf16 v[30:33], v[152:155], v[200:203], v[30:33]
	v_mfma_f32_16x16x32_bf16 v[30:33], v[156:159], v[204:207], v[30:33]
	v_mfma_f32_16x16x32_bf16 v[26:29], v[148:151], v[204:207], v[26:29]
	v_mfma_f32_16x16x32_bf16 v[26:29], v[142:145], v[200:203], v[26:29]
	s_setprio 0
	s_setprio 1
	v_mfma_f32_16x16x32_bf16 v[34:37], v[160:163], v[176:179], v[34:37]
	v_mfma_f32_16x16x32_bf16 v[34:37], v[164:167], v[180:183], v[34:37]
	v_mfma_f32_16x16x32_bf16 v[38:41], v[172:175], v[180:183], v[38:41]
	v_mfma_f32_16x16x32_bf16 v[38:41], v[168:171], v[176:179], v[38:41]
	v_mfma_f32_16x16x32_bf16 v[46:49], v[168:171], v[184:187], v[46:49]
	v_mfma_f32_16x16x32_bf16 v[46:49], v[172:175], v[188:191], v[46:49]
	v_mfma_f32_16x16x32_bf16 v[42:45], v[164:167], v[188:191], v[42:45]
	v_mfma_f32_16x16x32_bf16 v[42:45], v[160:163], v[184:187], v[42:45]
	v_mfma_f32_16x16x32_bf16 v[50:53], v[160:163], v[192:195], v[50:53]
	v_mfma_f32_16x16x32_bf16 v[50:53], v[164:167], v[196:199], v[50:53]
	v_mfma_f32_16x16x32_bf16 v[54:57], v[172:175], v[196:199], v[54:57]
	v_mfma_f32_16x16x32_bf16 v[54:57], v[168:171], v[192:195], v[54:57]
	v_mfma_f32_16x16x32_bf16 v[62:65], v[168:171], v[200:203], v[62:65]
	v_mfma_f32_16x16x32_bf16 v[62:65], v[172:175], v[204:207], v[62:65]
	v_mfma_f32_16x16x32_bf16 v[58:61], v[164:167], v[204:207], v[58:61]
	v_mfma_f32_16x16x32_bf16 v[58:61], v[160:163], v[200:203], v[58:61]
	s_setprio 0
	s_barrier
	s_add_i32 s44, s56, s21
	s_mov_b32 m0, s44
	ds_read_b128 v[176:179], v141 offset:16384
	ds_read_b128 v[180:183], v141 offset:17408
	ds_read_b128 v[184:187], v141 offset:18432
	ds_read_b128 v[188:191], v141 offset:19456
	ds_read_b128 v[192:195], v141 offset:20480
	ds_read_b128 v[196:199], v141 offset:21504
	ds_read_b128 v[200:203], v141 offset:22528
	ds_read_b128 v[204:207], v141 offset:23552
	global_load_lds_dwordx4 v136, s[38:39]
	s_add_i32 m0, s44, 0x2000
	s_add_u32 s44, s38, 0x80000
	s_addc_u32 s45, s39, 0
	s_add_i32 s59, s57, s21
	global_load_lds_dwordx4 v134, s[38:39]
	s_mov_b32 m0, s59
	v_mov_b32_e32 v137, v131
	global_load_lds_dwordx4 v136, s[44:45]
	s_add_i32 m0, s59, 0x2000
	v_mov_b32_e32 v135, v131
	global_load_lds_dwordx4 v134, s[44:45]
	s_mov_b32 m0, s33
	v_lshl_add_u64 v[138:139], s[38:39], 0, v[136:137]
	global_load_lds_dwordx4 v130, s[40:41]
	s_mov_b32 m0, s46
	v_lshl_add_u64 v[208:209], s[38:39], 0, v[134:135]
	global_load_lds_dwordx4 v132, s[40:41]
	s_waitcnt vmcnt(8)
	s_waitcnt lgkmcnt(0)
	v_lshl_add_u64 v[210:211], s[40:41], 0, v[130:131]
	v_lshl_add_u64 v[212:213], s[40:41], 0, v[132:133]
	s_barrier
	s_setprio 1
	s_waitcnt lgkmcnt(0)
	v_mfma_f32_16x16x32_bf16 v[122:125], v[142:145], v[176:179], v[122:125]
	v_mfma_f32_16x16x32_bf16 v[122:125], v[148:151], v[180:183], v[122:125]
	v_mfma_f32_16x16x32_bf16 v[126:129], v[156:159], v[180:183], v[126:129]
	v_mfma_f32_16x16x32_bf16 v[126:129], v[152:155], v[176:179], v[126:129]
	v_mfma_f32_16x16x32_bf16 v[70:73], v[152:155], v[184:187], v[70:73]
	v_mfma_f32_16x16x32_bf16 v[70:73], v[156:159], v[188:191], v[70:73]
	v_mfma_f32_16x16x32_bf16 v[66:69], v[148:151], v[188:191], v[66:69]
	v_mfma_f32_16x16x32_bf16 v[66:69], v[142:145], v[184:187], v[66:69]
	v_mfma_f32_16x16x32_bf16 v[74:77], v[142:145], v[192:195], v[74:77]
	v_mfma_f32_16x16x32_bf16 v[74:77], v[148:151], v[196:199], v[74:77]
	v_mfma_f32_16x16x32_bf16 v[78:81], v[156:159], v[196:199], v[78:81]
	v_mfma_f32_16x16x32_bf16 v[78:81], v[152:155], v[192:195], v[78:81]
	v_mfma_f32_16x16x32_bf16 v[86:89], v[152:155], v[200:203], v[86:89]
	v_mfma_f32_16x16x32_bf16 v[86:89], v[156:159], v[204:207], v[86:89]
	v_mfma_f32_16x16x32_bf16 v[82:85], v[148:151], v[204:207], v[82:85]
	v_mfma_f32_16x16x32_bf16 v[82:85], v[142:145], v[200:203], v[82:85]
	s_setprio 0
	s_setprio 1
	v_mfma_f32_16x16x32_bf16 v[90:93], v[160:163], v[176:179], v[90:93]
	v_mfma_f32_16x16x32_bf16 v[90:93], v[164:167], v[180:183], v[90:93]
	v_mfma_f32_16x16x32_bf16 v[94:97], v[172:175], v[180:183], v[94:97]
	v_mfma_f32_16x16x32_bf16 v[94:97], v[168:171], v[176:179], v[94:97]
	v_mfma_f32_16x16x32_bf16 v[102:105], v[168:171], v[184:187], v[102:105]
	v_mfma_f32_16x16x32_bf16 v[102:105], v[172:175], v[188:191], v[102:105]
	v_mfma_f32_16x16x32_bf16 v[98:101], v[164:167], v[188:191], v[98:101]
	v_mfma_f32_16x16x32_bf16 v[98:101], v[160:163], v[184:187], v[98:101]
	v_mfma_f32_16x16x32_bf16 v[106:109], v[160:163], v[192:195], v[106:109]
	v_mfma_f32_16x16x32_bf16 v[106:109], v[164:167], v[196:199], v[106:109]
	v_mfma_f32_16x16x32_bf16 v[110:113], v[172:175], v[196:199], v[110:113]
	v_mfma_f32_16x16x32_bf16 v[110:113], v[168:171], v[192:195], v[110:113]
	v_mfma_f32_16x16x32_bf16 v[118:121], v[168:171], v[200:203], v[118:121]
	v_mfma_f32_16x16x32_bf16 v[118:121], v[172:175], v[204:207], v[118:121]
	v_mfma_f32_16x16x32_bf16 v[114:117], v[164:167], v[204:207], v[114:117]
	v_mfma_f32_16x16x32_bf16 v[114:117], v[160:163], v[200:203], v[114:117]
	s_setprio 0
	s_barrier
	s_add_i32 s44, 0, 0x18000
	v_add_u32_e32 v135, s44, v140
	s_add_i32 s45, 0, 0x1c000
	ds_read_b128 v[142:145], v135
	ds_read_b128 v[148:151], v135 offset:1024
	ds_read_b128 v[152:155], v135 offset:2048
	ds_read_b128 v[156:159], v135 offset:3072
	v_add_u32_e32 v135, s45, v140
	ds_read_b128 v[160:163], v135
	ds_read_b128 v[164:167], v135 offset:1024
	ds_read_b128 v[168:171], v135 offset:2048
	ds_read_b128 v[172:175], v135 offset:3072
	s_add_u32 s40, s40, 0x80000
	s_addc_u32 s41, s41, 0
	s_mov_b32 m0, s47
	ds_read_b128 v[176:179], v141 offset:32768
	ds_read_b128 v[180:183], v141 offset:33792
	ds_read_b128 v[184:187], v141 offset:34816
	ds_read_b128 v[188:191], v141 offset:35840
	ds_read_b128 v[192:195], v141 offset:36864
	ds_read_b128 v[196:199], v141 offset:37888
	ds_read_b128 v[200:203], v141 offset:38912
	ds_read_b128 v[204:207], v141 offset:39936
	global_load_lds_dwordx4 v130, s[40:41]
	s_mov_b32 m0, s48
	s_nop 0
	global_load_lds_dwordx4 v132, s[40:41]
	s_waitcnt vmcnt(8)
	s_waitcnt lgkmcnt(0)
	s_barrier
	s_setprio 1
	s_waitcnt lgkmcnt(0)
	v_mfma_f32_16x16x32_bf16 v[2:5], v[142:145], v[176:179], v[2:5]
	v_mfma_f32_16x16x32_bf16 v[2:5], v[148:151], v[180:183], v[2:5]
	v_mfma_f32_16x16x32_bf16 v[6:9], v[156:159], v[180:183], v[6:9]
	v_mfma_f32_16x16x32_bf16 v[6:9], v[152:155], v[176:179], v[6:9]
	v_mfma_f32_16x16x32_bf16 v[14:17], v[152:155], v[184:187], v[14:17]
	v_mfma_f32_16x16x32_bf16 v[14:17], v[156:159], v[188:191], v[14:17]
	v_mfma_f32_16x16x32_bf16 v[10:13], v[148:151], v[188:191], v[10:13]
	v_mfma_f32_16x16x32_bf16 v[10:13], v[142:145], v[184:187], v[10:13]
	v_mfma_f32_16x16x32_bf16 v[18:21], v[142:145], v[192:195], v[18:21]
	v_mfma_f32_16x16x32_bf16 v[18:21], v[148:151], v[196:199], v[18:21]
	v_mfma_f32_16x16x32_bf16 v[22:25], v[156:159], v[196:199], v[22:25]
	v_mfma_f32_16x16x32_bf16 v[22:25], v[152:155], v[192:195], v[22:25]
	v_mfma_f32_16x16x32_bf16 v[30:33], v[152:155], v[200:203], v[30:33]
	v_mfma_f32_16x16x32_bf16 v[30:33], v[156:159], v[204:207], v[30:33]
	v_mfma_f32_16x16x32_bf16 v[26:29], v[148:151], v[204:207], v[26:29]
	v_mfma_f32_16x16x32_bf16 v[26:29], v[142:145], v[200:203], v[26:29]
	s_setprio 0
	s_setprio 1
	v_mfma_f32_16x16x32_bf16 v[34:37], v[160:163], v[176:179], v[34:37]
	v_mfma_f32_16x16x32_bf16 v[34:37], v[164:167], v[180:183], v[34:37]
	v_mfma_f32_16x16x32_bf16 v[38:41], v[172:175], v[180:183], v[38:41]
	v_mfma_f32_16x16x32_bf16 v[38:41], v[168:171], v[176:179], v[38:41]
	v_mfma_f32_16x16x32_bf16 v[46:49], v[168:171], v[184:187], v[46:49]
	v_mfma_f32_16x16x32_bf16 v[46:49], v[172:175], v[188:191], v[46:49]
	v_mfma_f32_16x16x32_bf16 v[42:45], v[164:167], v[188:191], v[42:45]
	v_mfma_f32_16x16x32_bf16 v[42:45], v[160:163], v[184:187], v[42:45]
	v_mfma_f32_16x16x32_bf16 v[50:53], v[160:163], v[192:195], v[50:53]
	v_mfma_f32_16x16x32_bf16 v[50:53], v[164:167], v[196:199], v[50:53]
	v_mfma_f32_16x16x32_bf16 v[54:57], v[172:175], v[196:199], v[54:57]
	v_mfma_f32_16x16x32_bf16 v[54:57], v[168:171], v[192:195], v[54:57]
	v_mfma_f32_16x16x32_bf16 v[62:65], v[168:171], v[200:203], v[62:65]
	v_mfma_f32_16x16x32_bf16 v[62:65], v[172:175], v[204:207], v[62:65]
	v_mfma_f32_16x16x32_bf16 v[58:61], v[164:167], v[204:207], v[58:61]
	v_mfma_f32_16x16x32_bf16 v[58:61], v[160:163], v[200:203], v[58:61]
	s_setprio 0
	s_barrier
	s_add_i32 s40, s44, s21
	v_lshl_add_u64 v[138:139], v[138:139], 0, s[6:7]
	s_mov_b32 m0, s40
	ds_read_b128 v[176:179], v141 offset:49152
	ds_read_b128 v[180:183], v141 offset:50176
	ds_read_b128 v[184:187], v141 offset:51200
	ds_read_b128 v[188:191], v141 offset:52224
	ds_read_b128 v[192:195], v141 offset:53248
	ds_read_b128 v[196:199], v141 offset:54272
	ds_read_b128 v[200:203], v141 offset:55296
	ds_read_b128 v[204:207], v141 offset:56320
	global_load_lds_dwordx4 v[138:139], off
	s_add_i32 m0, s40, 0x2000
	s_add_u32 s38, s38, 0x80080
	v_lshl_add_u64 v[138:139], v[208:209], 0, s[6:7]
	s_addc_u32 s39, s39, 0
	s_add_i32 s40, s45, s21
	global_load_lds_dwordx4 v[138:139], off
	s_mov_b32 m0, s40
	v_lshl_add_u64 v[138:139], v[210:211], 0, s[6:7]
	global_load_lds_dwordx4 v136, s[38:39]
	s_add_i32 m0, s40, 0x2000
	s_nop 0
	global_load_lds_dwordx4 v134, s[38:39]
	s_mov_b32 m0, s52
	s_nop 0
	global_load_lds_dwordx4 v[138:139], off
	v_lshl_add_u64 v[138:139], v[212:213], 0, s[6:7]
	s_mov_b32 m0, s53
	s_nop 0
	global_load_lds_dwordx4 v[138:139], off
	s_waitcnt vmcnt(8)
	s_waitcnt lgkmcnt(0)
	s_barrier
	s_setprio 1
	s_waitcnt lgkmcnt(0)
	v_mfma_f32_16x16x32_bf16 v[122:125], v[142:145], v[176:179], v[122:125]
	v_mfma_f32_16x16x32_bf16 v[122:125], v[148:151], v[180:183], v[122:125]
	v_mfma_f32_16x16x32_bf16 v[126:129], v[156:159], v[180:183], v[126:129]
	v_mfma_f32_16x16x32_bf16 v[126:129], v[152:155], v[176:179], v[126:129]
	v_mfma_f32_16x16x32_bf16 v[70:73], v[152:155], v[184:187], v[70:73]
	v_mfma_f32_16x16x32_bf16 v[70:73], v[156:159], v[188:191], v[70:73]
	v_mfma_f32_16x16x32_bf16 v[66:69], v[148:151], v[188:191], v[66:69]
	v_mfma_f32_16x16x32_bf16 v[66:69], v[142:145], v[184:187], v[66:69]
	v_mfma_f32_16x16x32_bf16 v[74:77], v[142:145], v[192:195], v[74:77]
	v_mfma_f32_16x16x32_bf16 v[74:77], v[148:151], v[196:199], v[74:77]
	v_mfma_f32_16x16x32_bf16 v[78:81], v[156:159], v[196:199], v[78:81]
	v_mfma_f32_16x16x32_bf16 v[78:81], v[152:155], v[192:195], v[78:81]
	v_mfma_f32_16x16x32_bf16 v[86:89], v[152:155], v[200:203], v[86:89]
	v_mfma_f32_16x16x32_bf16 v[86:89], v[156:159], v[204:207], v[86:89]
	v_mfma_f32_16x16x32_bf16 v[82:85], v[148:151], v[204:207], v[82:85]
	v_mfma_f32_16x16x32_bf16 v[82:85], v[142:145], v[200:203], v[82:85]
	s_setprio 0
	s_setprio 1
	v_mfma_f32_16x16x32_bf16 v[90:93], v[160:163], v[176:179], v[90:93]
	v_mfma_f32_16x16x32_bf16 v[90:93], v[164:167], v[180:183], v[90:93]
	v_mfma_f32_16x16x32_bf16 v[94:97], v[172:175], v[180:183], v[94:97]
	v_mfma_f32_16x16x32_bf16 v[94:97], v[168:171], v[176:179], v[94:97]
	v_mfma_f32_16x16x32_bf16 v[102:105], v[168:171], v[184:187], v[102:105]
	v_mfma_f32_16x16x32_bf16 v[102:105], v[172:175], v[188:191], v[102:105]
	v_mfma_f32_16x16x32_bf16 v[98:101], v[164:167], v[188:191], v[98:101]
	v_mfma_f32_16x16x32_bf16 v[98:101], v[160:163], v[184:187], v[98:101]
	v_mfma_f32_16x16x32_bf16 v[106:109], v[160:163], v[192:195], v[106:109]
	v_mfma_f32_16x16x32_bf16 v[106:109], v[164:167], v[196:199], v[106:109]
	v_mfma_f32_16x16x32_bf16 v[110:113], v[172:175], v[196:199], v[110:113]
	v_mfma_f32_16x16x32_bf16 v[110:113], v[168:171], v[192:195], v[110:113]
	v_mfma_f32_16x16x32_bf16 v[118:121], v[168:171], v[200:203], v[118:121]
	v_mfma_f32_16x16x32_bf16 v[118:121], v[172:175], v[204:207], v[118:121]
	v_mfma_f32_16x16x32_bf16 v[114:117], v[164:167], v[204:207], v[114:117]
	v_mfma_f32_16x16x32_bf16 v[114:117], v[160:163], v[200:203], v[114:117]
	s_setprio 0
	s_barrier
	s_add_i32 s43, s43, 2
	s_add_u32 s36, s36, 0x100
	s_addc_u32 s37, s37, 0
	s_add_u32 s15, s15, 0x100
	s_addc_u32 s42, s42, 0
	s_cmp_gt_u32 s43, 29
	s_cbranch_scc0 .LBB0_383
	s_and_b64 vcc, exec, s[8:9]
	s_cbranch_vccz .LBB0_386
	s_barrier

.LBB0_462:
	v_add_u32_e32 v14, s54, v140
	v_add_u32_e32 v30, s55, v140
	ds_read_b128 v[2:5], v14
	ds_read_b128 v[6:9], v14 offset:1024
	ds_read_b128 v[10:13], v14 offset:2048
	ds_read_b128 v[14:17], v14 offset:3072
	ds_read_b128 v[18:21], v30
	ds_read_b128 v[22:25], v30 offset:1024
	ds_read_b128 v[26:29], v30 offset:2048
	ds_read_b128 v[30:33], v30 offset:3072
	v_add_u32_e32 v141, 0, v1
	ds_read_b128 v[34:37], v141
	ds_read_b128 v[38:41], v141 offset:1024
	ds_read_b128 v[42:45], v141 offset:2048
	ds_read_b128 v[46:49], v141 offset:3072
	ds_read_b128 v[50:53], v141 offset:4096
	ds_read_b128 v[54:57], v141 offset:5120
	ds_read_b128 v[58:61], v141 offset:6144
	ds_read_b128 v[62:65], v141 offset:7168
	s_waitcnt vmcnt(8)
	s_waitcnt lgkmcnt(0)
	s_barrier
	s_setprio 1
	s_waitcnt lgkmcnt(0)
	v_mfma_f32_16x16x32_bf16 v[66:69], v[2:5], v[34:37], 0
	v_mfma_f32_16x16x32_bf16 v[66:69], v[6:9], v[38:41], v[66:69]
	v_mfma_f32_16x16x32_bf16 v[70:73], v[10:13], v[34:37], 0
	v_mfma_f32_16x16x32_bf16 v[70:73], v[14:17], v[38:41], v[70:73]
	v_mfma_f32_16x16x32_bf16 v[78:81], v[10:13], v[42:45], 0
	v_mfma_f32_16x16x32_bf16 v[78:81], v[14:17], v[46:49], v[78:81]
	v_mfma_f32_16x16x32_bf16 v[74:77], v[2:5], v[42:45], 0
	v_mfma_f32_16x16x32_bf16 v[74:77], v[6:9], v[46:49], v[74:77]
	v_mfma_f32_16x16x32_bf16 v[82:85], v[2:5], v[50:53], 0
	v_mfma_f32_16x16x32_bf16 v[82:85], v[6:9], v[54:57], v[82:85]
	v_mfma_f32_16x16x32_bf16 v[86:89], v[10:13], v[50:53], 0
	v_mfma_f32_16x16x32_bf16 v[86:89], v[14:17], v[54:57], v[86:89]
	v_mfma_f32_16x16x32_bf16 v[94:97], v[10:13], v[58:61], 0
	v_mfma_f32_16x16x32_bf16 v[94:97], v[14:17], v[62:65], v[94:97]
	v_mfma_f32_16x16x32_bf16 v[90:93], v[2:5], v[58:61], 0
	v_mfma_f32_16x16x32_bf16 v[90:93], v[6:9], v[62:65], v[90:93]
	s_setprio 0
	s_setprio 1
	v_mfma_f32_16x16x32_bf16 v[98:101], v[18:21], v[34:37], 0
	v_mfma_f32_16x16x32_bf16 v[34:37], v[26:29], v[34:37], 0
	v_mfma_f32_16x16x32_bf16 v[102:105], v[18:21], v[42:45], 0
	v_mfma_f32_16x16x32_bf16 v[42:45], v[26:29], v[42:45], 0
	v_mfma_f32_16x16x32_bf16 v[106:109], v[18:21], v[50:53], 0
	v_mfma_f32_16x16x32_bf16 v[50:53], v[26:29], v[50:53], 0
	v_mfma_f32_16x16x32_bf16 v[110:113], v[18:21], v[58:61], 0
	v_mfma_f32_16x16x32_bf16 v[58:61], v[26:29], v[58:61], 0
	v_mfma_f32_16x16x32_bf16 v[98:101], v[22:25], v[38:41], v[98:101]
	v_mfma_f32_16x16x32_bf16 v[38:41], v[30:33], v[38:41], v[34:37]
	v_mfma_f32_16x16x32_bf16 v[102:105], v[22:25], v[46:49], v[102:105]
	v_mfma_f32_16x16x32_bf16 v[46:49], v[30:33], v[46:49], v[42:45]
	v_mfma_f32_16x16x32_bf16 v[106:109], v[22:25], v[54:57], v[106:109]
	v_mfma_f32_16x16x32_bf16 v[54:57], v[30:33], v[54:57], v[50:53]
	v_mfma_f32_16x16x32_bf16 v[110:113], v[22:25], v[62:65], v[110:113]
	v_mfma_f32_16x16x32_bf16 v[62:65], v[30:33], v[62:65], v[58:61]
	s_setprio 0
	s_barrier
	v_lshl_add_u64 v[136:137], s[36:37], 0, v[130:131]
	s_add_i32 s62, s54, s21
	v_mov_b32_e32 v135, v131
	v_lshl_add_u64 v[142:143], v[136:137], 0, s[12:13]
	s_mov_b32 m0, s62
	v_lshl_add_u64 v[244:245], s[36:37], 0, v[134:135]
	ds_read_b128 v[34:37], v141 offset:16384
	ds_read_b128 v[42:45], v141 offset:17408
	ds_read_b128 v[50:53], v141 offset:18432
	ds_read_b128 v[58:61], v141 offset:19456
	ds_read_b128 v[114:117], v141 offset:20480
	ds_read_b128 v[118:121], v141 offset:21504
	ds_read_b128 v[122:125], v141 offset:22528
	ds_read_b128 v[126:129], v141 offset:23552
	global_load_lds_dwordx4 v[142:143], off
	v_lshl_add_u64 v[142:143], v[244:245], 0, s[12:13]
	s_add_i32 m0, s62, 0x2000
	s_add_i32 s62, s55, s21
	global_load_lds_dwordx4 v[142:143], off
	s_mov_b32 m0, s62
	v_mov_b32_e32 v139, v131
	global_load_lds_dwordx4 v130, s[38:39]
	s_add_i32 m0, s62, 0x2000
	v_lshl_add_u64 v[246:247], s[34:35], 0, v[138:139]
	v_mov_b32_e32 v133, v131
	global_load_lds_dwordx4 v134, s[38:39]
	v_lshl_add_u64 v[142:143], v[246:247], 0, s[12:13]
	s_mov_b32 m0, s33
	v_lshl_add_u64 v[248:249], s[34:35], 0, v[132:133]
	global_load_lds_dwordx4 v[142:143], off
	v_lshl_add_u64 v[142:143], v[248:249], 0, s[12:13]
	s_mov_b32 m0, s44
	s_nop 0
	global_load_lds_dwordx4 v[142:143], off
	s_waitcnt vmcnt(8)
	s_waitcnt lgkmcnt(0)
	s_barrier
	s_setprio 1
	s_waitcnt lgkmcnt(0)
	v_mfma_f32_16x16x32_bf16 v[142:145], v[2:5], v[34:37], 0
	v_mfma_f32_16x16x32_bf16 v[148:151], v[10:13], v[34:37], 0
	v_mfma_f32_16x16x32_bf16 v[152:155], v[2:5], v[50:53], 0
	v_mfma_f32_16x16x32_bf16 v[156:159], v[10:13], v[50:53], 0
	v_mfma_f32_16x16x32_bf16 v[160:163], v[2:5], v[114:117], 0
	v_mfma_f32_16x16x32_bf16 v[164:167], v[10:13], v[114:117], 0
	v_mfma_f32_16x16x32_bf16 v[2:5], v[2:5], v[122:125], 0
	v_mfma_f32_16x16x32_bf16 v[10:13], v[10:13], v[122:125], 0
	v_mfma_f32_16x16x32_bf16 v[142:145], v[6:9], v[42:45], v[142:145]
	v_mfma_f32_16x16x32_bf16 v[148:151], v[14:17], v[42:45], v[148:151]
	v_mfma_f32_16x16x32_bf16 v[152:155], v[6:9], v[58:61], v[152:155]
	v_mfma_f32_16x16x32_bf16 v[156:159], v[14:17], v[58:61], v[156:159]
	v_mfma_f32_16x16x32_bf16 v[160:163], v[6:9], v[118:121], v[160:163]
	v_mfma_f32_16x16x32_bf16 v[164:167], v[14:17], v[118:121], v[164:167]
	v_mfma_f32_16x16x32_bf16 v[168:171], v[6:9], v[126:129], v[2:5]
	v_mfma_f32_16x16x32_bf16 v[172:175], v[14:17], v[126:129], v[10:13]
	s_setprio 0
	s_setprio 1
	v_mfma_f32_16x16x32_bf16 v[2:5], v[18:21], v[34:37], 0
	v_mfma_f32_16x16x32_bf16 v[6:9], v[26:29], v[34:37], 0
	v_mfma_f32_16x16x32_bf16 v[10:13], v[18:21], v[50:53], 0
	v_mfma_f32_16x16x32_bf16 v[14:17], v[26:29], v[50:53], 0
	v_mfma_f32_16x16x32_bf16 v[34:37], v[18:21], v[114:117], 0
	v_mfma_f32_16x16x32_bf16 v[50:53], v[26:29], v[114:117], 0
	v_mfma_f32_16x16x32_bf16 v[18:21], v[18:21], v[122:125], 0
	v_mfma_f32_16x16x32_bf16 v[26:29], v[26:29], v[122:125], 0
	v_mfma_f32_16x16x32_bf16 v[114:117], v[22:25], v[42:45], v[2:5]
	v_mfma_f32_16x16x32_bf16 v[122:125], v[30:33], v[42:45], v[6:9]
	v_mfma_f32_16x16x32_bf16 v[184:187], v[22:25], v[118:121], v[34:37]
	v_mfma_f32_16x16x32_bf16 v[118:121], v[30:33], v[118:121], v[50:53]
	v_mfma_f32_16x16x32_bf16 v[188:191], v[22:25], v[126:129], v[18:21]
	v_mfma_f32_16x16x32_bf16 v[126:129], v[30:33], v[126:129], v[26:29]
	v_mfma_f32_16x16x32_bf16 v[176:179], v[22:25], v[58:61], v[10:13]
	v_mfma_f32_16x16x32_bf16 v[180:183], v[30:33], v[58:61], v[14:17]
	s_setprio 0
	s_barrier
	s_add_i32 s62, 0, 0x18000
	v_add_u32_e32 v2, s62, v140
	s_add_i32 s63, 0, 0x1c000
	ds_read_b128 v[192:195], v2
	ds_read_b128 v[196:199], v2 offset:1024
	ds_read_b128 v[200:203], v2 offset:2048
	ds_read_b128 v[204:207], v2 offset:3072
	v_add_u32_e32 v2, s63, v140
	ds_read_b128 v[208:211], v2
	ds_read_b128 v[212:215], v2 offset:1024
	ds_read_b128 v[216:219], v2 offset:2048
	ds_read_b128 v[220:223], v2 offset:3072
	s_mov_b32 m0, s45
	ds_read_b128 v[42:45], v141 offset:32768
	ds_read_b128 v[50:53], v141 offset:33792
	ds_read_b128 v[58:61], v141 offset:34816
	ds_read_b128 v[224:227], v141 offset:35840
	ds_read_b128 v[228:231], v141 offset:36864
	ds_read_b128 v[232:235], v141 offset:37888
	ds_read_b128 v[236:239], v141 offset:38912
	ds_read_b128 v[240:243], v141 offset:39936
	global_load_lds_dwordx4 v138, s[40:41]
	s_mov_b32 m0, s46
	s_nop 0
	global_load_lds_dwordx4 v132, s[40:41]
	s_waitcnt vmcnt(8)
	s_waitcnt lgkmcnt(0)
	s_barrier
	s_setprio 1
	s_waitcnt lgkmcnt(0)
	v_mfma_f32_16x16x32_bf16 v[2:5], v[192:195], v[42:45], v[66:69]
	v_mfma_f32_16x16x32_bf16 v[6:9], v[200:203], v[42:45], v[70:73]
	v_mfma_f32_16x16x32_bf16 v[10:13], v[192:195], v[58:61], v[74:77]
	v_mfma_f32_16x16x32_bf16 v[14:17], v[200:203], v[58:61], v[78:81]
	v_mfma_f32_16x16x32_bf16 v[18:21], v[192:195], v[228:231], v[82:85]
	v_mfma_f32_16x16x32_bf16 v[22:25], v[200:203], v[228:231], v[86:89]
	v_mfma_f32_16x16x32_bf16 v[26:29], v[192:195], v[236:239], v[90:93]
	v_mfma_f32_16x16x32_bf16 v[30:33], v[200:203], v[236:239], v[94:97]
	v_mfma_f32_16x16x32_bf16 v[2:5], v[196:199], v[50:53], v[2:5]
	v_mfma_f32_16x16x32_bf16 v[6:9], v[204:207], v[50:53], v[6:9]
	v_mfma_f32_16x16x32_bf16 v[10:13], v[196:199], v[224:227], v[10:13]
	v_mfma_f32_16x16x32_bf16 v[14:17], v[204:207], v[224:227], v[14:17]
	v_mfma_f32_16x16x32_bf16 v[18:21], v[196:199], v[232:235], v[18:21]
	v_mfma_f32_16x16x32_bf16 v[22:25], v[204:207], v[232:235], v[22:25]
	v_mfma_f32_16x16x32_bf16 v[26:29], v[196:199], v[240:243], v[26:29]
	v_mfma_f32_16x16x32_bf16 v[30:33], v[204:207], v[240:243], v[30:33]
	s_setprio 0
	s_setprio 1
	v_mfma_f32_16x16x32_bf16 v[34:37], v[208:211], v[42:45], v[98:101]
	v_mfma_f32_16x16x32_bf16 v[38:41], v[216:219], v[42:45], v[38:41]
	v_mfma_f32_16x16x32_bf16 v[34:37], v[212:215], v[50:53], v[34:37]
	v_mfma_f32_16x16x32_bf16 v[38:41], v[220:223], v[50:53], v[38:41]
	v_mfma_f32_16x16x32_bf16 v[42:45], v[208:211], v[58:61], v[102:105]
	v_mfma_f32_16x16x32_bf16 v[46:49], v[216:219], v[58:61], v[46:49]
	v_mfma_f32_16x16x32_bf16 v[50:53], v[208:211], v[228:231], v[106:109]
	v_mfma_f32_16x16x32_bf16 v[54:57], v[216:219], v[228:231], v[54:57]
	v_mfma_f32_16x16x32_bf16 v[58:61], v[208:211], v[236:239], v[110:113]
	v_mfma_f32_16x16x32_bf16 v[62:65], v[216:219], v[236:239], v[62:65]
	v_mfma_f32_16x16x32_bf16 v[42:45], v[212:215], v[224:227], v[42:45]
	v_mfma_f32_16x16x32_bf16 v[46:49], v[220:223], v[224:227], v[46:49]
	v_mfma_f32_16x16x32_bf16 v[50:53], v[212:215], v[232:235], v[50:53]
	v_mfma_f32_16x16x32_bf16 v[54:57], v[220:223], v[232:235], v[54:57]
	v_mfma_f32_16x16x32_bf16 v[58:61], v[212:215], v[240:243], v[58:61]
	v_mfma_f32_16x16x32_bf16 v[62:65], v[220:223], v[240:243], v[62:65]
	s_setprio 0
	s_barrier
	s_add_i32 s62, s62, s21
	v_lshl_add_u64 v[66:67], v[136:137], 0, s[14:15]
	s_mov_b32 m0, s62
	ds_read_b128 v[102:105], v141 offset:49152
	ds_read_b128 v[106:109], v141 offset:50176
	ds_read_b128 v[110:113], v141 offset:51200
	ds_read_b128 v[224:227], v141 offset:52224
	ds_read_b128 v[228:231], v141 offset:53248
	ds_read_b128 v[232:235], v141 offset:54272
	ds_read_b128 v[236:239], v141 offset:55296
	ds_read_b128 v[240:243], v141 offset:56320
	global_load_lds_dwordx4 v[66:67], off
	v_lshl_add_u64 v[66:67], v[244:245], 0, s[14:15]
	s_add_i32 m0, s62, 0x2000
	s_add_i32 s62, s63, s21
	global_load_lds_dwordx4 v[66:67], off
	s_mov_b32 m0, s62
	v_lshl_add_u64 v[66:67], v[246:247], 0, s[14:15]
	global_load_lds_dwordx4 v130, s[42:43]
	s_add_i32 m0, s62, 0x2000
	s_nop 0
	global_load_lds_dwordx4 v134, s[42:43]
	s_mov_b32 m0, s50
	s_nop 0
	global_load_lds_dwordx4 v[66:67], off
	v_lshl_add_u64 v[66:67], v[248:249], 0, s[14:15]
	s_mov_b32 m0, s51
	s_nop 0
	global_load_lds_dwordx4 v[66:67], off
	s_waitcnt vmcnt(8)
	s_waitcnt lgkmcnt(0)
	s_barrier
	s_setprio 1
	s_waitcnt lgkmcnt(0)
	v_mfma_f32_16x16x32_bf16 v[66:69], v[192:195], v[102:105], v[142:145]
	v_mfma_f32_16x16x32_bf16 v[70:73], v[200:203], v[102:105], v[148:151]
	v_mfma_f32_16x16x32_bf16 v[74:77], v[192:195], v[110:113], v[152:155]
	v_mfma_f32_16x16x32_bf16 v[78:81], v[200:203], v[110:113], v[156:159]
	v_mfma_f32_16x16x32_bf16 v[82:85], v[192:195], v[228:231], v[160:163]
	v_mfma_f32_16x16x32_bf16 v[86:89], v[200:203], v[228:231], v[164:167]
	v_mfma_f32_16x16x32_bf16 v[90:93], v[192:195], v[236:239], v[168:171]
	v_mfma_f32_16x16x32_bf16 v[94:97], v[200:203], v[236:239], v[172:175]
	v_mfma_f32_16x16x32_bf16 v[66:69], v[196:199], v[106:109], v[66:69]
	v_mfma_f32_16x16x32_bf16 v[70:73], v[204:207], v[106:109], v[70:73]
	v_mfma_f32_16x16x32_bf16 v[74:77], v[196:199], v[224:227], v[74:77]
	v_mfma_f32_16x16x32_bf16 v[78:81], v[204:207], v[224:227], v[78:81]
	v_mfma_f32_16x16x32_bf16 v[82:85], v[196:199], v[232:235], v[82:85]
	v_mfma_f32_16x16x32_bf16 v[86:89], v[204:207], v[232:235], v[86:89]
	v_mfma_f32_16x16x32_bf16 v[90:93], v[196:199], v[240:243], v[90:93]
	v_mfma_f32_16x16x32_bf16 v[94:97], v[204:207], v[240:243], v[94:97]
	s_setprio 0
	s_setprio 1
	v_mfma_f32_16x16x32_bf16 v[98:101], v[208:211], v[102:105], v[114:117]
	v_mfma_f32_16x16x32_bf16 v[102:105], v[216:219], v[102:105], v[122:125]
	v_mfma_f32_16x16x32_bf16 v[98:101], v[212:215], v[106:109], v[98:101]
	v_mfma_f32_16x16x32_bf16 v[102:105], v[220:223], v[106:109], v[102:105]
	v_mfma_f32_16x16x32_bf16 v[106:109], v[208:211], v[110:113], v[176:179]
	v_mfma_f32_16x16x32_bf16 v[110:113], v[216:219], v[110:113], v[180:183]
	v_mfma_f32_16x16x32_bf16 v[114:117], v[208:211], v[228:231], v[184:187]
	v_mfma_f32_16x16x32_bf16 v[118:121], v[216:219], v[228:231], v[118:121]
	v_mfma_f32_16x16x32_bf16 v[122:125], v[208:211], v[236:239], v[188:191]
	v_mfma_f32_16x16x32_bf16 v[126:129], v[216:219], v[236:239], v[126:129]
	v_mfma_f32_16x16x32_bf16 v[106:109], v[212:215], v[224:227], v[106:109]
	v_mfma_f32_16x16x32_bf16 v[110:113], v[220:223], v[224:227], v[110:113]
	v_mfma_f32_16x16x32_bf16 v[114:117], v[212:215], v[232:235], v[114:117]
	v_mfma_f32_16x16x32_bf16 v[118:121], v[220:223], v[232:235], v[118:121]
	v_mfma_f32_16x16x32_bf16 v[122:125], v[212:215], v[240:243], v[122:125]
	v_mfma_f32_16x16x32_bf16 v[126:129], v[220:223], v[240:243], v[126:129]
	s_setprio 0
	s_barrier
	s_add_i32 s61, s61, 2
	s_cmp_ge_i32 s61, s60
	s_cbranch_scc0 .LBB0_462
	v_mov_b32_e32 v136, v130
	s_branch .LBB0_465

.LBB0_466:
	v_add_u32_e32 v133, s54, v140
	ds_read_b128 v[142:145], v133
	ds_read_b128 v[148:151], v133 offset:1024
	ds_read_b128 v[152:155], v133 offset:2048
	ds_read_b128 v[156:159], v133 offset:3072
	v_add_u32_e32 v133, s55, v140
	ds_read_b128 v[160:163], v133
	ds_read_b128 v[164:167], v133 offset:1024
	ds_read_b128 v[168:171], v133 offset:2048
	ds_read_b128 v[172:175], v133 offset:3072
	s_add_u32 s36, s34, 0xffc00080
	s_addc_u32 s37, s35, -1
	s_cmp_eq_u32 s42, 4
	s_cselect_b32 s39, s29, s37
	s_cselect_b32 s38, s28, s36
	s_cselect_b32 s37, s31, s41
	s_cselect_b32 s36, s30, s40
	s_mov_b32 m0, s52
	v_add_u32_e32 v141, 0, v1
	ds_read_b128 v[176:179], v141
	ds_read_b128 v[180:183], v141 offset:1024
	ds_read_b128 v[184:187], v141 offset:2048
	ds_read_b128 v[188:191], v141 offset:3072
	ds_read_b128 v[192:195], v141 offset:4096
	ds_read_b128 v[196:199], v141 offset:5120
	ds_read_b128 v[200:203], v141 offset:6144
	ds_read_b128 v[204:207], v141 offset:7168
	global_load_lds_dwordx4 v130, s[34:35]
	s_mov_b32 m0, s53
	v_mov_b32_e32 v133, v131
	global_load_lds_dwordx4 v132, s[34:35]
	s_waitcnt vmcnt(8)
	s_waitcnt lgkmcnt(0)
	s_barrier
	s_setprio 1
	s_waitcnt lgkmcnt(0)
	v_mfma_f32_16x16x32_bf16 v[2:5], v[142:145], v[176:179], v[2:5]
	v_mfma_f32_16x16x32_bf16 v[2:5], v[148:151], v[180:183], v[2:5]
	v_mfma_f32_16x16x32_bf16 v[6:9], v[156:159], v[180:183], v[6:9]
	v_mfma_f32_16x16x32_bf16 v[6:9], v[152:155], v[176:179], v[6:9]
	v_mfma_f32_16x16x32_bf16 v[14:17], v[152:155], v[184:187], v[14:17]
	v_mfma_f32_16x16x32_bf16 v[14:17], v[156:159], v[188:191], v[14:17]
	v_mfma_f32_16x16x32_bf16 v[10:13], v[148:151], v[188:191], v[10:13]
	v_mfma_f32_16x16x32_bf16 v[10:13], v[142:145], v[184:187], v[10:13]
	v_mfma_f32_16x16x32_bf16 v[18:21], v[142:145], v[192:195], v[18:21]
	v_mfma_f32_16x16x32_bf16 v[18:21], v[148:151], v[196:199], v[18:21]
	v_mfma_f32_16x16x32_bf16 v[22:25], v[156:159], v[196:199], v[22:25]
	v_mfma_f32_16x16x32_bf16 v[22:25], v[152:155], v[192:195], v[22:25]
	v_mfma_f32_16x16x32_bf16 v[30:33], v[152:155], v[200:203], v[30:33]
	v_mfma_f32_16x16x32_bf16 v[30:33], v[156:159], v[204:207], v[30:33]
	v_mfma_f32_16x16x32_bf16 v[26:29], v[148:151], v[204:207], v[26:29]
	v_mfma_f32_16x16x32_bf16 v[26:29], v[142:145], v[200:203], v[26:29]
	s_setprio 0
	s_setprio 1
	v_mfma_f32_16x16x32_bf16 v[34:37], v[160:163], v[176:179], v[34:37]
	v_mfma_f32_16x16x32_bf16 v[34:37], v[164:167], v[180:183], v[34:37]
	v_mfma_f32_16x16x32_bf16 v[38:41], v[172:175], v[180:183], v[38:41]
	v_mfma_f32_16x16x32_bf16 v[38:41], v[168:171], v[176:179], v[38:41]
	v_mfma_f32_16x16x32_bf16 v[46:49], v[168:171], v[184:187], v[46:49]
	v_mfma_f32_16x16x32_bf16 v[46:49], v[172:175], v[188:191], v[46:49]
	v_mfma_f32_16x16x32_bf16 v[42:45], v[164:167], v[188:191], v[42:45]
	v_mfma_f32_16x16x32_bf16 v[42:45], v[160:163], v[184:187], v[42:45]
	v_mfma_f32_16x16x32_bf16 v[50:53], v[160:163], v[192:195], v[50:53]
	v_mfma_f32_16x16x32_bf16 v[50:53], v[164:167], v[196:199], v[50:53]
	v_mfma_f32_16x16x32_bf16 v[54:57], v[172:175], v[196:199], v[54:57]
	v_mfma_f32_16x16x32_bf16 v[54:57], v[168:171], v[192:195], v[54:57]
	v_mfma_f32_16x16x32_bf16 v[62:65], v[168:171], v[200:203], v[62:65]
	v_mfma_f32_16x16x32_bf16 v[62:65], v[172:175], v[204:207], v[62:65]
	v_mfma_f32_16x16x32_bf16 v[58:61], v[164:167], v[204:207], v[58:61]
	v_mfma_f32_16x16x32_bf16 v[58:61], v[160:163], v[200:203], v[58:61]
	s_setprio 0
	s_barrier
	s_add_i32 s43, s54, s21
	s_mov_b32 m0, s43
	ds_read_b128 v[176:179], v141 offset:16384
	ds_read_b128 v[180:183], v141 offset:17408
	ds_read_b128 v[184:187], v141 offset:18432
	ds_read_b128 v[188:191], v141 offset:19456
	ds_read_b128 v[192:195], v141 offset:20480
	ds_read_b128 v[196:199], v141 offset:21504
	ds_read_b128 v[200:203], v141 offset:22528
	ds_read_b128 v[204:207], v141 offset:23552
	global_load_lds_dwordx4 v136, s[36:37]
	s_add_i32 m0, s43, 0x2000
	s_add_u32 s60, s36, 0x80000
	s_addc_u32 s61, s37, 0
	s_add_i32 s43, s55, s21
	global_load_lds_dwordx4 v134, s[36:37]
	s_mov_b32 m0, s43
	v_mov_b32_e32 v137, v131
	global_load_lds_dwordx4 v136, s[60:61]
	s_add_i32 m0, s43, 0x2000
	v_mov_b32_e32 v135, v131
	global_load_lds_dwordx4 v134, s[60:61]
	s_mov_b32 m0, s33
	v_lshl_add_u64 v[138:139], s[36:37], 0, v[136:137]
	global_load_lds_dwordx4 v130, s[38:39]
	s_mov_b32 m0, s44
	v_lshl_add_u64 v[208:209], s[36:37], 0, v[134:135]
	global_load_lds_dwordx4 v132, s[38:39]
	s_waitcnt vmcnt(8)
	s_waitcnt lgkmcnt(0)
	v_lshl_add_u64 v[210:211], s[38:39], 0, v[130:131]
	v_lshl_add_u64 v[212:213], s[38:39], 0, v[132:133]
	s_barrier
	s_setprio 1
	s_waitcnt lgkmcnt(0)
	v_mfma_f32_16x16x32_bf16 v[66:69], v[142:145], v[176:179], v[66:69]
	v_mfma_f32_16x16x32_bf16 v[66:69], v[148:151], v[180:183], v[66:69]
	v_mfma_f32_16x16x32_bf16 v[70:73], v[156:159], v[180:183], v[70:73]
	v_mfma_f32_16x16x32_bf16 v[70:73], v[152:155], v[176:179], v[70:73]
	v_mfma_f32_16x16x32_bf16 v[78:81], v[152:155], v[184:187], v[78:81]
	v_mfma_f32_16x16x32_bf16 v[78:81], v[156:159], v[188:191], v[78:81]
	v_mfma_f32_16x16x32_bf16 v[74:77], v[148:151], v[188:191], v[74:77]
	v_mfma_f32_16x16x32_bf16 v[74:77], v[142:145], v[184:187], v[74:77]
	v_mfma_f32_16x16x32_bf16 v[82:85], v[142:145], v[192:195], v[82:85]
	v_mfma_f32_16x16x32_bf16 v[82:85], v[148:151], v[196:199], v[82:85]
	v_mfma_f32_16x16x32_bf16 v[86:89], v[156:159], v[196:199], v[86:89]
	v_mfma_f32_16x16x32_bf16 v[86:89], v[152:155], v[192:195], v[86:89]
	v_mfma_f32_16x16x32_bf16 v[94:97], v[152:155], v[200:203], v[94:97]
	v_mfma_f32_16x16x32_bf16 v[94:97], v[156:159], v[204:207], v[94:97]
	v_mfma_f32_16x16x32_bf16 v[90:93], v[148:151], v[204:207], v[90:93]
	v_mfma_f32_16x16x32_bf16 v[90:93], v[142:145], v[200:203], v[90:93]
	s_setprio 0
	s_setprio 1
	v_mfma_f32_16x16x32_bf16 v[98:101], v[160:163], v[176:179], v[98:101]
	v_mfma_f32_16x16x32_bf16 v[98:101], v[164:167], v[180:183], v[98:101]
	v_mfma_f32_16x16x32_bf16 v[102:105], v[172:175], v[180:183], v[102:105]
	v_mfma_f32_16x16x32_bf16 v[102:105], v[168:171], v[176:179], v[102:105]
	v_mfma_f32_16x16x32_bf16 v[110:113], v[168:171], v[184:187], v[110:113]
	v_mfma_f32_16x16x32_bf16 v[110:113], v[172:175], v[188:191], v[110:113]
	v_mfma_f32_16x16x32_bf16 v[106:109], v[164:167], v[188:191], v[106:109]
	v_mfma_f32_16x16x32_bf16 v[106:109], v[160:163], v[184:187], v[106:109]
	v_mfma_f32_16x16x32_bf16 v[114:117], v[160:163], v[192:195], v[114:117]
	v_mfma_f32_16x16x32_bf16 v[114:117], v[164:167], v[196:199], v[114:117]
	v_mfma_f32_16x16x32_bf16 v[118:121], v[172:175], v[196:199], v[118:121]
	v_mfma_f32_16x16x32_bf16 v[118:121], v[168:171], v[192:195], v[118:121]
	v_mfma_f32_16x16x32_bf16 v[126:129], v[168:171], v[200:203], v[126:129]
	v_mfma_f32_16x16x32_bf16 v[126:129], v[172:175], v[204:207], v[126:129]
	v_mfma_f32_16x16x32_bf16 v[122:125], v[164:167], v[204:207], v[122:125]
	v_mfma_f32_16x16x32_bf16 v[122:125], v[160:163], v[200:203], v[122:125]
	s_setprio 0
	s_barrier
	s_add_i32 s43, 0, 0x18000
	v_add_u32_e32 v135, s43, v140
	s_add_i32 s60, 0, 0x1c000
	ds_read_b128 v[142:145], v135
	ds_read_b128 v[148:151], v135 offset:1024
	ds_read_b128 v[152:155], v135 offset:2048
	ds_read_b128 v[156:159], v135 offset:3072
	v_add_u32_e32 v135, s60, v140
	ds_read_b128 v[160:163], v135
	ds_read_b128 v[164:167], v135 offset:1024
	ds_read_b128 v[168:171], v135 offset:2048
	ds_read_b128 v[172:175], v135 offset:3072
	s_add_u32 s38, s38, 0x400000
	s_addc_u32 s39, s39, 0
	s_mov_b32 m0, s45
	ds_read_b128 v[176:179], v141 offset:32768
	ds_read_b128 v[180:183], v141 offset:33792
	ds_read_b128 v[184:187], v141 offset:34816
	ds_read_b128 v[188:191], v141 offset:35840
	ds_read_b128 v[192:195], v141 offset:36864
	ds_read_b128 v[196:199], v141 offset:37888
	ds_read_b128 v[200:203], v141 offset:38912
	ds_read_b128 v[204:207], v141 offset:39936
	global_load_lds_dwordx4 v130, s[38:39]
	s_mov_b32 m0, s46
	s_nop 0
	global_load_lds_dwordx4 v132, s[38:39]
	s_waitcnt vmcnt(8)
	s_waitcnt lgkmcnt(0)
	s_barrier
	s_setprio 1
	s_waitcnt lgkmcnt(0)
	v_mfma_f32_16x16x32_bf16 v[2:5], v[142:145], v[176:179], v[2:5]
	v_mfma_f32_16x16x32_bf16 v[2:5], v[148:151], v[180:183], v[2:5]
	v_mfma_f32_16x16x32_bf16 v[6:9], v[156:159], v[180:183], v[6:9]
	v_mfma_f32_16x16x32_bf16 v[6:9], v[152:155], v[176:179], v[6:9]
	v_mfma_f32_16x16x32_bf16 v[14:17], v[152:155], v[184:187], v[14:17]
	v_mfma_f32_16x16x32_bf16 v[14:17], v[156:159], v[188:191], v[14:17]
	v_mfma_f32_16x16x32_bf16 v[10:13], v[148:151], v[188:191], v[10:13]
	v_mfma_f32_16x16x32_bf16 v[10:13], v[142:145], v[184:187], v[10:13]
	v_mfma_f32_16x16x32_bf16 v[18:21], v[142:145], v[192:195], v[18:21]
	v_mfma_f32_16x16x32_bf16 v[18:21], v[148:151], v[196:199], v[18:21]
	v_mfma_f32_16x16x32_bf16 v[22:25], v[156:159], v[196:199], v[22:25]
	v_mfma_f32_16x16x32_bf16 v[22:25], v[152:155], v[192:195], v[22:25]
	v_mfma_f32_16x16x32_bf16 v[30:33], v[152:155], v[200:203], v[30:33]
	v_mfma_f32_16x16x32_bf16 v[30:33], v[156:159], v[204:207], v[30:33]
	v_mfma_f32_16x16x32_bf16 v[26:29], v[148:151], v[204:207], v[26:29]
	v_mfma_f32_16x16x32_bf16 v[26:29], v[142:145], v[200:203], v[26:29]
	s_setprio 0
	s_setprio 1
	v_mfma_f32_16x16x32_bf16 v[34:37], v[160:163], v[176:179], v[34:37]
	v_mfma_f32_16x16x32_bf16 v[34:37], v[164:167], v[180:183], v[34:37]
	v_mfma_f32_16x16x32_bf16 v[38:41], v[172:175], v[180:183], v[38:41]
	v_mfma_f32_16x16x32_bf16 v[38:41], v[168:171], v[176:179], v[38:41]
	v_mfma_f32_16x16x32_bf16 v[46:49], v[168:171], v[184:187], v[46:49]
	v_mfma_f32_16x16x32_bf16 v[46:49], v[172:175], v[188:191], v[46:49]
	v_mfma_f32_16x16x32_bf16 v[42:45], v[164:167], v[188:191], v[42:45]
	v_mfma_f32_16x16x32_bf16 v[42:45], v[160:163], v[184:187], v[42:45]
	v_mfma_f32_16x16x32_bf16 v[50:53], v[160:163], v[192:195], v[50:53]
	v_mfma_f32_16x16x32_bf16 v[50:53], v[164:167], v[196:199], v[50:53]
	v_mfma_f32_16x16x32_bf16 v[54:57], v[172:175], v[196:199], v[54:57]
	v_mfma_f32_16x16x32_bf16 v[54:57], v[168:171], v[192:195], v[54:57]
	v_mfma_f32_16x16x32_bf16 v[62:65], v[168:171], v[200:203], v[62:65]
	v_mfma_f32_16x16x32_bf16 v[62:65], v[172:175], v[204:207], v[62:65]
	v_mfma_f32_16x16x32_bf16 v[58:61], v[164:167], v[204:207], v[58:61]
	v_mfma_f32_16x16x32_bf16 v[58:61], v[160:163], v[200:203], v[58:61]
	s_setprio 0
	s_barrier
	s_add_i32 s38, s43, s21
	v_lshl_add_u64 v[138:139], v[138:139], 0, s[8:9]
	s_mov_b32 m0, s38
	ds_read_b128 v[176:179], v141 offset:49152
	ds_read_b128 v[180:183], v141 offset:50176
	ds_read_b128 v[184:187], v141 offset:51200
	ds_read_b128 v[188:191], v141 offset:52224
	ds_read_b128 v[192:195], v141 offset:53248
	ds_read_b128 v[196:199], v141 offset:54272
	ds_read_b128 v[200:203], v141 offset:55296
	ds_read_b128 v[204:207], v141 offset:56320
	global_load_lds_dwordx4 v[138:139], off
	s_add_i32 m0, s38, 0x2000
	s_add_u32 s36, s36, 0x80080
	v_lshl_add_u64 v[138:139], v[208:209], 0, s[8:9]
	s_addc_u32 s37, s37, 0
	s_add_i32 s38, s60, s21
	global_load_lds_dwordx4 v[138:139], off
	s_mov_b32 m0, s38
	v_lshl_add_u64 v[138:139], v[210:211], 0, s[8:9]
	global_load_lds_dwordx4 v136, s[36:37]
	s_add_i32 m0, s38, 0x2000
	s_nop 0
	global_load_lds_dwordx4 v134, s[36:37]
	s_mov_b32 m0, s50
	s_nop 0
	global_load_lds_dwordx4 v[138:139], off
	v_lshl_add_u64 v[138:139], v[212:213], 0, s[8:9]
	s_mov_b32 m0, s51
	s_nop 0
	global_load_lds_dwordx4 v[138:139], off
	s_waitcnt vmcnt(8)
	s_waitcnt lgkmcnt(0)
	s_barrier
	s_setprio 1
	s_waitcnt lgkmcnt(0)
	v_mfma_f32_16x16x32_bf16 v[66:69], v[142:145], v[176:179], v[66:69]
	v_mfma_f32_16x16x32_bf16 v[66:69], v[148:151], v[180:183], v[66:69]
	v_mfma_f32_16x16x32_bf16 v[70:73], v[156:159], v[180:183], v[70:73]
	v_mfma_f32_16x16x32_bf16 v[70:73], v[152:155], v[176:179], v[70:73]
	v_mfma_f32_16x16x32_bf16 v[78:81], v[152:155], v[184:187], v[78:81]
	v_mfma_f32_16x16x32_bf16 v[78:81], v[156:159], v[188:191], v[78:81]
	v_mfma_f32_16x16x32_bf16 v[74:77], v[148:151], v[188:191], v[74:77]
	v_mfma_f32_16x16x32_bf16 v[74:77], v[142:145], v[184:187], v[74:77]
	v_mfma_f32_16x16x32_bf16 v[82:85], v[142:145], v[192:195], v[82:85]
	v_mfma_f32_16x16x32_bf16 v[82:85], v[148:151], v[196:199], v[82:85]
	v_mfma_f32_16x16x32_bf16 v[86:89], v[156:159], v[196:199], v[86:89]
	v_mfma_f32_16x16x32_bf16 v[86:89], v[152:155], v[192:195], v[86:89]
	v_mfma_f32_16x16x32_bf16 v[94:97], v[152:155], v[200:203], v[94:97]
	v_mfma_f32_16x16x32_bf16 v[94:97], v[156:159], v[204:207], v[94:97]
	v_mfma_f32_16x16x32_bf16 v[90:93], v[148:151], v[204:207], v[90:93]
	v_mfma_f32_16x16x32_bf16 v[90:93], v[142:145], v[200:203], v[90:93]
	s_setprio 0
	s_setprio 1
	v_mfma_f32_16x16x32_bf16 v[98:101], v[160:163], v[176:179], v[98:101]
	v_mfma_f32_16x16x32_bf16 v[98:101], v[164:167], v[180:183], v[98:101]
	v_mfma_f32_16x16x32_bf16 v[102:105], v[172:175], v[180:183], v[102:105]
	v_mfma_f32_16x16x32_bf16 v[102:105], v[168:171], v[176:179], v[102:105]
	v_mfma_f32_16x16x32_bf16 v[110:113], v[168:171], v[184:187], v[110:113]
	v_mfma_f32_16x16x32_bf16 v[110:113], v[172:175], v[188:191], v[110:113]
	v_mfma_f32_16x16x32_bf16 v[106:109], v[164:167], v[188:191], v[106:109]
	v_mfma_f32_16x16x32_bf16 v[106:109], v[160:163], v[184:187], v[106:109]
	v_mfma_f32_16x16x32_bf16 v[114:117], v[160:163], v[192:195], v[114:117]
	v_mfma_f32_16x16x32_bf16 v[114:117], v[164:167], v[196:199], v[114:117]
	v_mfma_f32_16x16x32_bf16 v[118:121], v[172:175], v[196:199], v[118:121]
	v_mfma_f32_16x16x32_bf16 v[118:121], v[168:171], v[192:195], v[118:121]
	v_mfma_f32_16x16x32_bf16 v[126:129], v[168:171], v[200:203], v[126:129]
	v_mfma_f32_16x16x32_bf16 v[126:129], v[172:175], v[204:207], v[126:129]
	v_mfma_f32_16x16x32_bf16 v[122:125], v[164:167], v[204:207], v[122:125]
	v_mfma_f32_16x16x32_bf16 v[122:125], v[160:163], v[200:203], v[122:125]
	s_setprio 0
	s_barrier
	s_add_i32 s42, s42, 2
	s_add_u32 s34, s34, 0x100
	s_addc_u32 s35, s35, 0
	s_add_u32 s40, s40, 0x100
	s_addc_u32 s41, s41, 0
	s_cmp_gt_u32 s42, 5
	s_cbranch_scc0 .LBB0_466
	s_and_b64 vcc, exec, s[10:11]
	s_cbranch_vccz .LBB0_469
	s_barrier

.LBB0_495:
	v_add_u32_e32 v14, s58, v140
	v_add_u32_e32 v30, s59, v140
	ds_read_b128 v[2:5], v14
	ds_read_b128 v[6:9], v14 offset:1024
	ds_read_b128 v[10:13], v14 offset:2048
	ds_read_b128 v[14:17], v14 offset:3072
	ds_read_b128 v[18:21], v30
	ds_read_b128 v[22:25], v30 offset:1024
	ds_read_b128 v[26:29], v30 offset:2048
	ds_read_b128 v[30:33], v30 offset:3072
	v_add_u32_e32 v141, 0, v1
	ds_read_b128 v[34:37], v141
	ds_read_b128 v[38:41], v141 offset:1024
	ds_read_b128 v[42:45], v141 offset:2048
	ds_read_b128 v[46:49], v141 offset:3072
	ds_read_b128 v[50:53], v141 offset:4096
	ds_read_b128 v[54:57], v141 offset:5120
	ds_read_b128 v[58:61], v141 offset:6144
	ds_read_b128 v[62:65], v141 offset:7168
	s_waitcnt vmcnt(8)
	s_waitcnt lgkmcnt(0)
	s_barrier
	s_setprio 1
	s_waitcnt lgkmcnt(0)
	v_mfma_f32_16x16x32_bf16 v[66:69], v[2:5], v[34:37], 0
	v_mfma_f32_16x16x32_bf16 v[66:69], v[6:9], v[38:41], v[66:69]
	v_mfma_f32_16x16x32_bf16 v[70:73], v[10:13], v[34:37], 0
	v_mfma_f32_16x16x32_bf16 v[70:73], v[14:17], v[38:41], v[70:73]
	v_mfma_f32_16x16x32_bf16 v[78:81], v[10:13], v[42:45], 0
	v_mfma_f32_16x16x32_bf16 v[78:81], v[14:17], v[46:49], v[78:81]
	v_mfma_f32_16x16x32_bf16 v[74:77], v[2:5], v[42:45], 0
	v_mfma_f32_16x16x32_bf16 v[74:77], v[6:9], v[46:49], v[74:77]
	v_mfma_f32_16x16x32_bf16 v[82:85], v[2:5], v[50:53], 0
	v_mfma_f32_16x16x32_bf16 v[82:85], v[6:9], v[54:57], v[82:85]
	v_mfma_f32_16x16x32_bf16 v[86:89], v[10:13], v[50:53], 0
	v_mfma_f32_16x16x32_bf16 v[86:89], v[14:17], v[54:57], v[86:89]
	v_mfma_f32_16x16x32_bf16 v[94:97], v[10:13], v[58:61], 0
	v_mfma_f32_16x16x32_bf16 v[94:97], v[14:17], v[62:65], v[94:97]
	v_mfma_f32_16x16x32_bf16 v[90:93], v[2:5], v[58:61], 0
	v_mfma_f32_16x16x32_bf16 v[90:93], v[6:9], v[62:65], v[90:93]
	s_setprio 0
	s_setprio 1
	v_mfma_f32_16x16x32_bf16 v[98:101], v[18:21], v[34:37], 0
	v_mfma_f32_16x16x32_bf16 v[34:37], v[26:29], v[34:37], 0
	v_mfma_f32_16x16x32_bf16 v[102:105], v[18:21], v[42:45], 0
	v_mfma_f32_16x16x32_bf16 v[42:45], v[26:29], v[42:45], 0
	v_mfma_f32_16x16x32_bf16 v[106:109], v[18:21], v[50:53], 0
	v_mfma_f32_16x16x32_bf16 v[50:53], v[26:29], v[50:53], 0
	v_mfma_f32_16x16x32_bf16 v[110:113], v[18:21], v[58:61], 0
	v_mfma_f32_16x16x32_bf16 v[58:61], v[26:29], v[58:61], 0
	v_mfma_f32_16x16x32_bf16 v[98:101], v[22:25], v[38:41], v[98:101]
	v_mfma_f32_16x16x32_bf16 v[38:41], v[30:33], v[38:41], v[34:37]
	v_mfma_f32_16x16x32_bf16 v[102:105], v[22:25], v[46:49], v[102:105]
	v_mfma_f32_16x16x32_bf16 v[46:49], v[30:33], v[46:49], v[42:45]
	v_mfma_f32_16x16x32_bf16 v[106:109], v[22:25], v[54:57], v[106:109]
	v_mfma_f32_16x16x32_bf16 v[54:57], v[30:33], v[54:57], v[50:53]
	v_mfma_f32_16x16x32_bf16 v[110:113], v[22:25], v[62:65], v[110:113]
	v_mfma_f32_16x16x32_bf16 v[62:65], v[30:33], v[62:65], v[58:61]
	s_setprio 0
	s_barrier
	v_lshl_add_u64 v[136:137], s[38:39], 0, v[130:131]
	s_add_i32 s62, s58, s46
	v_mov_b32_e32 v135, v131
	v_lshl_add_u64 v[142:143], v[136:137], 0, s[10:11]
	s_mov_b32 m0, s62
	v_lshl_add_u64 v[244:245], s[38:39], 0, v[134:135]
	ds_read_b128 v[34:37], v141 offset:16384
	ds_read_b128 v[42:45], v141 offset:17408
	ds_read_b128 v[50:53], v141 offset:18432
	ds_read_b128 v[58:61], v141 offset:19456
	ds_read_b128 v[114:117], v141 offset:20480
	ds_read_b128 v[118:121], v141 offset:21504
	ds_read_b128 v[122:125], v141 offset:22528
	ds_read_b128 v[126:129], v141 offset:23552
	global_load_lds_dwordx4 v[142:143], off
	v_lshl_add_u64 v[142:143], v[244:245], 0, s[10:11]
	s_add_i32 m0, s62, 0x2000
	s_add_i32 s62, s59, s46
	global_load_lds_dwordx4 v[142:143], off
	s_mov_b32 m0, s62
	v_mov_b32_e32 v139, v131
	global_load_lds_dwordx4 v130, s[40:41]
	s_add_i32 m0, s62, 0x2000
	v_lshl_add_u64 v[246:247], s[36:37], 0, v[138:139]
	v_mov_b32_e32 v133, v131
	global_load_lds_dwordx4 v134, s[40:41]
	v_lshl_add_u64 v[142:143], v[246:247], 0, s[10:11]
	s_mov_b32 m0, s47
	v_lshl_add_u64 v[248:249], s[36:37], 0, v[132:133]
	global_load_lds_dwordx4 v[142:143], off
	v_lshl_add_u64 v[142:143], v[248:249], 0, s[10:11]
	s_mov_b32 m0, s48
	s_nop 0
	global_load_lds_dwordx4 v[142:143], off
	s_waitcnt vmcnt(8)
	s_waitcnt lgkmcnt(0)
	s_barrier
	s_setprio 1
	s_waitcnt lgkmcnt(0)
	v_mfma_f32_16x16x32_bf16 v[142:145], v[2:5], v[34:37], 0
	v_mfma_f32_16x16x32_bf16 v[148:151], v[10:13], v[34:37], 0
	v_mfma_f32_16x16x32_bf16 v[152:155], v[2:5], v[50:53], 0
	v_mfma_f32_16x16x32_bf16 v[156:159], v[10:13], v[50:53], 0
	v_mfma_f32_16x16x32_bf16 v[160:163], v[2:5], v[114:117], 0
	v_mfma_f32_16x16x32_bf16 v[164:167], v[10:13], v[114:117], 0
	v_mfma_f32_16x16x32_bf16 v[2:5], v[2:5], v[122:125], 0
	v_mfma_f32_16x16x32_bf16 v[10:13], v[10:13], v[122:125], 0
	v_mfma_f32_16x16x32_bf16 v[142:145], v[6:9], v[42:45], v[142:145]
	v_mfma_f32_16x16x32_bf16 v[148:151], v[14:17], v[42:45], v[148:151]
	v_mfma_f32_16x16x32_bf16 v[152:155], v[6:9], v[58:61], v[152:155]
	v_mfma_f32_16x16x32_bf16 v[156:159], v[14:17], v[58:61], v[156:159]
	v_mfma_f32_16x16x32_bf16 v[160:163], v[6:9], v[118:121], v[160:163]
	v_mfma_f32_16x16x32_bf16 v[164:167], v[14:17], v[118:121], v[164:167]
	v_mfma_f32_16x16x32_bf16 v[168:171], v[6:9], v[126:129], v[2:5]
	v_mfma_f32_16x16x32_bf16 v[172:175], v[14:17], v[126:129], v[10:13]
	s_setprio 0
	s_setprio 1
	v_mfma_f32_16x16x32_bf16 v[2:5], v[18:21], v[34:37], 0
	v_mfma_f32_16x16x32_bf16 v[6:9], v[26:29], v[34:37], 0
	v_mfma_f32_16x16x32_bf16 v[10:13], v[18:21], v[50:53], 0
	v_mfma_f32_16x16x32_bf16 v[14:17], v[26:29], v[50:53], 0
	v_mfma_f32_16x16x32_bf16 v[34:37], v[18:21], v[114:117], 0
	v_mfma_f32_16x16x32_bf16 v[50:53], v[26:29], v[114:117], 0
	v_mfma_f32_16x16x32_bf16 v[18:21], v[18:21], v[122:125], 0
	v_mfma_f32_16x16x32_bf16 v[26:29], v[26:29], v[122:125], 0
	v_mfma_f32_16x16x32_bf16 v[114:117], v[22:25], v[42:45], v[2:5]
	v_mfma_f32_16x16x32_bf16 v[122:125], v[30:33], v[42:45], v[6:9]
	v_mfma_f32_16x16x32_bf16 v[184:187], v[22:25], v[118:121], v[34:37]
	v_mfma_f32_16x16x32_bf16 v[118:121], v[30:33], v[118:121], v[50:53]
	v_mfma_f32_16x16x32_bf16 v[188:191], v[22:25], v[126:129], v[18:21]
	v_mfma_f32_16x16x32_bf16 v[126:129], v[30:33], v[126:129], v[26:29]
	v_mfma_f32_16x16x32_bf16 v[176:179], v[22:25], v[58:61], v[10:13]
	v_mfma_f32_16x16x32_bf16 v[180:183], v[30:33], v[58:61], v[14:17]
	s_setprio 0
	s_barrier
	s_add_i32 s62, 0, 0x18000
	v_add_u32_e32 v2, s62, v140
	s_add_i32 s63, 0, 0x1c000
	ds_read_b128 v[192:195], v2
	ds_read_b128 v[196:199], v2 offset:1024
	ds_read_b128 v[200:203], v2 offset:2048
	ds_read_b128 v[204:207], v2 offset:3072
	v_add_u32_e32 v2, s63, v140
	ds_read_b128 v[208:211], v2
	ds_read_b128 v[212:215], v2 offset:1024
	ds_read_b128 v[216:219], v2 offset:2048
	ds_read_b128 v[220:223], v2 offset:3072
	s_mov_b32 m0, s49
	ds_read_b128 v[42:45], v141 offset:32768
	ds_read_b128 v[50:53], v141 offset:33792
	ds_read_b128 v[58:61], v141 offset:34816
	ds_read_b128 v[224:227], v141 offset:35840
	ds_read_b128 v[228:231], v141 offset:36864
	ds_read_b128 v[232:235], v141 offset:37888
	ds_read_b128 v[236:239], v141 offset:38912
	ds_read_b128 v[240:243], v141 offset:39936
	global_load_lds_dwordx4 v138, s[42:43]
	s_mov_b32 m0, s50
	s_nop 0
	global_load_lds_dwordx4 v132, s[42:43]
	s_waitcnt vmcnt(8)
	s_waitcnt lgkmcnt(0)
	s_barrier
	s_setprio 1
	s_waitcnt lgkmcnt(0)
	v_mfma_f32_16x16x32_bf16 v[2:5], v[192:195], v[42:45], v[66:69]
	v_mfma_f32_16x16x32_bf16 v[6:9], v[200:203], v[42:45], v[70:73]
	v_mfma_f32_16x16x32_bf16 v[10:13], v[192:195], v[58:61], v[74:77]
	v_mfma_f32_16x16x32_bf16 v[14:17], v[200:203], v[58:61], v[78:81]
	v_mfma_f32_16x16x32_bf16 v[18:21], v[192:195], v[228:231], v[82:85]
	v_mfma_f32_16x16x32_bf16 v[22:25], v[200:203], v[228:231], v[86:89]
	v_mfma_f32_16x16x32_bf16 v[26:29], v[192:195], v[236:239], v[90:93]
	v_mfma_f32_16x16x32_bf16 v[30:33], v[200:203], v[236:239], v[94:97]
	v_mfma_f32_16x16x32_bf16 v[2:5], v[196:199], v[50:53], v[2:5]
	v_mfma_f32_16x16x32_bf16 v[6:9], v[204:207], v[50:53], v[6:9]
	v_mfma_f32_16x16x32_bf16 v[10:13], v[196:199], v[224:227], v[10:13]
	v_mfma_f32_16x16x32_bf16 v[14:17], v[204:207], v[224:227], v[14:17]
	v_mfma_f32_16x16x32_bf16 v[18:21], v[196:199], v[232:235], v[18:21]
	v_mfma_f32_16x16x32_bf16 v[22:25], v[204:207], v[232:235], v[22:25]
	v_mfma_f32_16x16x32_bf16 v[26:29], v[196:199], v[240:243], v[26:29]
	v_mfma_f32_16x16x32_bf16 v[30:33], v[204:207], v[240:243], v[30:33]
	s_setprio 0
	s_setprio 1
	v_mfma_f32_16x16x32_bf16 v[34:37], v[208:211], v[42:45], v[98:101]
	v_mfma_f32_16x16x32_bf16 v[38:41], v[216:219], v[42:45], v[38:41]
	v_mfma_f32_16x16x32_bf16 v[34:37], v[212:215], v[50:53], v[34:37]
	v_mfma_f32_16x16x32_bf16 v[38:41], v[220:223], v[50:53], v[38:41]
	v_mfma_f32_16x16x32_bf16 v[42:45], v[208:211], v[58:61], v[102:105]
	v_mfma_f32_16x16x32_bf16 v[46:49], v[216:219], v[58:61], v[46:49]
	v_mfma_f32_16x16x32_bf16 v[50:53], v[208:211], v[228:231], v[106:109]
	v_mfma_f32_16x16x32_bf16 v[54:57], v[216:219], v[228:231], v[54:57]
	v_mfma_f32_16x16x32_bf16 v[58:61], v[208:211], v[236:239], v[110:113]
	v_mfma_f32_16x16x32_bf16 v[62:65], v[216:219], v[236:239], v[62:65]
	v_mfma_f32_16x16x32_bf16 v[42:45], v[212:215], v[224:227], v[42:45]
	v_mfma_f32_16x16x32_bf16 v[46:49], v[220:223], v[224:227], v[46:49]
	v_mfma_f32_16x16x32_bf16 v[50:53], v[212:215], v[232:235], v[50:53]
	v_mfma_f32_16x16x32_bf16 v[54:57], v[220:223], v[232:235], v[54:57]
	v_mfma_f32_16x16x32_bf16 v[58:61], v[212:215], v[240:243], v[58:61]
	v_mfma_f32_16x16x32_bf16 v[62:65], v[220:223], v[240:243], v[62:65]
	s_setprio 0
	s_barrier
	s_add_i32 s62, s62, s46
	v_lshl_add_u64 v[66:67], v[136:137], 0, s[12:13]
	s_mov_b32 m0, s62
	ds_read_b128 v[102:105], v141 offset:49152
	ds_read_b128 v[106:109], v141 offset:50176
	ds_read_b128 v[110:113], v141 offset:51200
	ds_read_b128 v[224:227], v141 offset:52224
	ds_read_b128 v[228:231], v141 offset:53248
	ds_read_b128 v[232:235], v141 offset:54272
	ds_read_b128 v[236:239], v141 offset:55296
	ds_read_b128 v[240:243], v141 offset:56320
	global_load_lds_dwordx4 v[66:67], off
	v_lshl_add_u64 v[66:67], v[244:245], 0, s[12:13]
	s_add_i32 m0, s62, 0x2000
	s_add_i32 s62, s63, s46
	global_load_lds_dwordx4 v[66:67], off
	s_mov_b32 m0, s62
	v_lshl_add_u64 v[66:67], v[246:247], 0, s[12:13]
	global_load_lds_dwordx4 v130, s[44:45]
	s_add_i32 m0, s62, 0x2000
	s_nop 0
	global_load_lds_dwordx4 v134, s[44:45]
	s_mov_b32 m0, s54
	s_nop 0
	global_load_lds_dwordx4 v[66:67], off
	v_lshl_add_u64 v[66:67], v[248:249], 0, s[12:13]
	s_mov_b32 m0, s55
	s_nop 0
	global_load_lds_dwordx4 v[66:67], off
	s_waitcnt vmcnt(8)
	s_waitcnt lgkmcnt(0)
	s_barrier
	s_setprio 1
	s_waitcnt lgkmcnt(0)
	v_mfma_f32_16x16x32_bf16 v[66:69], v[192:195], v[102:105], v[142:145]
	v_mfma_f32_16x16x32_bf16 v[70:73], v[200:203], v[102:105], v[148:151]
	v_mfma_f32_16x16x32_bf16 v[74:77], v[192:195], v[110:113], v[152:155]
	v_mfma_f32_16x16x32_bf16 v[78:81], v[200:203], v[110:113], v[156:159]
	v_mfma_f32_16x16x32_bf16 v[82:85], v[192:195], v[228:231], v[160:163]
	v_mfma_f32_16x16x32_bf16 v[86:89], v[200:203], v[228:231], v[164:167]
	v_mfma_f32_16x16x32_bf16 v[90:93], v[192:195], v[236:239], v[168:171]
	v_mfma_f32_16x16x32_bf16 v[94:97], v[200:203], v[236:239], v[172:175]
	v_mfma_f32_16x16x32_bf16 v[66:69], v[196:199], v[106:109], v[66:69]
	v_mfma_f32_16x16x32_bf16 v[70:73], v[204:207], v[106:109], v[70:73]
	v_mfma_f32_16x16x32_bf16 v[74:77], v[196:199], v[224:227], v[74:77]
	v_mfma_f32_16x16x32_bf16 v[78:81], v[204:207], v[224:227], v[78:81]
	v_mfma_f32_16x16x32_bf16 v[82:85], v[196:199], v[232:235], v[82:85]
	v_mfma_f32_16x16x32_bf16 v[86:89], v[204:207], v[232:235], v[86:89]
	v_mfma_f32_16x16x32_bf16 v[90:93], v[196:199], v[240:243], v[90:93]
	v_mfma_f32_16x16x32_bf16 v[94:97], v[204:207], v[240:243], v[94:97]
	s_setprio 0
	s_setprio 1
	v_mfma_f32_16x16x32_bf16 v[98:101], v[208:211], v[102:105], v[114:117]
	v_mfma_f32_16x16x32_bf16 v[102:105], v[216:219], v[102:105], v[122:125]
	v_mfma_f32_16x16x32_bf16 v[98:101], v[212:215], v[106:109], v[98:101]
	v_mfma_f32_16x16x32_bf16 v[102:105], v[220:223], v[106:109], v[102:105]
	v_mfma_f32_16x16x32_bf16 v[106:109], v[208:211], v[110:113], v[176:179]
	v_mfma_f32_16x16x32_bf16 v[110:113], v[216:219], v[110:113], v[180:183]
	v_mfma_f32_16x16x32_bf16 v[114:117], v[208:211], v[228:231], v[184:187]
	v_mfma_f32_16x16x32_bf16 v[118:121], v[216:219], v[228:231], v[118:121]
	v_mfma_f32_16x16x32_bf16 v[122:125], v[208:211], v[236:239], v[188:191]
	v_mfma_f32_16x16x32_bf16 v[126:129], v[216:219], v[236:239], v[126:129]
	v_mfma_f32_16x16x32_bf16 v[106:109], v[212:215], v[224:227], v[106:109]
	v_mfma_f32_16x16x32_bf16 v[110:113], v[220:223], v[224:227], v[110:113]
	v_mfma_f32_16x16x32_bf16 v[114:117], v[212:215], v[232:235], v[114:117]
	v_mfma_f32_16x16x32_bf16 v[118:121], v[220:223], v[232:235], v[118:121]
	v_mfma_f32_16x16x32_bf16 v[122:125], v[212:215], v[240:243], v[122:125]
	v_mfma_f32_16x16x32_bf16 v[126:129], v[220:223], v[240:243], v[126:129]
	s_setprio 0
	s_barrier
	s_add_i32 s27, s27, 2
	s_cmp_ge_i32 s27, s15
	s_cbranch_scc0 .LBB0_495
	v_mov_b32_e32 v136, v130
	s_branch .LBB0_498

.LBB0_499:
	v_add_u32_e32 v133, s58, v140
	ds_read_b128 v[142:145], v133
	ds_read_b128 v[148:151], v133 offset:1024
	ds_read_b128 v[152:155], v133 offset:2048
	ds_read_b128 v[156:159], v133 offset:3072
	v_add_u32_e32 v133, s59, v140
	ds_read_b128 v[160:163], v133
	ds_read_b128 v[164:167], v133 offset:1024
	ds_read_b128 v[168:171], v133 offset:2048
	ds_read_b128 v[172:175], v133 offset:3072
	s_add_u32 s38, s36, 0xfff80080
	s_addc_u32 s39, s37, -1
	s_cmp_eq_u32 s42, 4
	s_cselect_b32 s41, s31, s39
	s_cselect_b32 s40, s30, s38
	s_cselect_b32 s39, s35, s27
	s_cselect_b32 s38, s34, s15
	s_mov_b32 m0, s56
	v_add_u32_e32 v141, 0, v1
	ds_read_b128 v[176:179], v141
	ds_read_b128 v[180:183], v141 offset:1024
	ds_read_b128 v[184:187], v141 offset:2048
	ds_read_b128 v[188:191], v141 offset:3072
	ds_read_b128 v[192:195], v141 offset:4096
	ds_read_b128 v[196:199], v141 offset:5120
	ds_read_b128 v[200:203], v141 offset:6144
	ds_read_b128 v[204:207], v141 offset:7168
	global_load_lds_dwordx4 v130, s[36:37]
	s_mov_b32 m0, s57
	v_mov_b32_e32 v133, v131
	global_load_lds_dwordx4 v132, s[36:37]
	s_waitcnt vmcnt(8)
	s_waitcnt lgkmcnt(0)
	s_barrier
	s_setprio 1
	s_waitcnt lgkmcnt(0)
	v_mfma_f32_16x16x32_bf16 v[2:5], v[142:145], v[176:179], v[2:5]
	v_mfma_f32_16x16x32_bf16 v[2:5], v[148:151], v[180:183], v[2:5]
	v_mfma_f32_16x16x32_bf16 v[6:9], v[156:159], v[180:183], v[6:9]
	v_mfma_f32_16x16x32_bf16 v[6:9], v[152:155], v[176:179], v[6:9]
	v_mfma_f32_16x16x32_bf16 v[14:17], v[152:155], v[184:187], v[14:17]
	v_mfma_f32_16x16x32_bf16 v[14:17], v[156:159], v[188:191], v[14:17]
	v_mfma_f32_16x16x32_bf16 v[10:13], v[148:151], v[188:191], v[10:13]
	v_mfma_f32_16x16x32_bf16 v[10:13], v[142:145], v[184:187], v[10:13]
	v_mfma_f32_16x16x32_bf16 v[18:21], v[142:145], v[192:195], v[18:21]
	v_mfma_f32_16x16x32_bf16 v[18:21], v[148:151], v[196:199], v[18:21]
	v_mfma_f32_16x16x32_bf16 v[22:25], v[156:159], v[196:199], v[22:25]
	v_mfma_f32_16x16x32_bf16 v[22:25], v[152:155], v[192:195], v[22:25]
	v_mfma_f32_16x16x32_bf16 v[30:33], v[152:155], v[200:203], v[30:33]
	v_mfma_f32_16x16x32_bf16 v[30:33], v[156:159], v[204:207], v[30:33]
	v_mfma_f32_16x16x32_bf16 v[26:29], v[148:151], v[204:207], v[26:29]
	v_mfma_f32_16x16x32_bf16 v[26:29], v[142:145], v[200:203], v[26:29]
	s_setprio 0
	s_setprio 1
	v_mfma_f32_16x16x32_bf16 v[34:37], v[160:163], v[176:179], v[34:37]
	v_mfma_f32_16x16x32_bf16 v[34:37], v[164:167], v[180:183], v[34:37]
	v_mfma_f32_16x16x32_bf16 v[38:41], v[172:175], v[180:183], v[38:41]
	v_mfma_f32_16x16x32_bf16 v[38:41], v[168:171], v[176:179], v[38:41]
	v_mfma_f32_16x16x32_bf16 v[46:49], v[168:171], v[184:187], v[46:49]
	v_mfma_f32_16x16x32_bf16 v[46:49], v[172:175], v[188:191], v[46:49]
	v_mfma_f32_16x16x32_bf16 v[42:45], v[164:167], v[188:191], v[42:45]
	v_mfma_f32_16x16x32_bf16 v[42:45], v[160:163], v[184:187], v[42:45]
	v_mfma_f32_16x16x32_bf16 v[50:53], v[160:163], v[192:195], v[50:53]
	v_mfma_f32_16x16x32_bf16 v[50:53], v[164:167], v[196:199], v[50:53]
	v_mfma_f32_16x16x32_bf16 v[54:57], v[172:175], v[196:199], v[54:57]
	v_mfma_f32_16x16x32_bf16 v[54:57], v[168:171], v[192:195], v[54:57]
	v_mfma_f32_16x16x32_bf16 v[62:65], v[168:171], v[200:203], v[62:65]
	v_mfma_f32_16x16x32_bf16 v[62:65], v[172:175], v[204:207], v[62:65]
	v_mfma_f32_16x16x32_bf16 v[58:61], v[164:167], v[204:207], v[58:61]
	v_mfma_f32_16x16x32_bf16 v[58:61], v[160:163], v[200:203], v[58:61]
	s_setprio 0
	s_barrier
	s_add_i32 s43, s58, s46
	s_mov_b32 m0, s43
	ds_read_b128 v[176:179], v141 offset:16384
	ds_read_b128 v[180:183], v141 offset:17408
	ds_read_b128 v[184:187], v141 offset:18432
	ds_read_b128 v[188:191], v141 offset:19456
	ds_read_b128 v[192:195], v141 offset:20480
	ds_read_b128 v[196:199], v141 offset:21504
	ds_read_b128 v[200:203], v141 offset:22528
	ds_read_b128 v[204:207], v141 offset:23552
	global_load_lds_dwordx4 v136, s[38:39]
	s_add_i32 m0, s43, 0x2000
	s_add_u32 s44, s38, 0x400000
	s_addc_u32 s45, s39, 0
	s_add_i32 s43, s59, s46
	global_load_lds_dwordx4 v134, s[38:39]
	s_mov_b32 m0, s43
	v_mov_b32_e32 v137, v131
	global_load_lds_dwordx4 v136, s[44:45]
	s_add_i32 m0, s43, 0x2000
	v_mov_b32_e32 v135, v131
	global_load_lds_dwordx4 v134, s[44:45]
	s_mov_b32 m0, s47
	v_lshl_add_u64 v[138:139], s[38:39], 0, v[136:137]
	global_load_lds_dwordx4 v130, s[40:41]
	s_mov_b32 m0, s48
	v_lshl_add_u64 v[208:209], s[38:39], 0, v[134:135]
	global_load_lds_dwordx4 v132, s[40:41]
	s_waitcnt vmcnt(8)
	s_waitcnt lgkmcnt(0)
	v_lshl_add_u64 v[210:211], s[40:41], 0, v[130:131]
	v_lshl_add_u64 v[212:213], s[40:41], 0, v[132:133]
	s_barrier
	s_setprio 1
	s_waitcnt lgkmcnt(0)
	v_mfma_f32_16x16x32_bf16 v[66:69], v[142:145], v[176:179], v[66:69]
	v_mfma_f32_16x16x32_bf16 v[66:69], v[148:151], v[180:183], v[66:69]
	v_mfma_f32_16x16x32_bf16 v[70:73], v[156:159], v[180:183], v[70:73]
	v_mfma_f32_16x16x32_bf16 v[70:73], v[152:155], v[176:179], v[70:73]
	v_mfma_f32_16x16x32_bf16 v[78:81], v[152:155], v[184:187], v[78:81]
	v_mfma_f32_16x16x32_bf16 v[78:81], v[156:159], v[188:191], v[78:81]
	v_mfma_f32_16x16x32_bf16 v[74:77], v[148:151], v[188:191], v[74:77]
	v_mfma_f32_16x16x32_bf16 v[74:77], v[142:145], v[184:187], v[74:77]
	v_mfma_f32_16x16x32_bf16 v[82:85], v[142:145], v[192:195], v[82:85]
	v_mfma_f32_16x16x32_bf16 v[82:85], v[148:151], v[196:199], v[82:85]
	v_mfma_f32_16x16x32_bf16 v[86:89], v[156:159], v[196:199], v[86:89]
	v_mfma_f32_16x16x32_bf16 v[86:89], v[152:155], v[192:195], v[86:89]
	v_mfma_f32_16x16x32_bf16 v[94:97], v[152:155], v[200:203], v[94:97]
	v_mfma_f32_16x16x32_bf16 v[94:97], v[156:159], v[204:207], v[94:97]
	v_mfma_f32_16x16x32_bf16 v[90:93], v[148:151], v[204:207], v[90:93]
	v_mfma_f32_16x16x32_bf16 v[90:93], v[142:145], v[200:203], v[90:93]
	s_setprio 0
	s_setprio 1
	v_mfma_f32_16x16x32_bf16 v[98:101], v[160:163], v[176:179], v[98:101]
	v_mfma_f32_16x16x32_bf16 v[98:101], v[164:167], v[180:183], v[98:101]
	v_mfma_f32_16x16x32_bf16 v[102:105], v[172:175], v[180:183], v[102:105]
	v_mfma_f32_16x16x32_bf16 v[102:105], v[168:171], v[176:179], v[102:105]
	v_mfma_f32_16x16x32_bf16 v[110:113], v[168:171], v[184:187], v[110:113]
	v_mfma_f32_16x16x32_bf16 v[110:113], v[172:175], v[188:191], v[110:113]
	v_mfma_f32_16x16x32_bf16 v[106:109], v[164:167], v[188:191], v[106:109]
	v_mfma_f32_16x16x32_bf16 v[106:109], v[160:163], v[184:187], v[106:109]
	v_mfma_f32_16x16x32_bf16 v[114:117], v[160:163], v[192:195], v[114:117]
	v_mfma_f32_16x16x32_bf16 v[114:117], v[164:167], v[196:199], v[114:117]
	v_mfma_f32_16x16x32_bf16 v[118:121], v[172:175], v[196:199], v[118:121]
	v_mfma_f32_16x16x32_bf16 v[118:121], v[168:171], v[192:195], v[118:121]
	v_mfma_f32_16x16x32_bf16 v[126:129], v[168:171], v[200:203], v[126:129]
	v_mfma_f32_16x16x32_bf16 v[126:129], v[172:175], v[204:207], v[126:129]
	v_mfma_f32_16x16x32_bf16 v[122:125], v[164:167], v[204:207], v[122:125]
	v_mfma_f32_16x16x32_bf16 v[122:125], v[160:163], v[200:203], v[122:125]
	s_setprio 0
	s_barrier
	s_add_i32 s43, 0, 0x18000
	v_add_u32_e32 v135, s43, v140
	s_add_i32 s44, 0, 0x1c000
	ds_read_b128 v[142:145], v135
	ds_read_b128 v[148:151], v135 offset:1024
	ds_read_b128 v[152:155], v135 offset:2048
	ds_read_b128 v[156:159], v135 offset:3072
	v_add_u32_e32 v135, s44, v140
	ds_read_b128 v[160:163], v135
	ds_read_b128 v[164:167], v135 offset:1024
	ds_read_b128 v[168:171], v135 offset:2048
	ds_read_b128 v[172:175], v135 offset:3072
	s_add_u32 s40, s40, 0x80000
	s_addc_u32 s41, s41, 0
	s_mov_b32 m0, s49
	ds_read_b128 v[176:179], v141 offset:32768
	ds_read_b128 v[180:183], v141 offset:33792
	ds_read_b128 v[184:187], v141 offset:34816
	ds_read_b128 v[188:191], v141 offset:35840
	ds_read_b128 v[192:195], v141 offset:36864
	ds_read_b128 v[196:199], v141 offset:37888
	ds_read_b128 v[200:203], v141 offset:38912
	ds_read_b128 v[204:207], v141 offset:39936
	global_load_lds_dwordx4 v130, s[40:41]
	s_mov_b32 m0, s50
	s_nop 0
	global_load_lds_dwordx4 v132, s[40:41]
	s_waitcnt vmcnt(8)
	s_waitcnt lgkmcnt(0)
	s_barrier
	s_setprio 1
	s_waitcnt lgkmcnt(0)
	v_mfma_f32_16x16x32_bf16 v[2:5], v[142:145], v[176:179], v[2:5]
	v_mfma_f32_16x16x32_bf16 v[2:5], v[148:151], v[180:183], v[2:5]
	v_mfma_f32_16x16x32_bf16 v[6:9], v[156:159], v[180:183], v[6:9]
	v_mfma_f32_16x16x32_bf16 v[6:9], v[152:155], v[176:179], v[6:9]
	v_mfma_f32_16x16x32_bf16 v[14:17], v[152:155], v[184:187], v[14:17]
	v_mfma_f32_16x16x32_bf16 v[14:17], v[156:159], v[188:191], v[14:17]
	v_mfma_f32_16x16x32_bf16 v[10:13], v[148:151], v[188:191], v[10:13]
	v_mfma_f32_16x16x32_bf16 v[10:13], v[142:145], v[184:187], v[10:13]
	v_mfma_f32_16x16x32_bf16 v[18:21], v[142:145], v[192:195], v[18:21]
	v_mfma_f32_16x16x32_bf16 v[18:21], v[148:151], v[196:199], v[18:21]
	v_mfma_f32_16x16x32_bf16 v[22:25], v[156:159], v[196:199], v[22:25]
	v_mfma_f32_16x16x32_bf16 v[22:25], v[152:155], v[192:195], v[22:25]
	v_mfma_f32_16x16x32_bf16 v[30:33], v[152:155], v[200:203], v[30:33]
	v_mfma_f32_16x16x32_bf16 v[30:33], v[156:159], v[204:207], v[30:33]
	v_mfma_f32_16x16x32_bf16 v[26:29], v[148:151], v[204:207], v[26:29]
	v_mfma_f32_16x16x32_bf16 v[26:29], v[142:145], v[200:203], v[26:29]
	s_setprio 0
	s_setprio 1
	v_mfma_f32_16x16x32_bf16 v[34:37], v[160:163], v[176:179], v[34:37]
	v_mfma_f32_16x16x32_bf16 v[34:37], v[164:167], v[180:183], v[34:37]
	v_mfma_f32_16x16x32_bf16 v[38:41], v[172:175], v[180:183], v[38:41]
	v_mfma_f32_16x16x32_bf16 v[38:41], v[168:171], v[176:179], v[38:41]
	v_mfma_f32_16x16x32_bf16 v[46:49], v[168:171], v[184:187], v[46:49]
	v_mfma_f32_16x16x32_bf16 v[46:49], v[172:175], v[188:191], v[46:49]
	v_mfma_f32_16x16x32_bf16 v[42:45], v[164:167], v[188:191], v[42:45]
	v_mfma_f32_16x16x32_bf16 v[42:45], v[160:163], v[184:187], v[42:45]
	v_mfma_f32_16x16x32_bf16 v[50:53], v[160:163], v[192:195], v[50:53]
	v_mfma_f32_16x16x32_bf16 v[50:53], v[164:167], v[196:199], v[50:53]
	v_mfma_f32_16x16x32_bf16 v[54:57], v[172:175], v[196:199], v[54:57]
	v_mfma_f32_16x16x32_bf16 v[54:57], v[168:171], v[192:195], v[54:57]
	v_mfma_f32_16x16x32_bf16 v[62:65], v[168:171], v[200:203], v[62:65]
	v_mfma_f32_16x16x32_bf16 v[62:65], v[172:175], v[204:207], v[62:65]
	v_mfma_f32_16x16x32_bf16 v[58:61], v[164:167], v[204:207], v[58:61]
	v_mfma_f32_16x16x32_bf16 v[58:61], v[160:163], v[200:203], v[58:61]
	s_setprio 0
	s_barrier
	s_add_i32 s40, s43, s46
	v_lshl_add_u64 v[138:139], v[138:139], 0, s[6:7]
	s_mov_b32 m0, s40
	ds_read_b128 v[176:179], v141 offset:49152
	ds_read_b128 v[180:183], v141 offset:50176
	ds_read_b128 v[184:187], v141 offset:51200
	ds_read_b128 v[188:191], v141 offset:52224
	ds_read_b128 v[192:195], v141 offset:53248
	ds_read_b128 v[196:199], v141 offset:54272
	ds_read_b128 v[200:203], v141 offset:55296
	ds_read_b128 v[204:207], v141 offset:56320
	global_load_lds_dwordx4 v[138:139], off
	s_add_i32 m0, s40, 0x2000
	s_add_u32 s38, s38, 0x400080
	v_lshl_add_u64 v[138:139], v[208:209], 0, s[6:7]
	s_addc_u32 s39, s39, 0
	s_add_i32 s40, s44, s46
	global_load_lds_dwordx4 v[138:139], off
	s_mov_b32 m0, s40
	v_lshl_add_u64 v[138:139], v[210:211], 0, s[6:7]
	global_load_lds_dwordx4 v136, s[38:39]
	s_add_i32 m0, s40, 0x2000
	s_nop 0
	global_load_lds_dwordx4 v134, s[38:39]
	s_mov_b32 m0, s54
	s_nop 0
	global_load_lds_dwordx4 v[138:139], off
	v_lshl_add_u64 v[138:139], v[212:213], 0, s[6:7]
	s_mov_b32 m0, s55
	s_nop 0
	global_load_lds_dwordx4 v[138:139], off
	s_waitcnt vmcnt(8)
	s_waitcnt lgkmcnt(0)
	s_barrier
	s_setprio 1
	s_waitcnt lgkmcnt(0)
	v_mfma_f32_16x16x32_bf16 v[66:69], v[142:145], v[176:179], v[66:69]
	v_mfma_f32_16x16x32_bf16 v[66:69], v[148:151], v[180:183], v[66:69]
	v_mfma_f32_16x16x32_bf16 v[70:73], v[156:159], v[180:183], v[70:73]
	v_mfma_f32_16x16x32_bf16 v[70:73], v[152:155], v[176:179], v[70:73]
	v_mfma_f32_16x16x32_bf16 v[78:81], v[152:155], v[184:187], v[78:81]
	v_mfma_f32_16x16x32_bf16 v[78:81], v[156:159], v[188:191], v[78:81]
	v_mfma_f32_16x16x32_bf16 v[74:77], v[148:151], v[188:191], v[74:77]
	v_mfma_f32_16x16x32_bf16 v[74:77], v[142:145], v[184:187], v[74:77]
	v_mfma_f32_16x16x32_bf16 v[82:85], v[142:145], v[192:195], v[82:85]
	v_mfma_f32_16x16x32_bf16 v[82:85], v[148:151], v[196:199], v[82:85]
	v_mfma_f32_16x16x32_bf16 v[86:89], v[156:159], v[196:199], v[86:89]
	v_mfma_f32_16x16x32_bf16 v[86:89], v[152:155], v[192:195], v[86:89]
	v_mfma_f32_16x16x32_bf16 v[94:97], v[152:155], v[200:203], v[94:97]
	v_mfma_f32_16x16x32_bf16 v[94:97], v[156:159], v[204:207], v[94:97]
	v_mfma_f32_16x16x32_bf16 v[90:93], v[148:151], v[204:207], v[90:93]
	v_mfma_f32_16x16x32_bf16 v[90:93], v[142:145], v[200:203], v[90:93]
	s_setprio 0
	s_setprio 1
	v_mfma_f32_16x16x32_bf16 v[98:101], v[160:163], v[176:179], v[98:101]
	v_mfma_f32_16x16x32_bf16 v[98:101], v[164:167], v[180:183], v[98:101]
	v_mfma_f32_16x16x32_bf16 v[102:105], v[172:175], v[180:183], v[102:105]
	v_mfma_f32_16x16x32_bf16 v[102:105], v[168:171], v[176:179], v[102:105]
	v_mfma_f32_16x16x32_bf16 v[110:113], v[168:171], v[184:187], v[110:113]
	v_mfma_f32_16x16x32_bf16 v[110:113], v[172:175], v[188:191], v[110:113]
	v_mfma_f32_16x16x32_bf16 v[106:109], v[164:167], v[188:191], v[106:109]
	v_mfma_f32_16x16x32_bf16 v[106:109], v[160:163], v[184:187], v[106:109]
	v_mfma_f32_16x16x32_bf16 v[114:117], v[160:163], v[192:195], v[114:117]
	v_mfma_f32_16x16x32_bf16 v[114:117], v[164:167], v[196:199], v[114:117]
	v_mfma_f32_16x16x32_bf16 v[118:121], v[172:175], v[196:199], v[118:121]
	v_mfma_f32_16x16x32_bf16 v[118:121], v[168:171], v[192:195], v[118:121]
	v_mfma_f32_16x16x32_bf16 v[126:129], v[168:171], v[200:203], v[126:129]
	v_mfma_f32_16x16x32_bf16 v[126:129], v[172:175], v[204:207], v[126:129]
	v_mfma_f32_16x16x32_bf16 v[122:125], v[164:167], v[204:207], v[122:125]
	v_mfma_f32_16x16x32_bf16 v[122:125], v[160:163], v[200:203], v[122:125]
	s_setprio 0
	s_barrier
	s_add_i32 s42, s42, 2
	s_add_u32 s36, s36, 0x100
	s_addc_u32 s37, s37, 0
	s_add_u32 s15, s15, 0x100
	s_addc_u32 s27, s27, 0
	s_cmp_gt_u32 s42, 5
	s_cbranch_scc0 .LBB0_499
	s_and_b64 vcc, exec, s[8:9]
	s_cbranch_vccz .LBB0_502
	s_barrier

.LBB0_528:
	s_add_i32 s53, 0, 0x10000
	s_add_i32 s72, 0, 0x14000
	v_add_u32_e32 v16, s53, v147
	v_add_u32_e32 v32, s72, v147
	ds_read_b128 v[4:7], v16
	ds_read_b128 v[8:11], v16 offset:1024
	ds_read_b128 v[12:15], v16 offset:2048
	ds_read_b128 v[16:19], v16 offset:3072
	ds_read_b128 v[20:23], v32
	ds_read_b128 v[24:27], v32 offset:1024
	ds_read_b128 v[28:31], v32 offset:2048
	ds_read_b128 v[32:35], v32 offset:3072
	v_add_u32_e32 v231, 0, v146
	ds_read_b128 v[36:39], v231
	ds_read_b128 v[40:43], v231 offset:1024
	ds_read_b128 v[44:47], v231 offset:2048
	ds_read_b128 v[48:51], v231 offset:3072
	ds_read_b128 v[52:55], v231 offset:4096
	ds_read_b128 v[56:59], v231 offset:5120
	ds_read_b128 v[60:63], v231 offset:6144
	ds_read_b128 v[64:67], v231 offset:7168
	s_waitcnt vmcnt(8)
	s_waitcnt lgkmcnt(0)
	s_barrier
	s_setprio 1
	s_waitcnt lgkmcnt(0)
	v_mfma_f32_16x16x32_f16 v[68:71], v[4:7], v[36:39], 0
	v_mfma_f32_16x16x32_f16 v[68:71], v[8:11], v[40:43], v[68:71]
	v_mfma_f32_16x16x32_f16 v[72:75], v[12:15], v[36:39], 0
	v_mfma_f32_16x16x32_f16 v[72:75], v[16:19], v[40:43], v[72:75]
	v_mfma_f32_16x16x32_f16 v[80:83], v[12:15], v[44:47], 0
	v_mfma_f32_16x16x32_f16 v[80:83], v[16:19], v[48:51], v[80:83]
	v_mfma_f32_16x16x32_f16 v[76:79], v[4:7], v[44:47], 0
	v_mfma_f32_16x16x32_f16 v[76:79], v[8:11], v[48:51], v[76:79]
	v_mfma_f32_16x16x32_f16 v[84:87], v[4:7], v[52:55], 0
	v_mfma_f32_16x16x32_f16 v[84:87], v[8:11], v[56:59], v[84:87]
	v_mfma_f32_16x16x32_f16 v[88:91], v[12:15], v[52:55], 0
	v_mfma_f32_16x16x32_f16 v[88:91], v[16:19], v[56:59], v[88:91]
	v_mfma_f32_16x16x32_f16 v[96:99], v[12:15], v[60:63], 0
	v_mfma_f32_16x16x32_f16 v[96:99], v[16:19], v[64:67], v[96:99]
	v_mfma_f32_16x16x32_f16 v[92:95], v[4:7], v[60:63], 0
	v_mfma_f32_16x16x32_f16 v[92:95], v[8:11], v[64:67], v[92:95]
	s_setprio 0
	s_setprio 1
	v_mfma_f32_16x16x32_f16 v[100:103], v[20:23], v[36:39], 0
	v_mfma_f32_16x16x32_f16 v[36:39], v[28:31], v[36:39], 0
	v_mfma_f32_16x16x32_f16 v[104:107], v[20:23], v[44:47], 0
	v_mfma_f32_16x16x32_f16 v[44:47], v[28:31], v[44:47], 0
	v_mfma_f32_16x16x32_f16 v[108:111], v[20:23], v[52:55], 0
	v_mfma_f32_16x16x32_f16 v[52:55], v[28:31], v[52:55], 0
	v_mfma_f32_16x16x32_f16 v[112:115], v[20:23], v[60:63], 0
	v_mfma_f32_16x16x32_f16 v[60:63], v[28:31], v[60:63], 0
	v_mfma_f32_16x16x32_f16 v[100:103], v[24:27], v[40:43], v[100:103]
	v_mfma_f32_16x16x32_f16 v[40:43], v[32:35], v[40:43], v[36:39]
	v_mfma_f32_16x16x32_f16 v[104:107], v[24:27], v[48:51], v[104:107]
	v_mfma_f32_16x16x32_f16 v[48:51], v[32:35], v[48:51], v[44:47]
	v_mfma_f32_16x16x32_f16 v[108:111], v[24:27], v[56:59], v[108:111]
	v_mfma_f32_16x16x32_f16 v[56:59], v[32:35], v[56:59], v[52:55]
	v_mfma_f32_16x16x32_f16 v[112:115], v[24:27], v[64:67], v[112:115]
	v_mfma_f32_16x16x32_f16 v[64:67], v[32:35], v[64:67], v[60:63]
	s_setprio 0
	s_barrier
	v_lshl_add_u64 v[136:137], s[6:7], 0, v[2:3]
	s_add_i32 s53, s53, s38
	v_mov_b32_e32 v135, v3
	v_lshl_add_u64 v[140:141], v[136:137], 0, s[74:75]
	s_mov_b32 m0, s53
	v_lshl_add_u64 v[144:145], s[6:7], 0, v[134:135]
	ds_read_b128 v[36:39], v231 offset:16384
	ds_read_b128 v[44:47], v231 offset:17408
	ds_read_b128 v[52:55], v231 offset:18432
	ds_read_b128 v[60:63], v231 offset:19456
	ds_read_b128 v[116:119], v231 offset:20480
	ds_read_b128 v[120:123], v231 offset:21504
	ds_read_b128 v[124:127], v231 offset:22528
	ds_read_b128 v[128:131], v231 offset:23552
	global_load_lds_dwordx4 v[140:141], off
	v_lshl_add_u64 v[140:141], v[144:145], 0, s[74:75]
	s_add_i32 m0, s53, 0x2000
	s_add_i32 s53, s72, s38
	global_load_lds_dwordx4 v[140:141], off
	s_mov_b32 m0, s53
	v_mov_b32_e32 v139, v3
	global_load_lds_dwordx4 v2, s[16:17]
	s_add_i32 m0, s53, 0x2000
	v_lshl_add_u64 v[248:249], s[8:9], 0, v[138:139]
	v_mov_b32_e32 v133, v3
	global_load_lds_dwordx4 v134, s[16:17]
	v_lshl_add_u64 v[140:141], v[248:249], 0, s[74:75]
	s_mov_b32 m0, s58
	v_lshl_add_u64 v[250:251], s[8:9], 0, v[132:133]
	global_load_lds_dwordx4 v[140:141], off
	v_lshl_add_u64 v[140:141], v[250:251], 0, s[74:75]
	s_mov_b32 m0, s59
	s_nop 0
	global_load_lds_dwordx4 v[140:141], off
	s_waitcnt vmcnt(8)
	s_waitcnt lgkmcnt(0)
	s_barrier
	s_setprio 1
	s_waitcnt lgkmcnt(0)
	v_mfma_f32_16x16x32_f16 v[140:143], v[4:7], v[36:39], 0
	v_mfma_f32_16x16x32_f16 v[148:151], v[12:15], v[36:39], 0
	v_mfma_f32_16x16x32_f16 v[152:155], v[4:7], v[52:55], 0
	v_mfma_f32_16x16x32_f16 v[156:159], v[12:15], v[52:55], 0
	v_mfma_f32_16x16x32_f16 v[160:163], v[4:7], v[116:119], 0
	v_mfma_f32_16x16x32_f16 v[164:167], v[12:15], v[116:119], 0
	v_mfma_f32_16x16x32_f16 v[4:7], v[4:7], v[124:127], 0
	v_mfma_f32_16x16x32_f16 v[12:15], v[12:15], v[124:127], 0
	v_mfma_f32_16x16x32_f16 v[140:143], v[8:11], v[44:47], v[140:143]
	v_mfma_f32_16x16x32_f16 v[148:151], v[16:19], v[44:47], v[148:151]
	v_mfma_f32_16x16x32_f16 v[152:155], v[8:11], v[60:63], v[152:155]
	v_mfma_f32_16x16x32_f16 v[156:159], v[16:19], v[60:63], v[156:159]
	v_mfma_f32_16x16x32_f16 v[160:163], v[8:11], v[120:123], v[160:163]
	v_mfma_f32_16x16x32_f16 v[164:167], v[16:19], v[120:123], v[164:167]
	v_mfma_f32_16x16x32_f16 v[168:171], v[8:11], v[128:131], v[4:7]
	v_mfma_f32_16x16x32_f16 v[172:175], v[16:19], v[128:131], v[12:15]
	s_setprio 0
	s_setprio 1
	v_mfma_f32_16x16x32_f16 v[4:7], v[20:23], v[36:39], 0
	v_mfma_f32_16x16x32_f16 v[8:11], v[28:31], v[36:39], 0
	v_mfma_f32_16x16x32_f16 v[12:15], v[20:23], v[52:55], 0
	v_mfma_f32_16x16x32_f16 v[16:19], v[28:31], v[52:55], 0
	v_mfma_f32_16x16x32_f16 v[36:39], v[20:23], v[116:119], 0
	v_mfma_f32_16x16x32_f16 v[52:55], v[28:31], v[116:119], 0
	v_mfma_f32_16x16x32_f16 v[20:23], v[20:23], v[124:127], 0
	v_mfma_f32_16x16x32_f16 v[28:31], v[28:31], v[124:127], 0
	v_mfma_f32_16x16x32_f16 v[116:119], v[24:27], v[44:47], v[4:7]
	v_mfma_f32_16x16x32_f16 v[124:127], v[32:35], v[44:47], v[8:11]
	v_mfma_f32_16x16x32_f16 v[184:187], v[24:27], v[120:123], v[36:39]
	v_mfma_f32_16x16x32_f16 v[120:123], v[32:35], v[120:123], v[52:55]
	v_mfma_f32_16x16x32_f16 v[188:191], v[24:27], v[128:131], v[20:23]
	v_mfma_f32_16x16x32_f16 v[128:131], v[32:35], v[128:131], v[28:31]
	v_mfma_f32_16x16x32_f16 v[176:179], v[24:27], v[60:63], v[12:15]
	v_mfma_f32_16x16x32_f16 v[180:183], v[32:35], v[60:63], v[16:19]
	s_setprio 0
	s_barrier
	s_add_i32 s53, 0, 0x18000
	v_add_u32_e32 v4, s53, v147
	s_add_i32 s72, 0, 0x1c000
	ds_read_b128 v[192:195], v4
	ds_read_b128 v[196:199], v4 offset:1024
	ds_read_b128 v[200:203], v4 offset:2048
	ds_read_b128 v[204:207], v4 offset:3072
	v_add_u32_e32 v4, s72, v147
	ds_read_b128 v[208:211], v4
	ds_read_b128 v[212:215], v4 offset:1024
	ds_read_b128 v[216:219], v4 offset:2048
	ds_read_b128 v[220:223], v4 offset:3072
	s_mov_b32 m0, s60
	ds_read_b128 v[44:47], v231 offset:32768
	ds_read_b128 v[52:55], v231 offset:33792
	ds_read_b128 v[60:63], v231 offset:34816
	ds_read_b128 v[224:227], v231 offset:35840
	ds_read_b128 v[232:235], v231 offset:36864
	ds_read_b128 v[236:239], v231 offset:37888
	ds_read_b128 v[240:243], v231 offset:38912
	ds_read_b128 v[244:247], v231 offset:39936
	global_load_lds_dwordx4 v138, s[26:27]
	s_mov_b32 m0, s61
	s_nop 0
	global_load_lds_dwordx4 v132, s[26:27]
	s_waitcnt vmcnt(8)
	s_waitcnt lgkmcnt(0)
	s_barrier
	s_setprio 1
	s_waitcnt lgkmcnt(0)
	v_mfma_f32_16x16x32_f16 v[4:7], v[192:195], v[44:47], v[68:71]
	v_mfma_f32_16x16x32_f16 v[8:11], v[200:203], v[44:47], v[72:75]
	v_mfma_f32_16x16x32_f16 v[12:15], v[192:195], v[60:63], v[76:79]
	v_mfma_f32_16x16x32_f16 v[16:19], v[200:203], v[60:63], v[80:83]
	v_mfma_f32_16x16x32_f16 v[20:23], v[192:195], v[232:235], v[84:87]
	v_mfma_f32_16x16x32_f16 v[24:27], v[200:203], v[232:235], v[88:91]
	v_mfma_f32_16x16x32_f16 v[28:31], v[192:195], v[240:243], v[92:95]
	v_mfma_f32_16x16x32_f16 v[32:35], v[200:203], v[240:243], v[96:99]
	v_mfma_f32_16x16x32_f16 v[4:7], v[196:199], v[52:55], v[4:7]
	v_mfma_f32_16x16x32_f16 v[8:11], v[204:207], v[52:55], v[8:11]
	v_mfma_f32_16x16x32_f16 v[12:15], v[196:199], v[224:227], v[12:15]
	v_mfma_f32_16x16x32_f16 v[16:19], v[204:207], v[224:227], v[16:19]
	v_mfma_f32_16x16x32_f16 v[20:23], v[196:199], v[236:239], v[20:23]
	v_mfma_f32_16x16x32_f16 v[24:27], v[204:207], v[236:239], v[24:27]
	v_mfma_f32_16x16x32_f16 v[28:31], v[196:199], v[244:247], v[28:31]
	v_mfma_f32_16x16x32_f16 v[32:35], v[204:207], v[244:247], v[32:35]
	s_setprio 0
	s_setprio 1
	v_mfma_f32_16x16x32_f16 v[36:39], v[208:211], v[44:47], v[100:103]
	v_mfma_f32_16x16x32_f16 v[40:43], v[216:219], v[44:47], v[40:43]
	v_mfma_f32_16x16x32_f16 v[36:39], v[212:215], v[52:55], v[36:39]
	v_mfma_f32_16x16x32_f16 v[40:43], v[220:223], v[52:55], v[40:43]
	v_mfma_f32_16x16x32_f16 v[44:47], v[208:211], v[60:63], v[104:107]
	v_mfma_f32_16x16x32_f16 v[48:51], v[216:219], v[60:63], v[48:51]
	v_mfma_f32_16x16x32_f16 v[52:55], v[208:211], v[232:235], v[108:111]
	v_mfma_f32_16x16x32_f16 v[56:59], v[216:219], v[232:235], v[56:59]
	v_mfma_f32_16x16x32_f16 v[60:63], v[208:211], v[240:243], v[112:115]
	v_mfma_f32_16x16x32_f16 v[64:67], v[216:219], v[240:243], v[64:67]
	v_mfma_f32_16x16x32_f16 v[44:47], v[212:215], v[224:227], v[44:47]
	v_mfma_f32_16x16x32_f16 v[48:51], v[220:223], v[224:227], v[48:51]
	v_mfma_f32_16x16x32_f16 v[52:55], v[212:215], v[236:239], v[52:55]
	v_mfma_f32_16x16x32_f16 v[56:59], v[220:223], v[236:239], v[56:59]
	v_mfma_f32_16x16x32_f16 v[60:63], v[212:215], v[244:247], v[60:63]
	v_mfma_f32_16x16x32_f16 v[64:67], v[220:223], v[244:247], v[64:67]
	s_setprio 0
	s_barrier
	s_add_i32 s53, s53, s38
	v_lshl_add_u64 v[68:69], v[136:137], 0, s[24:25]
	s_mov_b32 m0, s53
	ds_read_b128 v[104:107], v231 offset:49152
	ds_read_b128 v[108:111], v231 offset:50176
	ds_read_b128 v[112:115], v231 offset:51200
	ds_read_b128 v[224:227], v231 offset:52224
	ds_read_b128 v[232:235], v231 offset:53248
	ds_read_b128 v[236:239], v231 offset:54272
	ds_read_b128 v[240:243], v231 offset:55296
	ds_read_b128 v[244:247], v231 offset:56320
	global_load_lds_dwordx4 v[68:69], off
	v_lshl_add_u64 v[68:69], v[144:145], 0, s[24:25]
	s_add_i32 m0, s53, 0x2000
	s_add_i32 s53, s72, s38
	global_load_lds_dwordx4 v[68:69], off
	s_mov_b32 m0, s53
	v_lshl_add_u64 v[68:69], v[248:249], 0, s[24:25]
	global_load_lds_dwordx4 v2, s[28:29]
	s_add_i32 m0, s53, 0x2000
	s_nop 0
	global_load_lds_dwordx4 v134, s[28:29]
	s_mov_b32 m0, s64
	s_nop 0
	global_load_lds_dwordx4 v[68:69], off
	v_lshl_add_u64 v[68:69], v[250:251], 0, s[24:25]
	s_mov_b32 m0, s65
	s_nop 0
	global_load_lds_dwordx4 v[68:69], off
	s_waitcnt vmcnt(8)
	s_waitcnt lgkmcnt(0)
	s_barrier
	s_setprio 1
	s_waitcnt lgkmcnt(0)
	v_mfma_f32_16x16x32_f16 v[68:71], v[192:195], v[104:107], v[140:143]
	v_mfma_f32_16x16x32_f16 v[72:75], v[200:203], v[104:107], v[148:151]
	v_mfma_f32_16x16x32_f16 v[76:79], v[192:195], v[112:115], v[152:155]
	v_mfma_f32_16x16x32_f16 v[80:83], v[200:203], v[112:115], v[156:159]
	v_mfma_f32_16x16x32_f16 v[84:87], v[192:195], v[232:235], v[160:163]
	v_mfma_f32_16x16x32_f16 v[88:91], v[200:203], v[232:235], v[164:167]
	v_mfma_f32_16x16x32_f16 v[92:95], v[192:195], v[240:243], v[168:171]
	v_mfma_f32_16x16x32_f16 v[96:99], v[200:203], v[240:243], v[172:175]
	v_mfma_f32_16x16x32_f16 v[68:71], v[196:199], v[108:111], v[68:71]
	v_mfma_f32_16x16x32_f16 v[72:75], v[204:207], v[108:111], v[72:75]
	v_mfma_f32_16x16x32_f16 v[76:79], v[196:199], v[224:227], v[76:79]
	v_mfma_f32_16x16x32_f16 v[80:83], v[204:207], v[224:227], v[80:83]
	v_mfma_f32_16x16x32_f16 v[84:87], v[196:199], v[236:239], v[84:87]
	v_mfma_f32_16x16x32_f16 v[88:91], v[204:207], v[236:239], v[88:91]
	v_mfma_f32_16x16x32_f16 v[92:95], v[196:199], v[244:247], v[92:95]
	v_mfma_f32_16x16x32_f16 v[96:99], v[204:207], v[244:247], v[96:99]
	s_setprio 0
	s_setprio 1
	v_mfma_f32_16x16x32_f16 v[100:103], v[208:211], v[104:107], v[116:119]
	v_mfma_f32_16x16x32_f16 v[104:107], v[216:219], v[104:107], v[124:127]
	v_mfma_f32_16x16x32_f16 v[100:103], v[212:215], v[108:111], v[100:103]
	v_mfma_f32_16x16x32_f16 v[104:107], v[220:223], v[108:111], v[104:107]
	v_mfma_f32_16x16x32_f16 v[108:111], v[208:211], v[112:115], v[176:179]
	v_mfma_f32_16x16x32_f16 v[112:115], v[216:219], v[112:115], v[180:183]
	v_mfma_f32_16x16x32_f16 v[116:119], v[208:211], v[232:235], v[184:187]
	v_mfma_f32_16x16x32_f16 v[120:123], v[216:219], v[232:235], v[120:123]
	v_mfma_f32_16x16x32_f16 v[124:127], v[208:211], v[240:243], v[188:191]
	v_mfma_f32_16x16x32_f16 v[128:131], v[216:219], v[240:243], v[128:131]
	v_mfma_f32_16x16x32_f16 v[108:111], v[212:215], v[224:227], v[108:111]
	v_mfma_f32_16x16x32_f16 v[112:115], v[220:223], v[224:227], v[112:115]
	v_mfma_f32_16x16x32_f16 v[116:119], v[212:215], v[236:239], v[116:119]
	v_mfma_f32_16x16x32_f16 v[120:123], v[220:223], v[236:239], v[120:123]
	v_mfma_f32_16x16x32_f16 v[124:127], v[212:215], v[244:247], v[124:127]
	v_mfma_f32_16x16x32_f16 v[128:131], v[220:223], v[244:247], v[128:131]
	s_setprio 0
	s_barrier
	s_add_i32 s41, s41, 2
	s_cmp_ge_i32 s41, s40
	s_cbranch_scc0 .LBB0_528
	v_mov_b32_e32 v136, v2
	s_branch .LBB0_531

.LBB0_532:
	s_add_u32 s6, s8, 0xfff80080
	s_addc_u32 s7, s9, -1
	s_add_i32 s29, 0, 0x10000
	s_cmp_eq_u32 s28, 28
	s_cselect_b32 s17, s13, s7
	s_cselect_b32 s16, s12, s6
	v_add_u32_e32 v133, s29, v147
	s_cselect_b32 s7, s15, s27
	s_cselect_b32 s6, s14, s26
	s_add_i32 s53, 0, 0x14000
	ds_read_b128 v[138:141], v133
	ds_read_b128 v[142:145], v133 offset:1024
	ds_read_b128 v[148:151], v133 offset:2048
	ds_read_b128 v[152:155], v133 offset:3072
	v_add_u32_e32 v133, s53, v147
	ds_read_b128 v[156:159], v133
	ds_read_b128 v[160:163], v133 offset:1024
	ds_read_b128 v[164:167], v133 offset:2048
	ds_read_b128 v[168:171], v133 offset:3072
	s_mov_b32 m0, s66
	v_add_u32_e32 v212, 0, v146
	ds_read_b128 v[172:175], v212
	ds_read_b128 v[176:179], v212 offset:1024
	ds_read_b128 v[180:183], v212 offset:2048
	ds_read_b128 v[184:187], v212 offset:3072
	ds_read_b128 v[188:191], v212 offset:4096
	ds_read_b128 v[192:195], v212 offset:5120
	ds_read_b128 v[196:199], v212 offset:6144
	ds_read_b128 v[200:203], v212 offset:7168
	global_load_lds_dwordx4 v2, s[8:9]
	s_mov_b32 m0, s67
	v_mov_b32_e32 v133, v3
	global_load_lds_dwordx4 v132, s[8:9]
	s_waitcnt vmcnt(8)
	s_waitcnt lgkmcnt(0)
	s_barrier
	s_setprio 1
	s_waitcnt lgkmcnt(0)
	v_mfma_f32_16x16x32_f16 v[4:7], v[138:141], v[172:175], v[4:7]
	v_mfma_f32_16x16x32_f16 v[4:7], v[142:145], v[176:179], v[4:7]
	v_mfma_f32_16x16x32_f16 v[8:11], v[152:155], v[176:179], v[8:11]
	v_mfma_f32_16x16x32_f16 v[8:11], v[148:151], v[172:175], v[8:11]
	v_mfma_f32_16x16x32_f16 v[16:19], v[148:151], v[180:183], v[16:19]
	v_mfma_f32_16x16x32_f16 v[16:19], v[152:155], v[184:187], v[16:19]
	v_mfma_f32_16x16x32_f16 v[12:15], v[142:145], v[184:187], v[12:15]
	v_mfma_f32_16x16x32_f16 v[12:15], v[138:141], v[180:183], v[12:15]
	v_mfma_f32_16x16x32_f16 v[20:23], v[138:141], v[188:191], v[20:23]
	v_mfma_f32_16x16x32_f16 v[20:23], v[142:145], v[192:195], v[20:23]
	v_mfma_f32_16x16x32_f16 v[24:27], v[152:155], v[192:195], v[24:27]
	v_mfma_f32_16x16x32_f16 v[24:27], v[148:151], v[188:191], v[24:27]
	v_mfma_f32_16x16x32_f16 v[32:35], v[148:151], v[196:199], v[32:35]
	v_mfma_f32_16x16x32_f16 v[32:35], v[152:155], v[200:203], v[32:35]
	v_mfma_f32_16x16x32_f16 v[28:31], v[142:145], v[200:203], v[28:31]
	v_mfma_f32_16x16x32_f16 v[28:31], v[138:141], v[196:199], v[28:31]
	s_setprio 0
	s_setprio 1
	v_mfma_f32_16x16x32_f16 v[36:39], v[156:159], v[172:175], v[36:39]
	v_mfma_f32_16x16x32_f16 v[36:39], v[160:163], v[176:179], v[36:39]
	v_mfma_f32_16x16x32_f16 v[40:43], v[168:171], v[176:179], v[40:43]
	v_mfma_f32_16x16x32_f16 v[40:43], v[164:167], v[172:175], v[40:43]
	v_mfma_f32_16x16x32_f16 v[48:51], v[164:167], v[180:183], v[48:51]
	v_mfma_f32_16x16x32_f16 v[48:51], v[168:171], v[184:187], v[48:51]
	v_mfma_f32_16x16x32_f16 v[44:47], v[160:163], v[184:187], v[44:47]
	v_mfma_f32_16x16x32_f16 v[44:47], v[156:159], v[180:183], v[44:47]
	v_mfma_f32_16x16x32_f16 v[52:55], v[156:159], v[188:191], v[52:55]
	v_mfma_f32_16x16x32_f16 v[52:55], v[160:163], v[192:195], v[52:55]
	v_mfma_f32_16x16x32_f16 v[56:59], v[168:171], v[192:195], v[56:59]
	v_mfma_f32_16x16x32_f16 v[56:59], v[164:167], v[188:191], v[56:59]
	v_mfma_f32_16x16x32_f16 v[64:67], v[164:167], v[196:199], v[64:67]
	v_mfma_f32_16x16x32_f16 v[64:67], v[168:171], v[200:203], v[64:67]
	v_mfma_f32_16x16x32_f16 v[60:63], v[160:163], v[200:203], v[60:63]
	v_mfma_f32_16x16x32_f16 v[60:63], v[156:159], v[196:199], v[60:63]
	s_setprio 0
	s_barrier
	s_add_i32 s29, s29, s38
	s_mov_b32 m0, s29
	ds_read_b128 v[172:175], v212 offset:16384
	ds_read_b128 v[176:179], v212 offset:17408
	ds_read_b128 v[180:183], v212 offset:18432
	ds_read_b128 v[184:187], v212 offset:19456
	ds_read_b128 v[188:191], v212 offset:20480
	ds_read_b128 v[192:195], v212 offset:21504
	ds_read_b128 v[196:199], v212 offset:22528
	ds_read_b128 v[200:203], v212 offset:23552
	global_load_lds_dwordx4 v136, s[6:7]
	s_add_i32 m0, s29, 0x2000
	s_add_u32 s40, s6, 0x80000
	s_addc_u32 s41, s7, 0
	s_add_i32 s29, s53, s38
	global_load_lds_dwordx4 v134, s[6:7]
	s_mov_b32 m0, s29
	v_mov_b32_e32 v137, v3
	global_load_lds_dwordx4 v136, s[40:41]
	s_add_i32 m0, s29, 0x2000
	v_mov_b32_e32 v135, v3
	global_load_lds_dwordx4 v134, s[40:41]
	s_mov_b32 m0, s58
	v_lshl_add_u64 v[204:205], s[6:7], 0, v[136:137]
	global_load_lds_dwordx4 v2, s[16:17]
	s_mov_b32 m0, s59
	v_lshl_add_u64 v[206:207], s[6:7], 0, v[134:135]
	global_load_lds_dwordx4 v132, s[16:17]
	s_waitcnt vmcnt(8)
	s_waitcnt lgkmcnt(0)
	v_lshl_add_u64 v[208:209], s[16:17], 0, v[2:3]
	v_lshl_add_u64 v[210:211], s[16:17], 0, v[132:133]
	s_barrier
	s_setprio 1
	s_waitcnt lgkmcnt(0)
	v_mfma_f32_16x16x32_f16 v[68:71], v[138:141], v[172:175], v[68:71]
	v_mfma_f32_16x16x32_f16 v[68:71], v[142:145], v[176:179], v[68:71]
	v_mfma_f32_16x16x32_f16 v[72:75], v[152:155], v[176:179], v[72:75]
	v_mfma_f32_16x16x32_f16 v[72:75], v[148:151], v[172:175], v[72:75]
	v_mfma_f32_16x16x32_f16 v[80:83], v[148:151], v[180:183], v[80:83]
	v_mfma_f32_16x16x32_f16 v[80:83], v[152:155], v[184:187], v[80:83]
	v_mfma_f32_16x16x32_f16 v[76:79], v[142:145], v[184:187], v[76:79]
	v_mfma_f32_16x16x32_f16 v[76:79], v[138:141], v[180:183], v[76:79]
	v_mfma_f32_16x16x32_f16 v[84:87], v[138:141], v[188:191], v[84:87]
	v_mfma_f32_16x16x32_f16 v[84:87], v[142:145], v[192:195], v[84:87]
	v_mfma_f32_16x16x32_f16 v[88:91], v[152:155], v[192:195], v[88:91]
	v_mfma_f32_16x16x32_f16 v[88:91], v[148:151], v[188:191], v[88:91]
	v_mfma_f32_16x16x32_f16 v[96:99], v[148:151], v[196:199], v[96:99]
	v_mfma_f32_16x16x32_f16 v[96:99], v[152:155], v[200:203], v[96:99]
	v_mfma_f32_16x16x32_f16 v[92:95], v[142:145], v[200:203], v[92:95]
	v_mfma_f32_16x16x32_f16 v[92:95], v[138:141], v[196:199], v[92:95]
	s_setprio 0
	s_setprio 1
	v_mfma_f32_16x16x32_f16 v[100:103], v[156:159], v[172:175], v[100:103]
	v_mfma_f32_16x16x32_f16 v[100:103], v[160:163], v[176:179], v[100:103]
	v_mfma_f32_16x16x32_f16 v[104:107], v[168:171], v[176:179], v[104:107]
	v_mfma_f32_16x16x32_f16 v[104:107], v[164:167], v[172:175], v[104:107]
	v_mfma_f32_16x16x32_f16 v[112:115], v[164:167], v[180:183], v[112:115]
	v_mfma_f32_16x16x32_f16 v[112:115], v[168:171], v[184:187], v[112:115]
	v_mfma_f32_16x16x32_f16 v[108:111], v[160:163], v[184:187], v[108:111]
	v_mfma_f32_16x16x32_f16 v[108:111], v[156:159], v[180:183], v[108:111]
	v_mfma_f32_16x16x32_f16 v[116:119], v[156:159], v[188:191], v[116:119]
	v_mfma_f32_16x16x32_f16 v[116:119], v[160:163], v[192:195], v[116:119]
	v_mfma_f32_16x16x32_f16 v[120:123], v[168:171], v[192:195], v[120:123]
	v_mfma_f32_16x16x32_f16 v[120:123], v[164:167], v[188:191], v[120:123]
	v_mfma_f32_16x16x32_f16 v[128:131], v[164:167], v[196:199], v[128:131]
	v_mfma_f32_16x16x32_f16 v[128:131], v[168:171], v[200:203], v[128:131]
	v_mfma_f32_16x16x32_f16 v[124:127], v[160:163], v[200:203], v[124:127]
	v_mfma_f32_16x16x32_f16 v[124:127], v[156:159], v[196:199], v[124:127]
	s_setprio 0
	s_barrier
	s_add_i32 s29, 0, 0x18000
	v_add_u32_e32 v135, s29, v147
	s_add_i32 s40, 0, 0x1c000
	ds_read_b128 v[138:141], v135
	ds_read_b128 v[142:145], v135 offset:1024
	ds_read_b128 v[148:151], v135 offset:2048
	ds_read_b128 v[152:155], v135 offset:3072
	v_add_u32_e32 v135, s40, v147
	ds_read_b128 v[156:159], v135
	ds_read_b128 v[160:163], v135 offset:1024
	ds_read_b128 v[164:167], v135 offset:2048
	ds_read_b128 v[168:171], v135 offset:3072
	s_add_u32 s16, s16, 0x80000
	s_addc_u32 s17, s17, 0
	s_mov_b32 m0, s60
	ds_read_b128 v[172:175], v212 offset:32768
	ds_read_b128 v[176:179], v212 offset:33792
	ds_read_b128 v[180:183], v212 offset:34816
	ds_read_b128 v[184:187], v212 offset:35840
	ds_read_b128 v[188:191], v212 offset:36864
	ds_read_b128 v[192:195], v212 offset:37888
	ds_read_b128 v[196:199], v212 offset:38912
	ds_read_b128 v[200:203], v212 offset:39936
	global_load_lds_dwordx4 v2, s[16:17]
	s_mov_b32 m0, s61
	s_nop 0
	global_load_lds_dwordx4 v132, s[16:17]
	s_waitcnt vmcnt(8)
	s_waitcnt lgkmcnt(0)
	s_barrier
	s_setprio 1
	s_waitcnt lgkmcnt(0)
	v_mfma_f32_16x16x32_f16 v[4:7], v[138:141], v[172:175], v[4:7]
	v_mfma_f32_16x16x32_f16 v[4:7], v[142:145], v[176:179], v[4:7]
	v_mfma_f32_16x16x32_f16 v[8:11], v[152:155], v[176:179], v[8:11]
	v_mfma_f32_16x16x32_f16 v[8:11], v[148:151], v[172:175], v[8:11]
	v_mfma_f32_16x16x32_f16 v[16:19], v[148:151], v[180:183], v[16:19]
	v_mfma_f32_16x16x32_f16 v[16:19], v[152:155], v[184:187], v[16:19]
	v_mfma_f32_16x16x32_f16 v[12:15], v[142:145], v[184:187], v[12:15]
	v_mfma_f32_16x16x32_f16 v[12:15], v[138:141], v[180:183], v[12:15]
	v_mfma_f32_16x16x32_f16 v[20:23], v[138:141], v[188:191], v[20:23]
	v_mfma_f32_16x16x32_f16 v[20:23], v[142:145], v[192:195], v[20:23]
	v_mfma_f32_16x16x32_f16 v[24:27], v[152:155], v[192:195], v[24:27]
	v_mfma_f32_16x16x32_f16 v[24:27], v[148:151], v[188:191], v[24:27]
	v_mfma_f32_16x16x32_f16 v[32:35], v[148:151], v[196:199], v[32:35]
	v_mfma_f32_16x16x32_f16 v[32:35], v[152:155], v[200:203], v[32:35]
	v_mfma_f32_16x16x32_f16 v[28:31], v[142:145], v[200:203], v[28:31]
	v_mfma_f32_16x16x32_f16 v[28:31], v[138:141], v[196:199], v[28:31]
	s_setprio 0
	s_setprio 1
	v_mfma_f32_16x16x32_f16 v[36:39], v[156:159], v[172:175], v[36:39]
	v_mfma_f32_16x16x32_f16 v[36:39], v[160:163], v[176:179], v[36:39]
	v_mfma_f32_16x16x32_f16 v[40:43], v[168:171], v[176:179], v[40:43]
	v_mfma_f32_16x16x32_f16 v[40:43], v[164:167], v[172:175], v[40:43]
	v_mfma_f32_16x16x32_f16 v[48:51], v[164:167], v[180:183], v[48:51]
	v_mfma_f32_16x16x32_f16 v[48:51], v[168:171], v[184:187], v[48:51]
	v_mfma_f32_16x16x32_f16 v[44:47], v[160:163], v[184:187], v[44:47]
	v_mfma_f32_16x16x32_f16 v[44:47], v[156:159], v[180:183], v[44:47]
	v_mfma_f32_16x16x32_f16 v[52:55], v[156:159], v[188:191], v[52:55]
	v_mfma_f32_16x16x32_f16 v[52:55], v[160:163], v[192:195], v[52:55]
	v_mfma_f32_16x16x32_f16 v[56:59], v[168:171], v[192:195], v[56:59]
	v_mfma_f32_16x16x32_f16 v[56:59], v[164:167], v[188:191], v[56:59]
	v_mfma_f32_16x16x32_f16 v[64:67], v[164:167], v[196:199], v[64:67]
	v_mfma_f32_16x16x32_f16 v[64:67], v[168:171], v[200:203], v[64:67]
	v_mfma_f32_16x16x32_f16 v[60:63], v[160:163], v[200:203], v[60:63]
	v_mfma_f32_16x16x32_f16 v[60:63], v[156:159], v[196:199], v[60:63]
	s_setprio 0
	s_barrier
	s_add_i32 s16, s29, s38
	v_lshl_add_u64 v[204:205], v[204:205], 0, s[86:87]
	s_mov_b32 m0, s16
	ds_read_b128 v[172:175], v212 offset:49152
	ds_read_b128 v[176:179], v212 offset:50176
	ds_read_b128 v[180:183], v212 offset:51200
	ds_read_b128 v[184:187], v212 offset:52224
	ds_read_b128 v[188:191], v212 offset:53248
	ds_read_b128 v[192:195], v212 offset:54272
	ds_read_b128 v[196:199], v212 offset:55296
	ds_read_b128 v[200:203], v212 offset:56320
	global_load_lds_dwordx4 v[204:205], off
	s_add_i32 m0, s16, 0x2000
	s_add_u32 s6, s6, 0x80080
	v_lshl_add_u64 v[204:205], v[206:207], 0, s[86:87]
	s_addc_u32 s7, s7, 0
	s_add_i32 s16, s40, s38
	global_load_lds_dwordx4 v[204:205], off
	s_mov_b32 m0, s16
	v_lshl_add_u64 v[204:205], v[208:209], 0, s[86:87]
	global_load_lds_dwordx4 v136, s[6:7]
	s_add_i32 m0, s16, 0x2000
	s_nop 0
	global_load_lds_dwordx4 v134, s[6:7]
	s_mov_b32 m0, s64
	s_nop 0
	global_load_lds_dwordx4 v[204:205], off
	v_lshl_add_u64 v[204:205], v[210:211], 0, s[86:87]
	s_mov_b32 m0, s65
	s_nop 0
	global_load_lds_dwordx4 v[204:205], off
	s_waitcnt vmcnt(8)
	s_waitcnt lgkmcnt(0)
	s_barrier
	s_setprio 1
	s_waitcnt lgkmcnt(0)
	v_mfma_f32_16x16x32_f16 v[68:71], v[138:141], v[172:175], v[68:71]
	v_mfma_f32_16x16x32_f16 v[68:71], v[142:145], v[176:179], v[68:71]
	v_mfma_f32_16x16x32_f16 v[72:75], v[152:155], v[176:179], v[72:75]
	v_mfma_f32_16x16x32_f16 v[72:75], v[148:151], v[172:175], v[72:75]
	v_mfma_f32_16x16x32_f16 v[80:83], v[148:151], v[180:183], v[80:83]
	v_mfma_f32_16x16x32_f16 v[80:83], v[152:155], v[184:187], v[80:83]
	v_mfma_f32_16x16x32_f16 v[76:79], v[142:145], v[184:187], v[76:79]
	v_mfma_f32_16x16x32_f16 v[76:79], v[138:141], v[180:183], v[76:79]
	v_mfma_f32_16x16x32_f16 v[84:87], v[138:141], v[188:191], v[84:87]
	v_mfma_f32_16x16x32_f16 v[84:87], v[142:145], v[192:195], v[84:87]
	v_mfma_f32_16x16x32_f16 v[88:91], v[152:155], v[192:195], v[88:91]
	v_mfma_f32_16x16x32_f16 v[88:91], v[148:151], v[188:191], v[88:91]
	v_mfma_f32_16x16x32_f16 v[96:99], v[148:151], v[196:199], v[96:99]
	v_mfma_f32_16x16x32_f16 v[96:99], v[152:155], v[200:203], v[96:99]
	v_mfma_f32_16x16x32_f16 v[92:95], v[142:145], v[200:203], v[92:95]
	v_mfma_f32_16x16x32_f16 v[92:95], v[138:141], v[196:199], v[92:95]
	s_setprio 0
	s_setprio 1
	v_mfma_f32_16x16x32_f16 v[100:103], v[156:159], v[172:175], v[100:103]
	v_mfma_f32_16x16x32_f16 v[100:103], v[160:163], v[176:179], v[100:103]
	v_mfma_f32_16x16x32_f16 v[104:107], v[168:171], v[176:179], v[104:107]
	v_mfma_f32_16x16x32_f16 v[104:107], v[164:167], v[172:175], v[104:107]
	v_mfma_f32_16x16x32_f16 v[112:115], v[164:167], v[180:183], v[112:115]
	v_mfma_f32_16x16x32_f16 v[112:115], v[168:171], v[184:187], v[112:115]
	v_mfma_f32_16x16x32_f16 v[108:111], v[160:163], v[184:187], v[108:111]
	v_mfma_f32_16x16x32_f16 v[108:111], v[156:159], v[180:183], v[108:111]
	v_mfma_f32_16x16x32_f16 v[116:119], v[156:159], v[188:191], v[116:119]
	v_mfma_f32_16x16x32_f16 v[116:119], v[160:163], v[192:195], v[116:119]
	v_mfma_f32_16x16x32_f16 v[120:123], v[168:171], v[192:195], v[120:123]
	v_mfma_f32_16x16x32_f16 v[120:123], v[164:167], v[188:191], v[120:123]
	v_mfma_f32_16x16x32_f16 v[128:131], v[164:167], v[196:199], v[128:131]
	v_mfma_f32_16x16x32_f16 v[128:131], v[168:171], v[200:203], v[128:131]
	v_mfma_f32_16x16x32_f16 v[124:127], v[160:163], v[200:203], v[124:127]
	v_mfma_f32_16x16x32_f16 v[124:127], v[156:159], v[196:199], v[124:127]
	s_setprio 0
	s_barrier
	s_add_i32 s28, s28, 2
	s_add_u32 s8, s8, 0x100
	s_addc_u32 s9, s9, 0
	s_add_u32 s26, s26, 0x100
	s_addc_u32 s27, s27, 0
	s_cmp_gt_u32 s28, 29
	s_cbranch_scc0 .LBB0_532
	s_and_b64 vcc, exec, s[50:51]
	s_cbranch_vccz .LBB0_535
	s_barrier

.LBB0_641:
	s_add_i32 s43, 0, 0x10000
	s_add_i32 s71, 0, 0x14000
	v_add_u32_e32 v16, s43, v232
	v_add_u32_e32 v32, s71, v232
	ds_read_b128 v[4:7], v16
	ds_read_b128 v[8:11], v16 offset:1024
	ds_read_b128 v[12:15], v16 offset:2048
	ds_read_b128 v[16:19], v16 offset:3072
	ds_read_b128 v[20:23], v32
	ds_read_b128 v[24:27], v32 offset:1024
	ds_read_b128 v[28:31], v32 offset:2048
	ds_read_b128 v[32:35], v32 offset:3072
	v_add_u32_e32 v233, 0, v231
	ds_read_b128 v[36:39], v233
	ds_read_b128 v[40:43], v233 offset:1024
	ds_read_b128 v[44:47], v233 offset:2048
	ds_read_b128 v[48:51], v233 offset:3072
	ds_read_b128 v[52:55], v233 offset:4096
	ds_read_b128 v[56:59], v233 offset:5120
	ds_read_b128 v[60:63], v233 offset:6144
	ds_read_b128 v[64:67], v233 offset:7168
	s_waitcnt vmcnt(8)
	s_waitcnt lgkmcnt(0)
	s_barrier
	s_setprio 1
	s_waitcnt lgkmcnt(0)
	v_mfma_f32_16x16x32_bf16 v[68:71], v[4:7], v[36:39], 0
	v_mfma_f32_16x16x32_bf16 v[68:71], v[8:11], v[40:43], v[68:71]
	v_mfma_f32_16x16x32_bf16 v[72:75], v[12:15], v[36:39], 0
	v_mfma_f32_16x16x32_bf16 v[72:75], v[16:19], v[40:43], v[72:75]
	v_mfma_f32_16x16x32_bf16 v[80:83], v[12:15], v[44:47], 0
	v_mfma_f32_16x16x32_bf16 v[80:83], v[16:19], v[48:51], v[80:83]
	v_mfma_f32_16x16x32_bf16 v[76:79], v[4:7], v[44:47], 0
	v_mfma_f32_16x16x32_bf16 v[76:79], v[8:11], v[48:51], v[76:79]
	v_mfma_f32_16x16x32_bf16 v[84:87], v[4:7], v[52:55], 0
	v_mfma_f32_16x16x32_bf16 v[84:87], v[8:11], v[56:59], v[84:87]
	v_mfma_f32_16x16x32_bf16 v[88:91], v[12:15], v[52:55], 0
	v_mfma_f32_16x16x32_bf16 v[88:91], v[16:19], v[56:59], v[88:91]
	v_mfma_f32_16x16x32_bf16 v[96:99], v[12:15], v[60:63], 0
	v_mfma_f32_16x16x32_bf16 v[96:99], v[16:19], v[64:67], v[96:99]
	v_mfma_f32_16x16x32_bf16 v[92:95], v[4:7], v[60:63], 0
	v_mfma_f32_16x16x32_bf16 v[92:95], v[8:11], v[64:67], v[92:95]
	s_setprio 0
	s_setprio 1
	v_mfma_f32_16x16x32_bf16 v[100:103], v[20:23], v[36:39], 0
	v_mfma_f32_16x16x32_bf16 v[36:39], v[28:31], v[36:39], 0
	v_mfma_f32_16x16x32_bf16 v[104:107], v[20:23], v[44:47], 0
	v_mfma_f32_16x16x32_bf16 v[44:47], v[28:31], v[44:47], 0
	v_mfma_f32_16x16x32_bf16 v[108:111], v[20:23], v[52:55], 0
	v_mfma_f32_16x16x32_bf16 v[52:55], v[28:31], v[52:55], 0
	v_mfma_f32_16x16x32_bf16 v[112:115], v[20:23], v[60:63], 0
	v_mfma_f32_16x16x32_bf16 v[60:63], v[28:31], v[60:63], 0
	v_mfma_f32_16x16x32_bf16 v[100:103], v[24:27], v[40:43], v[100:103]
	v_mfma_f32_16x16x32_bf16 v[40:43], v[32:35], v[40:43], v[36:39]
	v_mfma_f32_16x16x32_bf16 v[104:107], v[24:27], v[48:51], v[104:107]
	v_mfma_f32_16x16x32_bf16 v[48:51], v[32:35], v[48:51], v[44:47]
	v_mfma_f32_16x16x32_bf16 v[108:111], v[24:27], v[56:59], v[108:111]
	v_mfma_f32_16x16x32_bf16 v[56:59], v[32:35], v[56:59], v[52:55]
	v_mfma_f32_16x16x32_bf16 v[112:115], v[24:27], v[64:67], v[112:115]
	v_mfma_f32_16x16x32_bf16 v[64:67], v[32:35], v[64:67], v[60:63]
	s_setprio 0
	s_barrier
	v_lshl_add_u64 v[186:187], s[8:9], 0, v[2:3]
	s_add_i32 s43, s43, s54
	v_mov_b32_e32 v191, v3
	v_lshl_add_u64 v[134:135], v[186:187], 0, s[80:81]
	s_mov_b32 m0, s43
	v_lshl_add_u64 v[246:247], s[8:9], 0, v[190:191]
	ds_read_b128 v[36:39], v233 offset:16384
	ds_read_b128 v[44:47], v233 offset:17408
	ds_read_b128 v[52:55], v233 offset:18432
	ds_read_b128 v[60:63], v233 offset:19456
	ds_read_b128 v[116:119], v233 offset:20480
	ds_read_b128 v[120:123], v233 offset:21504
	ds_read_b128 v[124:127], v233 offset:22528
	ds_read_b128 v[128:131], v233 offset:23552
	global_load_lds_dwordx4 v[134:135], off
	v_lshl_add_u64 v[134:135], v[246:247], 0, s[80:81]
	s_add_i32 m0, s43, 0x2000
	s_add_i32 s43, s71, s54
	global_load_lds_dwordx4 v[134:135], off
	s_mov_b32 m0, s43
	v_mov_b32_e32 v133, v3
	global_load_lds_dwordx4 v2, s[16:17]
	s_add_i32 m0, s43, 0x2000
	v_lshl_add_u64 v[248:249], s[6:7], 0, v[132:133]
	v_mov_b32_e32 v189, v3
	global_load_lds_dwordx4 v190, s[16:17]
	v_lshl_add_u64 v[134:135], v[248:249], 0, s[80:81]
	s_mov_b32 m0, s55
	v_lshl_add_u64 v[250:251], s[6:7], 0, v[188:189]
	global_load_lds_dwordx4 v[134:135], off
	v_lshl_add_u64 v[134:135], v[250:251], 0, s[80:81]
	s_mov_b32 m0, s56
	s_nop 0
	global_load_lds_dwordx4 v[134:135], off
	s_waitcnt vmcnt(8)
	s_waitcnt lgkmcnt(0)
	s_barrier
	s_setprio 1
	s_waitcnt lgkmcnt(0)
	v_mfma_f32_16x16x32_bf16 v[134:137], v[4:7], v[36:39], 0
	v_mfma_f32_16x16x32_bf16 v[138:141], v[12:15], v[36:39], 0
	v_mfma_f32_16x16x32_bf16 v[142:145], v[4:7], v[52:55], 0
	v_mfma_f32_16x16x32_bf16 v[146:149], v[12:15], v[52:55], 0
	v_mfma_f32_16x16x32_bf16 v[150:153], v[4:7], v[116:119], 0
	v_mfma_f32_16x16x32_bf16 v[154:157], v[12:15], v[116:119], 0
	v_mfma_f32_16x16x32_bf16 v[4:7], v[4:7], v[124:127], 0
	v_mfma_f32_16x16x32_bf16 v[12:15], v[12:15], v[124:127], 0
	v_mfma_f32_16x16x32_bf16 v[134:137], v[8:11], v[44:47], v[134:137]
	v_mfma_f32_16x16x32_bf16 v[138:141], v[16:19], v[44:47], v[138:141]
	v_mfma_f32_16x16x32_bf16 v[142:145], v[8:11], v[60:63], v[142:145]
	v_mfma_f32_16x16x32_bf16 v[146:149], v[16:19], v[60:63], v[146:149]
	v_mfma_f32_16x16x32_bf16 v[150:153], v[8:11], v[120:123], v[150:153]
	v_mfma_f32_16x16x32_bf16 v[154:157], v[16:19], v[120:123], v[154:157]
	v_mfma_f32_16x16x32_bf16 v[158:161], v[8:11], v[128:131], v[4:7]
	v_mfma_f32_16x16x32_bf16 v[162:165], v[16:19], v[128:131], v[12:15]
	s_setprio 0
	s_setprio 1
	v_mfma_f32_16x16x32_bf16 v[4:7], v[20:23], v[36:39], 0
	v_mfma_f32_16x16x32_bf16 v[8:11], v[28:31], v[36:39], 0
	v_mfma_f32_16x16x32_bf16 v[12:15], v[20:23], v[52:55], 0
	v_mfma_f32_16x16x32_bf16 v[16:19], v[28:31], v[52:55], 0
	v_mfma_f32_16x16x32_bf16 v[36:39], v[20:23], v[116:119], 0
	v_mfma_f32_16x16x32_bf16 v[52:55], v[28:31], v[116:119], 0
	v_mfma_f32_16x16x32_bf16 v[20:23], v[20:23], v[124:127], 0
	v_mfma_f32_16x16x32_bf16 v[28:31], v[28:31], v[124:127], 0
	v_mfma_f32_16x16x32_bf16 v[116:119], v[24:27], v[44:47], v[4:7]
	v_mfma_f32_16x16x32_bf16 v[124:127], v[32:35], v[44:47], v[8:11]
	v_mfma_f32_16x16x32_bf16 v[174:177], v[24:27], v[120:123], v[36:39]
	v_mfma_f32_16x16x32_bf16 v[120:123], v[32:35], v[120:123], v[52:55]
	v_mfma_f32_16x16x32_bf16 v[178:181], v[24:27], v[128:131], v[20:23]
	v_mfma_f32_16x16x32_bf16 v[128:131], v[32:35], v[128:131], v[28:31]
	v_mfma_f32_16x16x32_bf16 v[166:169], v[24:27], v[60:63], v[12:15]
	v_mfma_f32_16x16x32_bf16 v[170:173], v[32:35], v[60:63], v[16:19]
	s_setprio 0
	s_barrier
	s_add_i32 s43, 0, 0x18000
	v_add_u32_e32 v4, s43, v232
	s_add_i32 s71, 0, 0x1c000
	ds_read_b128 v[182:185], v4
	ds_read_b128 v[192:195], v4 offset:1024
	ds_read_b128 v[196:199], v4 offset:2048
	ds_read_b128 v[200:203], v4 offset:3072
	v_add_u32_e32 v4, s71, v232
	ds_read_b128 v[204:207], v4
	ds_read_b128 v[208:211], v4 offset:1024
	ds_read_b128 v[212:215], v4 offset:2048
	ds_read_b128 v[216:219], v4 offset:3072
	s_mov_b32 m0, s57
	ds_read_b128 v[44:47], v233 offset:32768
	ds_read_b128 v[52:55], v233 offset:33792
	ds_read_b128 v[60:63], v233 offset:34816
	ds_read_b128 v[220:223], v233 offset:35840
	ds_read_b128 v[224:227], v233 offset:36864
	ds_read_b128 v[234:237], v233 offset:37888
	ds_read_b128 v[238:241], v233 offset:38912
	ds_read_b128 v[242:245], v233 offset:39936
	global_load_lds_dwordx4 v132, s[26:27]
	s_mov_b32 m0, s58
	s_nop 0
	global_load_lds_dwordx4 v188, s[26:27]
	s_waitcnt vmcnt(8)
	s_waitcnt lgkmcnt(0)
	s_barrier
	s_setprio 1
	s_waitcnt lgkmcnt(0)
	v_mfma_f32_16x16x32_bf16 v[4:7], v[182:185], v[44:47], v[68:71]
	v_mfma_f32_16x16x32_bf16 v[8:11], v[196:199], v[44:47], v[72:75]
	v_mfma_f32_16x16x32_bf16 v[12:15], v[182:185], v[60:63], v[76:79]
	v_mfma_f32_16x16x32_bf16 v[16:19], v[196:199], v[60:63], v[80:83]
	v_mfma_f32_16x16x32_bf16 v[20:23], v[182:185], v[224:227], v[84:87]
	v_mfma_f32_16x16x32_bf16 v[24:27], v[196:199], v[224:227], v[88:91]
	v_mfma_f32_16x16x32_bf16 v[28:31], v[182:185], v[238:241], v[92:95]
	v_mfma_f32_16x16x32_bf16 v[32:35], v[196:199], v[238:241], v[96:99]
	v_mfma_f32_16x16x32_bf16 v[4:7], v[192:195], v[52:55], v[4:7]
	v_mfma_f32_16x16x32_bf16 v[8:11], v[200:203], v[52:55], v[8:11]
	v_mfma_f32_16x16x32_bf16 v[12:15], v[192:195], v[220:223], v[12:15]
	v_mfma_f32_16x16x32_bf16 v[16:19], v[200:203], v[220:223], v[16:19]
	v_mfma_f32_16x16x32_bf16 v[20:23], v[192:195], v[234:237], v[20:23]
	v_mfma_f32_16x16x32_bf16 v[24:27], v[200:203], v[234:237], v[24:27]
	v_mfma_f32_16x16x32_bf16 v[28:31], v[192:195], v[242:245], v[28:31]
	v_mfma_f32_16x16x32_bf16 v[32:35], v[200:203], v[242:245], v[32:35]
	s_setprio 0
	s_setprio 1
	v_mfma_f32_16x16x32_bf16 v[36:39], v[204:207], v[44:47], v[100:103]
	v_mfma_f32_16x16x32_bf16 v[40:43], v[212:215], v[44:47], v[40:43]
	v_mfma_f32_16x16x32_bf16 v[36:39], v[208:211], v[52:55], v[36:39]
	v_mfma_f32_16x16x32_bf16 v[40:43], v[216:219], v[52:55], v[40:43]
	v_mfma_f32_16x16x32_bf16 v[44:47], v[204:207], v[60:63], v[104:107]
	v_mfma_f32_16x16x32_bf16 v[48:51], v[212:215], v[60:63], v[48:51]
	v_mfma_f32_16x16x32_bf16 v[52:55], v[204:207], v[224:227], v[108:111]
	v_mfma_f32_16x16x32_bf16 v[56:59], v[212:215], v[224:227], v[56:59]
	v_mfma_f32_16x16x32_bf16 v[60:63], v[204:207], v[238:241], v[112:115]
	v_mfma_f32_16x16x32_bf16 v[64:67], v[212:215], v[238:241], v[64:67]
	v_mfma_f32_16x16x32_bf16 v[44:47], v[208:211], v[220:223], v[44:47]
	v_mfma_f32_16x16x32_bf16 v[48:51], v[216:219], v[220:223], v[48:51]
	v_mfma_f32_16x16x32_bf16 v[52:55], v[208:211], v[234:237], v[52:55]
	v_mfma_f32_16x16x32_bf16 v[56:59], v[216:219], v[234:237], v[56:59]
	v_mfma_f32_16x16x32_bf16 v[60:63], v[208:211], v[242:245], v[60:63]
	v_mfma_f32_16x16x32_bf16 v[64:67], v[216:219], v[242:245], v[64:67]
	s_setprio 0
	s_barrier
	s_add_i32 s43, s43, s54
	v_lshl_add_u64 v[68:69], v[186:187], 0, s[0:1]
	s_mov_b32 m0, s43
	ds_read_b128 v[104:107], v233 offset:49152
	ds_read_b128 v[108:111], v233 offset:50176
	ds_read_b128 v[112:115], v233 offset:51200
	ds_read_b128 v[220:223], v233 offset:52224
	ds_read_b128 v[224:227], v233 offset:53248
	ds_read_b128 v[234:237], v233 offset:54272
	ds_read_b128 v[238:241], v233 offset:55296
	ds_read_b128 v[242:245], v233 offset:56320
	global_load_lds_dwordx4 v[68:69], off
	v_lshl_add_u64 v[68:69], v[246:247], 0, s[0:1]
	s_add_i32 m0, s43, 0x2000
	s_add_i32 s43, s71, s54
	global_load_lds_dwordx4 v[68:69], off
	s_mov_b32 m0, s43
	v_lshl_add_u64 v[68:69], v[248:249], 0, s[0:1]
	global_load_lds_dwordx4 v2, s[28:29]
	s_add_i32 m0, s43, 0x2000
	s_nop 0
	global_load_lds_dwordx4 v190, s[28:29]
	s_mov_b32 m0, s62
	s_nop 0
	global_load_lds_dwordx4 v[68:69], off
	v_lshl_add_u64 v[68:69], v[250:251], 0, s[0:1]
	s_mov_b32 m0, s63
	s_nop 0
	global_load_lds_dwordx4 v[68:69], off
	s_waitcnt vmcnt(8)
	s_waitcnt lgkmcnt(0)
	s_barrier
	s_setprio 1
	s_waitcnt lgkmcnt(0)
	v_mfma_f32_16x16x32_bf16 v[68:71], v[182:185], v[104:107], v[134:137]
	v_mfma_f32_16x16x32_bf16 v[72:75], v[196:199], v[104:107], v[138:141]
	v_mfma_f32_16x16x32_bf16 v[76:79], v[182:185], v[112:115], v[142:145]
	v_mfma_f32_16x16x32_bf16 v[80:83], v[196:199], v[112:115], v[146:149]
	v_mfma_f32_16x16x32_bf16 v[84:87], v[182:185], v[224:227], v[150:153]
	v_mfma_f32_16x16x32_bf16 v[88:91], v[196:199], v[224:227], v[154:157]
	v_mfma_f32_16x16x32_bf16 v[92:95], v[182:185], v[238:241], v[158:161]
	v_mfma_f32_16x16x32_bf16 v[96:99], v[196:199], v[238:241], v[162:165]
	v_mfma_f32_16x16x32_bf16 v[68:71], v[192:195], v[108:111], v[68:71]
	v_mfma_f32_16x16x32_bf16 v[72:75], v[200:203], v[108:111], v[72:75]
	v_mfma_f32_16x16x32_bf16 v[76:79], v[192:195], v[220:223], v[76:79]
	v_mfma_f32_16x16x32_bf16 v[80:83], v[200:203], v[220:223], v[80:83]
	v_mfma_f32_16x16x32_bf16 v[84:87], v[192:195], v[234:237], v[84:87]
	v_mfma_f32_16x16x32_bf16 v[88:91], v[200:203], v[234:237], v[88:91]
	v_mfma_f32_16x16x32_bf16 v[92:95], v[192:195], v[242:245], v[92:95]
	v_mfma_f32_16x16x32_bf16 v[96:99], v[200:203], v[242:245], v[96:99]
	s_setprio 0
	s_setprio 1
	v_mfma_f32_16x16x32_bf16 v[100:103], v[204:207], v[104:107], v[116:119]
	v_mfma_f32_16x16x32_bf16 v[104:107], v[212:215], v[104:107], v[124:127]
	v_mfma_f32_16x16x32_bf16 v[100:103], v[208:211], v[108:111], v[100:103]
	v_mfma_f32_16x16x32_bf16 v[104:107], v[216:219], v[108:111], v[104:107]
	v_mfma_f32_16x16x32_bf16 v[108:111], v[204:207], v[112:115], v[166:169]
	v_mfma_f32_16x16x32_bf16 v[112:115], v[212:215], v[112:115], v[170:173]
	v_mfma_f32_16x16x32_bf16 v[116:119], v[204:207], v[224:227], v[174:177]
	v_mfma_f32_16x16x32_bf16 v[120:123], v[212:215], v[224:227], v[120:123]
	v_mfma_f32_16x16x32_bf16 v[124:127], v[204:207], v[238:241], v[178:181]
	v_mfma_f32_16x16x32_bf16 v[128:131], v[212:215], v[238:241], v[128:131]
	v_mfma_f32_16x16x32_bf16 v[108:111], v[208:211], v[220:223], v[108:111]
	v_mfma_f32_16x16x32_bf16 v[112:115], v[216:219], v[220:223], v[112:115]
	v_mfma_f32_16x16x32_bf16 v[116:119], v[208:211], v[234:237], v[116:119]
	v_mfma_f32_16x16x32_bf16 v[120:123], v[216:219], v[234:237], v[120:123]
	v_mfma_f32_16x16x32_bf16 v[124:127], v[208:211], v[242:245], v[124:127]
	v_mfma_f32_16x16x32_bf16 v[128:131], v[216:219], v[242:245], v[128:131]
	s_setprio 0
	s_barrier
	s_add_i32 s42, s42, 2
	s_cmp_ge_i32 s42, s38
	s_cbranch_scc0 .LBB0_641
	v_mov_b32_e32 v192, v2
	s_branch .LBB0_644

.LBB0_649:
	s_or_b32 s38, s28, 1
	s_lshl_b64 s[42:43], s[38:39], 7
	s_sub_u32 s38, 0, s42
	s_subb_u32 s42, 0, s43
	s_add_u32 s38, s6, s38
	s_addc_u32 s43, s7, s42
	s_add_i32 s71, 0, 0x10000
	s_add_i32 s72, 0, 0x14000
	v_add_u32_e32 v144, s71, v232
	v_add_u32_e32 v160, s72, v232
	s_waitcnt lgkmcnt(0)
	ds_read_b128 v[132:135], v144
	ds_read_b128 v[136:139], v144 offset:1024
	ds_read_b128 v[140:143], v144 offset:2048
	ds_read_b128 v[144:147], v144 offset:3072
	ds_read_b128 v[148:151], v160
	ds_read_b128 v[152:155], v160 offset:1024
	ds_read_b128 v[156:159], v160 offset:2048
	ds_read_b128 v[160:163], v160 offset:3072
	s_add_u32 s42, s38, 0x160000
	s_mov_b32 m0, s64
	v_add_u32_e32 v210, 0, v231
	s_addc_u32 s43, s43, 0
	ds_read_b128 v[164:167], v210
	ds_read_b128 v[168:171], v210 offset:1024
	ds_read_b128 v[172:175], v210 offset:2048
	ds_read_b128 v[176:179], v210 offset:3072
	ds_read_b128 v[180:183], v210 offset:4096
	ds_read_b128 v[184:187], v210 offset:5120
	ds_read_b128 v[194:197], v210 offset:6144
	ds_read_b128 v[198:201], v210 offset:7168
	global_load_lds_dwordx4 v2, s[42:43]
	s_mov_b32 m0, s65
	v_mov_b32_e32 v189, v3
	global_load_lds_dwordx4 v188, s[42:43]
	s_waitcnt vmcnt(8)
	s_waitcnt lgkmcnt(0)
	s_barrier
	s_setprio 1
	s_waitcnt lgkmcnt(0)
	v_mfma_f32_16x16x32_bf16 v[4:7], v[132:135], v[164:167], v[4:7]
	v_mfma_f32_16x16x32_bf16 v[4:7], v[136:139], v[168:171], v[4:7]
	v_mfma_f32_16x16x32_bf16 v[8:11], v[144:147], v[168:171], v[8:11]
	v_mfma_f32_16x16x32_bf16 v[8:11], v[140:143], v[164:167], v[8:11]
	v_mfma_f32_16x16x32_bf16 v[16:19], v[140:143], v[172:175], v[16:19]
	v_mfma_f32_16x16x32_bf16 v[16:19], v[144:147], v[176:179], v[16:19]
	v_mfma_f32_16x16x32_bf16 v[12:15], v[136:139], v[176:179], v[12:15]
	v_mfma_f32_16x16x32_bf16 v[12:15], v[132:135], v[172:175], v[12:15]
	v_mfma_f32_16x16x32_bf16 v[20:23], v[132:135], v[180:183], v[20:23]
	v_mfma_f32_16x16x32_bf16 v[20:23], v[136:139], v[184:187], v[20:23]
	v_mfma_f32_16x16x32_bf16 v[24:27], v[144:147], v[184:187], v[24:27]
	v_mfma_f32_16x16x32_bf16 v[24:27], v[140:143], v[180:183], v[24:27]
	v_mfma_f32_16x16x32_bf16 v[32:35], v[140:143], v[194:197], v[32:35]
	v_mfma_f32_16x16x32_bf16 v[32:35], v[144:147], v[198:201], v[32:35]
	v_mfma_f32_16x16x32_bf16 v[28:31], v[136:139], v[198:201], v[28:31]
	v_mfma_f32_16x16x32_bf16 v[28:31], v[132:135], v[194:197], v[28:31]
	s_setprio 0
	s_setprio 1
	v_mfma_f32_16x16x32_bf16 v[36:39], v[148:151], v[164:167], v[36:39]
	v_mfma_f32_16x16x32_bf16 v[36:39], v[152:155], v[168:171], v[36:39]
	v_mfma_f32_16x16x32_bf16 v[40:43], v[160:163], v[168:171], v[40:43]
	v_mfma_f32_16x16x32_bf16 v[40:43], v[156:159], v[164:167], v[40:43]
	v_mfma_f32_16x16x32_bf16 v[48:51], v[156:159], v[172:175], v[48:51]
	v_mfma_f32_16x16x32_bf16 v[48:51], v[160:163], v[176:179], v[48:51]
	v_mfma_f32_16x16x32_bf16 v[44:47], v[152:155], v[176:179], v[44:47]
	v_mfma_f32_16x16x32_bf16 v[44:47], v[148:151], v[172:175], v[44:47]
	v_mfma_f32_16x16x32_bf16 v[52:55], v[148:151], v[180:183], v[52:55]
	v_mfma_f32_16x16x32_bf16 v[52:55], v[152:155], v[184:187], v[52:55]
	v_mfma_f32_16x16x32_bf16 v[56:59], v[160:163], v[184:187], v[56:59]
	v_mfma_f32_16x16x32_bf16 v[56:59], v[156:159], v[180:183], v[56:59]
	v_mfma_f32_16x16x32_bf16 v[64:67], v[156:159], v[194:197], v[64:67]
	v_mfma_f32_16x16x32_bf16 v[64:67], v[160:163], v[198:201], v[64:67]
	v_mfma_f32_16x16x32_bf16 v[60:63], v[152:155], v[198:201], v[60:63]
	v_mfma_f32_16x16x32_bf16 v[60:63], v[148:151], v[194:197], v[60:63]
	s_setprio 0
	s_barrier
	s_add_i32 s38, s71, s54
	s_mov_b32 m0, s38
	ds_read_b128 v[164:167], v210 offset:16384
	ds_read_b128 v[168:171], v210 offset:17408
	ds_read_b128 v[172:175], v210 offset:18432
	ds_read_b128 v[176:179], v210 offset:19456
	ds_read_b128 v[180:183], v210 offset:20480
	ds_read_b128 v[184:187], v210 offset:21504
	ds_read_b128 v[194:197], v210 offset:22528
	ds_read_b128 v[198:201], v210 offset:23552
	global_load_lds_dwordx4 v192, s[16:17]
	s_add_i32 m0, s38, 0x2000
	s_add_u32 s42, s16, 0x160000
	s_addc_u32 s43, s17, 0
	s_add_i32 s38, s72, s54
	global_load_lds_dwordx4 v190, s[16:17]
	s_mov_b32 m0, s38
	v_mov_b32_e32 v193, v3
	global_load_lds_dwordx4 v192, s[42:43]
	s_add_i32 m0, s38, 0x2000
	v_mov_b32_e32 v191, v3
	global_load_lds_dwordx4 v190, s[42:43]
	s_mov_b32 m0, s55
	v_lshl_add_u64 v[202:203], s[16:17], 0, v[192:193]
	global_load_lds_dwordx4 v2, s[26:27]
	s_mov_b32 m0, s56
	v_lshl_add_u64 v[204:205], s[16:17], 0, v[190:191]
	global_load_lds_dwordx4 v188, s[26:27]
	s_waitcnt vmcnt(8)
	s_waitcnt lgkmcnt(0)
	v_lshl_add_u64 v[206:207], s[26:27], 0, v[2:3]
	v_lshl_add_u64 v[208:209], s[26:27], 0, v[188:189]
	s_barrier
	s_setprio 1
	s_waitcnt lgkmcnt(0)
	v_mfma_f32_16x16x32_bf16 v[68:71], v[132:135], v[164:167], v[68:71]
	v_mfma_f32_16x16x32_bf16 v[68:71], v[136:139], v[168:171], v[68:71]
	v_mfma_f32_16x16x32_bf16 v[72:75], v[144:147], v[168:171], v[72:75]
	v_mfma_f32_16x16x32_bf16 v[72:75], v[140:143], v[164:167], v[72:75]
	v_mfma_f32_16x16x32_bf16 v[80:83], v[140:143], v[172:175], v[80:83]
	v_mfma_f32_16x16x32_bf16 v[80:83], v[144:147], v[176:179], v[80:83]
	v_mfma_f32_16x16x32_bf16 v[76:79], v[136:139], v[176:179], v[76:79]
	v_mfma_f32_16x16x32_bf16 v[76:79], v[132:135], v[172:175], v[76:79]
	v_mfma_f32_16x16x32_bf16 v[84:87], v[132:135], v[180:183], v[84:87]
	v_mfma_f32_16x16x32_bf16 v[84:87], v[136:139], v[184:187], v[84:87]
	v_mfma_f32_16x16x32_bf16 v[88:91], v[144:147], v[184:187], v[88:91]
	v_mfma_f32_16x16x32_bf16 v[88:91], v[140:143], v[180:183], v[88:91]
	v_mfma_f32_16x16x32_bf16 v[96:99], v[140:143], v[194:197], v[96:99]
	v_mfma_f32_16x16x32_bf16 v[96:99], v[144:147], v[198:201], v[96:99]
	v_mfma_f32_16x16x32_bf16 v[92:95], v[136:139], v[198:201], v[92:95]
	v_mfma_f32_16x16x32_bf16 v[92:95], v[132:135], v[194:197], v[92:95]
	s_setprio 0
	s_setprio 1
	v_mfma_f32_16x16x32_bf16 v[100:103], v[148:151], v[164:167], v[100:103]
	v_mfma_f32_16x16x32_bf16 v[100:103], v[152:155], v[168:171], v[100:103]
	v_mfma_f32_16x16x32_bf16 v[104:107], v[160:163], v[168:171], v[104:107]
	v_mfma_f32_16x16x32_bf16 v[104:107], v[156:159], v[164:167], v[104:107]
	v_mfma_f32_16x16x32_bf16 v[112:115], v[156:159], v[172:175], v[112:115]
	v_mfma_f32_16x16x32_bf16 v[112:115], v[160:163], v[176:179], v[112:115]
	v_mfma_f32_16x16x32_bf16 v[108:111], v[152:155], v[176:179], v[108:111]
	v_mfma_f32_16x16x32_bf16 v[108:111], v[148:151], v[172:175], v[108:111]
	v_mfma_f32_16x16x32_bf16 v[116:119], v[148:151], v[180:183], v[116:119]
	v_mfma_f32_16x16x32_bf16 v[116:119], v[152:155], v[184:187], v[116:119]
	v_mfma_f32_16x16x32_bf16 v[120:123], v[160:163], v[184:187], v[120:123]
	v_mfma_f32_16x16x32_bf16 v[120:123], v[156:159], v[180:183], v[120:123]
	v_mfma_f32_16x16x32_bf16 v[128:131], v[156:159], v[194:197], v[128:131]
	v_mfma_f32_16x16x32_bf16 v[128:131], v[160:163], v[198:201], v[128:131]
	v_mfma_f32_16x16x32_bf16 v[124:127], v[152:155], v[198:201], v[124:127]
	v_mfma_f32_16x16x32_bf16 v[124:127], v[148:151], v[194:197], v[124:127]
	s_setprio 0
	s_barrier
	s_add_i32 s38, 0, 0x18000
	s_add_i32 s42, 0, 0x1c000
	v_add_u32_e32 v144, s38, v232
	v_add_u32_e32 v160, s42, v232
	ds_read_b128 v[132:135], v144
	ds_read_b128 v[136:139], v144 offset:1024
	ds_read_b128 v[140:143], v144 offset:2048
	ds_read_b128 v[144:147], v144 offset:3072
	ds_read_b128 v[148:151], v160
	ds_read_b128 v[152:155], v160 offset:1024
	ds_read_b128 v[156:159], v160 offset:2048
	ds_read_b128 v[160:163], v160 offset:3072
	s_add_u32 s26, s26, 0x160000
	s_addc_u32 s27, s27, 0
	s_mov_b32 m0, s57
	ds_read_b128 v[164:167], v210 offset:32768
	ds_read_b128 v[168:171], v210 offset:33792
	ds_read_b128 v[172:175], v210 offset:34816
	ds_read_b128 v[176:179], v210 offset:35840
	ds_read_b128 v[180:183], v210 offset:36864
	ds_read_b128 v[184:187], v210 offset:37888
	ds_read_b128 v[194:197], v210 offset:38912
	ds_read_b128 v[198:201], v210 offset:39936
	global_load_lds_dwordx4 v2, s[26:27]
	s_mov_b32 m0, s58
	s_nop 0
	global_load_lds_dwordx4 v188, s[26:27]
	s_waitcnt vmcnt(8)
	s_waitcnt lgkmcnt(0)
	s_barrier
	s_setprio 1
	s_waitcnt lgkmcnt(0)
	v_mfma_f32_16x16x32_bf16 v[4:7], v[132:135], v[164:167], v[4:7]
	v_mfma_f32_16x16x32_bf16 v[4:7], v[136:139], v[168:171], v[4:7]
	v_mfma_f32_16x16x32_bf16 v[8:11], v[144:147], v[168:171], v[8:11]
	v_mfma_f32_16x16x32_bf16 v[8:11], v[140:143], v[164:167], v[8:11]
	v_mfma_f32_16x16x32_bf16 v[16:19], v[140:143], v[172:175], v[16:19]
	v_mfma_f32_16x16x32_bf16 v[16:19], v[144:147], v[176:179], v[16:19]
	v_mfma_f32_16x16x32_bf16 v[12:15], v[136:139], v[176:179], v[12:15]
	v_mfma_f32_16x16x32_bf16 v[12:15], v[132:135], v[172:175], v[12:15]
	v_mfma_f32_16x16x32_bf16 v[20:23], v[132:135], v[180:183], v[20:23]
	v_mfma_f32_16x16x32_bf16 v[20:23], v[136:139], v[184:187], v[20:23]
	v_mfma_f32_16x16x32_bf16 v[24:27], v[144:147], v[184:187], v[24:27]
	v_mfma_f32_16x16x32_bf16 v[24:27], v[140:143], v[180:183], v[24:27]
	v_mfma_f32_16x16x32_bf16 v[32:35], v[140:143], v[194:197], v[32:35]
	v_mfma_f32_16x16x32_bf16 v[32:35], v[144:147], v[198:201], v[32:35]
	v_mfma_f32_16x16x32_bf16 v[28:31], v[136:139], v[198:201], v[28:31]
	v_mfma_f32_16x16x32_bf16 v[28:31], v[132:135], v[194:197], v[28:31]
	s_setprio 0
	s_setprio 1
	v_mfma_f32_16x16x32_bf16 v[36:39], v[148:151], v[164:167], v[36:39]
	v_mfma_f32_16x16x32_bf16 v[36:39], v[152:155], v[168:171], v[36:39]
	v_mfma_f32_16x16x32_bf16 v[40:43], v[160:163], v[168:171], v[40:43]
	v_mfma_f32_16x16x32_bf16 v[40:43], v[156:159], v[164:167], v[40:43]
	v_mfma_f32_16x16x32_bf16 v[48:51], v[156:159], v[172:175], v[48:51]
	v_mfma_f32_16x16x32_bf16 v[48:51], v[160:163], v[176:179], v[48:51]
	v_mfma_f32_16x16x32_bf16 v[44:47], v[152:155], v[176:179], v[44:47]
	v_mfma_f32_16x16x32_bf16 v[44:47], v[148:151], v[172:175], v[44:47]
	v_mfma_f32_16x16x32_bf16 v[52:55], v[148:151], v[180:183], v[52:55]
	v_mfma_f32_16x16x32_bf16 v[52:55], v[152:155], v[184:187], v[52:55]
	v_mfma_f32_16x16x32_bf16 v[56:59], v[160:163], v[184:187], v[56:59]
	v_mfma_f32_16x16x32_bf16 v[56:59], v[156:159], v[180:183], v[56:59]
	v_mfma_f32_16x16x32_bf16 v[64:67], v[156:159], v[194:197], v[64:67]
	v_mfma_f32_16x16x32_bf16 v[64:67], v[160:163], v[198:201], v[64:67]
	v_mfma_f32_16x16x32_bf16 v[60:63], v[152:155], v[198:201], v[60:63]
	v_mfma_f32_16x16x32_bf16 v[60:63], v[148:151], v[194:197], v[60:63]
	s_setprio 0
	s_barrier
	s_add_i32 s26, s38, s54
	v_lshl_add_u64 v[202:203], v[202:203], 0, s[4:5]
	s_mov_b32 m0, s26
	ds_read_b128 v[164:167], v210 offset:49152
	ds_read_b128 v[168:171], v210 offset:50176
	ds_read_b128 v[172:175], v210 offset:51200
	ds_read_b128 v[176:179], v210 offset:52224
	ds_read_b128 v[180:183], v210 offset:53248
	ds_read_b128 v[184:187], v210 offset:54272
	ds_read_b128 v[194:197], v210 offset:55296
	ds_read_b128 v[198:201], v210 offset:56320
	global_load_lds_dwordx4 v[202:203], off
	s_add_i32 m0, s26, 0x2000
	s_add_u32 s16, s16, 0x15ff80
	v_lshl_add_u64 v[202:203], v[204:205], 0, s[4:5]
	s_addc_u32 s17, s17, 0
	s_add_i32 s26, s42, s54
	global_load_lds_dwordx4 v[202:203], off
	s_mov_b32 m0, s26
	v_lshl_add_u64 v[202:203], v[206:207], 0, s[4:5]
	global_load_lds_dwordx4 v192, s[16:17]
	s_add_i32 m0, s26, 0x2000
	s_nop 0
	global_load_lds_dwordx4 v190, s[16:17]
	s_mov_b32 m0, s62
	s_nop 0
	global_load_lds_dwordx4 v[202:203], off
	v_lshl_add_u64 v[202:203], v[208:209], 0, s[4:5]
	s_mov_b32 m0, s63
	s_nop 0
	global_load_lds_dwordx4 v[202:203], off
	s_waitcnt vmcnt(8)
	s_waitcnt lgkmcnt(0)
	s_barrier
	s_setprio 1
	s_waitcnt lgkmcnt(0)
	v_mfma_f32_16x16x32_bf16 v[68:71], v[132:135], v[164:167], v[68:71]
	v_mfma_f32_16x16x32_bf16 v[68:71], v[136:139], v[168:171], v[68:71]
	v_mfma_f32_16x16x32_bf16 v[72:75], v[144:147], v[168:171], v[72:75]
	v_mfma_f32_16x16x32_bf16 v[72:75], v[140:143], v[164:167], v[72:75]
	v_mfma_f32_16x16x32_bf16 v[80:83], v[140:143], v[172:175], v[80:83]
	v_mfma_f32_16x16x32_bf16 v[80:83], v[144:147], v[176:179], v[80:83]
	v_mfma_f32_16x16x32_bf16 v[76:79], v[136:139], v[176:179], v[76:79]
	v_mfma_f32_16x16x32_bf16 v[76:79], v[132:135], v[172:175], v[76:79]
	v_mfma_f32_16x16x32_bf16 v[84:87], v[132:135], v[180:183], v[84:87]
	v_mfma_f32_16x16x32_bf16 v[84:87], v[136:139], v[184:187], v[84:87]
	v_mfma_f32_16x16x32_bf16 v[88:91], v[144:147], v[184:187], v[88:91]
	v_mfma_f32_16x16x32_bf16 v[88:91], v[140:143], v[180:183], v[88:91]
	v_mfma_f32_16x16x32_bf16 v[96:99], v[140:143], v[194:197], v[96:99]
	v_mfma_f32_16x16x32_bf16 v[96:99], v[144:147], v[198:201], v[96:99]
	v_mfma_f32_16x16x32_bf16 v[92:95], v[136:139], v[198:201], v[92:95]
	v_mfma_f32_16x16x32_bf16 v[92:95], v[132:135], v[194:197], v[92:95]
	s_setprio 0
	s_setprio 1
	v_mfma_f32_16x16x32_bf16 v[100:103], v[148:151], v[164:167], v[100:103]
	v_mfma_f32_16x16x32_bf16 v[100:103], v[152:155], v[168:171], v[100:103]
	v_mfma_f32_16x16x32_bf16 v[104:107], v[160:163], v[168:171], v[104:107]
	v_mfma_f32_16x16x32_bf16 v[104:107], v[156:159], v[164:167], v[104:107]
	v_mfma_f32_16x16x32_bf16 v[112:115], v[156:159], v[172:175], v[112:115]
	v_mfma_f32_16x16x32_bf16 v[112:115], v[160:163], v[176:179], v[112:115]
	v_mfma_f32_16x16x32_bf16 v[108:111], v[152:155], v[176:179], v[108:111]
	v_mfma_f32_16x16x32_bf16 v[108:111], v[148:151], v[172:175], v[108:111]
	v_mfma_f32_16x16x32_bf16 v[116:119], v[148:151], v[180:183], v[116:119]
	v_mfma_f32_16x16x32_bf16 v[116:119], v[152:155], v[184:187], v[116:119]
	v_mfma_f32_16x16x32_bf16 v[120:123], v[160:163], v[184:187], v[120:123]
	v_mfma_f32_16x16x32_bf16 v[120:123], v[156:159], v[180:183], v[120:123]
	v_mfma_f32_16x16x32_bf16 v[128:131], v[156:159], v[194:197], v[128:131]
	v_mfma_f32_16x16x32_bf16 v[128:131], v[160:163], v[198:201], v[128:131]
	v_mfma_f32_16x16x32_bf16 v[124:127], v[152:155], v[198:201], v[124:127]
	v_mfma_f32_16x16x32_bf16 v[124:127], v[148:151], v[194:197], v[124:127]
	s_setprio 0
	s_barrier
	s_cmpk_gt_u32 s28, 0x55
	s_cbranch_scc1 .LBB0_651
	s_mov_b32 s28, s29
	s_branch .LBB0_645

.LBB0_749:
	s_add_i32 s47, 0, 0x10000
	s_add_i32 s49, 0, 0x14000
	v_add_u32_e32 v16, s47, v147
	v_add_u32_e32 v32, s49, v147
	ds_read_b128 v[4:7], v16
	ds_read_b128 v[8:11], v16 offset:1024
	ds_read_b128 v[12:15], v16 offset:2048
	ds_read_b128 v[16:19], v16 offset:3072
	ds_read_b128 v[20:23], v32
	ds_read_b128 v[24:27], v32 offset:1024
	ds_read_b128 v[28:31], v32 offset:2048
	ds_read_b128 v[32:35], v32 offset:3072
	v_add_u32_e32 v231, 0, v146
	ds_read_b128 v[36:39], v231
	ds_read_b128 v[40:43], v231 offset:1024
	ds_read_b128 v[44:47], v231 offset:2048
	ds_read_b128 v[48:51], v231 offset:3072
	ds_read_b128 v[52:55], v231 offset:4096
	ds_read_b128 v[56:59], v231 offset:5120
	ds_read_b128 v[60:63], v231 offset:6144
	ds_read_b128 v[64:67], v231 offset:7168
	s_waitcnt vmcnt(8)
	s_waitcnt lgkmcnt(0)
	s_barrier
	s_setprio 1
	s_waitcnt lgkmcnt(0)
	v_mfma_f32_16x16x32_f16 v[68:71], v[4:7], v[36:39], 0
	v_mfma_f32_16x16x32_f16 v[68:71], v[8:11], v[40:43], v[68:71]
	v_mfma_f32_16x16x32_f16 v[72:75], v[12:15], v[36:39], 0
	v_mfma_f32_16x16x32_f16 v[72:75], v[16:19], v[40:43], v[72:75]
	v_mfma_f32_16x16x32_f16 v[80:83], v[12:15], v[44:47], 0
	v_mfma_f32_16x16x32_f16 v[80:83], v[16:19], v[48:51], v[80:83]
	v_mfma_f32_16x16x32_f16 v[76:79], v[4:7], v[44:47], 0
	v_mfma_f32_16x16x32_f16 v[76:79], v[8:11], v[48:51], v[76:79]
	v_mfma_f32_16x16x32_f16 v[84:87], v[4:7], v[52:55], 0
	v_mfma_f32_16x16x32_f16 v[84:87], v[8:11], v[56:59], v[84:87]
	v_mfma_f32_16x16x32_f16 v[88:91], v[12:15], v[52:55], 0
	v_mfma_f32_16x16x32_f16 v[88:91], v[16:19], v[56:59], v[88:91]
	v_mfma_f32_16x16x32_f16 v[96:99], v[12:15], v[60:63], 0
	v_mfma_f32_16x16x32_f16 v[96:99], v[16:19], v[64:67], v[96:99]
	v_mfma_f32_16x16x32_f16 v[92:95], v[4:7], v[60:63], 0
	v_mfma_f32_16x16x32_f16 v[92:95], v[8:11], v[64:67], v[92:95]
	s_setprio 0
	s_setprio 1
	v_mfma_f32_16x16x32_f16 v[100:103], v[20:23], v[36:39], 0
	v_mfma_f32_16x16x32_f16 v[36:39], v[28:31], v[36:39], 0
	v_mfma_f32_16x16x32_f16 v[104:107], v[20:23], v[44:47], 0
	v_mfma_f32_16x16x32_f16 v[44:47], v[28:31], v[44:47], 0
	v_mfma_f32_16x16x32_f16 v[108:111], v[20:23], v[52:55], 0
	v_mfma_f32_16x16x32_f16 v[52:55], v[28:31], v[52:55], 0
	v_mfma_f32_16x16x32_f16 v[112:115], v[20:23], v[60:63], 0
	v_mfma_f32_16x16x32_f16 v[60:63], v[28:31], v[60:63], 0
	v_mfma_f32_16x16x32_f16 v[100:103], v[24:27], v[40:43], v[100:103]
	v_mfma_f32_16x16x32_f16 v[40:43], v[32:35], v[40:43], v[36:39]
	v_mfma_f32_16x16x32_f16 v[104:107], v[24:27], v[48:51], v[104:107]
	v_mfma_f32_16x16x32_f16 v[48:51], v[32:35], v[48:51], v[44:47]
	v_mfma_f32_16x16x32_f16 v[108:111], v[24:27], v[56:59], v[108:111]
	v_mfma_f32_16x16x32_f16 v[56:59], v[32:35], v[56:59], v[52:55]
	v_mfma_f32_16x16x32_f16 v[112:115], v[24:27], v[64:67], v[112:115]
	v_mfma_f32_16x16x32_f16 v[64:67], v[32:35], v[64:67], v[60:63]
	s_setprio 0
	s_barrier
	v_lshl_add_u64 v[136:137], s[6:7], 0, v[2:3]
	s_add_i32 s47, s47, s62
	v_mov_b32_e32 v135, v3
	v_lshl_add_u64 v[140:141], v[136:137], 0, s[74:75]
	s_mov_b32 m0, s47
	v_lshl_add_u64 v[144:145], s[6:7], 0, v[134:135]
	ds_read_b128 v[36:39], v231 offset:16384
	ds_read_b128 v[44:47], v231 offset:17408
	ds_read_b128 v[52:55], v231 offset:18432
	ds_read_b128 v[60:63], v231 offset:19456
	ds_read_b128 v[116:119], v231 offset:20480
	ds_read_b128 v[120:123], v231 offset:21504
	ds_read_b128 v[124:127], v231 offset:22528
	ds_read_b128 v[128:131], v231 offset:23552
	global_load_lds_dwordx4 v[140:141], off
	v_lshl_add_u64 v[140:141], v[144:145], 0, s[74:75]
	s_add_i32 m0, s47, 0x2000
	s_add_i32 s47, s49, s62
	global_load_lds_dwordx4 v[140:141], off
	s_mov_b32 m0, s47
	v_mov_b32_e32 v139, v3
	global_load_lds_dwordx4 v2, s[16:17]
	s_add_i32 m0, s47, 0x2000
	v_lshl_add_u64 v[248:249], s[8:9], 0, v[138:139]
	v_mov_b32_e32 v133, v3
	global_load_lds_dwordx4 v134, s[16:17]
	v_lshl_add_u64 v[140:141], v[248:249], 0, s[74:75]
	s_mov_b32 m0, s63
	v_lshl_add_u64 v[250:251], s[8:9], 0, v[132:133]
	global_load_lds_dwordx4 v[140:141], off
	v_lshl_add_u64 v[140:141], v[250:251], 0, s[74:75]
	s_mov_b32 m0, s64
	s_nop 0
	global_load_lds_dwordx4 v[140:141], off
	s_waitcnt vmcnt(8)
	s_waitcnt lgkmcnt(0)
	s_barrier
	s_setprio 1
	s_waitcnt lgkmcnt(0)
	v_mfma_f32_16x16x32_f16 v[140:143], v[4:7], v[36:39], 0
	v_mfma_f32_16x16x32_f16 v[148:151], v[12:15], v[36:39], 0
	v_mfma_f32_16x16x32_f16 v[152:155], v[4:7], v[52:55], 0
	v_mfma_f32_16x16x32_f16 v[156:159], v[12:15], v[52:55], 0
	v_mfma_f32_16x16x32_f16 v[160:163], v[4:7], v[116:119], 0
	v_mfma_f32_16x16x32_f16 v[164:167], v[12:15], v[116:119], 0
	v_mfma_f32_16x16x32_f16 v[4:7], v[4:7], v[124:127], 0
	v_mfma_f32_16x16x32_f16 v[12:15], v[12:15], v[124:127], 0
	v_mfma_f32_16x16x32_f16 v[140:143], v[8:11], v[44:47], v[140:143]
	v_mfma_f32_16x16x32_f16 v[148:151], v[16:19], v[44:47], v[148:151]
	v_mfma_f32_16x16x32_f16 v[152:155], v[8:11], v[60:63], v[152:155]
	v_mfma_f32_16x16x32_f16 v[156:159], v[16:19], v[60:63], v[156:159]
	v_mfma_f32_16x16x32_f16 v[160:163], v[8:11], v[120:123], v[160:163]
	v_mfma_f32_16x16x32_f16 v[164:167], v[16:19], v[120:123], v[164:167]
	v_mfma_f32_16x16x32_f16 v[168:171], v[8:11], v[128:131], v[4:7]
	v_mfma_f32_16x16x32_f16 v[172:175], v[16:19], v[128:131], v[12:15]
	s_setprio 0
	s_setprio 1
	v_mfma_f32_16x16x32_f16 v[4:7], v[20:23], v[36:39], 0
	v_mfma_f32_16x16x32_f16 v[8:11], v[28:31], v[36:39], 0
	v_mfma_f32_16x16x32_f16 v[12:15], v[20:23], v[52:55], 0
	v_mfma_f32_16x16x32_f16 v[16:19], v[28:31], v[52:55], 0
	v_mfma_f32_16x16x32_f16 v[36:39], v[20:23], v[116:119], 0
	v_mfma_f32_16x16x32_f16 v[52:55], v[28:31], v[116:119], 0
	v_mfma_f32_16x16x32_f16 v[20:23], v[20:23], v[124:127], 0
	v_mfma_f32_16x16x32_f16 v[28:31], v[28:31], v[124:127], 0
	v_mfma_f32_16x16x32_f16 v[116:119], v[24:27], v[44:47], v[4:7]
	v_mfma_f32_16x16x32_f16 v[124:127], v[32:35], v[44:47], v[8:11]
	v_mfma_f32_16x16x32_f16 v[184:187], v[24:27], v[120:123], v[36:39]
	v_mfma_f32_16x16x32_f16 v[120:123], v[32:35], v[120:123], v[52:55]
	v_mfma_f32_16x16x32_f16 v[188:191], v[24:27], v[128:131], v[20:23]
	v_mfma_f32_16x16x32_f16 v[128:131], v[32:35], v[128:131], v[28:31]
	v_mfma_f32_16x16x32_f16 v[176:179], v[24:27], v[60:63], v[12:15]
	v_mfma_f32_16x16x32_f16 v[180:183], v[32:35], v[60:63], v[16:19]
	s_setprio 0
	s_barrier
	s_add_i32 s47, 0, 0x18000
	v_add_u32_e32 v4, s47, v147
	s_add_i32 s49, 0, 0x1c000
	ds_read_b128 v[192:195], v4
	ds_read_b128 v[196:199], v4 offset:1024
	ds_read_b128 v[200:203], v4 offset:2048
	ds_read_b128 v[204:207], v4 offset:3072
	v_add_u32_e32 v4, s49, v147
	ds_read_b128 v[208:211], v4
	ds_read_b128 v[212:215], v4 offset:1024
	ds_read_b128 v[216:219], v4 offset:2048
	ds_read_b128 v[220:223], v4 offset:3072
	s_mov_b32 m0, s65
	ds_read_b128 v[44:47], v231 offset:32768
	ds_read_b128 v[52:55], v231 offset:33792
	ds_read_b128 v[60:63], v231 offset:34816
	ds_read_b128 v[224:227], v231 offset:35840
	ds_read_b128 v[232:235], v231 offset:36864
	ds_read_b128 v[236:239], v231 offset:37888
	ds_read_b128 v[240:243], v231 offset:38912
	ds_read_b128 v[244:247], v231 offset:39936
	global_load_lds_dwordx4 v138, s[26:27]
	s_mov_b32 m0, s66
	s_nop 0
	global_load_lds_dwordx4 v132, s[26:27]
	s_waitcnt vmcnt(8)
	s_waitcnt lgkmcnt(0)
	s_barrier
	s_setprio 1
	s_waitcnt lgkmcnt(0)
	v_mfma_f32_16x16x32_f16 v[4:7], v[192:195], v[44:47], v[68:71]
	v_mfma_f32_16x16x32_f16 v[8:11], v[200:203], v[44:47], v[72:75]
	v_mfma_f32_16x16x32_f16 v[12:15], v[192:195], v[60:63], v[76:79]
	v_mfma_f32_16x16x32_f16 v[16:19], v[200:203], v[60:63], v[80:83]
	v_mfma_f32_16x16x32_f16 v[20:23], v[192:195], v[232:235], v[84:87]
	v_mfma_f32_16x16x32_f16 v[24:27], v[200:203], v[232:235], v[88:91]
	v_mfma_f32_16x16x32_f16 v[28:31], v[192:195], v[240:243], v[92:95]
	v_mfma_f32_16x16x32_f16 v[32:35], v[200:203], v[240:243], v[96:99]
	v_mfma_f32_16x16x32_f16 v[4:7], v[196:199], v[52:55], v[4:7]
	v_mfma_f32_16x16x32_f16 v[8:11], v[204:207], v[52:55], v[8:11]
	v_mfma_f32_16x16x32_f16 v[12:15], v[196:199], v[224:227], v[12:15]
	v_mfma_f32_16x16x32_f16 v[16:19], v[204:207], v[224:227], v[16:19]
	v_mfma_f32_16x16x32_f16 v[20:23], v[196:199], v[236:239], v[20:23]
	v_mfma_f32_16x16x32_f16 v[24:27], v[204:207], v[236:239], v[24:27]
	v_mfma_f32_16x16x32_f16 v[28:31], v[196:199], v[244:247], v[28:31]
	v_mfma_f32_16x16x32_f16 v[32:35], v[204:207], v[244:247], v[32:35]
	s_setprio 0
	s_setprio 1
	v_mfma_f32_16x16x32_f16 v[36:39], v[208:211], v[44:47], v[100:103]
	v_mfma_f32_16x16x32_f16 v[40:43], v[216:219], v[44:47], v[40:43]
	v_mfma_f32_16x16x32_f16 v[36:39], v[212:215], v[52:55], v[36:39]
	v_mfma_f32_16x16x32_f16 v[40:43], v[220:223], v[52:55], v[40:43]
	v_mfma_f32_16x16x32_f16 v[44:47], v[208:211], v[60:63], v[104:107]
	v_mfma_f32_16x16x32_f16 v[48:51], v[216:219], v[60:63], v[48:51]
	v_mfma_f32_16x16x32_f16 v[52:55], v[208:211], v[232:235], v[108:111]
	v_mfma_f32_16x16x32_f16 v[56:59], v[216:219], v[232:235], v[56:59]
	v_mfma_f32_16x16x32_f16 v[60:63], v[208:211], v[240:243], v[112:115]
	v_mfma_f32_16x16x32_f16 v[64:67], v[216:219], v[240:243], v[64:67]
	v_mfma_f32_16x16x32_f16 v[44:47], v[212:215], v[224:227], v[44:47]
	v_mfma_f32_16x16x32_f16 v[48:51], v[220:223], v[224:227], v[48:51]
	v_mfma_f32_16x16x32_f16 v[52:55], v[212:215], v[236:239], v[52:55]
	v_mfma_f32_16x16x32_f16 v[56:59], v[220:223], v[236:239], v[56:59]
	v_mfma_f32_16x16x32_f16 v[60:63], v[212:215], v[244:247], v[60:63]
	v_mfma_f32_16x16x32_f16 v[64:67], v[220:223], v[244:247], v[64:67]
	s_setprio 0
	s_barrier
	s_add_i32 s47, s47, s62
	v_lshl_add_u64 v[68:69], v[136:137], 0, s[24:25]
	s_mov_b32 m0, s47
	ds_read_b128 v[104:107], v231 offset:49152
	ds_read_b128 v[108:111], v231 offset:50176
	ds_read_b128 v[112:115], v231 offset:51200
	ds_read_b128 v[224:227], v231 offset:52224
	ds_read_b128 v[232:235], v231 offset:53248
	ds_read_b128 v[236:239], v231 offset:54272
	ds_read_b128 v[240:243], v231 offset:55296
	ds_read_b128 v[244:247], v231 offset:56320
	global_load_lds_dwordx4 v[68:69], off
	v_lshl_add_u64 v[68:69], v[144:145], 0, s[24:25]
	s_add_i32 m0, s47, 0x2000
	s_add_i32 s47, s49, s62
	global_load_lds_dwordx4 v[68:69], off
	s_mov_b32 m0, s47
	v_lshl_add_u64 v[68:69], v[248:249], 0, s[24:25]
	global_load_lds_dwordx4 v2, s[28:29]
	s_add_i32 m0, s47, 0x2000
	s_nop 0
	global_load_lds_dwordx4 v134, s[28:29]
	s_mov_b32 m0, s69
	s_nop 0
	global_load_lds_dwordx4 v[68:69], off
	v_lshl_add_u64 v[68:69], v[250:251], 0, s[24:25]
	s_mov_b32 m0, s70
	s_nop 0
	global_load_lds_dwordx4 v[68:69], off
	s_waitcnt vmcnt(8)
	s_waitcnt lgkmcnt(0)
	s_barrier
	s_setprio 1
	s_waitcnt lgkmcnt(0)
	v_mfma_f32_16x16x32_f16 v[68:71], v[192:195], v[104:107], v[140:143]
	v_mfma_f32_16x16x32_f16 v[72:75], v[200:203], v[104:107], v[148:151]
	v_mfma_f32_16x16x32_f16 v[76:79], v[192:195], v[112:115], v[152:155]
	v_mfma_f32_16x16x32_f16 v[80:83], v[200:203], v[112:115], v[156:159]
	v_mfma_f32_16x16x32_f16 v[84:87], v[192:195], v[232:235], v[160:163]
	v_mfma_f32_16x16x32_f16 v[88:91], v[200:203], v[232:235], v[164:167]
	v_mfma_f32_16x16x32_f16 v[92:95], v[192:195], v[240:243], v[168:171]
	v_mfma_f32_16x16x32_f16 v[96:99], v[200:203], v[240:243], v[172:175]
	v_mfma_f32_16x16x32_f16 v[68:71], v[196:199], v[108:111], v[68:71]
	v_mfma_f32_16x16x32_f16 v[72:75], v[204:207], v[108:111], v[72:75]
	v_mfma_f32_16x16x32_f16 v[76:79], v[196:199], v[224:227], v[76:79]
	v_mfma_f32_16x16x32_f16 v[80:83], v[204:207], v[224:227], v[80:83]
	v_mfma_f32_16x16x32_f16 v[84:87], v[196:199], v[236:239], v[84:87]
	v_mfma_f32_16x16x32_f16 v[88:91], v[204:207], v[236:239], v[88:91]
	v_mfma_f32_16x16x32_f16 v[92:95], v[196:199], v[244:247], v[92:95]
	v_mfma_f32_16x16x32_f16 v[96:99], v[204:207], v[244:247], v[96:99]
	s_setprio 0
	s_setprio 1
	v_mfma_f32_16x16x32_f16 v[100:103], v[208:211], v[104:107], v[116:119]
	v_mfma_f32_16x16x32_f16 v[104:107], v[216:219], v[104:107], v[124:127]
	v_mfma_f32_16x16x32_f16 v[100:103], v[212:215], v[108:111], v[100:103]
	v_mfma_f32_16x16x32_f16 v[104:107], v[220:223], v[108:111], v[104:107]
	v_mfma_f32_16x16x32_f16 v[108:111], v[208:211], v[112:115], v[176:179]
	v_mfma_f32_16x16x32_f16 v[112:115], v[216:219], v[112:115], v[180:183]
	v_mfma_f32_16x16x32_f16 v[116:119], v[208:211], v[232:235], v[184:187]
	v_mfma_f32_16x16x32_f16 v[120:123], v[216:219], v[232:235], v[120:123]
	v_mfma_f32_16x16x32_f16 v[124:127], v[208:211], v[240:243], v[188:191]
	v_mfma_f32_16x16x32_f16 v[128:131], v[216:219], v[240:243], v[128:131]
	v_mfma_f32_16x16x32_f16 v[108:111], v[212:215], v[224:227], v[108:111]
	v_mfma_f32_16x16x32_f16 v[112:115], v[220:223], v[224:227], v[112:115]
	v_mfma_f32_16x16x32_f16 v[116:119], v[212:215], v[236:239], v[116:119]
	v_mfma_f32_16x16x32_f16 v[120:123], v[220:223], v[236:239], v[120:123]
	v_mfma_f32_16x16x32_f16 v[124:127], v[212:215], v[244:247], v[124:127]
	v_mfma_f32_16x16x32_f16 v[128:131], v[220:223], v[244:247], v[128:131]
	s_setprio 0
	s_barrier
	s_add_i32 s45, s45, 2
	s_cmp_ge_i32 s45, s44
	s_cbranch_scc0 .LBB0_749
	v_mov_b32_e32 v136, v2
	s_branch .LBB0_752

.LBB0_753:
	s_add_u32 s6, s8, 0xfff80080
	s_addc_u32 s7, s9, -1
	s_add_i32 s29, 0, 0x10000
	s_cmp_eq_u32 s28, 28
	s_cselect_b32 s17, s13, s7
	s_cselect_b32 s16, s12, s6
	v_add_u32_e32 v133, s29, v147
	s_cselect_b32 s7, s15, s27
	s_cselect_b32 s6, s14, s26
	s_add_i32 s47, 0, 0x14000
	ds_read_b128 v[138:141], v133
	ds_read_b128 v[142:145], v133 offset:1024
	ds_read_b128 v[148:151], v133 offset:2048
	ds_read_b128 v[152:155], v133 offset:3072
	v_add_u32_e32 v133, s47, v147
	ds_read_b128 v[156:159], v133
	ds_read_b128 v[160:163], v133 offset:1024
	ds_read_b128 v[164:167], v133 offset:2048
	ds_read_b128 v[168:171], v133 offset:3072
	s_mov_b32 m0, s71
	v_add_u32_e32 v212, 0, v146
	ds_read_b128 v[172:175], v212
	ds_read_b128 v[176:179], v212 offset:1024
	ds_read_b128 v[180:183], v212 offset:2048
	ds_read_b128 v[184:187], v212 offset:3072
	ds_read_b128 v[188:191], v212 offset:4096
	ds_read_b128 v[192:195], v212 offset:5120
	ds_read_b128 v[196:199], v212 offset:6144
	ds_read_b128 v[200:203], v212 offset:7168
	global_load_lds_dwordx4 v2, s[8:9]
	s_mov_b32 m0, s72
	v_mov_b32_e32 v133, v3
	global_load_lds_dwordx4 v132, s[8:9]
	s_waitcnt vmcnt(8)
	s_waitcnt lgkmcnt(0)
	s_barrier
	s_setprio 1
	s_waitcnt lgkmcnt(0)
	v_mfma_f32_16x16x32_f16 v[4:7], v[138:141], v[172:175], v[4:7]
	v_mfma_f32_16x16x32_f16 v[4:7], v[142:145], v[176:179], v[4:7]
	v_mfma_f32_16x16x32_f16 v[8:11], v[152:155], v[176:179], v[8:11]
	v_mfma_f32_16x16x32_f16 v[8:11], v[148:151], v[172:175], v[8:11]
	v_mfma_f32_16x16x32_f16 v[16:19], v[148:151], v[180:183], v[16:19]
	v_mfma_f32_16x16x32_f16 v[16:19], v[152:155], v[184:187], v[16:19]
	v_mfma_f32_16x16x32_f16 v[12:15], v[142:145], v[184:187], v[12:15]
	v_mfma_f32_16x16x32_f16 v[12:15], v[138:141], v[180:183], v[12:15]
	v_mfma_f32_16x16x32_f16 v[20:23], v[138:141], v[188:191], v[20:23]
	v_mfma_f32_16x16x32_f16 v[20:23], v[142:145], v[192:195], v[20:23]
	v_mfma_f32_16x16x32_f16 v[24:27], v[152:155], v[192:195], v[24:27]
	v_mfma_f32_16x16x32_f16 v[24:27], v[148:151], v[188:191], v[24:27]
	v_mfma_f32_16x16x32_f16 v[32:35], v[148:151], v[196:199], v[32:35]
	v_mfma_f32_16x16x32_f16 v[32:35], v[152:155], v[200:203], v[32:35]
	v_mfma_f32_16x16x32_f16 v[28:31], v[142:145], v[200:203], v[28:31]
	v_mfma_f32_16x16x32_f16 v[28:31], v[138:141], v[196:199], v[28:31]
	s_setprio 0
	s_setprio 1
	v_mfma_f32_16x16x32_f16 v[36:39], v[156:159], v[172:175], v[36:39]
	v_mfma_f32_16x16x32_f16 v[36:39], v[160:163], v[176:179], v[36:39]
	v_mfma_f32_16x16x32_f16 v[40:43], v[168:171], v[176:179], v[40:43]
	v_mfma_f32_16x16x32_f16 v[40:43], v[164:167], v[172:175], v[40:43]
	v_mfma_f32_16x16x32_f16 v[48:51], v[164:167], v[180:183], v[48:51]
	v_mfma_f32_16x16x32_f16 v[48:51], v[168:171], v[184:187], v[48:51]
	v_mfma_f32_16x16x32_f16 v[44:47], v[160:163], v[184:187], v[44:47]
	v_mfma_f32_16x16x32_f16 v[44:47], v[156:159], v[180:183], v[44:47]
	v_mfma_f32_16x16x32_f16 v[52:55], v[156:159], v[188:191], v[52:55]
	v_mfma_f32_16x16x32_f16 v[52:55], v[160:163], v[192:195], v[52:55]
	v_mfma_f32_16x16x32_f16 v[56:59], v[168:171], v[192:195], v[56:59]
	v_mfma_f32_16x16x32_f16 v[56:59], v[164:167], v[188:191], v[56:59]
	v_mfma_f32_16x16x32_f16 v[64:67], v[164:167], v[196:199], v[64:67]
	v_mfma_f32_16x16x32_f16 v[64:67], v[168:171], v[200:203], v[64:67]
	v_mfma_f32_16x16x32_f16 v[60:63], v[160:163], v[200:203], v[60:63]
	v_mfma_f32_16x16x32_f16 v[60:63], v[156:159], v[196:199], v[60:63]
	s_setprio 0
	s_barrier
	s_add_i32 s29, s29, s62
	s_mov_b32 m0, s29
	ds_read_b128 v[172:175], v212 offset:16384
	ds_read_b128 v[176:179], v212 offset:17408
	ds_read_b128 v[180:183], v212 offset:18432
	ds_read_b128 v[184:187], v212 offset:19456
	ds_read_b128 v[188:191], v212 offset:20480
	ds_read_b128 v[192:195], v212 offset:21504
	ds_read_b128 v[196:199], v212 offset:22528
	ds_read_b128 v[200:203], v212 offset:23552
	global_load_lds_dwordx4 v136, s[6:7]
	s_add_i32 m0, s29, 0x2000
	s_add_u32 s44, s6, 0x80000
	s_addc_u32 s45, s7, 0
	s_add_i32 s29, s47, s62
	global_load_lds_dwordx4 v134, s[6:7]
	s_mov_b32 m0, s29
	v_mov_b32_e32 v137, v3
	global_load_lds_dwordx4 v136, s[44:45]
	s_add_i32 m0, s29, 0x2000
	v_mov_b32_e32 v135, v3
	global_load_lds_dwordx4 v134, s[44:45]
	s_mov_b32 m0, s63
	v_lshl_add_u64 v[204:205], s[6:7], 0, v[136:137]
	global_load_lds_dwordx4 v2, s[16:17]
	s_mov_b32 m0, s64
	v_lshl_add_u64 v[206:207], s[6:7], 0, v[134:135]
	global_load_lds_dwordx4 v132, s[16:17]
	s_waitcnt vmcnt(8)
	s_waitcnt lgkmcnt(0)
	v_lshl_add_u64 v[208:209], s[16:17], 0, v[2:3]
	v_lshl_add_u64 v[210:211], s[16:17], 0, v[132:133]
	s_barrier
	s_setprio 1
	s_waitcnt lgkmcnt(0)
	v_mfma_f32_16x16x32_f16 v[68:71], v[138:141], v[172:175], v[68:71]
	v_mfma_f32_16x16x32_f16 v[68:71], v[142:145], v[176:179], v[68:71]
	v_mfma_f32_16x16x32_f16 v[72:75], v[152:155], v[176:179], v[72:75]
	v_mfma_f32_16x16x32_f16 v[72:75], v[148:151], v[172:175], v[72:75]
	v_mfma_f32_16x16x32_f16 v[80:83], v[148:151], v[180:183], v[80:83]
	v_mfma_f32_16x16x32_f16 v[80:83], v[152:155], v[184:187], v[80:83]
	v_mfma_f32_16x16x32_f16 v[76:79], v[142:145], v[184:187], v[76:79]
	v_mfma_f32_16x16x32_f16 v[76:79], v[138:141], v[180:183], v[76:79]
	v_mfma_f32_16x16x32_f16 v[84:87], v[138:141], v[188:191], v[84:87]
	v_mfma_f32_16x16x32_f16 v[84:87], v[142:145], v[192:195], v[84:87]
	v_mfma_f32_16x16x32_f16 v[88:91], v[152:155], v[192:195], v[88:91]
	v_mfma_f32_16x16x32_f16 v[88:91], v[148:151], v[188:191], v[88:91]
	v_mfma_f32_16x16x32_f16 v[96:99], v[148:151], v[196:199], v[96:99]
	v_mfma_f32_16x16x32_f16 v[96:99], v[152:155], v[200:203], v[96:99]
	v_mfma_f32_16x16x32_f16 v[92:95], v[142:145], v[200:203], v[92:95]
	v_mfma_f32_16x16x32_f16 v[92:95], v[138:141], v[196:199], v[92:95]
	s_setprio 0
	s_setprio 1
	v_mfma_f32_16x16x32_f16 v[100:103], v[156:159], v[172:175], v[100:103]
	v_mfma_f32_16x16x32_f16 v[100:103], v[160:163], v[176:179], v[100:103]
	v_mfma_f32_16x16x32_f16 v[104:107], v[168:171], v[176:179], v[104:107]
	v_mfma_f32_16x16x32_f16 v[104:107], v[164:167], v[172:175], v[104:107]
	v_mfma_f32_16x16x32_f16 v[112:115], v[164:167], v[180:183], v[112:115]
	v_mfma_f32_16x16x32_f16 v[112:115], v[168:171], v[184:187], v[112:115]
	v_mfma_f32_16x16x32_f16 v[108:111], v[160:163], v[184:187], v[108:111]
	v_mfma_f32_16x16x32_f16 v[108:111], v[156:159], v[180:183], v[108:111]
	v_mfma_f32_16x16x32_f16 v[116:119], v[156:159], v[188:191], v[116:119]
	v_mfma_f32_16x16x32_f16 v[116:119], v[160:163], v[192:195], v[116:119]
	v_mfma_f32_16x16x32_f16 v[120:123], v[168:171], v[192:195], v[120:123]
	v_mfma_f32_16x16x32_f16 v[120:123], v[164:167], v[188:191], v[120:123]
	v_mfma_f32_16x16x32_f16 v[128:131], v[164:167], v[196:199], v[128:131]
	v_mfma_f32_16x16x32_f16 v[128:131], v[168:171], v[200:203], v[128:131]
	v_mfma_f32_16x16x32_f16 v[124:127], v[160:163], v[200:203], v[124:127]
	v_mfma_f32_16x16x32_f16 v[124:127], v[156:159], v[196:199], v[124:127]
	s_setprio 0
	s_barrier
	s_add_i32 s29, 0, 0x18000
	v_add_u32_e32 v135, s29, v147
	s_add_i32 s44, 0, 0x1c000
	ds_read_b128 v[138:141], v135
	ds_read_b128 v[142:145], v135 offset:1024
	ds_read_b128 v[148:151], v135 offset:2048
	ds_read_b128 v[152:155], v135 offset:3072
	v_add_u32_e32 v135, s44, v147
	ds_read_b128 v[156:159], v135
	ds_read_b128 v[160:163], v135 offset:1024
	ds_read_b128 v[164:167], v135 offset:2048
	ds_read_b128 v[168:171], v135 offset:3072
	s_add_u32 s16, s16, 0x80000
	s_addc_u32 s17, s17, 0
	s_mov_b32 m0, s65
	ds_read_b128 v[172:175], v212 offset:32768
	ds_read_b128 v[176:179], v212 offset:33792
	ds_read_b128 v[180:183], v212 offset:34816
	ds_read_b128 v[184:187], v212 offset:35840
	ds_read_b128 v[188:191], v212 offset:36864
	ds_read_b128 v[192:195], v212 offset:37888
	ds_read_b128 v[196:199], v212 offset:38912
	ds_read_b128 v[200:203], v212 offset:39936
	global_load_lds_dwordx4 v2, s[16:17]
	s_mov_b32 m0, s66
	s_nop 0
	global_load_lds_dwordx4 v132, s[16:17]
	s_waitcnt vmcnt(8)
	s_waitcnt lgkmcnt(0)
	s_barrier
	s_setprio 1
	s_waitcnt lgkmcnt(0)
	v_mfma_f32_16x16x32_f16 v[4:7], v[138:141], v[172:175], v[4:7]
	v_mfma_f32_16x16x32_f16 v[4:7], v[142:145], v[176:179], v[4:7]
	v_mfma_f32_16x16x32_f16 v[8:11], v[152:155], v[176:179], v[8:11]
	v_mfma_f32_16x16x32_f16 v[8:11], v[148:151], v[172:175], v[8:11]
	v_mfma_f32_16x16x32_f16 v[16:19], v[148:151], v[180:183], v[16:19]
	v_mfma_f32_16x16x32_f16 v[16:19], v[152:155], v[184:187], v[16:19]
	v_mfma_f32_16x16x32_f16 v[12:15], v[142:145], v[184:187], v[12:15]
	v_mfma_f32_16x16x32_f16 v[12:15], v[138:141], v[180:183], v[12:15]
	v_mfma_f32_16x16x32_f16 v[20:23], v[138:141], v[188:191], v[20:23]
	v_mfma_f32_16x16x32_f16 v[20:23], v[142:145], v[192:195], v[20:23]
	v_mfma_f32_16x16x32_f16 v[24:27], v[152:155], v[192:195], v[24:27]
	v_mfma_f32_16x16x32_f16 v[24:27], v[148:151], v[188:191], v[24:27]
	v_mfma_f32_16x16x32_f16 v[32:35], v[148:151], v[196:199], v[32:35]
	v_mfma_f32_16x16x32_f16 v[32:35], v[152:155], v[200:203], v[32:35]
	v_mfma_f32_16x16x32_f16 v[28:31], v[142:145], v[200:203], v[28:31]
	v_mfma_f32_16x16x32_f16 v[28:31], v[138:141], v[196:199], v[28:31]
	s_setprio 0
	s_setprio 1
	v_mfma_f32_16x16x32_f16 v[36:39], v[156:159], v[172:175], v[36:39]
	v_mfma_f32_16x16x32_f16 v[36:39], v[160:163], v[176:179], v[36:39]
	v_mfma_f32_16x16x32_f16 v[40:43], v[168:171], v[176:179], v[40:43]
	v_mfma_f32_16x16x32_f16 v[40:43], v[164:167], v[172:175], v[40:43]
	v_mfma_f32_16x16x32_f16 v[48:51], v[164:167], v[180:183], v[48:51]
	v_mfma_f32_16x16x32_f16 v[48:51], v[168:171], v[184:187], v[48:51]
	v_mfma_f32_16x16x32_f16 v[44:47], v[160:163], v[184:187], v[44:47]
	v_mfma_f32_16x16x32_f16 v[44:47], v[156:159], v[180:183], v[44:47]
	v_mfma_f32_16x16x32_f16 v[52:55], v[156:159], v[188:191], v[52:55]
	v_mfma_f32_16x16x32_f16 v[52:55], v[160:163], v[192:195], v[52:55]
	v_mfma_f32_16x16x32_f16 v[56:59], v[168:171], v[192:195], v[56:59]
	v_mfma_f32_16x16x32_f16 v[56:59], v[164:167], v[188:191], v[56:59]
	v_mfma_f32_16x16x32_f16 v[64:67], v[164:167], v[196:199], v[64:67]
	v_mfma_f32_16x16x32_f16 v[64:67], v[168:171], v[200:203], v[64:67]
	v_mfma_f32_16x16x32_f16 v[60:63], v[160:163], v[200:203], v[60:63]
	v_mfma_f32_16x16x32_f16 v[60:63], v[156:159], v[196:199], v[60:63]
	s_setprio 0
	s_barrier
	s_add_i32 s16, s29, s62
	v_lshl_add_u64 v[204:205], v[204:205], 0, s[86:87]
	s_mov_b32 m0, s16
	ds_read_b128 v[172:175], v212 offset:49152
	ds_read_b128 v[176:179], v212 offset:50176
	ds_read_b128 v[180:183], v212 offset:51200
	ds_read_b128 v[184:187], v212 offset:52224
	ds_read_b128 v[188:191], v212 offset:53248
	ds_read_b128 v[192:195], v212 offset:54272
	ds_read_b128 v[196:199], v212 offset:55296
	ds_read_b128 v[200:203], v212 offset:56320
	global_load_lds_dwordx4 v[204:205], off
	s_add_i32 m0, s16, 0x2000
	s_add_u32 s6, s6, 0x80080
	v_lshl_add_u64 v[204:205], v[206:207], 0, s[86:87]
	s_addc_u32 s7, s7, 0
	s_add_i32 s16, s44, s62
	global_load_lds_dwordx4 v[204:205], off
	s_mov_b32 m0, s16
	v_lshl_add_u64 v[204:205], v[208:209], 0, s[86:87]
	global_load_lds_dwordx4 v136, s[6:7]
	s_add_i32 m0, s16, 0x2000
	s_nop 0
	global_load_lds_dwordx4 v134, s[6:7]
	s_mov_b32 m0, s69
	s_nop 0
	global_load_lds_dwordx4 v[204:205], off
	v_lshl_add_u64 v[204:205], v[210:211], 0, s[86:87]
	s_mov_b32 m0, s70
	s_nop 0
	global_load_lds_dwordx4 v[204:205], off
	s_waitcnt vmcnt(8)
	s_waitcnt lgkmcnt(0)
	s_barrier
	s_setprio 1
	s_waitcnt lgkmcnt(0)
	v_mfma_f32_16x16x32_f16 v[68:71], v[138:141], v[172:175], v[68:71]
	v_mfma_f32_16x16x32_f16 v[68:71], v[142:145], v[176:179], v[68:71]
	v_mfma_f32_16x16x32_f16 v[72:75], v[152:155], v[176:179], v[72:75]
	v_mfma_f32_16x16x32_f16 v[72:75], v[148:151], v[172:175], v[72:75]
	v_mfma_f32_16x16x32_f16 v[80:83], v[148:151], v[180:183], v[80:83]
	v_mfma_f32_16x16x32_f16 v[80:83], v[152:155], v[184:187], v[80:83]
	v_mfma_f32_16x16x32_f16 v[76:79], v[142:145], v[184:187], v[76:79]
	v_mfma_f32_16x16x32_f16 v[76:79], v[138:141], v[180:183], v[76:79]
	v_mfma_f32_16x16x32_f16 v[84:87], v[138:141], v[188:191], v[84:87]
	v_mfma_f32_16x16x32_f16 v[84:87], v[142:145], v[192:195], v[84:87]
	v_mfma_f32_16x16x32_f16 v[88:91], v[152:155], v[192:195], v[88:91]
	v_mfma_f32_16x16x32_f16 v[88:91], v[148:151], v[188:191], v[88:91]
	v_mfma_f32_16x16x32_f16 v[96:99], v[148:151], v[196:199], v[96:99]
	v_mfma_f32_16x16x32_f16 v[96:99], v[152:155], v[200:203], v[96:99]
	v_mfma_f32_16x16x32_f16 v[92:95], v[142:145], v[200:203], v[92:95]
	v_mfma_f32_16x16x32_f16 v[92:95], v[138:141], v[196:199], v[92:95]
	s_setprio 0
	s_setprio 1
	v_mfma_f32_16x16x32_f16 v[100:103], v[156:159], v[172:175], v[100:103]
	v_mfma_f32_16x16x32_f16 v[100:103], v[160:163], v[176:179], v[100:103]
	v_mfma_f32_16x16x32_f16 v[104:107], v[168:171], v[176:179], v[104:107]
	v_mfma_f32_16x16x32_f16 v[104:107], v[164:167], v[172:175], v[104:107]
	v_mfma_f32_16x16x32_f16 v[112:115], v[164:167], v[180:183], v[112:115]
	v_mfma_f32_16x16x32_f16 v[112:115], v[168:171], v[184:187], v[112:115]
	v_mfma_f32_16x16x32_f16 v[108:111], v[160:163], v[184:187], v[108:111]
	v_mfma_f32_16x16x32_f16 v[108:111], v[156:159], v[180:183], v[108:111]
	v_mfma_f32_16x16x32_f16 v[116:119], v[156:159], v[188:191], v[116:119]
	v_mfma_f32_16x16x32_f16 v[116:119], v[160:163], v[192:195], v[116:119]
	v_mfma_f32_16x16x32_f16 v[120:123], v[168:171], v[192:195], v[120:123]
	v_mfma_f32_16x16x32_f16 v[120:123], v[164:167], v[188:191], v[120:123]
	v_mfma_f32_16x16x32_f16 v[128:131], v[164:167], v[196:199], v[128:131]
	v_mfma_f32_16x16x32_f16 v[128:131], v[168:171], v[200:203], v[128:131]
	v_mfma_f32_16x16x32_f16 v[124:127], v[160:163], v[200:203], v[124:127]
	v_mfma_f32_16x16x32_f16 v[124:127], v[156:159], v[196:199], v[124:127]
	s_setprio 0
	s_barrier
	s_add_i32 s28, s28, 2
	s_add_u32 s8, s8, 0x100
	s_addc_u32 s9, s9, 0
	s_add_u32 s26, s26, 0x100
	s_addc_u32 s27, s27, 0
	s_cmp_gt_u32 s28, 29
	s_cbranch_scc0 .LBB0_753
	s_and_b64 vcc, exec, s[52:53]
	s_cbranch_vccz .LBB0_756
	s_barrier

.LBB0_1175:
	s_add_i32 s61, 0, 0x10000
	s_add_i32 s79, 0, 0x14000
	v_add_u32_e32 v16, s61, v209
	v_add_u32_e32 v32, s79, v209
	ds_read_b128 v[4:7], v16
	ds_read_b128 v[8:11], v16 offset:1024
	ds_read_b128 v[12:15], v16 offset:2048
	ds_read_b128 v[16:19], v16 offset:3072
	ds_read_b128 v[20:23], v32
	ds_read_b128 v[24:27], v32 offset:1024
	ds_read_b128 v[28:31], v32 offset:2048
	ds_read_b128 v[32:35], v32 offset:3072
	v_add_u32_e32 v231, 0, v208
	ds_read_b128 v[36:39], v231
	ds_read_b128 v[40:43], v231 offset:1024
	ds_read_b128 v[44:47], v231 offset:2048
	ds_read_b128 v[48:51], v231 offset:3072
	ds_read_b128 v[52:55], v231 offset:4096
	ds_read_b128 v[56:59], v231 offset:5120
	ds_read_b128 v[60:63], v231 offset:6144
	ds_read_b128 v[64:67], v231 offset:7168
	s_waitcnt vmcnt(8)
	s_waitcnt lgkmcnt(0)
	s_barrier
	s_setprio 1
	s_waitcnt lgkmcnt(0)
	v_mfma_f32_16x16x32_bf16 v[68:71], v[4:7], v[36:39], 0
	v_mfma_f32_16x16x32_bf16 v[68:71], v[8:11], v[40:43], v[68:71]
	v_mfma_f32_16x16x32_bf16 v[72:75], v[12:15], v[36:39], 0
	v_mfma_f32_16x16x32_bf16 v[72:75], v[16:19], v[40:43], v[72:75]
	v_mfma_f32_16x16x32_bf16 v[80:83], v[12:15], v[44:47], 0
	v_mfma_f32_16x16x32_bf16 v[80:83], v[16:19], v[48:51], v[80:83]
	v_mfma_f32_16x16x32_bf16 v[76:79], v[4:7], v[44:47], 0
	v_mfma_f32_16x16x32_bf16 v[76:79], v[8:11], v[48:51], v[76:79]
	v_mfma_f32_16x16x32_bf16 v[84:87], v[4:7], v[52:55], 0
	v_mfma_f32_16x16x32_bf16 v[84:87], v[8:11], v[56:59], v[84:87]
	v_mfma_f32_16x16x32_bf16 v[88:91], v[12:15], v[52:55], 0
	v_mfma_f32_16x16x32_bf16 v[88:91], v[16:19], v[56:59], v[88:91]
	v_mfma_f32_16x16x32_bf16 v[96:99], v[12:15], v[60:63], 0
	v_mfma_f32_16x16x32_bf16 v[96:99], v[16:19], v[64:67], v[96:99]
	v_mfma_f32_16x16x32_bf16 v[92:95], v[4:7], v[60:63], 0
	v_mfma_f32_16x16x32_bf16 v[92:95], v[8:11], v[64:67], v[92:95]
	s_setprio 0
	s_setprio 1
	v_mfma_f32_16x16x32_bf16 v[100:103], v[20:23], v[36:39], 0
	v_mfma_f32_16x16x32_bf16 v[36:39], v[28:31], v[36:39], 0
	v_mfma_f32_16x16x32_bf16 v[104:107], v[20:23], v[44:47], 0
	v_mfma_f32_16x16x32_bf16 v[44:47], v[28:31], v[44:47], 0
	v_mfma_f32_16x16x32_bf16 v[108:111], v[20:23], v[52:55], 0
	v_mfma_f32_16x16x32_bf16 v[52:55], v[28:31], v[52:55], 0
	v_mfma_f32_16x16x32_bf16 v[112:115], v[20:23], v[60:63], 0
	v_mfma_f32_16x16x32_bf16 v[60:63], v[28:31], v[60:63], 0
	v_mfma_f32_16x16x32_bf16 v[100:103], v[24:27], v[40:43], v[100:103]
	v_mfma_f32_16x16x32_bf16 v[40:43], v[32:35], v[40:43], v[36:39]
	v_mfma_f32_16x16x32_bf16 v[104:107], v[24:27], v[48:51], v[104:107]
	v_mfma_f32_16x16x32_bf16 v[48:51], v[32:35], v[48:51], v[44:47]
	v_mfma_f32_16x16x32_bf16 v[108:111], v[24:27], v[56:59], v[108:111]
	v_mfma_f32_16x16x32_bf16 v[56:59], v[32:35], v[56:59], v[52:55]
	v_mfma_f32_16x16x32_bf16 v[112:115], v[24:27], v[64:67], v[112:115]
	v_mfma_f32_16x16x32_bf16 v[64:67], v[32:35], v[64:67], v[60:63]
	s_setprio 0
	s_barrier
	v_lshl_add_u64 v[186:187], s[12:13], 0, v[2:3]
	s_add_i32 s61, s61, s36
	v_mov_b32_e32 v191, v3
	v_lshl_add_u64 v[134:135], v[186:187], 0, s[74:75]
	s_mov_b32 m0, s61
	v_lshl_add_u64 v[226:227], s[12:13], 0, v[190:191]
	ds_read_b128 v[36:39], v231 offset:16384
	ds_read_b128 v[44:47], v231 offset:17408
	ds_read_b128 v[52:55], v231 offset:18432
	ds_read_b128 v[60:63], v231 offset:19456
	ds_read_b128 v[116:119], v231 offset:20480
	ds_read_b128 v[120:123], v231 offset:21504
	ds_read_b128 v[124:127], v231 offset:22528
	ds_read_b128 v[128:131], v231 offset:23552
	global_load_lds_dwordx4 v[134:135], off
	v_lshl_add_u64 v[134:135], v[226:227], 0, s[74:75]
	s_add_i32 m0, s61, 0x2000
	s_add_i32 s61, s79, s36
	global_load_lds_dwordx4 v[134:135], off
	s_mov_b32 m0, s61
	v_mov_b32_e32 v133, v3
	global_load_lds_dwordx4 v2, s[16:17]
	s_add_i32 m0, s61, 0x2000
	v_lshl_add_u64 v[248:249], s[6:7], 0, v[132:133]
	v_mov_b32_e32 v189, v3
	global_load_lds_dwordx4 v190, s[16:17]
	v_lshl_add_u64 v[134:135], v[248:249], 0, s[74:75]
	s_mov_b32 m0, s37
	v_lshl_add_u64 v[250:251], s[6:7], 0, v[188:189]
	global_load_lds_dwordx4 v[134:135], off
	v_lshl_add_u64 v[134:135], v[250:251], 0, s[74:75]
	s_mov_b32 m0, s66
	s_nop 0
	global_load_lds_dwordx4 v[134:135], off
	s_waitcnt vmcnt(8)
	s_waitcnt lgkmcnt(0)
	s_barrier
	s_setprio 1
	s_waitcnt lgkmcnt(0)
	v_mfma_f32_16x16x32_bf16 v[134:137], v[4:7], v[36:39], 0
	v_mfma_f32_16x16x32_bf16 v[138:141], v[12:15], v[36:39], 0
	v_mfma_f32_16x16x32_bf16 v[142:145], v[4:7], v[52:55], 0
	v_mfma_f32_16x16x32_bf16 v[146:149], v[12:15], v[52:55], 0
	v_mfma_f32_16x16x32_bf16 v[150:153], v[4:7], v[116:119], 0
	v_mfma_f32_16x16x32_bf16 v[154:157], v[12:15], v[116:119], 0
	v_mfma_f32_16x16x32_bf16 v[4:7], v[4:7], v[124:127], 0
	v_mfma_f32_16x16x32_bf16 v[12:15], v[12:15], v[124:127], 0
	v_mfma_f32_16x16x32_bf16 v[134:137], v[8:11], v[44:47], v[134:137]
	v_mfma_f32_16x16x32_bf16 v[138:141], v[16:19], v[44:47], v[138:141]
	v_mfma_f32_16x16x32_bf16 v[142:145], v[8:11], v[60:63], v[142:145]
	v_mfma_f32_16x16x32_bf16 v[146:149], v[16:19], v[60:63], v[146:149]
	v_mfma_f32_16x16x32_bf16 v[150:153], v[8:11], v[120:123], v[150:153]
	v_mfma_f32_16x16x32_bf16 v[154:157], v[16:19], v[120:123], v[154:157]
	v_mfma_f32_16x16x32_bf16 v[158:161], v[8:11], v[128:131], v[4:7]
	v_mfma_f32_16x16x32_bf16 v[162:165], v[16:19], v[128:131], v[12:15]
	s_setprio 0
	s_setprio 1
	v_mfma_f32_16x16x32_bf16 v[4:7], v[20:23], v[36:39], 0
	v_mfma_f32_16x16x32_bf16 v[8:11], v[28:31], v[36:39], 0
	v_mfma_f32_16x16x32_bf16 v[12:15], v[20:23], v[52:55], 0
	v_mfma_f32_16x16x32_bf16 v[16:19], v[28:31], v[52:55], 0
	v_mfma_f32_16x16x32_bf16 v[36:39], v[20:23], v[116:119], 0
	v_mfma_f32_16x16x32_bf16 v[52:55], v[28:31], v[116:119], 0
	v_mfma_f32_16x16x32_bf16 v[20:23], v[20:23], v[124:127], 0
	v_mfma_f32_16x16x32_bf16 v[28:31], v[28:31], v[124:127], 0
	v_mfma_f32_16x16x32_bf16 v[116:119], v[24:27], v[44:47], v[4:7]
	v_mfma_f32_16x16x32_bf16 v[124:127], v[32:35], v[44:47], v[8:11]
	v_mfma_f32_16x16x32_bf16 v[174:177], v[24:27], v[120:123], v[36:39]
	v_mfma_f32_16x16x32_bf16 v[120:123], v[32:35], v[120:123], v[52:55]
	v_mfma_f32_16x16x32_bf16 v[178:181], v[24:27], v[128:131], v[20:23]
	v_mfma_f32_16x16x32_bf16 v[128:131], v[32:35], v[128:131], v[28:31]
	v_mfma_f32_16x16x32_bf16 v[166:169], v[24:27], v[60:63], v[12:15]
	v_mfma_f32_16x16x32_bf16 v[170:173], v[32:35], v[60:63], v[16:19]
	s_setprio 0
	s_barrier
	s_add_i32 s61, 0, 0x18000
	v_add_u32_e32 v4, s61, v209
	s_add_i32 s79, 0, 0x1c000
	ds_read_b128 v[182:185], v4
	ds_read_b128 v[192:195], v4 offset:1024
	ds_read_b128 v[196:199], v4 offset:2048
	ds_read_b128 v[200:203], v4 offset:3072
	v_add_u32_e32 v4, s79, v209
	ds_read_b128 v[204:207], v4
	ds_read_b128 v[210:213], v4 offset:1024
	ds_read_b128 v[214:217], v4 offset:2048
	ds_read_b128 v[218:221], v4 offset:3072
	s_mov_b32 m0, s67
	ds_read_b128 v[44:47], v231 offset:32768
	ds_read_b128 v[52:55], v231 offset:33792
	ds_read_b128 v[60:63], v231 offset:34816
	ds_read_b128 v[222:225], v231 offset:35840
	ds_read_b128 v[232:235], v231 offset:36864
	ds_read_b128 v[236:239], v231 offset:37888
	ds_read_b128 v[240:243], v231 offset:38912
	ds_read_b128 v[244:247], v231 offset:39936
	global_load_lds_dwordx4 v132, s[26:27]
	s_mov_b32 m0, s68
	s_nop 0
	global_load_lds_dwordx4 v188, s[26:27]
	s_waitcnt vmcnt(8)
	s_waitcnt lgkmcnt(0)
	s_barrier
	s_setprio 1
	s_waitcnt lgkmcnt(0)
	v_mfma_f32_16x16x32_bf16 v[4:7], v[182:185], v[44:47], v[68:71]
	v_mfma_f32_16x16x32_bf16 v[8:11], v[196:199], v[44:47], v[72:75]
	v_mfma_f32_16x16x32_bf16 v[12:15], v[182:185], v[60:63], v[76:79]
	v_mfma_f32_16x16x32_bf16 v[16:19], v[196:199], v[60:63], v[80:83]
	v_mfma_f32_16x16x32_bf16 v[20:23], v[182:185], v[232:235], v[84:87]
	v_mfma_f32_16x16x32_bf16 v[24:27], v[196:199], v[232:235], v[88:91]
	v_mfma_f32_16x16x32_bf16 v[28:31], v[182:185], v[240:243], v[92:95]
	v_mfma_f32_16x16x32_bf16 v[32:35], v[196:199], v[240:243], v[96:99]
	v_mfma_f32_16x16x32_bf16 v[4:7], v[192:195], v[52:55], v[4:7]
	v_mfma_f32_16x16x32_bf16 v[8:11], v[200:203], v[52:55], v[8:11]
	v_mfma_f32_16x16x32_bf16 v[12:15], v[192:195], v[222:225], v[12:15]
	v_mfma_f32_16x16x32_bf16 v[16:19], v[200:203], v[222:225], v[16:19]
	v_mfma_f32_16x16x32_bf16 v[20:23], v[192:195], v[236:239], v[20:23]
	v_mfma_f32_16x16x32_bf16 v[24:27], v[200:203], v[236:239], v[24:27]
	v_mfma_f32_16x16x32_bf16 v[28:31], v[192:195], v[244:247], v[28:31]
	v_mfma_f32_16x16x32_bf16 v[32:35], v[200:203], v[244:247], v[32:35]
	s_setprio 0
	s_setprio 1
	v_mfma_f32_16x16x32_bf16 v[36:39], v[204:207], v[44:47], v[100:103]
	v_mfma_f32_16x16x32_bf16 v[40:43], v[214:217], v[44:47], v[40:43]
	v_mfma_f32_16x16x32_bf16 v[36:39], v[210:213], v[52:55], v[36:39]
	v_mfma_f32_16x16x32_bf16 v[40:43], v[218:221], v[52:55], v[40:43]
	v_mfma_f32_16x16x32_bf16 v[44:47], v[204:207], v[60:63], v[104:107]
	v_mfma_f32_16x16x32_bf16 v[48:51], v[214:217], v[60:63], v[48:51]
	v_mfma_f32_16x16x32_bf16 v[52:55], v[204:207], v[232:235], v[108:111]
	v_mfma_f32_16x16x32_bf16 v[56:59], v[214:217], v[232:235], v[56:59]
	v_mfma_f32_16x16x32_bf16 v[60:63], v[204:207], v[240:243], v[112:115]
	v_mfma_f32_16x16x32_bf16 v[64:67], v[214:217], v[240:243], v[64:67]
	v_mfma_f32_16x16x32_bf16 v[44:47], v[210:213], v[222:225], v[44:47]
	v_mfma_f32_16x16x32_bf16 v[48:51], v[218:221], v[222:225], v[48:51]
	v_mfma_f32_16x16x32_bf16 v[52:55], v[210:213], v[236:239], v[52:55]
	v_mfma_f32_16x16x32_bf16 v[56:59], v[218:221], v[236:239], v[56:59]
	v_mfma_f32_16x16x32_bf16 v[60:63], v[210:213], v[244:247], v[60:63]
	v_mfma_f32_16x16x32_bf16 v[64:67], v[218:221], v[244:247], v[64:67]
	s_setprio 0
	s_barrier
	s_add_i32 s61, s61, s36
	v_lshl_add_u64 v[68:69], v[186:187], 0, s[24:25]
	s_mov_b32 m0, s61
	ds_read_b128 v[104:107], v231 offset:49152
	ds_read_b128 v[108:111], v231 offset:50176
	ds_read_b128 v[112:115], v231 offset:51200
	ds_read_b128 v[222:225], v231 offset:52224
	ds_read_b128 v[232:235], v231 offset:53248
	ds_read_b128 v[236:239], v231 offset:54272
	ds_read_b128 v[240:243], v231 offset:55296
	ds_read_b128 v[244:247], v231 offset:56320
	global_load_lds_dwordx4 v[68:69], off
	v_lshl_add_u64 v[68:69], v[226:227], 0, s[24:25]
	s_add_i32 m0, s61, 0x2000
	s_add_i32 s61, s79, s36
	global_load_lds_dwordx4 v[68:69], off
	s_mov_b32 m0, s61
	v_lshl_add_u64 v[68:69], v[248:249], 0, s[24:25]
	global_load_lds_dwordx4 v2, s[28:29]
	s_add_i32 m0, s61, 0x2000
	s_nop 0
	global_load_lds_dwordx4 v190, s[28:29]
	s_mov_b32 m0, s71
	s_nop 0
	global_load_lds_dwordx4 v[68:69], off
	v_lshl_add_u64 v[68:69], v[250:251], 0, s[24:25]
	s_mov_b32 m0, s72
	s_nop 0
	global_load_lds_dwordx4 v[68:69], off
	s_waitcnt vmcnt(8)
	s_waitcnt lgkmcnt(0)
	s_barrier
	s_setprio 1
	s_waitcnt lgkmcnt(0)
	v_mfma_f32_16x16x32_bf16 v[68:71], v[182:185], v[104:107], v[134:137]
	v_mfma_f32_16x16x32_bf16 v[72:75], v[196:199], v[104:107], v[138:141]
	v_mfma_f32_16x16x32_bf16 v[76:79], v[182:185], v[112:115], v[142:145]
	v_mfma_f32_16x16x32_bf16 v[80:83], v[196:199], v[112:115], v[146:149]
	v_mfma_f32_16x16x32_bf16 v[84:87], v[182:185], v[232:235], v[150:153]
	v_mfma_f32_16x16x32_bf16 v[88:91], v[196:199], v[232:235], v[154:157]
	v_mfma_f32_16x16x32_bf16 v[92:95], v[182:185], v[240:243], v[158:161]
	v_mfma_f32_16x16x32_bf16 v[96:99], v[196:199], v[240:243], v[162:165]
	v_mfma_f32_16x16x32_bf16 v[68:71], v[192:195], v[108:111], v[68:71]
	v_mfma_f32_16x16x32_bf16 v[72:75], v[200:203], v[108:111], v[72:75]
	v_mfma_f32_16x16x32_bf16 v[76:79], v[192:195], v[222:225], v[76:79]
	v_mfma_f32_16x16x32_bf16 v[80:83], v[200:203], v[222:225], v[80:83]
	v_mfma_f32_16x16x32_bf16 v[84:87], v[192:195], v[236:239], v[84:87]
	v_mfma_f32_16x16x32_bf16 v[88:91], v[200:203], v[236:239], v[88:91]
	v_mfma_f32_16x16x32_bf16 v[92:95], v[192:195], v[244:247], v[92:95]
	v_mfma_f32_16x16x32_bf16 v[96:99], v[200:203], v[244:247], v[96:99]
	s_setprio 0
	s_setprio 1
	v_mfma_f32_16x16x32_bf16 v[100:103], v[204:207], v[104:107], v[116:119]
	v_mfma_f32_16x16x32_bf16 v[104:107], v[214:217], v[104:107], v[124:127]
	v_mfma_f32_16x16x32_bf16 v[100:103], v[210:213], v[108:111], v[100:103]
	v_mfma_f32_16x16x32_bf16 v[104:107], v[218:221], v[108:111], v[104:107]
	v_mfma_f32_16x16x32_bf16 v[108:111], v[204:207], v[112:115], v[166:169]
	v_mfma_f32_16x16x32_bf16 v[112:115], v[214:217], v[112:115], v[170:173]
	v_mfma_f32_16x16x32_bf16 v[116:119], v[204:207], v[232:235], v[174:177]
	v_mfma_f32_16x16x32_bf16 v[120:123], v[214:217], v[232:235], v[120:123]
	v_mfma_f32_16x16x32_bf16 v[124:127], v[204:207], v[240:243], v[178:181]
	v_mfma_f32_16x16x32_bf16 v[128:131], v[214:217], v[240:243], v[128:131]
	v_mfma_f32_16x16x32_bf16 v[108:111], v[210:213], v[222:225], v[108:111]
	v_mfma_f32_16x16x32_bf16 v[112:115], v[218:221], v[222:225], v[112:115]
	v_mfma_f32_16x16x32_bf16 v[116:119], v[210:213], v[236:239], v[116:119]
	v_mfma_f32_16x16x32_bf16 v[120:123], v[218:221], v[236:239], v[120:123]
	v_mfma_f32_16x16x32_bf16 v[124:127], v[210:213], v[244:247], v[124:127]
	v_mfma_f32_16x16x32_bf16 v[128:131], v[218:221], v[244:247], v[128:131]
	s_setprio 0
	s_barrier
	s_add_i32 s43, s43, 2
	s_cmp_ge_i32 s43, s42
	s_cbranch_scc0 .LBB0_1175
.LBB0_1176:
	s_add_i32 s12, 0, 0x10000
	s_add_i32 s13, 0, 0x14000
	v_mov_b32_e32 v192, v2
	v_mov_b32_e32 v2, v132
	v_add_u32_e32 v144, s12, v209
	v_add_u32_e32 v160, s13, v209
	ds_read_b128 v[132:135], v144
	ds_read_b128 v[136:139], v144 offset:1024
	ds_read_b128 v[140:143], v144 offset:2048
	ds_read_b128 v[144:147], v144 offset:3072
	ds_read_b128 v[148:151], v160
	ds_read_b128 v[152:155], v160 offset:1024
	ds_read_b128 v[156:159], v160 offset:2048
	ds_read_b128 v[160:163], v160 offset:3072
	s_add_u32 s6, s6, 0x80180
	s_mov_b32 m0, s73
	v_add_u32_e32 v212, 0, v208
	s_addc_u32 s7, s7, 0
	ds_read_b128 v[164:167], v212
	ds_read_b128 v[168:171], v212 offset:1024
	ds_read_b128 v[172:175], v212 offset:2048
	ds_read_b128 v[176:179], v212 offset:3072
	ds_read_b128 v[180:183], v212 offset:4096
	ds_read_b128 v[184:187], v212 offset:5120
	ds_read_b128 v[194:197], v212 offset:6144
	ds_read_b128 v[198:201], v212 offset:7168
	global_load_lds_dwordx4 v2, s[6:7]
	s_mov_b32 m0, s76
	v_mov_b32_e32 v189, v3
	global_load_lds_dwordx4 v188, s[6:7]
	s_waitcnt vmcnt(8)
	s_waitcnt lgkmcnt(0)
	s_barrier
	s_setprio 1
	s_waitcnt lgkmcnt(0)
	v_mfma_f32_16x16x32_bf16 v[4:7], v[132:135], v[164:167], v[4:7]
	v_mfma_f32_16x16x32_bf16 v[4:7], v[136:139], v[168:171], v[4:7]
	v_mfma_f32_16x16x32_bf16 v[8:11], v[144:147], v[168:171], v[8:11]
	v_mfma_f32_16x16x32_bf16 v[8:11], v[140:143], v[164:167], v[8:11]
	v_mfma_f32_16x16x32_bf16 v[16:19], v[140:143], v[172:175], v[16:19]
	v_mfma_f32_16x16x32_bf16 v[16:19], v[144:147], v[176:179], v[16:19]
	v_mfma_f32_16x16x32_bf16 v[12:15], v[136:139], v[176:179], v[12:15]
	v_mfma_f32_16x16x32_bf16 v[12:15], v[132:135], v[172:175], v[12:15]
	v_mfma_f32_16x16x32_bf16 v[20:23], v[132:135], v[180:183], v[20:23]
	v_mfma_f32_16x16x32_bf16 v[20:23], v[136:139], v[184:187], v[20:23]
	v_mfma_f32_16x16x32_bf16 v[24:27], v[144:147], v[184:187], v[24:27]
	v_mfma_f32_16x16x32_bf16 v[24:27], v[140:143], v[180:183], v[24:27]
	v_mfma_f32_16x16x32_bf16 v[32:35], v[140:143], v[194:197], v[32:35]
	v_mfma_f32_16x16x32_bf16 v[32:35], v[144:147], v[198:201], v[32:35]
	v_mfma_f32_16x16x32_bf16 v[28:31], v[136:139], v[198:201], v[28:31]
	v_mfma_f32_16x16x32_bf16 v[28:31], v[132:135], v[194:197], v[28:31]
	s_setprio 0
	s_setprio 1
	v_mfma_f32_16x16x32_bf16 v[36:39], v[148:151], v[164:167], v[36:39]
	v_mfma_f32_16x16x32_bf16 v[36:39], v[152:155], v[168:171], v[36:39]
	v_mfma_f32_16x16x32_bf16 v[40:43], v[160:163], v[168:171], v[40:43]
	v_mfma_f32_16x16x32_bf16 v[40:43], v[156:159], v[164:167], v[40:43]
	v_mfma_f32_16x16x32_bf16 v[48:51], v[156:159], v[172:175], v[48:51]
	v_mfma_f32_16x16x32_bf16 v[48:51], v[160:163], v[176:179], v[48:51]
	v_mfma_f32_16x16x32_bf16 v[44:47], v[152:155], v[176:179], v[44:47]
	v_mfma_f32_16x16x32_bf16 v[44:47], v[148:151], v[172:175], v[44:47]
	v_mfma_f32_16x16x32_bf16 v[52:55], v[148:151], v[180:183], v[52:55]
	v_mfma_f32_16x16x32_bf16 v[52:55], v[152:155], v[184:187], v[52:55]
	v_mfma_f32_16x16x32_bf16 v[56:59], v[160:163], v[184:187], v[56:59]
	v_mfma_f32_16x16x32_bf16 v[56:59], v[156:159], v[180:183], v[56:59]
	v_mfma_f32_16x16x32_bf16 v[64:67], v[156:159], v[194:197], v[64:67]
	v_mfma_f32_16x16x32_bf16 v[64:67], v[160:163], v[198:201], v[64:67]
	v_mfma_f32_16x16x32_bf16 v[60:63], v[152:155], v[198:201], v[60:63]
	v_mfma_f32_16x16x32_bf16 v[60:63], v[148:151], v[194:197], v[60:63]
	s_setprio 0
	s_barrier
	s_add_i32 s6, s12, s36
	s_mov_b32 m0, s6
	ds_read_b128 v[164:167], v212 offset:16384
	ds_read_b128 v[168:171], v212 offset:17408
	ds_read_b128 v[172:175], v212 offset:18432
	ds_read_b128 v[176:179], v212 offset:19456
	ds_read_b128 v[180:183], v212 offset:20480
	ds_read_b128 v[184:187], v212 offset:21504
	ds_read_b128 v[194:197], v212 offset:22528
	ds_read_b128 v[198:201], v212 offset:23552
	global_load_lds_dwordx4 v192, s[14:15]
	s_add_i32 m0, s6, 0x2000
	s_add_u32 s6, s14, 0x10000
	s_addc_u32 s7, s15, 0
	s_add_i32 s12, s13, s36
	global_load_lds_dwordx4 v190, s[14:15]
	s_mov_b32 m0, s12
	v_mov_b32_e32 v193, v3
	global_load_lds_dwordx4 v192, s[6:7]
	s_add_i32 m0, s12, 0x2000
	v_mov_b32_e32 v191, v3
	global_load_lds_dwordx4 v190, s[6:7]
	s_mov_b32 m0, s37
	v_lshl_add_u64 v[202:203], s[14:15], 0, v[192:193]
	global_load_lds_dwordx4 v2, s[10:11]
	s_mov_b32 m0, s66
	v_lshl_add_u64 v[204:205], s[14:15], 0, v[190:191]
	global_load_lds_dwordx4 v188, s[10:11]
	s_waitcnt vmcnt(8)
	s_waitcnt lgkmcnt(0)
	v_lshl_add_u64 v[206:207], s[10:11], 0, v[2:3]
	v_lshl_add_u64 v[210:211], s[10:11], 0, v[188:189]
	s_barrier
	s_setprio 1
	s_waitcnt lgkmcnt(0)
	v_mfma_f32_16x16x32_bf16 v[68:71], v[132:135], v[164:167], v[68:71]
	v_mfma_f32_16x16x32_bf16 v[68:71], v[136:139], v[168:171], v[68:71]
	v_mfma_f32_16x16x32_bf16 v[72:75], v[144:147], v[168:171], v[72:75]
	v_mfma_f32_16x16x32_bf16 v[72:75], v[140:143], v[164:167], v[72:75]
	v_mfma_f32_16x16x32_bf16 v[80:83], v[140:143], v[172:175], v[80:83]
	v_mfma_f32_16x16x32_bf16 v[80:83], v[144:147], v[176:179], v[80:83]
	v_mfma_f32_16x16x32_bf16 v[76:79], v[136:139], v[176:179], v[76:79]
	v_mfma_f32_16x16x32_bf16 v[76:79], v[132:135], v[172:175], v[76:79]
	v_mfma_f32_16x16x32_bf16 v[84:87], v[132:135], v[180:183], v[84:87]
	v_mfma_f32_16x16x32_bf16 v[84:87], v[136:139], v[184:187], v[84:87]
	v_mfma_f32_16x16x32_bf16 v[88:91], v[144:147], v[184:187], v[88:91]
	v_mfma_f32_16x16x32_bf16 v[88:91], v[140:143], v[180:183], v[88:91]
	v_mfma_f32_16x16x32_bf16 v[96:99], v[140:143], v[194:197], v[96:99]
	v_mfma_f32_16x16x32_bf16 v[96:99], v[144:147], v[198:201], v[96:99]
	v_mfma_f32_16x16x32_bf16 v[92:95], v[136:139], v[198:201], v[92:95]
	v_mfma_f32_16x16x32_bf16 v[92:95], v[132:135], v[194:197], v[92:95]
	s_setprio 0
	s_setprio 1
	v_mfma_f32_16x16x32_bf16 v[100:103], v[148:151], v[164:167], v[100:103]
	v_mfma_f32_16x16x32_bf16 v[100:103], v[152:155], v[168:171], v[100:103]
	v_mfma_f32_16x16x32_bf16 v[104:107], v[160:163], v[168:171], v[104:107]
	v_mfma_f32_16x16x32_bf16 v[104:107], v[156:159], v[164:167], v[104:107]
	v_mfma_f32_16x16x32_bf16 v[112:115], v[156:159], v[172:175], v[112:115]
	v_mfma_f32_16x16x32_bf16 v[112:115], v[160:163], v[176:179], v[112:115]
	v_mfma_f32_16x16x32_bf16 v[108:111], v[152:155], v[176:179], v[108:111]
	v_mfma_f32_16x16x32_bf16 v[108:111], v[148:151], v[172:175], v[108:111]
	v_mfma_f32_16x16x32_bf16 v[116:119], v[148:151], v[180:183], v[116:119]
	v_mfma_f32_16x16x32_bf16 v[116:119], v[152:155], v[184:187], v[116:119]
	v_mfma_f32_16x16x32_bf16 v[120:123], v[160:163], v[184:187], v[120:123]
	v_mfma_f32_16x16x32_bf16 v[120:123], v[156:159], v[180:183], v[120:123]
	v_mfma_f32_16x16x32_bf16 v[128:131], v[156:159], v[194:197], v[128:131]
	v_mfma_f32_16x16x32_bf16 v[128:131], v[160:163], v[198:201], v[128:131]
	v_mfma_f32_16x16x32_bf16 v[124:127], v[152:155], v[198:201], v[124:127]
	v_mfma_f32_16x16x32_bf16 v[124:127], v[148:151], v[194:197], v[124:127]
	s_setprio 0
	s_barrier
	s_add_i32 s12, 0, 0x18000
	s_add_i32 s13, 0, 0x1c000
	v_add_u32_e32 v144, s12, v209
	v_add_u32_e32 v160, s13, v209
	ds_read_b128 v[132:135], v144
	ds_read_b128 v[136:139], v144 offset:1024
	ds_read_b128 v[140:143], v144 offset:2048
	ds_read_b128 v[144:147], v144 offset:3072
	ds_read_b128 v[148:151], v160
	ds_read_b128 v[152:155], v160 offset:1024
	ds_read_b128 v[156:159], v160 offset:2048
	ds_read_b128 v[160:163], v160 offset:3072
	s_add_u32 s6, s10, 0x80000
	s_addc_u32 s7, s11, 0
	s_mov_b32 m0, s67
	ds_read_b128 v[164:167], v212 offset:32768
	ds_read_b128 v[168:171], v212 offset:33792
	ds_read_b128 v[172:175], v212 offset:34816
	ds_read_b128 v[176:179], v212 offset:35840
	ds_read_b128 v[180:183], v212 offset:36864
	ds_read_b128 v[184:187], v212 offset:37888
	ds_read_b128 v[194:197], v212 offset:38912
	ds_read_b128 v[198:201], v212 offset:39936
	global_load_lds_dwordx4 v2, s[6:7]
	s_mov_b32 m0, s68
	s_nop 0
	global_load_lds_dwordx4 v188, s[6:7]
	s_waitcnt vmcnt(8)
	s_waitcnt lgkmcnt(0)
	s_barrier
	s_setprio 1
	s_waitcnt lgkmcnt(0)
	v_mfma_f32_16x16x32_bf16 v[4:7], v[132:135], v[164:167], v[4:7]
	v_mfma_f32_16x16x32_bf16 v[4:7], v[136:139], v[168:171], v[4:7]
	v_mfma_f32_16x16x32_bf16 v[8:11], v[144:147], v[168:171], v[8:11]
	v_mfma_f32_16x16x32_bf16 v[8:11], v[140:143], v[164:167], v[8:11]
	v_mfma_f32_16x16x32_bf16 v[16:19], v[140:143], v[172:175], v[16:19]
	v_mfma_f32_16x16x32_bf16 v[16:19], v[144:147], v[176:179], v[16:19]
	v_mfma_f32_16x16x32_bf16 v[12:15], v[136:139], v[176:179], v[12:15]
	v_mfma_f32_16x16x32_bf16 v[12:15], v[132:135], v[172:175], v[12:15]
	v_mfma_f32_16x16x32_bf16 v[20:23], v[132:135], v[180:183], v[20:23]
	v_mfma_f32_16x16x32_bf16 v[20:23], v[136:139], v[184:187], v[20:23]
	v_mfma_f32_16x16x32_bf16 v[24:27], v[144:147], v[184:187], v[24:27]
	v_mfma_f32_16x16x32_bf16 v[24:27], v[140:143], v[180:183], v[24:27]
	v_mfma_f32_16x16x32_bf16 v[32:35], v[140:143], v[194:197], v[32:35]
	v_mfma_f32_16x16x32_bf16 v[32:35], v[144:147], v[198:201], v[32:35]
	v_mfma_f32_16x16x32_bf16 v[28:31], v[136:139], v[198:201], v[28:31]
	v_mfma_f32_16x16x32_bf16 v[28:31], v[132:135], v[194:197], v[28:31]
	s_setprio 0
	s_setprio 1
	v_mfma_f32_16x16x32_bf16 v[36:39], v[148:151], v[164:167], v[36:39]
	v_mfma_f32_16x16x32_bf16 v[36:39], v[152:155], v[168:171], v[36:39]
	v_mfma_f32_16x16x32_bf16 v[40:43], v[160:163], v[168:171], v[40:43]
	v_mfma_f32_16x16x32_bf16 v[40:43], v[156:159], v[164:167], v[40:43]
	v_mfma_f32_16x16x32_bf16 v[48:51], v[156:159], v[172:175], v[48:51]
	v_mfma_f32_16x16x32_bf16 v[48:51], v[160:163], v[176:179], v[48:51]
	v_mfma_f32_16x16x32_bf16 v[44:47], v[152:155], v[176:179], v[44:47]
	v_mfma_f32_16x16x32_bf16 v[44:47], v[148:151], v[172:175], v[44:47]
	v_mfma_f32_16x16x32_bf16 v[52:55], v[148:151], v[180:183], v[52:55]
	v_mfma_f32_16x16x32_bf16 v[52:55], v[152:155], v[184:187], v[52:55]
	v_mfma_f32_16x16x32_bf16 v[56:59], v[160:163], v[184:187], v[56:59]
	v_mfma_f32_16x16x32_bf16 v[56:59], v[156:159], v[180:183], v[56:59]
	v_mfma_f32_16x16x32_bf16 v[64:67], v[156:159], v[194:197], v[64:67]
	v_mfma_f32_16x16x32_bf16 v[64:67], v[160:163], v[198:201], v[64:67]
	v_mfma_f32_16x16x32_bf16 v[60:63], v[152:155], v[198:201], v[60:63]
	v_mfma_f32_16x16x32_bf16 v[60:63], v[148:151], v[194:197], v[60:63]
	s_setprio 0
	s_barrier
	s_add_i32 s6, s12, s36
	v_lshl_add_u64 v[202:203], v[202:203], 0, s[86:87]
	s_mov_b32 m0, s6
	ds_read_b128 v[164:167], v212 offset:49152
	ds_read_b128 v[168:171], v212 offset:50176
	ds_read_b128 v[172:175], v212 offset:51200
	ds_read_b128 v[176:179], v212 offset:52224
	ds_read_b128 v[180:183], v212 offset:53248
	ds_read_b128 v[184:187], v212 offset:54272
	ds_read_b128 v[194:197], v212 offset:55296
	ds_read_b128 v[198:201], v212 offset:56320
	global_load_lds_dwordx4 v[202:203], off
	s_add_i32 m0, s6, 0x2000
	s_add_u32 s6, s14, 0x10080
	v_lshl_add_u64 v[202:203], v[204:205], 0, s[86:87]
	s_addc_u32 s7, s15, 0
	s_add_i32 s12, s13, s36
	global_load_lds_dwordx4 v[202:203], off
	s_mov_b32 m0, s12
	v_lshl_add_u64 v[202:203], v[206:207], 0, s[86:87]
	global_load_lds_dwordx4 v192, s[6:7]
	s_add_i32 m0, s12, 0x2000
	s_nop 0
	global_load_lds_dwordx4 v190, s[6:7]
	s_mov_b32 m0, s71
	s_nop 0
	global_load_lds_dwordx4 v[202:203], off
	v_lshl_add_u64 v[202:203], v[210:211], 0, s[86:87]
	s_mov_b32 m0, s72
	s_nop 0
	global_load_lds_dwordx4 v[202:203], off
	s_waitcnt vmcnt(8)
	s_waitcnt lgkmcnt(0)
	s_barrier
	s_setprio 1
	s_waitcnt lgkmcnt(0)
	v_mfma_f32_16x16x32_bf16 v[68:71], v[132:135], v[164:167], v[68:71]
	v_mfma_f32_16x16x32_bf16 v[68:71], v[136:139], v[168:171], v[68:71]
	v_mfma_f32_16x16x32_bf16 v[72:75], v[144:147], v[168:171], v[72:75]
	v_mfma_f32_16x16x32_bf16 v[72:75], v[140:143], v[164:167], v[72:75]
	v_mfma_f32_16x16x32_bf16 v[80:83], v[140:143], v[172:175], v[80:83]
	v_mfma_f32_16x16x32_bf16 v[80:83], v[144:147], v[176:179], v[80:83]
	v_mfma_f32_16x16x32_bf16 v[76:79], v[136:139], v[176:179], v[76:79]
	v_mfma_f32_16x16x32_bf16 v[76:79], v[132:135], v[172:175], v[76:79]
	v_mfma_f32_16x16x32_bf16 v[84:87], v[132:135], v[180:183], v[84:87]
	v_mfma_f32_16x16x32_bf16 v[84:87], v[136:139], v[184:187], v[84:87]
	v_mfma_f32_16x16x32_bf16 v[88:91], v[144:147], v[184:187], v[88:91]
	v_mfma_f32_16x16x32_bf16 v[88:91], v[140:143], v[180:183], v[88:91]
	v_mfma_f32_16x16x32_bf16 v[96:99], v[140:143], v[194:197], v[96:99]
	v_mfma_f32_16x16x32_bf16 v[96:99], v[144:147], v[198:201], v[96:99]
	v_mfma_f32_16x16x32_bf16 v[92:95], v[136:139], v[198:201], v[92:95]
	v_mfma_f32_16x16x32_bf16 v[92:95], v[132:135], v[194:197], v[92:95]
	s_setprio 0
	s_setprio 1
	v_mfma_f32_16x16x32_bf16 v[100:103], v[148:151], v[164:167], v[100:103]
	v_mfma_f32_16x16x32_bf16 v[100:103], v[152:155], v[168:171], v[100:103]
	v_mfma_f32_16x16x32_bf16 v[104:107], v[160:163], v[168:171], v[104:107]
	v_mfma_f32_16x16x32_bf16 v[104:107], v[156:159], v[164:167], v[104:107]
	v_mfma_f32_16x16x32_bf16 v[112:115], v[156:159], v[172:175], v[112:115]
	v_mfma_f32_16x16x32_bf16 v[112:115], v[160:163], v[176:179], v[112:115]
	v_mfma_f32_16x16x32_bf16 v[108:111], v[152:155], v[176:179], v[108:111]
	v_mfma_f32_16x16x32_bf16 v[108:111], v[148:151], v[172:175], v[108:111]
	v_mfma_f32_16x16x32_bf16 v[116:119], v[148:151], v[180:183], v[116:119]
	v_mfma_f32_16x16x32_bf16 v[116:119], v[152:155], v[184:187], v[116:119]
	v_mfma_f32_16x16x32_bf16 v[120:123], v[160:163], v[184:187], v[120:123]
	v_mfma_f32_16x16x32_bf16 v[120:123], v[156:159], v[180:183], v[120:123]
	v_mfma_f32_16x16x32_bf16 v[128:131], v[156:159], v[194:197], v[128:131]
	v_mfma_f32_16x16x32_bf16 v[128:131], v[160:163], v[198:201], v[128:131]
	v_mfma_f32_16x16x32_bf16 v[124:127], v[152:155], v[198:201], v[124:127]
	v_mfma_f32_16x16x32_bf16 v[124:127], v[148:151], v[194:197], v[124:127]
	s_setprio 0
	s_barrier
	s_and_b64 vcc, exec, s[58:59]
	s_cbranch_vccz .LBB0_1178
	s_barrier

.LBB0_1625:
	s_add_i32 s51, 0, 0x10000
	s_add_i32 s72, 0, 0x14000
	v_add_u32_e32 v16, s51, v232
	v_add_u32_e32 v32, s72, v232
	ds_read_b128 v[4:7], v16
	ds_read_b128 v[8:11], v16 offset:1024
	ds_read_b128 v[12:15], v16 offset:2048
	ds_read_b128 v[16:19], v16 offset:3072
	ds_read_b128 v[20:23], v32
	ds_read_b128 v[24:27], v32 offset:1024
	ds_read_b128 v[28:31], v32 offset:2048
	ds_read_b128 v[32:35], v32 offset:3072
	v_add_u32_e32 v233, 0, v231
	ds_read_b128 v[36:39], v233
	ds_read_b128 v[40:43], v233 offset:1024
	ds_read_b128 v[44:47], v233 offset:2048
	ds_read_b128 v[48:51], v233 offset:3072
	ds_read_b128 v[52:55], v233 offset:4096
	ds_read_b128 v[56:59], v233 offset:5120
	ds_read_b128 v[60:63], v233 offset:6144
	ds_read_b128 v[64:67], v233 offset:7168
	s_waitcnt vmcnt(8)
	s_waitcnt lgkmcnt(0)
	s_barrier
	s_setprio 1
	s_waitcnt lgkmcnt(0)
	v_mfma_f32_16x16x32_bf16 v[68:71], v[4:7], v[36:39], 0
	v_mfma_f32_16x16x32_bf16 v[68:71], v[8:11], v[40:43], v[68:71]
	v_mfma_f32_16x16x32_bf16 v[72:75], v[12:15], v[36:39], 0
	v_mfma_f32_16x16x32_bf16 v[72:75], v[16:19], v[40:43], v[72:75]
	v_mfma_f32_16x16x32_bf16 v[80:83], v[12:15], v[44:47], 0
	v_mfma_f32_16x16x32_bf16 v[80:83], v[16:19], v[48:51], v[80:83]
	v_mfma_f32_16x16x32_bf16 v[76:79], v[4:7], v[44:47], 0
	v_mfma_f32_16x16x32_bf16 v[76:79], v[8:11], v[48:51], v[76:79]
	v_mfma_f32_16x16x32_bf16 v[84:87], v[4:7], v[52:55], 0
	v_mfma_f32_16x16x32_bf16 v[84:87], v[8:11], v[56:59], v[84:87]
	v_mfma_f32_16x16x32_bf16 v[88:91], v[12:15], v[52:55], 0
	v_mfma_f32_16x16x32_bf16 v[88:91], v[16:19], v[56:59], v[88:91]
	v_mfma_f32_16x16x32_bf16 v[96:99], v[12:15], v[60:63], 0
	v_mfma_f32_16x16x32_bf16 v[96:99], v[16:19], v[64:67], v[96:99]
	v_mfma_f32_16x16x32_bf16 v[92:95], v[4:7], v[60:63], 0
	v_mfma_f32_16x16x32_bf16 v[92:95], v[8:11], v[64:67], v[92:95]
	s_setprio 0
	s_setprio 1
	v_mfma_f32_16x16x32_bf16 v[100:103], v[20:23], v[36:39], 0
	v_mfma_f32_16x16x32_bf16 v[36:39], v[28:31], v[36:39], 0
	v_mfma_f32_16x16x32_bf16 v[104:107], v[20:23], v[44:47], 0
	v_mfma_f32_16x16x32_bf16 v[44:47], v[28:31], v[44:47], 0
	v_mfma_f32_16x16x32_bf16 v[108:111], v[20:23], v[52:55], 0
	v_mfma_f32_16x16x32_bf16 v[52:55], v[28:31], v[52:55], 0
	v_mfma_f32_16x16x32_bf16 v[112:115], v[20:23], v[60:63], 0
	v_mfma_f32_16x16x32_bf16 v[60:63], v[28:31], v[60:63], 0
	v_mfma_f32_16x16x32_bf16 v[100:103], v[24:27], v[40:43], v[100:103]
	v_mfma_f32_16x16x32_bf16 v[40:43], v[32:35], v[40:43], v[36:39]
	v_mfma_f32_16x16x32_bf16 v[104:107], v[24:27], v[48:51], v[104:107]
	v_mfma_f32_16x16x32_bf16 v[48:51], v[32:35], v[48:51], v[44:47]
	v_mfma_f32_16x16x32_bf16 v[108:111], v[24:27], v[56:59], v[108:111]
	v_mfma_f32_16x16x32_bf16 v[56:59], v[32:35], v[56:59], v[52:55]
	v_mfma_f32_16x16x32_bf16 v[112:115], v[24:27], v[64:67], v[112:115]
	v_mfma_f32_16x16x32_bf16 v[64:67], v[32:35], v[64:67], v[60:63]
	s_setprio 0
	s_barrier
	v_lshl_add_u64 v[186:187], s[12:13], 0, v[2:3]
	s_add_i32 s51, s51, s56
	v_mov_b32_e32 v191, v3
	v_lshl_add_u64 v[134:135], v[186:187], 0, s[74:75]
	s_mov_b32 m0, s51
	v_lshl_add_u64 v[246:247], s[12:13], 0, v[190:191]
	ds_read_b128 v[36:39], v233 offset:16384
	ds_read_b128 v[44:47], v233 offset:17408
	ds_read_b128 v[52:55], v233 offset:18432
	ds_read_b128 v[60:63], v233 offset:19456
	ds_read_b128 v[116:119], v233 offset:20480
	ds_read_b128 v[120:123], v233 offset:21504
	ds_read_b128 v[124:127], v233 offset:22528
	ds_read_b128 v[128:131], v233 offset:23552
	global_load_lds_dwordx4 v[134:135], off
	v_lshl_add_u64 v[134:135], v[246:247], 0, s[74:75]
	s_add_i32 m0, s51, 0x2000
	s_add_i32 s51, s72, s56
	global_load_lds_dwordx4 v[134:135], off
	s_mov_b32 m0, s51
	v_mov_b32_e32 v133, v3
	global_load_lds_dwordx4 v2, s[16:17]
	s_add_i32 m0, s51, 0x2000
	v_lshl_add_u64 v[248:249], s[14:15], 0, v[132:133]
	v_mov_b32_e32 v189, v3
	global_load_lds_dwordx4 v190, s[16:17]
	v_lshl_add_u64 v[134:135], v[248:249], 0, s[74:75]
	s_mov_b32 m0, s57
	v_lshl_add_u64 v[250:251], s[14:15], 0, v[188:189]
	global_load_lds_dwordx4 v[134:135], off
	v_lshl_add_u64 v[134:135], v[250:251], 0, s[74:75]
	s_mov_b32 m0, s58
	s_nop 0
	global_load_lds_dwordx4 v[134:135], off
	s_waitcnt vmcnt(8)
	s_waitcnt lgkmcnt(0)
	s_barrier
	s_setprio 1
	s_waitcnt lgkmcnt(0)
	v_mfma_f32_16x16x32_bf16 v[134:137], v[4:7], v[36:39], 0
	v_mfma_f32_16x16x32_bf16 v[138:141], v[12:15], v[36:39], 0
	v_mfma_f32_16x16x32_bf16 v[142:145], v[4:7], v[52:55], 0
	v_mfma_f32_16x16x32_bf16 v[146:149], v[12:15], v[52:55], 0
	v_mfma_f32_16x16x32_bf16 v[150:153], v[4:7], v[116:119], 0
	v_mfma_f32_16x16x32_bf16 v[154:157], v[12:15], v[116:119], 0
	v_mfma_f32_16x16x32_bf16 v[4:7], v[4:7], v[124:127], 0
	v_mfma_f32_16x16x32_bf16 v[12:15], v[12:15], v[124:127], 0
	v_mfma_f32_16x16x32_bf16 v[134:137], v[8:11], v[44:47], v[134:137]
	v_mfma_f32_16x16x32_bf16 v[138:141], v[16:19], v[44:47], v[138:141]
	v_mfma_f32_16x16x32_bf16 v[142:145], v[8:11], v[60:63], v[142:145]
	v_mfma_f32_16x16x32_bf16 v[146:149], v[16:19], v[60:63], v[146:149]
	v_mfma_f32_16x16x32_bf16 v[150:153], v[8:11], v[120:123], v[150:153]
	v_mfma_f32_16x16x32_bf16 v[154:157], v[16:19], v[120:123], v[154:157]
	v_mfma_f32_16x16x32_bf16 v[158:161], v[8:11], v[128:131], v[4:7]
	v_mfma_f32_16x16x32_bf16 v[162:165], v[16:19], v[128:131], v[12:15]
	s_setprio 0
	s_setprio 1
	v_mfma_f32_16x16x32_bf16 v[4:7], v[20:23], v[36:39], 0
	v_mfma_f32_16x16x32_bf16 v[8:11], v[28:31], v[36:39], 0
	v_mfma_f32_16x16x32_bf16 v[12:15], v[20:23], v[52:55], 0
	v_mfma_f32_16x16x32_bf16 v[16:19], v[28:31], v[52:55], 0
	v_mfma_f32_16x16x32_bf16 v[36:39], v[20:23], v[116:119], 0
	v_mfma_f32_16x16x32_bf16 v[52:55], v[28:31], v[116:119], 0
	v_mfma_f32_16x16x32_bf16 v[20:23], v[20:23], v[124:127], 0
	v_mfma_f32_16x16x32_bf16 v[28:31], v[28:31], v[124:127], 0
	v_mfma_f32_16x16x32_bf16 v[116:119], v[24:27], v[44:47], v[4:7]
	v_mfma_f32_16x16x32_bf16 v[124:127], v[32:35], v[44:47], v[8:11]
	v_mfma_f32_16x16x32_bf16 v[174:177], v[24:27], v[120:123], v[36:39]
	v_mfma_f32_16x16x32_bf16 v[120:123], v[32:35], v[120:123], v[52:55]
	v_mfma_f32_16x16x32_bf16 v[178:181], v[24:27], v[128:131], v[20:23]
	v_mfma_f32_16x16x32_bf16 v[128:131], v[32:35], v[128:131], v[28:31]
	v_mfma_f32_16x16x32_bf16 v[166:169], v[24:27], v[60:63], v[12:15]
	v_mfma_f32_16x16x32_bf16 v[170:173], v[32:35], v[60:63], v[16:19]
	s_setprio 0
	s_barrier
	s_add_i32 s51, 0, 0x18000
	v_add_u32_e32 v4, s51, v232
	s_add_i32 s72, 0, 0x1c000
	ds_read_b128 v[182:185], v4
	ds_read_b128 v[192:195], v4 offset:1024
	ds_read_b128 v[196:199], v4 offset:2048
	ds_read_b128 v[200:203], v4 offset:3072
	v_add_u32_e32 v4, s72, v232
	ds_read_b128 v[204:207], v4
	ds_read_b128 v[208:211], v4 offset:1024
	ds_read_b128 v[212:215], v4 offset:2048
	ds_read_b128 v[216:219], v4 offset:3072
	s_mov_b32 m0, s59
	ds_read_b128 v[44:47], v233 offset:32768
	ds_read_b128 v[52:55], v233 offset:33792
	ds_read_b128 v[60:63], v233 offset:34816
	ds_read_b128 v[220:223], v233 offset:35840
	ds_read_b128 v[224:227], v233 offset:36864
	ds_read_b128 v[234:237], v233 offset:37888
	ds_read_b128 v[238:241], v233 offset:38912
	ds_read_b128 v[242:245], v233 offset:39936
	global_load_lds_dwordx4 v132, s[26:27]
	s_mov_b32 m0, s60
	s_nop 0
	global_load_lds_dwordx4 v188, s[26:27]
	s_waitcnt vmcnt(8)
	s_waitcnt lgkmcnt(0)
	s_barrier
	s_setprio 1
	s_waitcnt lgkmcnt(0)
	v_mfma_f32_16x16x32_bf16 v[4:7], v[182:185], v[44:47], v[68:71]
	v_mfma_f32_16x16x32_bf16 v[8:11], v[196:199], v[44:47], v[72:75]
	v_mfma_f32_16x16x32_bf16 v[12:15], v[182:185], v[60:63], v[76:79]
	v_mfma_f32_16x16x32_bf16 v[16:19], v[196:199], v[60:63], v[80:83]
	v_mfma_f32_16x16x32_bf16 v[20:23], v[182:185], v[224:227], v[84:87]
	v_mfma_f32_16x16x32_bf16 v[24:27], v[196:199], v[224:227], v[88:91]
	v_mfma_f32_16x16x32_bf16 v[28:31], v[182:185], v[238:241], v[92:95]
	v_mfma_f32_16x16x32_bf16 v[32:35], v[196:199], v[238:241], v[96:99]
	v_mfma_f32_16x16x32_bf16 v[4:7], v[192:195], v[52:55], v[4:7]
	v_mfma_f32_16x16x32_bf16 v[8:11], v[200:203], v[52:55], v[8:11]
	v_mfma_f32_16x16x32_bf16 v[12:15], v[192:195], v[220:223], v[12:15]
	v_mfma_f32_16x16x32_bf16 v[16:19], v[200:203], v[220:223], v[16:19]
	v_mfma_f32_16x16x32_bf16 v[20:23], v[192:195], v[234:237], v[20:23]
	v_mfma_f32_16x16x32_bf16 v[24:27], v[200:203], v[234:237], v[24:27]
	v_mfma_f32_16x16x32_bf16 v[28:31], v[192:195], v[242:245], v[28:31]
	v_mfma_f32_16x16x32_bf16 v[32:35], v[200:203], v[242:245], v[32:35]
	s_setprio 0
	s_setprio 1
	v_mfma_f32_16x16x32_bf16 v[36:39], v[204:207], v[44:47], v[100:103]
	v_mfma_f32_16x16x32_bf16 v[40:43], v[212:215], v[44:47], v[40:43]
	v_mfma_f32_16x16x32_bf16 v[36:39], v[208:211], v[52:55], v[36:39]
	v_mfma_f32_16x16x32_bf16 v[40:43], v[216:219], v[52:55], v[40:43]
	v_mfma_f32_16x16x32_bf16 v[44:47], v[204:207], v[60:63], v[104:107]
	v_mfma_f32_16x16x32_bf16 v[48:51], v[212:215], v[60:63], v[48:51]
	v_mfma_f32_16x16x32_bf16 v[52:55], v[204:207], v[224:227], v[108:111]
	v_mfma_f32_16x16x32_bf16 v[56:59], v[212:215], v[224:227], v[56:59]
	v_mfma_f32_16x16x32_bf16 v[60:63], v[204:207], v[238:241], v[112:115]
	v_mfma_f32_16x16x32_bf16 v[64:67], v[212:215], v[238:241], v[64:67]
	v_mfma_f32_16x16x32_bf16 v[44:47], v[208:211], v[220:223], v[44:47]
	v_mfma_f32_16x16x32_bf16 v[48:51], v[216:219], v[220:223], v[48:51]
	v_mfma_f32_16x16x32_bf16 v[52:55], v[208:211], v[234:237], v[52:55]
	v_mfma_f32_16x16x32_bf16 v[56:59], v[216:219], v[234:237], v[56:59]
	v_mfma_f32_16x16x32_bf16 v[60:63], v[208:211], v[242:245], v[60:63]
	v_mfma_f32_16x16x32_bf16 v[64:67], v[216:219], v[242:245], v[64:67]
	s_setprio 0
	s_barrier
	s_add_i32 s51, s51, s56
	v_lshl_add_u64 v[68:69], v[186:187], 0, s[24:25]
	s_mov_b32 m0, s51
	ds_read_b128 v[104:107], v233 offset:49152
	ds_read_b128 v[108:111], v233 offset:50176
	ds_read_b128 v[112:115], v233 offset:51200
	ds_read_b128 v[220:223], v233 offset:52224
	ds_read_b128 v[224:227], v233 offset:53248
	ds_read_b128 v[234:237], v233 offset:54272
	ds_read_b128 v[238:241], v233 offset:55296
	ds_read_b128 v[242:245], v233 offset:56320
	global_load_lds_dwordx4 v[68:69], off
	v_lshl_add_u64 v[68:69], v[246:247], 0, s[24:25]
	s_add_i32 m0, s51, 0x2000
	s_add_i32 s51, s72, s56
	global_load_lds_dwordx4 v[68:69], off
	s_mov_b32 m0, s51
	v_lshl_add_u64 v[68:69], v[248:249], 0, s[24:25]
	global_load_lds_dwordx4 v2, s[28:29]
	s_add_i32 m0, s51, 0x2000
	s_nop 0
	global_load_lds_dwordx4 v190, s[28:29]
	s_mov_b32 m0, s64
	s_nop 0
	global_load_lds_dwordx4 v[68:69], off
	v_lshl_add_u64 v[68:69], v[250:251], 0, s[24:25]
	s_mov_b32 m0, s65
	s_nop 0
	global_load_lds_dwordx4 v[68:69], off
	s_waitcnt vmcnt(8)
	s_waitcnt lgkmcnt(0)
	s_barrier
	s_setprio 1
	s_waitcnt lgkmcnt(0)
	v_mfma_f32_16x16x32_bf16 v[68:71], v[182:185], v[104:107], v[134:137]
	v_mfma_f32_16x16x32_bf16 v[72:75], v[196:199], v[104:107], v[138:141]
	v_mfma_f32_16x16x32_bf16 v[76:79], v[182:185], v[112:115], v[142:145]
	v_mfma_f32_16x16x32_bf16 v[80:83], v[196:199], v[112:115], v[146:149]
	v_mfma_f32_16x16x32_bf16 v[84:87], v[182:185], v[224:227], v[150:153]
	v_mfma_f32_16x16x32_bf16 v[88:91], v[196:199], v[224:227], v[154:157]
	v_mfma_f32_16x16x32_bf16 v[92:95], v[182:185], v[238:241], v[158:161]
	v_mfma_f32_16x16x32_bf16 v[96:99], v[196:199], v[238:241], v[162:165]
	v_mfma_f32_16x16x32_bf16 v[68:71], v[192:195], v[108:111], v[68:71]
	v_mfma_f32_16x16x32_bf16 v[72:75], v[200:203], v[108:111], v[72:75]
	v_mfma_f32_16x16x32_bf16 v[76:79], v[192:195], v[220:223], v[76:79]
	v_mfma_f32_16x16x32_bf16 v[80:83], v[200:203], v[220:223], v[80:83]
	v_mfma_f32_16x16x32_bf16 v[84:87], v[192:195], v[234:237], v[84:87]
	v_mfma_f32_16x16x32_bf16 v[88:91], v[200:203], v[234:237], v[88:91]
	v_mfma_f32_16x16x32_bf16 v[92:95], v[192:195], v[242:245], v[92:95]
	v_mfma_f32_16x16x32_bf16 v[96:99], v[200:203], v[242:245], v[96:99]
	s_setprio 0
	s_setprio 1
	v_mfma_f32_16x16x32_bf16 v[100:103], v[204:207], v[104:107], v[116:119]
	v_mfma_f32_16x16x32_bf16 v[104:107], v[212:215], v[104:107], v[124:127]
	v_mfma_f32_16x16x32_bf16 v[100:103], v[208:211], v[108:111], v[100:103]
	v_mfma_f32_16x16x32_bf16 v[104:107], v[216:219], v[108:111], v[104:107]
	v_mfma_f32_16x16x32_bf16 v[108:111], v[204:207], v[112:115], v[166:169]
	v_mfma_f32_16x16x32_bf16 v[112:115], v[212:215], v[112:115], v[170:173]
	v_mfma_f32_16x16x32_bf16 v[116:119], v[204:207], v[224:227], v[174:177]
	v_mfma_f32_16x16x32_bf16 v[120:123], v[212:215], v[224:227], v[120:123]
	v_mfma_f32_16x16x32_bf16 v[124:127], v[204:207], v[238:241], v[178:181]
	v_mfma_f32_16x16x32_bf16 v[128:131], v[212:215], v[238:241], v[128:131]
	v_mfma_f32_16x16x32_bf16 v[108:111], v[208:211], v[220:223], v[108:111]
	v_mfma_f32_16x16x32_bf16 v[112:115], v[216:219], v[220:223], v[112:115]
	v_mfma_f32_16x16x32_bf16 v[116:119], v[208:211], v[234:237], v[116:119]
	v_mfma_f32_16x16x32_bf16 v[120:123], v[216:219], v[234:237], v[120:123]
	v_mfma_f32_16x16x32_bf16 v[124:127], v[208:211], v[242:245], v[124:127]
	v_mfma_f32_16x16x32_bf16 v[128:131], v[216:219], v[242:245], v[128:131]
	s_setprio 0
	s_barrier
	s_add_i32 s43, s43, 2
	s_cmp_ge_i32 s43, s42
	s_cbranch_scc0 .LBB0_1625
	v_mov_b32_e32 v192, v2
	s_branch .LBB0_1628

.LBB0_1629:
	s_add_u32 s12, s14, 0xfff80080
	s_addc_u32 s13, s15, -1
	s_add_i32 s29, 0, 0x10000
	s_cmp_eq_u32 s28, 28
	s_cselect_b32 s17, s9, s13
	s_cselect_b32 s16, s8, s12
	s_cselect_b32 s13, s11, s27
	s_cselect_b32 s12, s10, s26
	s_add_i32 s51, 0, 0x14000
	v_add_u32_e32 v144, s29, v232
	v_add_u32_e32 v160, s51, v232
	s_waitcnt lgkmcnt(0)
	ds_read_b128 v[132:135], v144
	ds_read_b128 v[136:139], v144 offset:1024
	ds_read_b128 v[140:143], v144 offset:2048
	ds_read_b128 v[144:147], v144 offset:3072
	ds_read_b128 v[148:151], v160
	ds_read_b128 v[152:155], v160 offset:1024
	ds_read_b128 v[156:159], v160 offset:2048
	ds_read_b128 v[160:163], v160 offset:3072
	s_mov_b32 m0, s66
	v_add_u32_e32 v210, 0, v231
	ds_read_b128 v[164:167], v210
	ds_read_b128 v[168:171], v210 offset:1024
	ds_read_b128 v[172:175], v210 offset:2048
	ds_read_b128 v[176:179], v210 offset:3072
	ds_read_b128 v[180:183], v210 offset:4096
	ds_read_b128 v[184:187], v210 offset:5120
	ds_read_b128 v[194:197], v210 offset:6144
	ds_read_b128 v[198:201], v210 offset:7168
	global_load_lds_dwordx4 v2, s[14:15]
	s_mov_b32 m0, s67
	v_mov_b32_e32 v189, v3
	global_load_lds_dwordx4 v188, s[14:15]
	s_waitcnt vmcnt(8)
	s_waitcnt lgkmcnt(0)
	s_barrier
	s_setprio 1
	s_waitcnt lgkmcnt(0)
	v_mfma_f32_16x16x32_bf16 v[4:7], v[132:135], v[164:167], v[4:7]
	v_mfma_f32_16x16x32_bf16 v[4:7], v[136:139], v[168:171], v[4:7]
	v_mfma_f32_16x16x32_bf16 v[8:11], v[144:147], v[168:171], v[8:11]
	v_mfma_f32_16x16x32_bf16 v[8:11], v[140:143], v[164:167], v[8:11]
	v_mfma_f32_16x16x32_bf16 v[16:19], v[140:143], v[172:175], v[16:19]
	v_mfma_f32_16x16x32_bf16 v[16:19], v[144:147], v[176:179], v[16:19]
	v_mfma_f32_16x16x32_bf16 v[12:15], v[136:139], v[176:179], v[12:15]
	v_mfma_f32_16x16x32_bf16 v[12:15], v[132:135], v[172:175], v[12:15]
	v_mfma_f32_16x16x32_bf16 v[20:23], v[132:135], v[180:183], v[20:23]
	v_mfma_f32_16x16x32_bf16 v[20:23], v[136:139], v[184:187], v[20:23]
	v_mfma_f32_16x16x32_bf16 v[24:27], v[144:147], v[184:187], v[24:27]
	v_mfma_f32_16x16x32_bf16 v[24:27], v[140:143], v[180:183], v[24:27]
	v_mfma_f32_16x16x32_bf16 v[32:35], v[140:143], v[194:197], v[32:35]
	v_mfma_f32_16x16x32_bf16 v[32:35], v[144:147], v[198:201], v[32:35]
	v_mfma_f32_16x16x32_bf16 v[28:31], v[136:139], v[198:201], v[28:31]
	v_mfma_f32_16x16x32_bf16 v[28:31], v[132:135], v[194:197], v[28:31]
	s_setprio 0
	s_setprio 1
	v_mfma_f32_16x16x32_bf16 v[36:39], v[148:151], v[164:167], v[36:39]
	v_mfma_f32_16x16x32_bf16 v[36:39], v[152:155], v[168:171], v[36:39]
	v_mfma_f32_16x16x32_bf16 v[40:43], v[160:163], v[168:171], v[40:43]
	v_mfma_f32_16x16x32_bf16 v[40:43], v[156:159], v[164:167], v[40:43]
	v_mfma_f32_16x16x32_bf16 v[48:51], v[156:159], v[172:175], v[48:51]
	v_mfma_f32_16x16x32_bf16 v[48:51], v[160:163], v[176:179], v[48:51]
	v_mfma_f32_16x16x32_bf16 v[44:47], v[152:155], v[176:179], v[44:47]
	v_mfma_f32_16x16x32_bf16 v[44:47], v[148:151], v[172:175], v[44:47]
	v_mfma_f32_16x16x32_bf16 v[52:55], v[148:151], v[180:183], v[52:55]
	v_mfma_f32_16x16x32_bf16 v[52:55], v[152:155], v[184:187], v[52:55]
	v_mfma_f32_16x16x32_bf16 v[56:59], v[160:163], v[184:187], v[56:59]
	v_mfma_f32_16x16x32_bf16 v[56:59], v[156:159], v[180:183], v[56:59]
	v_mfma_f32_16x16x32_bf16 v[64:67], v[156:159], v[194:197], v[64:67]
	v_mfma_f32_16x16x32_bf16 v[64:67], v[160:163], v[198:201], v[64:67]
	v_mfma_f32_16x16x32_bf16 v[60:63], v[152:155], v[198:201], v[60:63]
	v_mfma_f32_16x16x32_bf16 v[60:63], v[148:151], v[194:197], v[60:63]
	s_setprio 0
	s_barrier
	s_add_i32 s29, s29, s56
	s_mov_b32 m0, s29
	ds_read_b128 v[164:167], v210 offset:16384
	ds_read_b128 v[168:171], v210 offset:17408
	ds_read_b128 v[172:175], v210 offset:18432
	ds_read_b128 v[176:179], v210 offset:19456
	ds_read_b128 v[180:183], v210 offset:20480
	ds_read_b128 v[184:187], v210 offset:21504
	ds_read_b128 v[194:197], v210 offset:22528
	ds_read_b128 v[198:201], v210 offset:23552
	global_load_lds_dwordx4 v192, s[12:13]
	s_add_i32 m0, s29, 0x2000
	s_add_u32 s42, s12, 0x80000
	s_addc_u32 s43, s13, 0
	s_add_i32 s29, s51, s56
	global_load_lds_dwordx4 v190, s[12:13]
	s_mov_b32 m0, s29
	v_mov_b32_e32 v193, v3
	global_load_lds_dwordx4 v192, s[42:43]
	s_add_i32 m0, s29, 0x2000
	v_mov_b32_e32 v191, v3
	global_load_lds_dwordx4 v190, s[42:43]
	s_mov_b32 m0, s57
	v_lshl_add_u64 v[202:203], s[12:13], 0, v[192:193]
	global_load_lds_dwordx4 v2, s[16:17]
	s_mov_b32 m0, s58
	v_lshl_add_u64 v[204:205], s[12:13], 0, v[190:191]
	global_load_lds_dwordx4 v188, s[16:17]
	s_waitcnt vmcnt(8)
	s_waitcnt lgkmcnt(0)
	v_lshl_add_u64 v[206:207], s[16:17], 0, v[2:3]
	v_lshl_add_u64 v[208:209], s[16:17], 0, v[188:189]
	s_barrier
	s_setprio 1
	s_waitcnt lgkmcnt(0)
	v_mfma_f32_16x16x32_bf16 v[68:71], v[132:135], v[164:167], v[68:71]
	v_mfma_f32_16x16x32_bf16 v[68:71], v[136:139], v[168:171], v[68:71]
	v_mfma_f32_16x16x32_bf16 v[72:75], v[144:147], v[168:171], v[72:75]
	v_mfma_f32_16x16x32_bf16 v[72:75], v[140:143], v[164:167], v[72:75]
	v_mfma_f32_16x16x32_bf16 v[80:83], v[140:143], v[172:175], v[80:83]
	v_mfma_f32_16x16x32_bf16 v[80:83], v[144:147], v[176:179], v[80:83]
	v_mfma_f32_16x16x32_bf16 v[76:79], v[136:139], v[176:179], v[76:79]
	v_mfma_f32_16x16x32_bf16 v[76:79], v[132:135], v[172:175], v[76:79]
	v_mfma_f32_16x16x32_bf16 v[84:87], v[132:135], v[180:183], v[84:87]
	v_mfma_f32_16x16x32_bf16 v[84:87], v[136:139], v[184:187], v[84:87]
	v_mfma_f32_16x16x32_bf16 v[88:91], v[144:147], v[184:187], v[88:91]
	v_mfma_f32_16x16x32_bf16 v[88:91], v[140:143], v[180:183], v[88:91]
	v_mfma_f32_16x16x32_bf16 v[96:99], v[140:143], v[194:197], v[96:99]
	v_mfma_f32_16x16x32_bf16 v[96:99], v[144:147], v[198:201], v[96:99]
	v_mfma_f32_16x16x32_bf16 v[92:95], v[136:139], v[198:201], v[92:95]
	v_mfma_f32_16x16x32_bf16 v[92:95], v[132:135], v[194:197], v[92:95]
	s_setprio 0
	s_setprio 1
	v_mfma_f32_16x16x32_bf16 v[100:103], v[148:151], v[164:167], v[100:103]
	v_mfma_f32_16x16x32_bf16 v[100:103], v[152:155], v[168:171], v[100:103]
	v_mfma_f32_16x16x32_bf16 v[104:107], v[160:163], v[168:171], v[104:107]
	v_mfma_f32_16x16x32_bf16 v[104:107], v[156:159], v[164:167], v[104:107]
	v_mfma_f32_16x16x32_bf16 v[112:115], v[156:159], v[172:175], v[112:115]
	v_mfma_f32_16x16x32_bf16 v[112:115], v[160:163], v[176:179], v[112:115]
	v_mfma_f32_16x16x32_bf16 v[108:111], v[152:155], v[176:179], v[108:111]
	v_mfma_f32_16x16x32_bf16 v[108:111], v[148:151], v[172:175], v[108:111]
	v_mfma_f32_16x16x32_bf16 v[116:119], v[148:151], v[180:183], v[116:119]
	v_mfma_f32_16x16x32_bf16 v[116:119], v[152:155], v[184:187], v[116:119]
	v_mfma_f32_16x16x32_bf16 v[120:123], v[160:163], v[184:187], v[120:123]
	v_mfma_f32_16x16x32_bf16 v[120:123], v[156:159], v[180:183], v[120:123]
	v_mfma_f32_16x16x32_bf16 v[128:131], v[156:159], v[194:197], v[128:131]
	v_mfma_f32_16x16x32_bf16 v[128:131], v[160:163], v[198:201], v[128:131]
	v_mfma_f32_16x16x32_bf16 v[124:127], v[152:155], v[198:201], v[124:127]
	v_mfma_f32_16x16x32_bf16 v[124:127], v[148:151], v[194:197], v[124:127]
	s_setprio 0
	s_barrier
	s_add_i32 s29, 0, 0x18000
	s_add_i32 s42, 0, 0x1c000
	v_add_u32_e32 v144, s29, v232
	v_add_u32_e32 v160, s42, v232
	ds_read_b128 v[132:135], v144
	ds_read_b128 v[136:139], v144 offset:1024
	ds_read_b128 v[140:143], v144 offset:2048
	ds_read_b128 v[144:147], v144 offset:3072
	ds_read_b128 v[148:151], v160
	ds_read_b128 v[152:155], v160 offset:1024
	ds_read_b128 v[156:159], v160 offset:2048
	ds_read_b128 v[160:163], v160 offset:3072
	s_add_u32 s16, s16, 0x80000
	s_addc_u32 s17, s17, 0
	s_mov_b32 m0, s59
	ds_read_b128 v[164:167], v210 offset:32768
	ds_read_b128 v[168:171], v210 offset:33792
	ds_read_b128 v[172:175], v210 offset:34816
	ds_read_b128 v[176:179], v210 offset:35840
	ds_read_b128 v[180:183], v210 offset:36864
	ds_read_b128 v[184:187], v210 offset:37888
	ds_read_b128 v[194:197], v210 offset:38912
	ds_read_b128 v[198:201], v210 offset:39936
	global_load_lds_dwordx4 v2, s[16:17]
	s_mov_b32 m0, s60
	s_nop 0
	global_load_lds_dwordx4 v188, s[16:17]
	s_waitcnt vmcnt(8)
	s_waitcnt lgkmcnt(0)
	s_barrier
	s_setprio 1
	s_waitcnt lgkmcnt(0)
	v_mfma_f32_16x16x32_bf16 v[4:7], v[132:135], v[164:167], v[4:7]
	v_mfma_f32_16x16x32_bf16 v[4:7], v[136:139], v[168:171], v[4:7]
	v_mfma_f32_16x16x32_bf16 v[8:11], v[144:147], v[168:171], v[8:11]
	v_mfma_f32_16x16x32_bf16 v[8:11], v[140:143], v[164:167], v[8:11]
	v_mfma_f32_16x16x32_bf16 v[16:19], v[140:143], v[172:175], v[16:19]
	v_mfma_f32_16x16x32_bf16 v[16:19], v[144:147], v[176:179], v[16:19]
	v_mfma_f32_16x16x32_bf16 v[12:15], v[136:139], v[176:179], v[12:15]
	v_mfma_f32_16x16x32_bf16 v[12:15], v[132:135], v[172:175], v[12:15]
	v_mfma_f32_16x16x32_bf16 v[20:23], v[132:135], v[180:183], v[20:23]
	v_mfma_f32_16x16x32_bf16 v[20:23], v[136:139], v[184:187], v[20:23]
	v_mfma_f32_16x16x32_bf16 v[24:27], v[144:147], v[184:187], v[24:27]
	v_mfma_f32_16x16x32_bf16 v[24:27], v[140:143], v[180:183], v[24:27]
	v_mfma_f32_16x16x32_bf16 v[32:35], v[140:143], v[194:197], v[32:35]
	v_mfma_f32_16x16x32_bf16 v[32:35], v[144:147], v[198:201], v[32:35]
	v_mfma_f32_16x16x32_bf16 v[28:31], v[136:139], v[198:201], v[28:31]
	v_mfma_f32_16x16x32_bf16 v[28:31], v[132:135], v[194:197], v[28:31]
	s_setprio 0
	s_setprio 1
	v_mfma_f32_16x16x32_bf16 v[36:39], v[148:151], v[164:167], v[36:39]
	v_mfma_f32_16x16x32_bf16 v[36:39], v[152:155], v[168:171], v[36:39]
	v_mfma_f32_16x16x32_bf16 v[40:43], v[160:163], v[168:171], v[40:43]
	v_mfma_f32_16x16x32_bf16 v[40:43], v[156:159], v[164:167], v[40:43]
	v_mfma_f32_16x16x32_bf16 v[48:51], v[156:159], v[172:175], v[48:51]
	v_mfma_f32_16x16x32_bf16 v[48:51], v[160:163], v[176:179], v[48:51]
	v_mfma_f32_16x16x32_bf16 v[44:47], v[152:155], v[176:179], v[44:47]
	v_mfma_f32_16x16x32_bf16 v[44:47], v[148:151], v[172:175], v[44:47]
	v_mfma_f32_16x16x32_bf16 v[52:55], v[148:151], v[180:183], v[52:55]
	v_mfma_f32_16x16x32_bf16 v[52:55], v[152:155], v[184:187], v[52:55]
	v_mfma_f32_16x16x32_bf16 v[56:59], v[160:163], v[184:187], v[56:59]
	v_mfma_f32_16x16x32_bf16 v[56:59], v[156:159], v[180:183], v[56:59]
	v_mfma_f32_16x16x32_bf16 v[64:67], v[156:159], v[194:197], v[64:67]
	v_mfma_f32_16x16x32_bf16 v[64:67], v[160:163], v[198:201], v[64:67]
	v_mfma_f32_16x16x32_bf16 v[60:63], v[152:155], v[198:201], v[60:63]
	v_mfma_f32_16x16x32_bf16 v[60:63], v[148:151], v[194:197], v[60:63]
	s_setprio 0
	s_barrier
	s_add_i32 s16, s29, s56
	v_lshl_add_u64 v[202:203], v[202:203], 0, s[86:87]
	s_mov_b32 m0, s16
	ds_read_b128 v[164:167], v210 offset:49152
	ds_read_b128 v[168:171], v210 offset:50176
	ds_read_b128 v[172:175], v210 offset:51200
	ds_read_b128 v[176:179], v210 offset:52224
	ds_read_b128 v[180:183], v210 offset:53248
	ds_read_b128 v[184:187], v210 offset:54272
	ds_read_b128 v[194:197], v210 offset:55296
	ds_read_b128 v[198:201], v210 offset:56320
	global_load_lds_dwordx4 v[202:203], off
	s_add_i32 m0, s16, 0x2000
	s_add_u32 s12, s12, 0x80080
	v_lshl_add_u64 v[202:203], v[204:205], 0, s[86:87]
	s_addc_u32 s13, s13, 0
	s_add_i32 s16, s42, s56
	global_load_lds_dwordx4 v[202:203], off
	s_mov_b32 m0, s16
	v_lshl_add_u64 v[202:203], v[206:207], 0, s[86:87]
	global_load_lds_dwordx4 v192, s[12:13]
	s_add_i32 m0, s16, 0x2000
	s_nop 0
	global_load_lds_dwordx4 v190, s[12:13]
	s_mov_b32 m0, s64
	s_nop 0
	global_load_lds_dwordx4 v[202:203], off
	v_lshl_add_u64 v[202:203], v[208:209], 0, s[86:87]
	s_mov_b32 m0, s65
	s_nop 0
	global_load_lds_dwordx4 v[202:203], off
	s_waitcnt vmcnt(8)
	s_waitcnt lgkmcnt(0)
	s_barrier
	s_setprio 1
	s_waitcnt lgkmcnt(0)
	v_mfma_f32_16x16x32_bf16 v[68:71], v[132:135], v[164:167], v[68:71]
	v_mfma_f32_16x16x32_bf16 v[68:71], v[136:139], v[168:171], v[68:71]
	v_mfma_f32_16x16x32_bf16 v[72:75], v[144:147], v[168:171], v[72:75]
	v_mfma_f32_16x16x32_bf16 v[72:75], v[140:143], v[164:167], v[72:75]
	v_mfma_f32_16x16x32_bf16 v[80:83], v[140:143], v[172:175], v[80:83]
	v_mfma_f32_16x16x32_bf16 v[80:83], v[144:147], v[176:179], v[80:83]
	v_mfma_f32_16x16x32_bf16 v[76:79], v[136:139], v[176:179], v[76:79]
	v_mfma_f32_16x16x32_bf16 v[76:79], v[132:135], v[172:175], v[76:79]
	v_mfma_f32_16x16x32_bf16 v[84:87], v[132:135], v[180:183], v[84:87]
	v_mfma_f32_16x16x32_bf16 v[84:87], v[136:139], v[184:187], v[84:87]
	v_mfma_f32_16x16x32_bf16 v[88:91], v[144:147], v[184:187], v[88:91]
	v_mfma_f32_16x16x32_bf16 v[88:91], v[140:143], v[180:183], v[88:91]
	v_mfma_f32_16x16x32_bf16 v[96:99], v[140:143], v[194:197], v[96:99]
	v_mfma_f32_16x16x32_bf16 v[96:99], v[144:147], v[198:201], v[96:99]
	v_mfma_f32_16x16x32_bf16 v[92:95], v[136:139], v[198:201], v[92:95]
	v_mfma_f32_16x16x32_bf16 v[92:95], v[132:135], v[194:197], v[92:95]
	s_setprio 0
	s_setprio 1
	v_mfma_f32_16x16x32_bf16 v[100:103], v[148:151], v[164:167], v[100:103]
	v_mfma_f32_16x16x32_bf16 v[100:103], v[152:155], v[168:171], v[100:103]
	v_mfma_f32_16x16x32_bf16 v[104:107], v[160:163], v[168:171], v[104:107]
	v_mfma_f32_16x16x32_bf16 v[104:107], v[156:159], v[164:167], v[104:107]
	v_mfma_f32_16x16x32_bf16 v[112:115], v[156:159], v[172:175], v[112:115]
	v_mfma_f32_16x16x32_bf16 v[112:115], v[160:163], v[176:179], v[112:115]
	v_mfma_f32_16x16x32_bf16 v[108:111], v[152:155], v[176:179], v[108:111]
	v_mfma_f32_16x16x32_bf16 v[108:111], v[148:151], v[172:175], v[108:111]
	v_mfma_f32_16x16x32_bf16 v[116:119], v[148:151], v[180:183], v[116:119]
	v_mfma_f32_16x16x32_bf16 v[116:119], v[152:155], v[184:187], v[116:119]
	v_mfma_f32_16x16x32_bf16 v[120:123], v[160:163], v[184:187], v[120:123]
	v_mfma_f32_16x16x32_bf16 v[120:123], v[156:159], v[180:183], v[120:123]
	v_mfma_f32_16x16x32_bf16 v[128:131], v[156:159], v[194:197], v[128:131]
	v_mfma_f32_16x16x32_bf16 v[128:131], v[160:163], v[198:201], v[128:131]
	v_mfma_f32_16x16x32_bf16 v[124:127], v[152:155], v[198:201], v[124:127]
	v_mfma_f32_16x16x32_bf16 v[124:127], v[148:151], v[194:197], v[124:127]
	s_setprio 0
	s_barrier
	s_add_i32 s28, s28, 2
	s_add_u32 s14, s14, 0x100
	s_addc_u32 s15, s15, 0
	s_add_u32 s26, s26, 0x100
	s_addc_u32 s27, s27, 0
	s_cmp_gt_u32 s28, 29
	s_cbranch_scc0 .LBB0_1629
	s_and_b64 vcc, exec, s[48:49]
	s_cbranch_vccz .LBB0_1632
	s_barrier

.LBB0_2065:
	s_add_i32 s51, 0, 0x10000
	s_add_i32 s71, 0, 0x14000
	v_add_u32_e32 v16, s51, v232
	v_add_u32_e32 v32, s71, v232
	ds_read_b128 v[4:7], v16
	ds_read_b128 v[8:11], v16 offset:1024
	ds_read_b128 v[12:15], v16 offset:2048
	ds_read_b128 v[16:19], v16 offset:3072
	ds_read_b128 v[20:23], v32
	ds_read_b128 v[24:27], v32 offset:1024
	ds_read_b128 v[28:31], v32 offset:2048
	ds_read_b128 v[32:35], v32 offset:3072
	v_add_u32_e32 v233, 0, v231
	ds_read_b128 v[36:39], v233
	ds_read_b128 v[40:43], v233 offset:1024
	ds_read_b128 v[44:47], v233 offset:2048
	ds_read_b128 v[48:51], v233 offset:3072
	ds_read_b128 v[52:55], v233 offset:4096
	ds_read_b128 v[56:59], v233 offset:5120
	ds_read_b128 v[60:63], v233 offset:6144
	ds_read_b128 v[64:67], v233 offset:7168
	s_waitcnt vmcnt(8)
	s_waitcnt lgkmcnt(0)
	s_barrier
	s_setprio 1
	s_waitcnt lgkmcnt(0)
	v_mfma_f32_16x16x32_bf16 v[68:71], v[4:7], v[36:39], 0
	v_mfma_f32_16x16x32_bf16 v[68:71], v[8:11], v[40:43], v[68:71]
	v_mfma_f32_16x16x32_bf16 v[72:75], v[12:15], v[36:39], 0
	v_mfma_f32_16x16x32_bf16 v[72:75], v[16:19], v[40:43], v[72:75]
	v_mfma_f32_16x16x32_bf16 v[80:83], v[12:15], v[44:47], 0
	v_mfma_f32_16x16x32_bf16 v[80:83], v[16:19], v[48:51], v[80:83]
	v_mfma_f32_16x16x32_bf16 v[76:79], v[4:7], v[44:47], 0
	v_mfma_f32_16x16x32_bf16 v[76:79], v[8:11], v[48:51], v[76:79]
	v_mfma_f32_16x16x32_bf16 v[84:87], v[4:7], v[52:55], 0
	v_mfma_f32_16x16x32_bf16 v[84:87], v[8:11], v[56:59], v[84:87]
	v_mfma_f32_16x16x32_bf16 v[88:91], v[12:15], v[52:55], 0
	v_mfma_f32_16x16x32_bf16 v[88:91], v[16:19], v[56:59], v[88:91]
	v_mfma_f32_16x16x32_bf16 v[96:99], v[12:15], v[60:63], 0
	v_mfma_f32_16x16x32_bf16 v[96:99], v[16:19], v[64:67], v[96:99]
	v_mfma_f32_16x16x32_bf16 v[92:95], v[4:7], v[60:63], 0
	v_mfma_f32_16x16x32_bf16 v[92:95], v[8:11], v[64:67], v[92:95]
	s_setprio 0
	s_setprio 1
	v_mfma_f32_16x16x32_bf16 v[100:103], v[20:23], v[36:39], 0
	v_mfma_f32_16x16x32_bf16 v[36:39], v[28:31], v[36:39], 0
	v_mfma_f32_16x16x32_bf16 v[104:107], v[20:23], v[44:47], 0
	v_mfma_f32_16x16x32_bf16 v[44:47], v[28:31], v[44:47], 0
	v_mfma_f32_16x16x32_bf16 v[108:111], v[20:23], v[52:55], 0
	v_mfma_f32_16x16x32_bf16 v[52:55], v[28:31], v[52:55], 0
	v_mfma_f32_16x16x32_bf16 v[112:115], v[20:23], v[60:63], 0
	v_mfma_f32_16x16x32_bf16 v[60:63], v[28:31], v[60:63], 0
	v_mfma_f32_16x16x32_bf16 v[100:103], v[24:27], v[40:43], v[100:103]
	v_mfma_f32_16x16x32_bf16 v[40:43], v[32:35], v[40:43], v[36:39]
	v_mfma_f32_16x16x32_bf16 v[104:107], v[24:27], v[48:51], v[104:107]
	v_mfma_f32_16x16x32_bf16 v[48:51], v[32:35], v[48:51], v[44:47]
	v_mfma_f32_16x16x32_bf16 v[108:111], v[24:27], v[56:59], v[108:111]
	v_mfma_f32_16x16x32_bf16 v[56:59], v[32:35], v[56:59], v[52:55]
	v_mfma_f32_16x16x32_bf16 v[112:115], v[24:27], v[64:67], v[112:115]
	v_mfma_f32_16x16x32_bf16 v[64:67], v[32:35], v[64:67], v[60:63]
	s_setprio 0
	s_barrier
	v_lshl_add_u64 v[186:187], s[12:13], 0, v[2:3]
	s_add_i32 s51, s51, s38
	v_mov_b32_e32 v191, v3
	v_lshl_add_u64 v[134:135], v[186:187], 0, s[74:75]
	s_mov_b32 m0, s51
	v_lshl_add_u64 v[246:247], s[12:13], 0, v[190:191]
	ds_read_b128 v[36:39], v233 offset:16384
	ds_read_b128 v[44:47], v233 offset:17408
	ds_read_b128 v[52:55], v233 offset:18432
	ds_read_b128 v[60:63], v233 offset:19456
	ds_read_b128 v[116:119], v233 offset:20480
	ds_read_b128 v[120:123], v233 offset:21504
	ds_read_b128 v[124:127], v233 offset:22528
	ds_read_b128 v[128:131], v233 offset:23552
	global_load_lds_dwordx4 v[134:135], off
	v_lshl_add_u64 v[134:135], v[246:247], 0, s[74:75]
	s_add_i32 m0, s51, 0x2000
	s_add_i32 s51, s71, s38
	global_load_lds_dwordx4 v[134:135], off
	s_mov_b32 m0, s51
	v_mov_b32_e32 v133, v3
	global_load_lds_dwordx4 v2, s[16:17]
	s_add_i32 m0, s51, 0x2000
	v_lshl_add_u64 v[248:249], s[14:15], 0, v[132:133]
	v_mov_b32_e32 v189, v3
	global_load_lds_dwordx4 v190, s[16:17]
	v_lshl_add_u64 v[134:135], v[248:249], 0, s[74:75]
	s_mov_b32 m0, s56
	v_lshl_add_u64 v[250:251], s[14:15], 0, v[188:189]
	global_load_lds_dwordx4 v[134:135], off
	v_lshl_add_u64 v[134:135], v[250:251], 0, s[74:75]
	s_mov_b32 m0, s57
	s_nop 0
	global_load_lds_dwordx4 v[134:135], off
	s_waitcnt vmcnt(8)
	s_waitcnt lgkmcnt(0)
	s_barrier
	s_setprio 1
	s_waitcnt lgkmcnt(0)
	v_mfma_f32_16x16x32_bf16 v[134:137], v[4:7], v[36:39], 0
	v_mfma_f32_16x16x32_bf16 v[138:141], v[12:15], v[36:39], 0
	v_mfma_f32_16x16x32_bf16 v[142:145], v[4:7], v[52:55], 0
	v_mfma_f32_16x16x32_bf16 v[146:149], v[12:15], v[52:55], 0
	v_mfma_f32_16x16x32_bf16 v[150:153], v[4:7], v[116:119], 0
	v_mfma_f32_16x16x32_bf16 v[154:157], v[12:15], v[116:119], 0
	v_mfma_f32_16x16x32_bf16 v[4:7], v[4:7], v[124:127], 0
	v_mfma_f32_16x16x32_bf16 v[12:15], v[12:15], v[124:127], 0
	v_mfma_f32_16x16x32_bf16 v[134:137], v[8:11], v[44:47], v[134:137]
	v_mfma_f32_16x16x32_bf16 v[138:141], v[16:19], v[44:47], v[138:141]
	v_mfma_f32_16x16x32_bf16 v[142:145], v[8:11], v[60:63], v[142:145]
	v_mfma_f32_16x16x32_bf16 v[146:149], v[16:19], v[60:63], v[146:149]
	v_mfma_f32_16x16x32_bf16 v[150:153], v[8:11], v[120:123], v[150:153]
	v_mfma_f32_16x16x32_bf16 v[154:157], v[16:19], v[120:123], v[154:157]
	v_mfma_f32_16x16x32_bf16 v[158:161], v[8:11], v[128:131], v[4:7]
	v_mfma_f32_16x16x32_bf16 v[162:165], v[16:19], v[128:131], v[12:15]
	s_setprio 0
	s_setprio 1
	v_mfma_f32_16x16x32_bf16 v[4:7], v[20:23], v[36:39], 0
	v_mfma_f32_16x16x32_bf16 v[8:11], v[28:31], v[36:39], 0
	v_mfma_f32_16x16x32_bf16 v[12:15], v[20:23], v[52:55], 0
	v_mfma_f32_16x16x32_bf16 v[16:19], v[28:31], v[52:55], 0
	v_mfma_f32_16x16x32_bf16 v[36:39], v[20:23], v[116:119], 0
	v_mfma_f32_16x16x32_bf16 v[52:55], v[28:31], v[116:119], 0
	v_mfma_f32_16x16x32_bf16 v[20:23], v[20:23], v[124:127], 0
	v_mfma_f32_16x16x32_bf16 v[28:31], v[28:31], v[124:127], 0
	v_mfma_f32_16x16x32_bf16 v[116:119], v[24:27], v[44:47], v[4:7]
	v_mfma_f32_16x16x32_bf16 v[124:127], v[32:35], v[44:47], v[8:11]
	v_mfma_f32_16x16x32_bf16 v[174:177], v[24:27], v[120:123], v[36:39]
	v_mfma_f32_16x16x32_bf16 v[120:123], v[32:35], v[120:123], v[52:55]
	v_mfma_f32_16x16x32_bf16 v[178:181], v[24:27], v[128:131], v[20:23]
	v_mfma_f32_16x16x32_bf16 v[128:131], v[32:35], v[128:131], v[28:31]
	v_mfma_f32_16x16x32_bf16 v[166:169], v[24:27], v[60:63], v[12:15]
	v_mfma_f32_16x16x32_bf16 v[170:173], v[32:35], v[60:63], v[16:19]
	s_setprio 0
	s_barrier
	s_add_i32 s51, 0, 0x18000
	v_add_u32_e32 v4, s51, v232
	s_add_i32 s71, 0, 0x1c000
	ds_read_b128 v[182:185], v4
	ds_read_b128 v[192:195], v4 offset:1024
	ds_read_b128 v[196:199], v4 offset:2048
	ds_read_b128 v[200:203], v4 offset:3072
	v_add_u32_e32 v4, s71, v232
	ds_read_b128 v[204:207], v4
	ds_read_b128 v[208:211], v4 offset:1024
	ds_read_b128 v[212:215], v4 offset:2048
	ds_read_b128 v[216:219], v4 offset:3072
	s_mov_b32 m0, s58
	ds_read_b128 v[44:47], v233 offset:32768
	ds_read_b128 v[52:55], v233 offset:33792
	ds_read_b128 v[60:63], v233 offset:34816
	ds_read_b128 v[220:223], v233 offset:35840
	ds_read_b128 v[224:227], v233 offset:36864
	ds_read_b128 v[234:237], v233 offset:37888
	ds_read_b128 v[238:241], v233 offset:38912
	ds_read_b128 v[242:245], v233 offset:39936
	global_load_lds_dwordx4 v132, s[26:27]
	s_mov_b32 m0, s59
	s_nop 0
	global_load_lds_dwordx4 v188, s[26:27]
	s_waitcnt vmcnt(8)
	s_waitcnt lgkmcnt(0)
	s_barrier
	s_setprio 1
	s_waitcnt lgkmcnt(0)
	v_mfma_f32_16x16x32_bf16 v[4:7], v[182:185], v[44:47], v[68:71]
	v_mfma_f32_16x16x32_bf16 v[8:11], v[196:199], v[44:47], v[72:75]
	v_mfma_f32_16x16x32_bf16 v[12:15], v[182:185], v[60:63], v[76:79]
	v_mfma_f32_16x16x32_bf16 v[16:19], v[196:199], v[60:63], v[80:83]
	v_mfma_f32_16x16x32_bf16 v[20:23], v[182:185], v[224:227], v[84:87]
	v_mfma_f32_16x16x32_bf16 v[24:27], v[196:199], v[224:227], v[88:91]
	v_mfma_f32_16x16x32_bf16 v[28:31], v[182:185], v[238:241], v[92:95]
	v_mfma_f32_16x16x32_bf16 v[32:35], v[196:199], v[238:241], v[96:99]
	v_mfma_f32_16x16x32_bf16 v[4:7], v[192:195], v[52:55], v[4:7]
	v_mfma_f32_16x16x32_bf16 v[8:11], v[200:203], v[52:55], v[8:11]
	v_mfma_f32_16x16x32_bf16 v[12:15], v[192:195], v[220:223], v[12:15]
	v_mfma_f32_16x16x32_bf16 v[16:19], v[200:203], v[220:223], v[16:19]
	v_mfma_f32_16x16x32_bf16 v[20:23], v[192:195], v[234:237], v[20:23]
	v_mfma_f32_16x16x32_bf16 v[24:27], v[200:203], v[234:237], v[24:27]
	v_mfma_f32_16x16x32_bf16 v[28:31], v[192:195], v[242:245], v[28:31]
	v_mfma_f32_16x16x32_bf16 v[32:35], v[200:203], v[242:245], v[32:35]
	s_setprio 0
	s_setprio 1
	v_mfma_f32_16x16x32_bf16 v[36:39], v[204:207], v[44:47], v[100:103]
	v_mfma_f32_16x16x32_bf16 v[40:43], v[212:215], v[44:47], v[40:43]
	v_mfma_f32_16x16x32_bf16 v[36:39], v[208:211], v[52:55], v[36:39]
	v_mfma_f32_16x16x32_bf16 v[40:43], v[216:219], v[52:55], v[40:43]
	v_mfma_f32_16x16x32_bf16 v[44:47], v[204:207], v[60:63], v[104:107]
	v_mfma_f32_16x16x32_bf16 v[48:51], v[212:215], v[60:63], v[48:51]
	v_mfma_f32_16x16x32_bf16 v[52:55], v[204:207], v[224:227], v[108:111]
	v_mfma_f32_16x16x32_bf16 v[56:59], v[212:215], v[224:227], v[56:59]
	v_mfma_f32_16x16x32_bf16 v[60:63], v[204:207], v[238:241], v[112:115]
	v_mfma_f32_16x16x32_bf16 v[64:67], v[212:215], v[238:241], v[64:67]
	v_mfma_f32_16x16x32_bf16 v[44:47], v[208:211], v[220:223], v[44:47]
	v_mfma_f32_16x16x32_bf16 v[48:51], v[216:219], v[220:223], v[48:51]
	v_mfma_f32_16x16x32_bf16 v[52:55], v[208:211], v[234:237], v[52:55]
	v_mfma_f32_16x16x32_bf16 v[56:59], v[216:219], v[234:237], v[56:59]
	v_mfma_f32_16x16x32_bf16 v[60:63], v[208:211], v[242:245], v[60:63]
	v_mfma_f32_16x16x32_bf16 v[64:67], v[216:219], v[242:245], v[64:67]
	s_setprio 0
	s_barrier
	s_add_i32 s51, s51, s38
	v_lshl_add_u64 v[68:69], v[186:187], 0, s[24:25]
	s_mov_b32 m0, s51
	ds_read_b128 v[104:107], v233 offset:49152
	ds_read_b128 v[108:111], v233 offset:50176
	ds_read_b128 v[112:115], v233 offset:51200
	ds_read_b128 v[220:223], v233 offset:52224
	ds_read_b128 v[224:227], v233 offset:53248
	ds_read_b128 v[234:237], v233 offset:54272
	ds_read_b128 v[238:241], v233 offset:55296
	ds_read_b128 v[242:245], v233 offset:56320
	global_load_lds_dwordx4 v[68:69], off
	v_lshl_add_u64 v[68:69], v[246:247], 0, s[24:25]
	s_add_i32 m0, s51, 0x2000
	s_add_i32 s51, s71, s38
	global_load_lds_dwordx4 v[68:69], off
	s_mov_b32 m0, s51
	v_lshl_add_u64 v[68:69], v[248:249], 0, s[24:25]
	global_load_lds_dwordx4 v2, s[28:29]
	s_add_i32 m0, s51, 0x2000
	s_nop 0
	global_load_lds_dwordx4 v190, s[28:29]
	s_mov_b32 m0, s63
	s_nop 0
	global_load_lds_dwordx4 v[68:69], off
	v_lshl_add_u64 v[68:69], v[250:251], 0, s[24:25]
	s_mov_b32 m0, s64
	s_nop 0
	global_load_lds_dwordx4 v[68:69], off
	s_waitcnt vmcnt(8)
	s_waitcnt lgkmcnt(0)
	s_barrier
	s_setprio 1
	s_waitcnt lgkmcnt(0)
	v_mfma_f32_16x16x32_bf16 v[68:71], v[182:185], v[104:107], v[134:137]
	v_mfma_f32_16x16x32_bf16 v[72:75], v[196:199], v[104:107], v[138:141]
	v_mfma_f32_16x16x32_bf16 v[76:79], v[182:185], v[112:115], v[142:145]
	v_mfma_f32_16x16x32_bf16 v[80:83], v[196:199], v[112:115], v[146:149]
	v_mfma_f32_16x16x32_bf16 v[84:87], v[182:185], v[224:227], v[150:153]
	v_mfma_f32_16x16x32_bf16 v[88:91], v[196:199], v[224:227], v[154:157]
	v_mfma_f32_16x16x32_bf16 v[92:95], v[182:185], v[238:241], v[158:161]
	v_mfma_f32_16x16x32_bf16 v[96:99], v[196:199], v[238:241], v[162:165]
	v_mfma_f32_16x16x32_bf16 v[68:71], v[192:195], v[108:111], v[68:71]
	v_mfma_f32_16x16x32_bf16 v[72:75], v[200:203], v[108:111], v[72:75]
	v_mfma_f32_16x16x32_bf16 v[76:79], v[192:195], v[220:223], v[76:79]
	v_mfma_f32_16x16x32_bf16 v[80:83], v[200:203], v[220:223], v[80:83]
	v_mfma_f32_16x16x32_bf16 v[84:87], v[192:195], v[234:237], v[84:87]
	v_mfma_f32_16x16x32_bf16 v[88:91], v[200:203], v[234:237], v[88:91]
	v_mfma_f32_16x16x32_bf16 v[92:95], v[192:195], v[242:245], v[92:95]
	v_mfma_f32_16x16x32_bf16 v[96:99], v[200:203], v[242:245], v[96:99]
	s_setprio 0
	s_setprio 1
	v_mfma_f32_16x16x32_bf16 v[100:103], v[204:207], v[104:107], v[116:119]
	v_mfma_f32_16x16x32_bf16 v[104:107], v[212:215], v[104:107], v[124:127]
	v_mfma_f32_16x16x32_bf16 v[100:103], v[208:211], v[108:111], v[100:103]
	v_mfma_f32_16x16x32_bf16 v[104:107], v[216:219], v[108:111], v[104:107]
	v_mfma_f32_16x16x32_bf16 v[108:111], v[204:207], v[112:115], v[166:169]
	v_mfma_f32_16x16x32_bf16 v[112:115], v[212:215], v[112:115], v[170:173]
	v_mfma_f32_16x16x32_bf16 v[116:119], v[204:207], v[224:227], v[174:177]
	v_mfma_f32_16x16x32_bf16 v[120:123], v[212:215], v[224:227], v[120:123]
	v_mfma_f32_16x16x32_bf16 v[124:127], v[204:207], v[238:241], v[178:181]
	v_mfma_f32_16x16x32_bf16 v[128:131], v[212:215], v[238:241], v[128:131]
	v_mfma_f32_16x16x32_bf16 v[108:111], v[208:211], v[220:223], v[108:111]
	v_mfma_f32_16x16x32_bf16 v[112:115], v[216:219], v[220:223], v[112:115]
	v_mfma_f32_16x16x32_bf16 v[116:119], v[208:211], v[234:237], v[116:119]
	v_mfma_f32_16x16x32_bf16 v[120:123], v[216:219], v[234:237], v[120:123]
	v_mfma_f32_16x16x32_bf16 v[124:127], v[208:211], v[242:245], v[124:127]
	v_mfma_f32_16x16x32_bf16 v[128:131], v[216:219], v[242:245], v[128:131]
	s_setprio 0
	s_barrier
	s_add_i32 s45, s45, 2
	s_cmp_ge_i32 s45, s44
	s_cbranch_scc0 .LBB0_2065
	v_mov_b32_e32 v192, v2
	s_branch .LBB0_2068

.LBB0_2069:
	s_add_u32 s12, s14, 0xfff80080
	s_addc_u32 s13, s15, -1
	s_add_i32 s29, 0, 0x10000
	s_cmp_eq_u32 s28, 4
	s_cselect_b32 s17, s9, s13
	s_cselect_b32 s16, s8, s12
	s_cselect_b32 s13, s11, s27
	s_cselect_b32 s12, s10, s26
	s_add_i32 s51, 0, 0x14000
	v_add_u32_e32 v144, s29, v232
	v_add_u32_e32 v160, s51, v232
	s_waitcnt lgkmcnt(0)
	ds_read_b128 v[132:135], v144
	ds_read_b128 v[136:139], v144 offset:1024
	ds_read_b128 v[140:143], v144 offset:2048
	ds_read_b128 v[144:147], v144 offset:3072
	ds_read_b128 v[148:151], v160
	ds_read_b128 v[152:155], v160 offset:1024
	ds_read_b128 v[156:159], v160 offset:2048
	ds_read_b128 v[160:163], v160 offset:3072
	s_mov_b32 m0, s65
	v_add_u32_e32 v210, 0, v231
	ds_read_b128 v[164:167], v210
	ds_read_b128 v[168:171], v210 offset:1024
	ds_read_b128 v[172:175], v210 offset:2048
	ds_read_b128 v[176:179], v210 offset:3072
	ds_read_b128 v[180:183], v210 offset:4096
	ds_read_b128 v[184:187], v210 offset:5120
	ds_read_b128 v[194:197], v210 offset:6144
	ds_read_b128 v[198:201], v210 offset:7168
	global_load_lds_dwordx4 v2, s[14:15]
	s_mov_b32 m0, s66
	v_mov_b32_e32 v189, v3
	global_load_lds_dwordx4 v188, s[14:15]
	s_waitcnt vmcnt(8)
	s_waitcnt lgkmcnt(0)
	s_barrier
	s_setprio 1
	s_waitcnt lgkmcnt(0)
	v_mfma_f32_16x16x32_bf16 v[4:7], v[132:135], v[164:167], v[4:7]
	v_mfma_f32_16x16x32_bf16 v[4:7], v[136:139], v[168:171], v[4:7]
	v_mfma_f32_16x16x32_bf16 v[8:11], v[144:147], v[168:171], v[8:11]
	v_mfma_f32_16x16x32_bf16 v[8:11], v[140:143], v[164:167], v[8:11]
	v_mfma_f32_16x16x32_bf16 v[16:19], v[140:143], v[172:175], v[16:19]
	v_mfma_f32_16x16x32_bf16 v[16:19], v[144:147], v[176:179], v[16:19]
	v_mfma_f32_16x16x32_bf16 v[12:15], v[136:139], v[176:179], v[12:15]
	v_mfma_f32_16x16x32_bf16 v[12:15], v[132:135], v[172:175], v[12:15]
	v_mfma_f32_16x16x32_bf16 v[20:23], v[132:135], v[180:183], v[20:23]
	v_mfma_f32_16x16x32_bf16 v[20:23], v[136:139], v[184:187], v[20:23]
	v_mfma_f32_16x16x32_bf16 v[24:27], v[144:147], v[184:187], v[24:27]
	v_mfma_f32_16x16x32_bf16 v[24:27], v[140:143], v[180:183], v[24:27]
	v_mfma_f32_16x16x32_bf16 v[32:35], v[140:143], v[194:197], v[32:35]
	v_mfma_f32_16x16x32_bf16 v[32:35], v[144:147], v[198:201], v[32:35]
	v_mfma_f32_16x16x32_bf16 v[28:31], v[136:139], v[198:201], v[28:31]
	v_mfma_f32_16x16x32_bf16 v[28:31], v[132:135], v[194:197], v[28:31]
	s_setprio 0
	s_setprio 1
	v_mfma_f32_16x16x32_bf16 v[36:39], v[148:151], v[164:167], v[36:39]
	v_mfma_f32_16x16x32_bf16 v[36:39], v[152:155], v[168:171], v[36:39]
	v_mfma_f32_16x16x32_bf16 v[40:43], v[160:163], v[168:171], v[40:43]
	v_mfma_f32_16x16x32_bf16 v[40:43], v[156:159], v[164:167], v[40:43]
	v_mfma_f32_16x16x32_bf16 v[48:51], v[156:159], v[172:175], v[48:51]
	v_mfma_f32_16x16x32_bf16 v[48:51], v[160:163], v[176:179], v[48:51]
	v_mfma_f32_16x16x32_bf16 v[44:47], v[152:155], v[176:179], v[44:47]
	v_mfma_f32_16x16x32_bf16 v[44:47], v[148:151], v[172:175], v[44:47]
	v_mfma_f32_16x16x32_bf16 v[52:55], v[148:151], v[180:183], v[52:55]
	v_mfma_f32_16x16x32_bf16 v[52:55], v[152:155], v[184:187], v[52:55]
	v_mfma_f32_16x16x32_bf16 v[56:59], v[160:163], v[184:187], v[56:59]
	v_mfma_f32_16x16x32_bf16 v[56:59], v[156:159], v[180:183], v[56:59]
	v_mfma_f32_16x16x32_bf16 v[64:67], v[156:159], v[194:197], v[64:67]
	v_mfma_f32_16x16x32_bf16 v[64:67], v[160:163], v[198:201], v[64:67]
	v_mfma_f32_16x16x32_bf16 v[60:63], v[152:155], v[198:201], v[60:63]
	v_mfma_f32_16x16x32_bf16 v[60:63], v[148:151], v[194:197], v[60:63]
	s_setprio 0
	s_barrier
	s_add_i32 s29, s29, s38
	s_mov_b32 m0, s29
	ds_read_b128 v[164:167], v210 offset:16384
	ds_read_b128 v[168:171], v210 offset:17408
	ds_read_b128 v[172:175], v210 offset:18432
	ds_read_b128 v[176:179], v210 offset:19456
	ds_read_b128 v[180:183], v210 offset:20480
	ds_read_b128 v[184:187], v210 offset:21504
	ds_read_b128 v[194:197], v210 offset:22528
	ds_read_b128 v[198:201], v210 offset:23552
	global_load_lds_dwordx4 v192, s[12:13]
	s_add_i32 m0, s29, 0x2000
	s_add_u32 s44, s12, 0x20000
	s_addc_u32 s45, s13, 0
	s_add_i32 s29, s51, s38
	global_load_lds_dwordx4 v190, s[12:13]
	s_mov_b32 m0, s29
	v_mov_b32_e32 v193, v3
	global_load_lds_dwordx4 v192, s[44:45]
	s_add_i32 m0, s29, 0x2000
	v_mov_b32_e32 v191, v3
	global_load_lds_dwordx4 v190, s[44:45]
	s_mov_b32 m0, s56
	v_lshl_add_u64 v[202:203], s[12:13], 0, v[192:193]
	global_load_lds_dwordx4 v2, s[16:17]
	s_mov_b32 m0, s57
	v_lshl_add_u64 v[204:205], s[12:13], 0, v[190:191]
	global_load_lds_dwordx4 v188, s[16:17]
	s_waitcnt vmcnt(8)
	s_waitcnt lgkmcnt(0)
	v_lshl_add_u64 v[206:207], s[16:17], 0, v[2:3]
	v_lshl_add_u64 v[208:209], s[16:17], 0, v[188:189]
	s_barrier
	s_setprio 1
	s_waitcnt lgkmcnt(0)
	v_mfma_f32_16x16x32_bf16 v[68:71], v[132:135], v[164:167], v[68:71]
	v_mfma_f32_16x16x32_bf16 v[68:71], v[136:139], v[168:171], v[68:71]
	v_mfma_f32_16x16x32_bf16 v[72:75], v[144:147], v[168:171], v[72:75]
	v_mfma_f32_16x16x32_bf16 v[72:75], v[140:143], v[164:167], v[72:75]
	v_mfma_f32_16x16x32_bf16 v[80:83], v[140:143], v[172:175], v[80:83]
	v_mfma_f32_16x16x32_bf16 v[80:83], v[144:147], v[176:179], v[80:83]
	v_mfma_f32_16x16x32_bf16 v[76:79], v[136:139], v[176:179], v[76:79]
	v_mfma_f32_16x16x32_bf16 v[76:79], v[132:135], v[172:175], v[76:79]
	v_mfma_f32_16x16x32_bf16 v[84:87], v[132:135], v[180:183], v[84:87]
	v_mfma_f32_16x16x32_bf16 v[84:87], v[136:139], v[184:187], v[84:87]
	v_mfma_f32_16x16x32_bf16 v[88:91], v[144:147], v[184:187], v[88:91]
	v_mfma_f32_16x16x32_bf16 v[88:91], v[140:143], v[180:183], v[88:91]
	v_mfma_f32_16x16x32_bf16 v[96:99], v[140:143], v[194:197], v[96:99]
	v_mfma_f32_16x16x32_bf16 v[96:99], v[144:147], v[198:201], v[96:99]
	v_mfma_f32_16x16x32_bf16 v[92:95], v[136:139], v[198:201], v[92:95]
	v_mfma_f32_16x16x32_bf16 v[92:95], v[132:135], v[194:197], v[92:95]
	s_setprio 0
	s_setprio 1
	v_mfma_f32_16x16x32_bf16 v[100:103], v[148:151], v[164:167], v[100:103]
	v_mfma_f32_16x16x32_bf16 v[100:103], v[152:155], v[168:171], v[100:103]
	v_mfma_f32_16x16x32_bf16 v[104:107], v[160:163], v[168:171], v[104:107]
	v_mfma_f32_16x16x32_bf16 v[104:107], v[156:159], v[164:167], v[104:107]
	v_mfma_f32_16x16x32_bf16 v[112:115], v[156:159], v[172:175], v[112:115]
	v_mfma_f32_16x16x32_bf16 v[112:115], v[160:163], v[176:179], v[112:115]
	v_mfma_f32_16x16x32_bf16 v[108:111], v[152:155], v[176:179], v[108:111]
	v_mfma_f32_16x16x32_bf16 v[108:111], v[148:151], v[172:175], v[108:111]
	v_mfma_f32_16x16x32_bf16 v[116:119], v[148:151], v[180:183], v[116:119]
	v_mfma_f32_16x16x32_bf16 v[116:119], v[152:155], v[184:187], v[116:119]
	v_mfma_f32_16x16x32_bf16 v[120:123], v[160:163], v[184:187], v[120:123]
	v_mfma_f32_16x16x32_bf16 v[120:123], v[156:159], v[180:183], v[120:123]
	v_mfma_f32_16x16x32_bf16 v[128:131], v[156:159], v[194:197], v[128:131]
	v_mfma_f32_16x16x32_bf16 v[128:131], v[160:163], v[198:201], v[128:131]
	v_mfma_f32_16x16x32_bf16 v[124:127], v[152:155], v[198:201], v[124:127]
	v_mfma_f32_16x16x32_bf16 v[124:127], v[148:151], v[194:197], v[124:127]
	s_setprio 0
	s_barrier
	s_add_i32 s29, 0, 0x18000
	s_add_i32 s44, 0, 0x1c000
	v_add_u32_e32 v144, s29, v232
	v_add_u32_e32 v160, s44, v232
	ds_read_b128 v[132:135], v144
	ds_read_b128 v[136:139], v144 offset:1024
	ds_read_b128 v[140:143], v144 offset:2048
	ds_read_b128 v[144:147], v144 offset:3072
	ds_read_b128 v[148:151], v160
	ds_read_b128 v[152:155], v160 offset:1024
	ds_read_b128 v[156:159], v160 offset:2048
	ds_read_b128 v[160:163], v160 offset:3072
	s_add_u32 s16, s16, 0x80000
	s_addc_u32 s17, s17, 0
	s_mov_b32 m0, s58
	ds_read_b128 v[164:167], v210 offset:32768
	ds_read_b128 v[168:171], v210 offset:33792
	ds_read_b128 v[172:175], v210 offset:34816
	ds_read_b128 v[176:179], v210 offset:35840
	ds_read_b128 v[180:183], v210 offset:36864
	ds_read_b128 v[184:187], v210 offset:37888
	ds_read_b128 v[194:197], v210 offset:38912
	ds_read_b128 v[198:201], v210 offset:39936
	global_load_lds_dwordx4 v2, s[16:17]
	s_mov_b32 m0, s59
	s_nop 0
	global_load_lds_dwordx4 v188, s[16:17]
	s_waitcnt vmcnt(8)
	s_waitcnt lgkmcnt(0)
	s_barrier
	s_setprio 1
	s_waitcnt lgkmcnt(0)
	v_mfma_f32_16x16x32_bf16 v[4:7], v[132:135], v[164:167], v[4:7]
	v_mfma_f32_16x16x32_bf16 v[4:7], v[136:139], v[168:171], v[4:7]
	v_mfma_f32_16x16x32_bf16 v[8:11], v[144:147], v[168:171], v[8:11]
	v_mfma_f32_16x16x32_bf16 v[8:11], v[140:143], v[164:167], v[8:11]
	v_mfma_f32_16x16x32_bf16 v[16:19], v[140:143], v[172:175], v[16:19]
	v_mfma_f32_16x16x32_bf16 v[16:19], v[144:147], v[176:179], v[16:19]
	v_mfma_f32_16x16x32_bf16 v[12:15], v[136:139], v[176:179], v[12:15]
	v_mfma_f32_16x16x32_bf16 v[12:15], v[132:135], v[172:175], v[12:15]
	v_mfma_f32_16x16x32_bf16 v[20:23], v[132:135], v[180:183], v[20:23]
	v_mfma_f32_16x16x32_bf16 v[20:23], v[136:139], v[184:187], v[20:23]
	v_mfma_f32_16x16x32_bf16 v[24:27], v[144:147], v[184:187], v[24:27]
	v_mfma_f32_16x16x32_bf16 v[24:27], v[140:143], v[180:183], v[24:27]
	v_mfma_f32_16x16x32_bf16 v[32:35], v[140:143], v[194:197], v[32:35]
	v_mfma_f32_16x16x32_bf16 v[32:35], v[144:147], v[198:201], v[32:35]
	v_mfma_f32_16x16x32_bf16 v[28:31], v[136:139], v[198:201], v[28:31]
	v_mfma_f32_16x16x32_bf16 v[28:31], v[132:135], v[194:197], v[28:31]
	s_setprio 0
	s_setprio 1
	v_mfma_f32_16x16x32_bf16 v[36:39], v[148:151], v[164:167], v[36:39]
	v_mfma_f32_16x16x32_bf16 v[36:39], v[152:155], v[168:171], v[36:39]
	v_mfma_f32_16x16x32_bf16 v[40:43], v[160:163], v[168:171], v[40:43]
	v_mfma_f32_16x16x32_bf16 v[40:43], v[156:159], v[164:167], v[40:43]
	v_mfma_f32_16x16x32_bf16 v[48:51], v[156:159], v[172:175], v[48:51]
	v_mfma_f32_16x16x32_bf16 v[48:51], v[160:163], v[176:179], v[48:51]
	v_mfma_f32_16x16x32_bf16 v[44:47], v[152:155], v[176:179], v[44:47]
	v_mfma_f32_16x16x32_bf16 v[44:47], v[148:151], v[172:175], v[44:47]
	v_mfma_f32_16x16x32_bf16 v[52:55], v[148:151], v[180:183], v[52:55]
	v_mfma_f32_16x16x32_bf16 v[52:55], v[152:155], v[184:187], v[52:55]
	v_mfma_f32_16x16x32_bf16 v[56:59], v[160:163], v[184:187], v[56:59]
	v_mfma_f32_16x16x32_bf16 v[56:59], v[156:159], v[180:183], v[56:59]
	v_mfma_f32_16x16x32_bf16 v[64:67], v[156:159], v[194:197], v[64:67]
	v_mfma_f32_16x16x32_bf16 v[64:67], v[160:163], v[198:201], v[64:67]
	v_mfma_f32_16x16x32_bf16 v[60:63], v[152:155], v[198:201], v[60:63]
	v_mfma_f32_16x16x32_bf16 v[60:63], v[148:151], v[194:197], v[60:63]
	s_setprio 0
	s_barrier
	s_add_i32 s16, s29, s38
	v_lshl_add_u64 v[202:203], v[202:203], 0, s[86:87]
	s_mov_b32 m0, s16
	ds_read_b128 v[164:167], v210 offset:49152
	ds_read_b128 v[168:171], v210 offset:50176
	ds_read_b128 v[172:175], v210 offset:51200
	ds_read_b128 v[176:179], v210 offset:52224
	ds_read_b128 v[180:183], v210 offset:53248
	ds_read_b128 v[184:187], v210 offset:54272
	ds_read_b128 v[194:197], v210 offset:55296
	ds_read_b128 v[198:201], v210 offset:56320
	global_load_lds_dwordx4 v[202:203], off
	s_add_i32 m0, s16, 0x2000
	s_add_u32 s12, s12, 0x20080
	v_lshl_add_u64 v[202:203], v[204:205], 0, s[86:87]
	s_addc_u32 s13, s13, 0
	s_add_i32 s16, s44, s38
	global_load_lds_dwordx4 v[202:203], off
	s_mov_b32 m0, s16
	v_lshl_add_u64 v[202:203], v[206:207], 0, s[86:87]
	global_load_lds_dwordx4 v192, s[12:13]
	s_add_i32 m0, s16, 0x2000
	s_nop 0
	global_load_lds_dwordx4 v190, s[12:13]
	s_mov_b32 m0, s63
	s_nop 0
	global_load_lds_dwordx4 v[202:203], off
	v_lshl_add_u64 v[202:203], v[208:209], 0, s[86:87]
	s_mov_b32 m0, s64
	s_nop 0
	global_load_lds_dwordx4 v[202:203], off
	s_waitcnt vmcnt(8)
	s_waitcnt lgkmcnt(0)
	s_barrier
	s_setprio 1
	s_waitcnt lgkmcnt(0)
	v_mfma_f32_16x16x32_bf16 v[68:71], v[132:135], v[164:167], v[68:71]
	v_mfma_f32_16x16x32_bf16 v[68:71], v[136:139], v[168:171], v[68:71]
	v_mfma_f32_16x16x32_bf16 v[72:75], v[144:147], v[168:171], v[72:75]
	v_mfma_f32_16x16x32_bf16 v[72:75], v[140:143], v[164:167], v[72:75]
	v_mfma_f32_16x16x32_bf16 v[80:83], v[140:143], v[172:175], v[80:83]
	v_mfma_f32_16x16x32_bf16 v[80:83], v[144:147], v[176:179], v[80:83]
	v_mfma_f32_16x16x32_bf16 v[76:79], v[136:139], v[176:179], v[76:79]
	v_mfma_f32_16x16x32_bf16 v[76:79], v[132:135], v[172:175], v[76:79]
	v_mfma_f32_16x16x32_bf16 v[84:87], v[132:135], v[180:183], v[84:87]
	v_mfma_f32_16x16x32_bf16 v[84:87], v[136:139], v[184:187], v[84:87]
	v_mfma_f32_16x16x32_bf16 v[88:91], v[144:147], v[184:187], v[88:91]
	v_mfma_f32_16x16x32_bf16 v[88:91], v[140:143], v[180:183], v[88:91]
	v_mfma_f32_16x16x32_bf16 v[96:99], v[140:143], v[194:197], v[96:99]
	v_mfma_f32_16x16x32_bf16 v[96:99], v[144:147], v[198:201], v[96:99]
	v_mfma_f32_16x16x32_bf16 v[92:95], v[136:139], v[198:201], v[92:95]
	v_mfma_f32_16x16x32_bf16 v[92:95], v[132:135], v[194:197], v[92:95]
	s_setprio 0
	s_setprio 1
	v_mfma_f32_16x16x32_bf16 v[100:103], v[148:151], v[164:167], v[100:103]
	v_mfma_f32_16x16x32_bf16 v[100:103], v[152:155], v[168:171], v[100:103]
	v_mfma_f32_16x16x32_bf16 v[104:107], v[160:163], v[168:171], v[104:107]
	v_mfma_f32_16x16x32_bf16 v[104:107], v[156:159], v[164:167], v[104:107]
	v_mfma_f32_16x16x32_bf16 v[112:115], v[156:159], v[172:175], v[112:115]
	v_mfma_f32_16x16x32_bf16 v[112:115], v[160:163], v[176:179], v[112:115]
	v_mfma_f32_16x16x32_bf16 v[108:111], v[152:155], v[176:179], v[108:111]
	v_mfma_f32_16x16x32_bf16 v[108:111], v[148:151], v[172:175], v[108:111]
	v_mfma_f32_16x16x32_bf16 v[116:119], v[148:151], v[180:183], v[116:119]
	v_mfma_f32_16x16x32_bf16 v[116:119], v[152:155], v[184:187], v[116:119]
	v_mfma_f32_16x16x32_bf16 v[120:123], v[160:163], v[184:187], v[120:123]
	v_mfma_f32_16x16x32_bf16 v[120:123], v[156:159], v[180:183], v[120:123]
	v_mfma_f32_16x16x32_bf16 v[128:131], v[156:159], v[194:197], v[128:131]
	v_mfma_f32_16x16x32_bf16 v[128:131], v[160:163], v[198:201], v[128:131]
	v_mfma_f32_16x16x32_bf16 v[124:127], v[152:155], v[198:201], v[124:127]
	v_mfma_f32_16x16x32_bf16 v[124:127], v[148:151], v[194:197], v[124:127]
	s_setprio 0
	s_barrier
	s_add_i32 s28, s28, 2
	s_add_u32 s14, s14, 0x100
	s_addc_u32 s15, s15, 0
	s_add_u32 s26, s26, 0x100
	s_addc_u32 s27, s27, 0
	s_cmp_gt_u32 s28, 5
	s_cbranch_scc0 .LBB0_2069
	s_and_b64 vcc, exec, s[48:49]
	s_cbranch_vccz .LBB0_2072
	s_barrier

.LBB0_2161:
	s_add_u32 s68, s6, s40
	s_addc_u32 s69, s7, s41
	s_add_u32 s42, s68, 0x200
	s_addc_u32 s43, s69, 0
	s_add_u32 s44, s8, s40
	s_addc_u32 s45, s9, s41
	s_add_u32 s67, s44, 0x200
	s_addc_u32 s70, s45, 0
	s_add_i32 s71, 0, 0x10000
	s_cmp_eq_u32 s11, 28
	s_cselect_b32 s45, s29, s43
	s_cselect_b32 s44, s28, s42
	v_add_u32_e32 v133, s71, v143
	s_cselect_b32 s43, s37, s70
	s_cselect_b32 s42, s36, s67
	s_add_i32 s67, 0, 0x14000
	ds_read_b128 v[144:147], v133
	ds_read_b128 v[148:151], v133 offset:1024
	ds_read_b128 v[152:155], v133 offset:2048
	ds_read_b128 v[156:159], v133 offset:3072
	v_add_u32_e32 v133, s67, v143
	ds_read_b128 v[160:163], v133
	ds_read_b128 v[164:167], v133 offset:1024
	ds_read_b128 v[168:171], v133 offset:2048
	ds_read_b128 v[172:175], v133 offset:3072
	v_lshl_add_u64 v[136:137], s[68:69], 0, v[2:3]
	s_mov_b32 m0, s61
	v_add_u32_e32 v216, 0, v142
	v_lshl_add_u64 v[136:137], v[136:137], 0, s[34:35]
	v_mov_b32_e32 v133, v3
	ds_read_b128 v[176:179], v216
	ds_read_b128 v[180:183], v216 offset:1024
	ds_read_b128 v[184:187], v216 offset:2048
	ds_read_b128 v[188:191], v216 offset:3072
	ds_read_b128 v[196:199], v216 offset:4096
	ds_read_b128 v[200:203], v216 offset:5120
	ds_read_b128 v[204:207], v216 offset:6144
	ds_read_b128 v[208:211], v216 offset:7168
	global_load_lds_dwordx4 v[136:137], off
	v_lshl_add_u64 v[136:137], s[68:69], 0, v[132:133]
	v_lshl_add_u64 v[136:137], v[136:137], 0, s[34:35]
	s_mov_b32 m0, s62
	s_nop 0
	global_load_lds_dwordx4 v[136:137], off
	s_waitcnt vmcnt(8)
	s_waitcnt lgkmcnt(0)
	s_barrier
	s_setprio 1
	s_waitcnt lgkmcnt(0)
	v_mfma_f32_16x16x32_f16 v[128:131], v[144:147], v[176:179], v[128:131]
	v_mfma_f32_16x16x32_f16 v[128:131], v[148:151], v[180:183], v[128:131]
	v_mfma_f32_16x16x32_f16 v[120:123], v[156:159], v[180:183], v[120:123]
	v_mfma_f32_16x16x32_f16 v[120:123], v[152:155], v[176:179], v[120:123]
	v_mfma_f32_16x16x32_f16 v[104:107], v[152:155], v[184:187], v[104:107]
	v_mfma_f32_16x16x32_f16 v[104:107], v[156:159], v[188:191], v[104:107]
	v_mfma_f32_16x16x32_f16 v[112:115], v[148:151], v[188:191], v[112:115]
	v_mfma_f32_16x16x32_f16 v[112:115], v[144:147], v[184:187], v[112:115]
	v_mfma_f32_16x16x32_f16 v[96:99], v[144:147], v[196:199], v[96:99]
	v_mfma_f32_16x16x32_f16 v[96:99], v[148:151], v[200:203], v[96:99]
	v_mfma_f32_16x16x32_f16 v[88:91], v[156:159], v[200:203], v[88:91]
	v_mfma_f32_16x16x32_f16 v[88:91], v[152:155], v[196:199], v[88:91]
	v_mfma_f32_16x16x32_f16 v[72:75], v[152:155], v[204:207], v[72:75]
	v_mfma_f32_16x16x32_f16 v[72:75], v[156:159], v[208:211], v[72:75]
	v_mfma_f32_16x16x32_f16 v[80:83], v[148:151], v[208:211], v[80:83]
	v_mfma_f32_16x16x32_f16 v[80:83], v[144:147], v[204:207], v[80:83]
	s_setprio 0
	s_setprio 1
	v_mfma_f32_16x16x32_f16 v[124:127], v[160:163], v[176:179], v[124:127]
	v_mfma_f32_16x16x32_f16 v[124:127], v[164:167], v[180:183], v[124:127]
	v_mfma_f32_16x16x32_f16 v[116:119], v[172:175], v[180:183], v[116:119]
	v_mfma_f32_16x16x32_f16 v[116:119], v[168:171], v[176:179], v[116:119]
	v_mfma_f32_16x16x32_f16 v[100:103], v[168:171], v[184:187], v[100:103]
	v_mfma_f32_16x16x32_f16 v[100:103], v[172:175], v[188:191], v[100:103]
	v_mfma_f32_16x16x32_f16 v[108:111], v[164:167], v[188:191], v[108:111]
	v_mfma_f32_16x16x32_f16 v[108:111], v[160:163], v[184:187], v[108:111]
	v_mfma_f32_16x16x32_f16 v[92:95], v[160:163], v[196:199], v[92:95]
	v_mfma_f32_16x16x32_f16 v[92:95], v[164:167], v[200:203], v[92:95]
	v_mfma_f32_16x16x32_f16 v[84:87], v[172:175], v[200:203], v[84:87]
	v_mfma_f32_16x16x32_f16 v[84:87], v[168:171], v[196:199], v[84:87]
	v_mfma_f32_16x16x32_f16 v[68:71], v[168:171], v[204:207], v[68:71]
	v_mfma_f32_16x16x32_f16 v[68:71], v[172:175], v[208:211], v[68:71]
	v_mfma_f32_16x16x32_f16 v[76:79], v[164:167], v[208:211], v[76:79]
	v_mfma_f32_16x16x32_f16 v[76:79], v[160:163], v[204:207], v[76:79]
	s_setprio 0
	s_barrier
	s_add_i32 s68, s71, s53
	s_mov_b32 m0, s68
	ds_read_b128 v[176:179], v216 offset:16384
	ds_read_b128 v[180:183], v216 offset:17408
	ds_read_b128 v[184:187], v216 offset:18432
	ds_read_b128 v[188:191], v216 offset:19456
	ds_read_b128 v[196:199], v216 offset:20480
	ds_read_b128 v[200:203], v216 offset:21504
	ds_read_b128 v[204:207], v216 offset:22528
	ds_read_b128 v[208:211], v216 offset:23552
	global_load_lds_dwordx4 v138, s[42:43]
	s_add_i32 m0, s68, 0x2000
	s_add_u32 s68, s42, 0x80000
	s_addc_u32 s69, s43, 0
	s_add_i32 s67, s67, s53
	global_load_lds_dwordx4 v134, s[42:43]
	s_mov_b32 m0, s67
	v_mov_b32_e32 v139, v3
	global_load_lds_dwordx4 v138, s[68:69]
	s_add_i32 m0, s67, 0x2000
	v_mov_b32_e32 v135, v3
	global_load_lds_dwordx4 v134, s[68:69]
	s_mov_b32 m0, s54
	v_lshl_add_u64 v[136:137], s[42:43], 0, v[138:139]
	global_load_lds_dwordx4 v2, s[44:45]
	s_mov_b32 m0, s55
	v_lshl_add_u64 v[192:193], s[42:43], 0, v[134:135]
	global_load_lds_dwordx4 v132, s[44:45]
	s_waitcnt vmcnt(8)
	s_waitcnt lgkmcnt(0)
	v_lshl_add_u64 v[212:213], s[44:45], 0, v[2:3]
	v_lshl_add_u64 v[214:215], s[44:45], 0, v[132:133]
	s_barrier
	s_setprio 1
	s_waitcnt lgkmcnt(0)
	v_mfma_f32_16x16x32_f16 v[64:67], v[144:147], v[176:179], v[64:67]
	v_mfma_f32_16x16x32_f16 v[64:67], v[148:151], v[180:183], v[64:67]
	v_mfma_f32_16x16x32_f16 v[56:59], v[156:159], v[180:183], v[56:59]
	v_mfma_f32_16x16x32_f16 v[56:59], v[152:155], v[176:179], v[56:59]
	v_mfma_f32_16x16x32_f16 v[40:43], v[152:155], v[184:187], v[40:43]
	v_mfma_f32_16x16x32_f16 v[40:43], v[156:159], v[188:191], v[40:43]
	v_mfma_f32_16x16x32_f16 v[48:51], v[148:151], v[188:191], v[48:51]
	v_mfma_f32_16x16x32_f16 v[48:51], v[144:147], v[184:187], v[48:51]
	v_mfma_f32_16x16x32_f16 v[32:35], v[144:147], v[196:199], v[32:35]
	v_mfma_f32_16x16x32_f16 v[32:35], v[148:151], v[200:203], v[32:35]
	v_mfma_f32_16x16x32_f16 v[24:27], v[156:159], v[200:203], v[24:27]
	v_mfma_f32_16x16x32_f16 v[24:27], v[152:155], v[196:199], v[24:27]
	v_mfma_f32_16x16x32_f16 v[8:11], v[152:155], v[204:207], v[8:11]
	v_mfma_f32_16x16x32_f16 v[8:11], v[156:159], v[208:211], v[8:11]
	v_mfma_f32_16x16x32_f16 v[16:19], v[148:151], v[208:211], v[16:19]
	v_mfma_f32_16x16x32_f16 v[16:19], v[144:147], v[204:207], v[16:19]
	s_setprio 0
	s_setprio 1
	v_mfma_f32_16x16x32_f16 v[60:63], v[160:163], v[176:179], v[60:63]
	v_mfma_f32_16x16x32_f16 v[60:63], v[164:167], v[180:183], v[60:63]
	v_mfma_f32_16x16x32_f16 v[52:55], v[172:175], v[180:183], v[52:55]
	v_mfma_f32_16x16x32_f16 v[52:55], v[168:171], v[176:179], v[52:55]
	v_mfma_f32_16x16x32_f16 v[36:39], v[168:171], v[184:187], v[36:39]
	v_mfma_f32_16x16x32_f16 v[36:39], v[172:175], v[188:191], v[36:39]
	v_mfma_f32_16x16x32_f16 v[44:47], v[164:167], v[188:191], v[44:47]
	v_mfma_f32_16x16x32_f16 v[44:47], v[160:163], v[184:187], v[44:47]
	v_mfma_f32_16x16x32_f16 v[28:31], v[160:163], v[196:199], v[28:31]
	v_mfma_f32_16x16x32_f16 v[28:31], v[164:167], v[200:203], v[28:31]
	v_mfma_f32_16x16x32_f16 v[20:23], v[172:175], v[200:203], v[20:23]
	v_mfma_f32_16x16x32_f16 v[20:23], v[168:171], v[196:199], v[20:23]
	v_mfma_f32_16x16x32_f16 v[4:7], v[168:171], v[204:207], v[4:7]
	v_mfma_f32_16x16x32_f16 v[4:7], v[172:175], v[208:211], v[4:7]
	v_mfma_f32_16x16x32_f16 v[12:15], v[164:167], v[208:211], v[12:15]
	v_mfma_f32_16x16x32_f16 v[12:15], v[160:163], v[204:207], v[12:15]
	s_setprio 0
	s_barrier
	s_add_i32 s67, 0, 0x18000
	v_add_u32_e32 v135, s67, v143
	s_add_i32 s68, 0, 0x1c000
	ds_read_b128 v[144:147], v135
	ds_read_b128 v[148:151], v135 offset:1024
	ds_read_b128 v[152:155], v135 offset:2048
	ds_read_b128 v[156:159], v135 offset:3072
	v_add_u32_e32 v135, s68, v143
	ds_read_b128 v[160:163], v135
	ds_read_b128 v[164:167], v135 offset:1024
	ds_read_b128 v[168:171], v135 offset:2048
	ds_read_b128 v[172:175], v135 offset:3072
	s_add_u32 s44, s44, 0x80000
	s_addc_u32 s45, s45, 0
	s_mov_b32 m0, s56
	ds_read_b128 v[176:179], v216 offset:32768
	ds_read_b128 v[180:183], v216 offset:33792
	ds_read_b128 v[184:187], v216 offset:34816
	ds_read_b128 v[188:191], v216 offset:35840
	ds_read_b128 v[196:199], v216 offset:36864
	ds_read_b128 v[200:203], v216 offset:37888
	ds_read_b128 v[204:207], v216 offset:38912
	ds_read_b128 v[208:211], v216 offset:39936
	global_load_lds_dwordx4 v2, s[44:45]
	s_mov_b32 m0, s57
	s_nop 0
	global_load_lds_dwordx4 v132, s[44:45]
	s_waitcnt vmcnt(8)
	s_waitcnt lgkmcnt(0)
	s_barrier
	s_setprio 1
	s_waitcnt lgkmcnt(0)
	v_mfma_f32_16x16x32_f16 v[128:131], v[144:147], v[176:179], v[128:131]
	v_mfma_f32_16x16x32_f16 v[128:131], v[148:151], v[180:183], v[128:131]
	v_mfma_f32_16x16x32_f16 v[120:123], v[156:159], v[180:183], v[120:123]
	v_mfma_f32_16x16x32_f16 v[120:123], v[152:155], v[176:179], v[120:123]
	v_mfma_f32_16x16x32_f16 v[104:107], v[152:155], v[184:187], v[104:107]
	v_mfma_f32_16x16x32_f16 v[104:107], v[156:159], v[188:191], v[104:107]
	v_mfma_f32_16x16x32_f16 v[112:115], v[148:151], v[188:191], v[112:115]
	v_mfma_f32_16x16x32_f16 v[112:115], v[144:147], v[184:187], v[112:115]
	v_mfma_f32_16x16x32_f16 v[96:99], v[144:147], v[196:199], v[96:99]
	v_mfma_f32_16x16x32_f16 v[96:99], v[148:151], v[200:203], v[96:99]
	v_mfma_f32_16x16x32_f16 v[88:91], v[156:159], v[200:203], v[88:91]
	v_mfma_f32_16x16x32_f16 v[88:91], v[152:155], v[196:199], v[88:91]
	v_mfma_f32_16x16x32_f16 v[72:75], v[152:155], v[204:207], v[72:75]
	v_mfma_f32_16x16x32_f16 v[72:75], v[156:159], v[208:211], v[72:75]
	v_mfma_f32_16x16x32_f16 v[80:83], v[148:151], v[208:211], v[80:83]
	v_mfma_f32_16x16x32_f16 v[80:83], v[144:147], v[204:207], v[80:83]
	s_setprio 0
	s_setprio 1
	v_mfma_f32_16x16x32_f16 v[124:127], v[160:163], v[176:179], v[124:127]
	v_mfma_f32_16x16x32_f16 v[124:127], v[164:167], v[180:183], v[124:127]
	v_mfma_f32_16x16x32_f16 v[116:119], v[172:175], v[180:183], v[116:119]
	v_mfma_f32_16x16x32_f16 v[116:119], v[168:171], v[176:179], v[116:119]
	v_mfma_f32_16x16x32_f16 v[100:103], v[168:171], v[184:187], v[100:103]
	v_mfma_f32_16x16x32_f16 v[100:103], v[172:175], v[188:191], v[100:103]
	v_mfma_f32_16x16x32_f16 v[108:111], v[164:167], v[188:191], v[108:111]
	v_mfma_f32_16x16x32_f16 v[108:111], v[160:163], v[184:187], v[108:111]
	v_mfma_f32_16x16x32_f16 v[92:95], v[160:163], v[196:199], v[92:95]
	v_mfma_f32_16x16x32_f16 v[92:95], v[164:167], v[200:203], v[92:95]
	v_mfma_f32_16x16x32_f16 v[84:87], v[172:175], v[200:203], v[84:87]
	v_mfma_f32_16x16x32_f16 v[84:87], v[168:171], v[196:199], v[84:87]
	v_mfma_f32_16x16x32_f16 v[68:71], v[168:171], v[204:207], v[68:71]
	v_mfma_f32_16x16x32_f16 v[68:71], v[172:175], v[208:211], v[68:71]
	v_mfma_f32_16x16x32_f16 v[76:79], v[164:167], v[208:211], v[76:79]
	v_mfma_f32_16x16x32_f16 v[76:79], v[160:163], v[204:207], v[76:79]
	s_setprio 0
	s_barrier
	s_add_i32 s44, s67, s53
	v_lshl_add_u64 v[136:137], v[136:137], 0, s[86:87]
	s_mov_b32 m0, s44
	ds_read_b128 v[176:179], v216 offset:49152
	ds_read_b128 v[180:183], v216 offset:50176
	ds_read_b128 v[184:187], v216 offset:51200
	ds_read_b128 v[188:191], v216 offset:52224
	ds_read_b128 v[196:199], v216 offset:53248
	ds_read_b128 v[200:203], v216 offset:54272
	ds_read_b128 v[204:207], v216 offset:55296
	ds_read_b128 v[208:211], v216 offset:56320
	global_load_lds_dwordx4 v[136:137], off
	s_add_i32 m0, s44, 0x2000
	s_add_u32 s42, s42, 0x80080
	v_lshl_add_u64 v[136:137], v[192:193], 0, s[86:87]
	s_addc_u32 s43, s43, 0
	s_add_i32 s44, s68, s53
	global_load_lds_dwordx4 v[136:137], off
	s_mov_b32 m0, s44
	v_lshl_add_u64 v[136:137], v[212:213], 0, s[86:87]
	global_load_lds_dwordx4 v138, s[42:43]
	s_add_i32 m0, s44, 0x2000
	s_nop 0
	global_load_lds_dwordx4 v134, s[42:43]
	s_mov_b32 m0, s59
	s_nop 0
	global_load_lds_dwordx4 v[136:137], off
	v_lshl_add_u64 v[136:137], v[214:215], 0, s[86:87]
	s_mov_b32 m0, s60
	s_nop 0
	global_load_lds_dwordx4 v[136:137], off
	s_waitcnt vmcnt(8)
	s_waitcnt lgkmcnt(0)
	s_barrier
	s_setprio 1
	s_waitcnt lgkmcnt(0)
	v_mfma_f32_16x16x32_f16 v[64:67], v[144:147], v[176:179], v[64:67]
	v_mfma_f32_16x16x32_f16 v[64:67], v[148:151], v[180:183], v[64:67]
	v_mfma_f32_16x16x32_f16 v[56:59], v[156:159], v[180:183], v[56:59]
	v_mfma_f32_16x16x32_f16 v[56:59], v[152:155], v[176:179], v[56:59]
	v_mfma_f32_16x16x32_f16 v[40:43], v[152:155], v[184:187], v[40:43]
	v_mfma_f32_16x16x32_f16 v[40:43], v[156:159], v[188:191], v[40:43]
	v_mfma_f32_16x16x32_f16 v[48:51], v[148:151], v[188:191], v[48:51]
	v_mfma_f32_16x16x32_f16 v[48:51], v[144:147], v[184:187], v[48:51]
	v_mfma_f32_16x16x32_f16 v[32:35], v[144:147], v[196:199], v[32:35]
	v_mfma_f32_16x16x32_f16 v[32:35], v[148:151], v[200:203], v[32:35]
	v_mfma_f32_16x16x32_f16 v[24:27], v[156:159], v[200:203], v[24:27]
	v_mfma_f32_16x16x32_f16 v[24:27], v[152:155], v[196:199], v[24:27]
	v_mfma_f32_16x16x32_f16 v[8:11], v[152:155], v[204:207], v[8:11]
	v_mfma_f32_16x16x32_f16 v[8:11], v[156:159], v[208:211], v[8:11]
	v_mfma_f32_16x16x32_f16 v[16:19], v[148:151], v[208:211], v[16:19]
	v_mfma_f32_16x16x32_f16 v[16:19], v[144:147], v[204:207], v[16:19]
	s_setprio 0
	s_setprio 1
	v_mfma_f32_16x16x32_f16 v[60:63], v[160:163], v[176:179], v[60:63]
	v_mfma_f32_16x16x32_f16 v[60:63], v[164:167], v[180:183], v[60:63]
	v_mfma_f32_16x16x32_f16 v[52:55], v[172:175], v[180:183], v[52:55]
	v_mfma_f32_16x16x32_f16 v[52:55], v[168:171], v[176:179], v[52:55]
	v_mfma_f32_16x16x32_f16 v[36:39], v[168:171], v[184:187], v[36:39]
	v_mfma_f32_16x16x32_f16 v[36:39], v[172:175], v[188:191], v[36:39]
	v_mfma_f32_16x16x32_f16 v[44:47], v[164:167], v[188:191], v[44:47]
	v_mfma_f32_16x16x32_f16 v[44:47], v[160:163], v[184:187], v[44:47]
	v_mfma_f32_16x16x32_f16 v[28:31], v[160:163], v[196:199], v[28:31]
	v_mfma_f32_16x16x32_f16 v[28:31], v[164:167], v[200:203], v[28:31]
	v_mfma_f32_16x16x32_f16 v[20:23], v[172:175], v[200:203], v[20:23]
	v_mfma_f32_16x16x32_f16 v[20:23], v[168:171], v[196:199], v[20:23]
	v_mfma_f32_16x16x32_f16 v[4:7], v[168:171], v[204:207], v[4:7]
	v_mfma_f32_16x16x32_f16 v[4:7], v[172:175], v[208:211], v[4:7]
	v_mfma_f32_16x16x32_f16 v[12:15], v[164:167], v[208:211], v[12:15]
	v_mfma_f32_16x16x32_f16 v[12:15], v[160:163], v[204:207], v[12:15]
	s_setprio 0
	s_barrier
	s_add_i32 s11, s11, 2
	s_add_u32 s40, s40, 0x100
	s_addc_u32 s41, s41, 0
	s_cmp_gt_u32 s11, 29
	s_cbranch_scc0 .LBB0_2161
	s_andn2_b64 vcc, exec, s[26:27]
	s_cbranch_vccnz .LBB0_2164
	s_add_u32 s6, s28, 0x80080
	s_addc_u32 s7, s29, 0
	s_mov_b32 m0, s61
	v_lshl_add_u64 v[144:145], s[6:7], 0, v[2:3]
	v_lshl_add_u64 v[136:137], s[6:7], 0, v[132:133]
	global_load_lds_dwordx4 v[144:145], off
	s_mov_b32 m0, s62
	s_mov_b32 s47, s65
	global_load_lds_dwordx4 v[136:137], off
	s_mov_b32 s64, s10
	s_mov_b64 s[8:9], s[14:15]
	s_mov_b64 s[6:7], s[12:13]
	s_mov_b32 s63, s66

.LBB0_2269:
	s_add_i32 s51, 0, 0x10000
	s_add_i32 s71, 0, 0x14000
	v_add_u32_e32 v16, s51, v232
	v_add_u32_e32 v32, s71, v232
	ds_read_b128 v[4:7], v16
	ds_read_b128 v[8:11], v16 offset:1024
	ds_read_b128 v[12:15], v16 offset:2048
	ds_read_b128 v[16:19], v16 offset:3072
	ds_read_b128 v[20:23], v32
	ds_read_b128 v[24:27], v32 offset:1024
	ds_read_b128 v[28:31], v32 offset:2048
	ds_read_b128 v[32:35], v32 offset:3072
	v_add_u32_e32 v233, 0, v231
	ds_read_b128 v[36:39], v233
	ds_read_b128 v[40:43], v233 offset:1024
	ds_read_b128 v[44:47], v233 offset:2048
	ds_read_b128 v[48:51], v233 offset:3072
	ds_read_b128 v[52:55], v233 offset:4096
	ds_read_b128 v[56:59], v233 offset:5120
	ds_read_b128 v[60:63], v233 offset:6144
	ds_read_b128 v[64:67], v233 offset:7168
	s_waitcnt vmcnt(8)
	s_waitcnt lgkmcnt(0)
	s_barrier
	s_setprio 1
	s_waitcnt lgkmcnt(0)
	v_mfma_f32_16x16x32_bf16 v[68:71], v[4:7], v[36:39], 0
	v_mfma_f32_16x16x32_bf16 v[68:71], v[8:11], v[40:43], v[68:71]
	v_mfma_f32_16x16x32_bf16 v[72:75], v[12:15], v[36:39], 0
	v_mfma_f32_16x16x32_bf16 v[72:75], v[16:19], v[40:43], v[72:75]
	v_mfma_f32_16x16x32_bf16 v[80:83], v[12:15], v[44:47], 0
	v_mfma_f32_16x16x32_bf16 v[80:83], v[16:19], v[48:51], v[80:83]
	v_mfma_f32_16x16x32_bf16 v[76:79], v[4:7], v[44:47], 0
	v_mfma_f32_16x16x32_bf16 v[76:79], v[8:11], v[48:51], v[76:79]
	v_mfma_f32_16x16x32_bf16 v[84:87], v[4:7], v[52:55], 0
	v_mfma_f32_16x16x32_bf16 v[84:87], v[8:11], v[56:59], v[84:87]
	v_mfma_f32_16x16x32_bf16 v[88:91], v[12:15], v[52:55], 0
	v_mfma_f32_16x16x32_bf16 v[88:91], v[16:19], v[56:59], v[88:91]
	v_mfma_f32_16x16x32_bf16 v[96:99], v[12:15], v[60:63], 0
	v_mfma_f32_16x16x32_bf16 v[96:99], v[16:19], v[64:67], v[96:99]
	v_mfma_f32_16x16x32_bf16 v[92:95], v[4:7], v[60:63], 0
	v_mfma_f32_16x16x32_bf16 v[92:95], v[8:11], v[64:67], v[92:95]
	s_setprio 0
	s_setprio 1
	v_mfma_f32_16x16x32_bf16 v[100:103], v[20:23], v[36:39], 0
	v_mfma_f32_16x16x32_bf16 v[36:39], v[28:31], v[36:39], 0
	v_mfma_f32_16x16x32_bf16 v[104:107], v[20:23], v[44:47], 0
	v_mfma_f32_16x16x32_bf16 v[44:47], v[28:31], v[44:47], 0
	v_mfma_f32_16x16x32_bf16 v[108:111], v[20:23], v[52:55], 0
	v_mfma_f32_16x16x32_bf16 v[52:55], v[28:31], v[52:55], 0
	v_mfma_f32_16x16x32_bf16 v[112:115], v[20:23], v[60:63], 0
	v_mfma_f32_16x16x32_bf16 v[60:63], v[28:31], v[60:63], 0
	v_mfma_f32_16x16x32_bf16 v[100:103], v[24:27], v[40:43], v[100:103]
	v_mfma_f32_16x16x32_bf16 v[40:43], v[32:35], v[40:43], v[36:39]
	v_mfma_f32_16x16x32_bf16 v[104:107], v[24:27], v[48:51], v[104:107]
	v_mfma_f32_16x16x32_bf16 v[48:51], v[32:35], v[48:51], v[44:47]
	v_mfma_f32_16x16x32_bf16 v[108:111], v[24:27], v[56:59], v[108:111]
	v_mfma_f32_16x16x32_bf16 v[56:59], v[32:35], v[56:59], v[52:55]
	v_mfma_f32_16x16x32_bf16 v[112:115], v[24:27], v[64:67], v[112:115]
	v_mfma_f32_16x16x32_bf16 v[64:67], v[32:35], v[64:67], v[60:63]
	s_setprio 0
	s_barrier
	v_lshl_add_u64 v[186:187], s[12:13], 0, v[2:3]
	s_add_i32 s51, s51, s38
	v_mov_b32_e32 v191, v3
	v_lshl_add_u64 v[134:135], v[186:187], 0, s[74:75]
	s_mov_b32 m0, s51
	v_lshl_add_u64 v[246:247], s[12:13], 0, v[190:191]
	ds_read_b128 v[36:39], v233 offset:16384
	ds_read_b128 v[44:47], v233 offset:17408
	ds_read_b128 v[52:55], v233 offset:18432
	ds_read_b128 v[60:63], v233 offset:19456
	ds_read_b128 v[116:119], v233 offset:20480
	ds_read_b128 v[120:123], v233 offset:21504
	ds_read_b128 v[124:127], v233 offset:22528
	ds_read_b128 v[128:131], v233 offset:23552
	global_load_lds_dwordx4 v[134:135], off
	v_lshl_add_u64 v[134:135], v[246:247], 0, s[74:75]
	s_add_i32 m0, s51, 0x2000
	s_add_i32 s51, s71, s38
	global_load_lds_dwordx4 v[134:135], off
	s_mov_b32 m0, s51
	v_mov_b32_e32 v133, v3
	global_load_lds_dwordx4 v2, s[16:17]
	s_add_i32 m0, s51, 0x2000
	v_lshl_add_u64 v[248:249], s[14:15], 0, v[132:133]
	v_mov_b32_e32 v189, v3
	global_load_lds_dwordx4 v190, s[16:17]
	v_lshl_add_u64 v[134:135], v[248:249], 0, s[74:75]
	s_mov_b32 m0, s56
	v_lshl_add_u64 v[250:251], s[14:15], 0, v[188:189]
	global_load_lds_dwordx4 v[134:135], off
	v_lshl_add_u64 v[134:135], v[250:251], 0, s[74:75]
	s_mov_b32 m0, s57
	s_nop 0
	global_load_lds_dwordx4 v[134:135], off
	s_waitcnt vmcnt(8)
	s_waitcnt lgkmcnt(0)
	s_barrier
	s_setprio 1
	s_waitcnt lgkmcnt(0)
	v_mfma_f32_16x16x32_bf16 v[134:137], v[4:7], v[36:39], 0
	v_mfma_f32_16x16x32_bf16 v[138:141], v[12:15], v[36:39], 0
	v_mfma_f32_16x16x32_bf16 v[142:145], v[4:7], v[52:55], 0
	v_mfma_f32_16x16x32_bf16 v[146:149], v[12:15], v[52:55], 0
	v_mfma_f32_16x16x32_bf16 v[150:153], v[4:7], v[116:119], 0
	v_mfma_f32_16x16x32_bf16 v[154:157], v[12:15], v[116:119], 0
	v_mfma_f32_16x16x32_bf16 v[4:7], v[4:7], v[124:127], 0
	v_mfma_f32_16x16x32_bf16 v[12:15], v[12:15], v[124:127], 0
	v_mfma_f32_16x16x32_bf16 v[134:137], v[8:11], v[44:47], v[134:137]
	v_mfma_f32_16x16x32_bf16 v[138:141], v[16:19], v[44:47], v[138:141]
	v_mfma_f32_16x16x32_bf16 v[142:145], v[8:11], v[60:63], v[142:145]
	v_mfma_f32_16x16x32_bf16 v[146:149], v[16:19], v[60:63], v[146:149]
	v_mfma_f32_16x16x32_bf16 v[150:153], v[8:11], v[120:123], v[150:153]
	v_mfma_f32_16x16x32_bf16 v[154:157], v[16:19], v[120:123], v[154:157]
	v_mfma_f32_16x16x32_bf16 v[158:161], v[8:11], v[128:131], v[4:7]
	v_mfma_f32_16x16x32_bf16 v[162:165], v[16:19], v[128:131], v[12:15]
	s_setprio 0
	s_setprio 1
	v_mfma_f32_16x16x32_bf16 v[4:7], v[20:23], v[36:39], 0
	v_mfma_f32_16x16x32_bf16 v[8:11], v[28:31], v[36:39], 0
	v_mfma_f32_16x16x32_bf16 v[12:15], v[20:23], v[52:55], 0
	v_mfma_f32_16x16x32_bf16 v[16:19], v[28:31], v[52:55], 0
	v_mfma_f32_16x16x32_bf16 v[36:39], v[20:23], v[116:119], 0
	v_mfma_f32_16x16x32_bf16 v[52:55], v[28:31], v[116:119], 0
	v_mfma_f32_16x16x32_bf16 v[20:23], v[20:23], v[124:127], 0
	v_mfma_f32_16x16x32_bf16 v[28:31], v[28:31], v[124:127], 0
	v_mfma_f32_16x16x32_bf16 v[116:119], v[24:27], v[44:47], v[4:7]
	v_mfma_f32_16x16x32_bf16 v[124:127], v[32:35], v[44:47], v[8:11]
	v_mfma_f32_16x16x32_bf16 v[174:177], v[24:27], v[120:123], v[36:39]
	v_mfma_f32_16x16x32_bf16 v[120:123], v[32:35], v[120:123], v[52:55]
	v_mfma_f32_16x16x32_bf16 v[178:181], v[24:27], v[128:131], v[20:23]
	v_mfma_f32_16x16x32_bf16 v[128:131], v[32:35], v[128:131], v[28:31]
	v_mfma_f32_16x16x32_bf16 v[166:169], v[24:27], v[60:63], v[12:15]
	v_mfma_f32_16x16x32_bf16 v[170:173], v[32:35], v[60:63], v[16:19]
	s_setprio 0
	s_barrier
	s_add_i32 s51, 0, 0x18000
	v_add_u32_e32 v4, s51, v232
	s_add_i32 s71, 0, 0x1c000
	ds_read_b128 v[182:185], v4
	ds_read_b128 v[192:195], v4 offset:1024
	ds_read_b128 v[196:199], v4 offset:2048
	ds_read_b128 v[200:203], v4 offset:3072
	v_add_u32_e32 v4, s71, v232
	ds_read_b128 v[204:207], v4
	ds_read_b128 v[208:211], v4 offset:1024
	ds_read_b128 v[212:215], v4 offset:2048
	ds_read_b128 v[216:219], v4 offset:3072
	s_mov_b32 m0, s58
	ds_read_b128 v[44:47], v233 offset:32768
	ds_read_b128 v[52:55], v233 offset:33792
	ds_read_b128 v[60:63], v233 offset:34816
	ds_read_b128 v[220:223], v233 offset:35840
	ds_read_b128 v[224:227], v233 offset:36864
	ds_read_b128 v[234:237], v233 offset:37888
	ds_read_b128 v[238:241], v233 offset:38912
	ds_read_b128 v[242:245], v233 offset:39936
	global_load_lds_dwordx4 v132, s[26:27]
	s_mov_b32 m0, s59
	s_nop 0
	global_load_lds_dwordx4 v188, s[26:27]
	s_waitcnt vmcnt(8)
	s_waitcnt lgkmcnt(0)
	s_barrier
	s_setprio 1
	s_waitcnt lgkmcnt(0)
	v_mfma_f32_16x16x32_bf16 v[4:7], v[182:185], v[44:47], v[68:71]
	v_mfma_f32_16x16x32_bf16 v[8:11], v[196:199], v[44:47], v[72:75]
	v_mfma_f32_16x16x32_bf16 v[12:15], v[182:185], v[60:63], v[76:79]
	v_mfma_f32_16x16x32_bf16 v[16:19], v[196:199], v[60:63], v[80:83]
	v_mfma_f32_16x16x32_bf16 v[20:23], v[182:185], v[224:227], v[84:87]
	v_mfma_f32_16x16x32_bf16 v[24:27], v[196:199], v[224:227], v[88:91]
	v_mfma_f32_16x16x32_bf16 v[28:31], v[182:185], v[238:241], v[92:95]
	v_mfma_f32_16x16x32_bf16 v[32:35], v[196:199], v[238:241], v[96:99]
	v_mfma_f32_16x16x32_bf16 v[4:7], v[192:195], v[52:55], v[4:7]
	v_mfma_f32_16x16x32_bf16 v[8:11], v[200:203], v[52:55], v[8:11]
	v_mfma_f32_16x16x32_bf16 v[12:15], v[192:195], v[220:223], v[12:15]
	v_mfma_f32_16x16x32_bf16 v[16:19], v[200:203], v[220:223], v[16:19]
	v_mfma_f32_16x16x32_bf16 v[20:23], v[192:195], v[234:237], v[20:23]
	v_mfma_f32_16x16x32_bf16 v[24:27], v[200:203], v[234:237], v[24:27]
	v_mfma_f32_16x16x32_bf16 v[28:31], v[192:195], v[242:245], v[28:31]
	v_mfma_f32_16x16x32_bf16 v[32:35], v[200:203], v[242:245], v[32:35]
	s_setprio 0
	s_setprio 1
	v_mfma_f32_16x16x32_bf16 v[36:39], v[204:207], v[44:47], v[100:103]
	v_mfma_f32_16x16x32_bf16 v[40:43], v[212:215], v[44:47], v[40:43]
	v_mfma_f32_16x16x32_bf16 v[36:39], v[208:211], v[52:55], v[36:39]
	v_mfma_f32_16x16x32_bf16 v[40:43], v[216:219], v[52:55], v[40:43]
	v_mfma_f32_16x16x32_bf16 v[44:47], v[204:207], v[60:63], v[104:107]
	v_mfma_f32_16x16x32_bf16 v[48:51], v[212:215], v[60:63], v[48:51]
	v_mfma_f32_16x16x32_bf16 v[52:55], v[204:207], v[224:227], v[108:111]
	v_mfma_f32_16x16x32_bf16 v[56:59], v[212:215], v[224:227], v[56:59]
	v_mfma_f32_16x16x32_bf16 v[60:63], v[204:207], v[238:241], v[112:115]
	v_mfma_f32_16x16x32_bf16 v[64:67], v[212:215], v[238:241], v[64:67]
	v_mfma_f32_16x16x32_bf16 v[44:47], v[208:211], v[220:223], v[44:47]
	v_mfma_f32_16x16x32_bf16 v[48:51], v[216:219], v[220:223], v[48:51]
	v_mfma_f32_16x16x32_bf16 v[52:55], v[208:211], v[234:237], v[52:55]
	v_mfma_f32_16x16x32_bf16 v[56:59], v[216:219], v[234:237], v[56:59]
	v_mfma_f32_16x16x32_bf16 v[60:63], v[208:211], v[242:245], v[60:63]
	v_mfma_f32_16x16x32_bf16 v[64:67], v[216:219], v[242:245], v[64:67]
	s_setprio 0
	s_barrier
	s_add_i32 s51, s51, s38
	v_lshl_add_u64 v[68:69], v[186:187], 0, s[24:25]
	s_mov_b32 m0, s51
	ds_read_b128 v[104:107], v233 offset:49152
	ds_read_b128 v[108:111], v233 offset:50176
	ds_read_b128 v[112:115], v233 offset:51200
	ds_read_b128 v[220:223], v233 offset:52224
	ds_read_b128 v[224:227], v233 offset:53248
	ds_read_b128 v[234:237], v233 offset:54272
	ds_read_b128 v[238:241], v233 offset:55296
	ds_read_b128 v[242:245], v233 offset:56320
	global_load_lds_dwordx4 v[68:69], off
	v_lshl_add_u64 v[68:69], v[246:247], 0, s[24:25]
	s_add_i32 m0, s51, 0x2000
	s_add_i32 s51, s71, s38
	global_load_lds_dwordx4 v[68:69], off
	s_mov_b32 m0, s51
	v_lshl_add_u64 v[68:69], v[248:249], 0, s[24:25]
	global_load_lds_dwordx4 v2, s[28:29]
	s_add_i32 m0, s51, 0x2000
	s_nop 0
	global_load_lds_dwordx4 v190, s[28:29]
	s_mov_b32 m0, s63
	s_nop 0
	global_load_lds_dwordx4 v[68:69], off
	v_lshl_add_u64 v[68:69], v[250:251], 0, s[24:25]
	s_mov_b32 m0, s64
	s_nop 0
	global_load_lds_dwordx4 v[68:69], off
	s_waitcnt vmcnt(8)
	s_waitcnt lgkmcnt(0)
	s_barrier
	s_setprio 1
	s_waitcnt lgkmcnt(0)
	v_mfma_f32_16x16x32_bf16 v[68:71], v[182:185], v[104:107], v[134:137]
	v_mfma_f32_16x16x32_bf16 v[72:75], v[196:199], v[104:107], v[138:141]
	v_mfma_f32_16x16x32_bf16 v[76:79], v[182:185], v[112:115], v[142:145]
	v_mfma_f32_16x16x32_bf16 v[80:83], v[196:199], v[112:115], v[146:149]
	v_mfma_f32_16x16x32_bf16 v[84:87], v[182:185], v[224:227], v[150:153]
	v_mfma_f32_16x16x32_bf16 v[88:91], v[196:199], v[224:227], v[154:157]
	v_mfma_f32_16x16x32_bf16 v[92:95], v[182:185], v[238:241], v[158:161]
	v_mfma_f32_16x16x32_bf16 v[96:99], v[196:199], v[238:241], v[162:165]
	v_mfma_f32_16x16x32_bf16 v[68:71], v[192:195], v[108:111], v[68:71]
	v_mfma_f32_16x16x32_bf16 v[72:75], v[200:203], v[108:111], v[72:75]
	v_mfma_f32_16x16x32_bf16 v[76:79], v[192:195], v[220:223], v[76:79]
	v_mfma_f32_16x16x32_bf16 v[80:83], v[200:203], v[220:223], v[80:83]
	v_mfma_f32_16x16x32_bf16 v[84:87], v[192:195], v[234:237], v[84:87]
	v_mfma_f32_16x16x32_bf16 v[88:91], v[200:203], v[234:237], v[88:91]
	v_mfma_f32_16x16x32_bf16 v[92:95], v[192:195], v[242:245], v[92:95]
	v_mfma_f32_16x16x32_bf16 v[96:99], v[200:203], v[242:245], v[96:99]
	s_setprio 0
	s_setprio 1
	v_mfma_f32_16x16x32_bf16 v[100:103], v[204:207], v[104:107], v[116:119]
	v_mfma_f32_16x16x32_bf16 v[104:107], v[212:215], v[104:107], v[124:127]
	v_mfma_f32_16x16x32_bf16 v[100:103], v[208:211], v[108:111], v[100:103]
	v_mfma_f32_16x16x32_bf16 v[104:107], v[216:219], v[108:111], v[104:107]
	v_mfma_f32_16x16x32_bf16 v[108:111], v[204:207], v[112:115], v[166:169]
	v_mfma_f32_16x16x32_bf16 v[112:115], v[212:215], v[112:115], v[170:173]
	v_mfma_f32_16x16x32_bf16 v[116:119], v[204:207], v[224:227], v[174:177]
	v_mfma_f32_16x16x32_bf16 v[120:123], v[212:215], v[224:227], v[120:123]
	v_mfma_f32_16x16x32_bf16 v[124:127], v[204:207], v[238:241], v[178:181]
	v_mfma_f32_16x16x32_bf16 v[128:131], v[212:215], v[238:241], v[128:131]
	v_mfma_f32_16x16x32_bf16 v[108:111], v[208:211], v[220:223], v[108:111]
	v_mfma_f32_16x16x32_bf16 v[112:115], v[216:219], v[220:223], v[112:115]
	v_mfma_f32_16x16x32_bf16 v[116:119], v[208:211], v[234:237], v[116:119]
	v_mfma_f32_16x16x32_bf16 v[120:123], v[216:219], v[234:237], v[120:123]
	v_mfma_f32_16x16x32_bf16 v[124:127], v[208:211], v[242:245], v[124:127]
	v_mfma_f32_16x16x32_bf16 v[128:131], v[216:219], v[242:245], v[128:131]
	s_setprio 0
	s_barrier
	s_add_i32 s41, s41, 2
	s_cmp_ge_i32 s41, s40
	s_cbranch_scc0 .LBB0_2269
	v_mov_b32_e32 v192, v2
	s_branch .LBB0_2272

.LBB0_2273:
	s_add_u32 s12, s14, 0xfffc0080
	s_addc_u32 s13, s15, -1
	s_add_i32 s29, 0, 0x10000
	s_cmp_eq_u32 s28, 12
	s_cselect_b32 s17, s9, s13
	s_cselect_b32 s16, s8, s12
	s_cselect_b32 s13, s11, s27
	s_cselect_b32 s12, s10, s26
	s_add_i32 s51, 0, 0x14000
	v_add_u32_e32 v144, s29, v232
	v_add_u32_e32 v160, s51, v232
	s_waitcnt lgkmcnt(0)
	ds_read_b128 v[132:135], v144
	ds_read_b128 v[136:139], v144 offset:1024
	ds_read_b128 v[140:143], v144 offset:2048
	ds_read_b128 v[144:147], v144 offset:3072
	ds_read_b128 v[148:151], v160
	ds_read_b128 v[152:155], v160 offset:1024
	ds_read_b128 v[156:159], v160 offset:2048
	ds_read_b128 v[160:163], v160 offset:3072
	s_mov_b32 m0, s65
	v_add_u32_e32 v210, 0, v231
	ds_read_b128 v[164:167], v210
	ds_read_b128 v[168:171], v210 offset:1024
	ds_read_b128 v[172:175], v210 offset:2048
	ds_read_b128 v[176:179], v210 offset:3072
	ds_read_b128 v[180:183], v210 offset:4096
	ds_read_b128 v[184:187], v210 offset:5120
	ds_read_b128 v[194:197], v210 offset:6144
	ds_read_b128 v[198:201], v210 offset:7168
	global_load_lds_dwordx4 v2, s[14:15]
	s_mov_b32 m0, s66
	v_mov_b32_e32 v189, v3
	global_load_lds_dwordx4 v188, s[14:15]
	s_waitcnt vmcnt(8)
	s_waitcnt lgkmcnt(0)
	s_barrier
	s_setprio 1
	s_waitcnt lgkmcnt(0)
	v_mfma_f32_16x16x32_bf16 v[4:7], v[132:135], v[164:167], v[4:7]
	v_mfma_f32_16x16x32_bf16 v[4:7], v[136:139], v[168:171], v[4:7]
	v_mfma_f32_16x16x32_bf16 v[8:11], v[144:147], v[168:171], v[8:11]
	v_mfma_f32_16x16x32_bf16 v[8:11], v[140:143], v[164:167], v[8:11]
	v_mfma_f32_16x16x32_bf16 v[16:19], v[140:143], v[172:175], v[16:19]
	v_mfma_f32_16x16x32_bf16 v[16:19], v[144:147], v[176:179], v[16:19]
	v_mfma_f32_16x16x32_bf16 v[12:15], v[136:139], v[176:179], v[12:15]
	v_mfma_f32_16x16x32_bf16 v[12:15], v[132:135], v[172:175], v[12:15]
	v_mfma_f32_16x16x32_bf16 v[20:23], v[132:135], v[180:183], v[20:23]
	v_mfma_f32_16x16x32_bf16 v[20:23], v[136:139], v[184:187], v[20:23]
	v_mfma_f32_16x16x32_bf16 v[24:27], v[144:147], v[184:187], v[24:27]
	v_mfma_f32_16x16x32_bf16 v[24:27], v[140:143], v[180:183], v[24:27]
	v_mfma_f32_16x16x32_bf16 v[32:35], v[140:143], v[194:197], v[32:35]
	v_mfma_f32_16x16x32_bf16 v[32:35], v[144:147], v[198:201], v[32:35]
	v_mfma_f32_16x16x32_bf16 v[28:31], v[136:139], v[198:201], v[28:31]
	v_mfma_f32_16x16x32_bf16 v[28:31], v[132:135], v[194:197], v[28:31]
	s_setprio 0
	s_setprio 1
	v_mfma_f32_16x16x32_bf16 v[36:39], v[148:151], v[164:167], v[36:39]
	v_mfma_f32_16x16x32_bf16 v[36:39], v[152:155], v[168:171], v[36:39]
	v_mfma_f32_16x16x32_bf16 v[40:43], v[160:163], v[168:171], v[40:43]
	v_mfma_f32_16x16x32_bf16 v[40:43], v[156:159], v[164:167], v[40:43]
	v_mfma_f32_16x16x32_bf16 v[48:51], v[156:159], v[172:175], v[48:51]
	v_mfma_f32_16x16x32_bf16 v[48:51], v[160:163], v[176:179], v[48:51]
	v_mfma_f32_16x16x32_bf16 v[44:47], v[152:155], v[176:179], v[44:47]
	v_mfma_f32_16x16x32_bf16 v[44:47], v[148:151], v[172:175], v[44:47]
	v_mfma_f32_16x16x32_bf16 v[52:55], v[148:151], v[180:183], v[52:55]
	v_mfma_f32_16x16x32_bf16 v[52:55], v[152:155], v[184:187], v[52:55]
	v_mfma_f32_16x16x32_bf16 v[56:59], v[160:163], v[184:187], v[56:59]
	v_mfma_f32_16x16x32_bf16 v[56:59], v[156:159], v[180:183], v[56:59]
	v_mfma_f32_16x16x32_bf16 v[64:67], v[156:159], v[194:197], v[64:67]
	v_mfma_f32_16x16x32_bf16 v[64:67], v[160:163], v[198:201], v[64:67]
	v_mfma_f32_16x16x32_bf16 v[60:63], v[152:155], v[198:201], v[60:63]
	v_mfma_f32_16x16x32_bf16 v[60:63], v[148:151], v[194:197], v[60:63]
	s_setprio 0
	s_barrier
	s_add_i32 s29, s29, s38
	s_mov_b32 m0, s29
	ds_read_b128 v[164:167], v210 offset:16384
	ds_read_b128 v[168:171], v210 offset:17408
	ds_read_b128 v[172:175], v210 offset:18432
	ds_read_b128 v[176:179], v210 offset:19456
	ds_read_b128 v[180:183], v210 offset:20480
	ds_read_b128 v[184:187], v210 offset:21504
	ds_read_b128 v[194:197], v210 offset:22528
	ds_read_b128 v[198:201], v210 offset:23552
	global_load_lds_dwordx4 v192, s[12:13]
	s_add_i32 m0, s29, 0x2000
	s_add_u32 s40, s12, 0x100000
	s_addc_u32 s41, s13, 0
	s_add_i32 s29, s51, s38
	global_load_lds_dwordx4 v190, s[12:13]
	s_mov_b32 m0, s29
	v_mov_b32_e32 v193, v3
	global_load_lds_dwordx4 v192, s[40:41]
	s_add_i32 m0, s29, 0x2000
	v_mov_b32_e32 v191, v3
	global_load_lds_dwordx4 v190, s[40:41]
	s_mov_b32 m0, s56
	v_lshl_add_u64 v[202:203], s[12:13], 0, v[192:193]
	global_load_lds_dwordx4 v2, s[16:17]
	s_mov_b32 m0, s57
	v_lshl_add_u64 v[204:205], s[12:13], 0, v[190:191]
	global_load_lds_dwordx4 v188, s[16:17]
	s_waitcnt vmcnt(8)
	s_waitcnt lgkmcnt(0)
	v_lshl_add_u64 v[206:207], s[16:17], 0, v[2:3]
	v_lshl_add_u64 v[208:209], s[16:17], 0, v[188:189]
	s_barrier
	s_setprio 1
	s_waitcnt lgkmcnt(0)
	v_mfma_f32_16x16x32_bf16 v[68:71], v[132:135], v[164:167], v[68:71]
	v_mfma_f32_16x16x32_bf16 v[68:71], v[136:139], v[168:171], v[68:71]
	v_mfma_f32_16x16x32_bf16 v[72:75], v[144:147], v[168:171], v[72:75]
	v_mfma_f32_16x16x32_bf16 v[72:75], v[140:143], v[164:167], v[72:75]
	v_mfma_f32_16x16x32_bf16 v[80:83], v[140:143], v[172:175], v[80:83]
	v_mfma_f32_16x16x32_bf16 v[80:83], v[144:147], v[176:179], v[80:83]
	v_mfma_f32_16x16x32_bf16 v[76:79], v[136:139], v[176:179], v[76:79]
	v_mfma_f32_16x16x32_bf16 v[76:79], v[132:135], v[172:175], v[76:79]
	v_mfma_f32_16x16x32_bf16 v[84:87], v[132:135], v[180:183], v[84:87]
	v_mfma_f32_16x16x32_bf16 v[84:87], v[136:139], v[184:187], v[84:87]
	v_mfma_f32_16x16x32_bf16 v[88:91], v[144:147], v[184:187], v[88:91]
	v_mfma_f32_16x16x32_bf16 v[88:91], v[140:143], v[180:183], v[88:91]
	v_mfma_f32_16x16x32_bf16 v[96:99], v[140:143], v[194:197], v[96:99]
	v_mfma_f32_16x16x32_bf16 v[96:99], v[144:147], v[198:201], v[96:99]
	v_mfma_f32_16x16x32_bf16 v[92:95], v[136:139], v[198:201], v[92:95]
	v_mfma_f32_16x16x32_bf16 v[92:95], v[132:135], v[194:197], v[92:95]
	s_setprio 0
	s_setprio 1
	v_mfma_f32_16x16x32_bf16 v[100:103], v[148:151], v[164:167], v[100:103]
	v_mfma_f32_16x16x32_bf16 v[100:103], v[152:155], v[168:171], v[100:103]
	v_mfma_f32_16x16x32_bf16 v[104:107], v[160:163], v[168:171], v[104:107]
	v_mfma_f32_16x16x32_bf16 v[104:107], v[156:159], v[164:167], v[104:107]
	v_mfma_f32_16x16x32_bf16 v[112:115], v[156:159], v[172:175], v[112:115]
	v_mfma_f32_16x16x32_bf16 v[112:115], v[160:163], v[176:179], v[112:115]
	v_mfma_f32_16x16x32_bf16 v[108:111], v[152:155], v[176:179], v[108:111]
	v_mfma_f32_16x16x32_bf16 v[108:111], v[148:151], v[172:175], v[108:111]
	v_mfma_f32_16x16x32_bf16 v[116:119], v[148:151], v[180:183], v[116:119]
	v_mfma_f32_16x16x32_bf16 v[116:119], v[152:155], v[184:187], v[116:119]
	v_mfma_f32_16x16x32_bf16 v[120:123], v[160:163], v[184:187], v[120:123]
	v_mfma_f32_16x16x32_bf16 v[120:123], v[156:159], v[180:183], v[120:123]
	v_mfma_f32_16x16x32_bf16 v[128:131], v[156:159], v[194:197], v[128:131]
	v_mfma_f32_16x16x32_bf16 v[128:131], v[160:163], v[198:201], v[128:131]
	v_mfma_f32_16x16x32_bf16 v[124:127], v[152:155], v[198:201], v[124:127]
	v_mfma_f32_16x16x32_bf16 v[124:127], v[148:151], v[194:197], v[124:127]
	s_setprio 0
	s_barrier
	s_add_i32 s29, 0, 0x18000
	s_add_i32 s40, 0, 0x1c000
	v_add_u32_e32 v144, s29, v232
	v_add_u32_e32 v160, s40, v232
	ds_read_b128 v[132:135], v144
	ds_read_b128 v[136:139], v144 offset:1024
	ds_read_b128 v[140:143], v144 offset:2048
	ds_read_b128 v[144:147], v144 offset:3072
	ds_read_b128 v[148:151], v160
	ds_read_b128 v[152:155], v160 offset:1024
	ds_read_b128 v[156:159], v160 offset:2048
	ds_read_b128 v[160:163], v160 offset:3072
	s_add_u32 s16, s16, 0x40000
	s_addc_u32 s17, s17, 0
	s_mov_b32 m0, s58
	ds_read_b128 v[164:167], v210 offset:32768
	ds_read_b128 v[168:171], v210 offset:33792
	ds_read_b128 v[172:175], v210 offset:34816
	ds_read_b128 v[176:179], v210 offset:35840
	ds_read_b128 v[180:183], v210 offset:36864
	ds_read_b128 v[184:187], v210 offset:37888
	ds_read_b128 v[194:197], v210 offset:38912
	ds_read_b128 v[198:201], v210 offset:39936
	global_load_lds_dwordx4 v2, s[16:17]
	s_mov_b32 m0, s59
	s_nop 0
	global_load_lds_dwordx4 v188, s[16:17]
	s_waitcnt vmcnt(8)
	s_waitcnt lgkmcnt(0)
	s_barrier
	s_setprio 1
	s_waitcnt lgkmcnt(0)
	v_mfma_f32_16x16x32_bf16 v[4:7], v[132:135], v[164:167], v[4:7]
	v_mfma_f32_16x16x32_bf16 v[4:7], v[136:139], v[168:171], v[4:7]
	v_mfma_f32_16x16x32_bf16 v[8:11], v[144:147], v[168:171], v[8:11]
	v_mfma_f32_16x16x32_bf16 v[8:11], v[140:143], v[164:167], v[8:11]
	v_mfma_f32_16x16x32_bf16 v[16:19], v[140:143], v[172:175], v[16:19]
	v_mfma_f32_16x16x32_bf16 v[16:19], v[144:147], v[176:179], v[16:19]
	v_mfma_f32_16x16x32_bf16 v[12:15], v[136:139], v[176:179], v[12:15]
	v_mfma_f32_16x16x32_bf16 v[12:15], v[132:135], v[172:175], v[12:15]
	v_mfma_f32_16x16x32_bf16 v[20:23], v[132:135], v[180:183], v[20:23]
	v_mfma_f32_16x16x32_bf16 v[20:23], v[136:139], v[184:187], v[20:23]
	v_mfma_f32_16x16x32_bf16 v[24:27], v[144:147], v[184:187], v[24:27]
	v_mfma_f32_16x16x32_bf16 v[24:27], v[140:143], v[180:183], v[24:27]
	v_mfma_f32_16x16x32_bf16 v[32:35], v[140:143], v[194:197], v[32:35]
	v_mfma_f32_16x16x32_bf16 v[32:35], v[144:147], v[198:201], v[32:35]
	v_mfma_f32_16x16x32_bf16 v[28:31], v[136:139], v[198:201], v[28:31]
	v_mfma_f32_16x16x32_bf16 v[28:31], v[132:135], v[194:197], v[28:31]
	s_setprio 0
	s_setprio 1
	v_mfma_f32_16x16x32_bf16 v[36:39], v[148:151], v[164:167], v[36:39]
	v_mfma_f32_16x16x32_bf16 v[36:39], v[152:155], v[168:171], v[36:39]
	v_mfma_f32_16x16x32_bf16 v[40:43], v[160:163], v[168:171], v[40:43]
	v_mfma_f32_16x16x32_bf16 v[40:43], v[156:159], v[164:167], v[40:43]
	v_mfma_f32_16x16x32_bf16 v[48:51], v[156:159], v[172:175], v[48:51]
	v_mfma_f32_16x16x32_bf16 v[48:51], v[160:163], v[176:179], v[48:51]
	v_mfma_f32_16x16x32_bf16 v[44:47], v[152:155], v[176:179], v[44:47]
	v_mfma_f32_16x16x32_bf16 v[44:47], v[148:151], v[172:175], v[44:47]
	v_mfma_f32_16x16x32_bf16 v[52:55], v[148:151], v[180:183], v[52:55]
	v_mfma_f32_16x16x32_bf16 v[52:55], v[152:155], v[184:187], v[52:55]
	v_mfma_f32_16x16x32_bf16 v[56:59], v[160:163], v[184:187], v[56:59]
	v_mfma_f32_16x16x32_bf16 v[56:59], v[156:159], v[180:183], v[56:59]
	v_mfma_f32_16x16x32_bf16 v[64:67], v[156:159], v[194:197], v[64:67]
	v_mfma_f32_16x16x32_bf16 v[64:67], v[160:163], v[198:201], v[64:67]
	v_mfma_f32_16x16x32_bf16 v[60:63], v[152:155], v[198:201], v[60:63]
	v_mfma_f32_16x16x32_bf16 v[60:63], v[148:151], v[194:197], v[60:63]
	s_setprio 0
	s_barrier
	s_add_i32 s16, s29, s38
	v_lshl_add_u64 v[202:203], v[202:203], 0, s[86:87]
	s_mov_b32 m0, s16
	ds_read_b128 v[164:167], v210 offset:49152
	ds_read_b128 v[168:171], v210 offset:50176
	ds_read_b128 v[172:175], v210 offset:51200
	ds_read_b128 v[176:179], v210 offset:52224
	ds_read_b128 v[180:183], v210 offset:53248
	ds_read_b128 v[184:187], v210 offset:54272
	ds_read_b128 v[194:197], v210 offset:55296
	ds_read_b128 v[198:201], v210 offset:56320
	global_load_lds_dwordx4 v[202:203], off
	s_add_i32 m0, s16, 0x2000
	s_add_u32 s12, s12, 0x100080
	v_lshl_add_u64 v[202:203], v[204:205], 0, s[86:87]
	s_addc_u32 s13, s13, 0
	s_add_i32 s16, s40, s38
	global_load_lds_dwordx4 v[202:203], off
	s_mov_b32 m0, s16
	v_lshl_add_u64 v[202:203], v[206:207], 0, s[86:87]
	global_load_lds_dwordx4 v192, s[12:13]
	s_add_i32 m0, s16, 0x2000
	s_nop 0
	global_load_lds_dwordx4 v190, s[12:13]
	s_mov_b32 m0, s63
	s_nop 0
	global_load_lds_dwordx4 v[202:203], off
	v_lshl_add_u64 v[202:203], v[208:209], 0, s[86:87]
	s_mov_b32 m0, s64
	s_nop 0
	global_load_lds_dwordx4 v[202:203], off
	s_waitcnt vmcnt(8)
	s_waitcnt lgkmcnt(0)
	s_barrier
	s_setprio 1
	s_waitcnt lgkmcnt(0)
	v_mfma_f32_16x16x32_bf16 v[68:71], v[132:135], v[164:167], v[68:71]
	v_mfma_f32_16x16x32_bf16 v[68:71], v[136:139], v[168:171], v[68:71]
	v_mfma_f32_16x16x32_bf16 v[72:75], v[144:147], v[168:171], v[72:75]
	v_mfma_f32_16x16x32_bf16 v[72:75], v[140:143], v[164:167], v[72:75]
	v_mfma_f32_16x16x32_bf16 v[80:83], v[140:143], v[172:175], v[80:83]
	v_mfma_f32_16x16x32_bf16 v[80:83], v[144:147], v[176:179], v[80:83]
	v_mfma_f32_16x16x32_bf16 v[76:79], v[136:139], v[176:179], v[76:79]
	v_mfma_f32_16x16x32_bf16 v[76:79], v[132:135], v[172:175], v[76:79]
	v_mfma_f32_16x16x32_bf16 v[84:87], v[132:135], v[180:183], v[84:87]
	v_mfma_f32_16x16x32_bf16 v[84:87], v[136:139], v[184:187], v[84:87]
	v_mfma_f32_16x16x32_bf16 v[88:91], v[144:147], v[184:187], v[88:91]
	v_mfma_f32_16x16x32_bf16 v[88:91], v[140:143], v[180:183], v[88:91]
	v_mfma_f32_16x16x32_bf16 v[96:99], v[140:143], v[194:197], v[96:99]
	v_mfma_f32_16x16x32_bf16 v[96:99], v[144:147], v[198:201], v[96:99]
	v_mfma_f32_16x16x32_bf16 v[92:95], v[136:139], v[198:201], v[92:95]
	v_mfma_f32_16x16x32_bf16 v[92:95], v[132:135], v[194:197], v[92:95]
	s_setprio 0
	s_setprio 1
	v_mfma_f32_16x16x32_bf16 v[100:103], v[148:151], v[164:167], v[100:103]
	v_mfma_f32_16x16x32_bf16 v[100:103], v[152:155], v[168:171], v[100:103]
	v_mfma_f32_16x16x32_bf16 v[104:107], v[160:163], v[168:171], v[104:107]
	v_mfma_f32_16x16x32_bf16 v[104:107], v[156:159], v[164:167], v[104:107]
	v_mfma_f32_16x16x32_bf16 v[112:115], v[156:159], v[172:175], v[112:115]
	v_mfma_f32_16x16x32_bf16 v[112:115], v[160:163], v[176:179], v[112:115]
	v_mfma_f32_16x16x32_bf16 v[108:111], v[152:155], v[176:179], v[108:111]
	v_mfma_f32_16x16x32_bf16 v[108:111], v[148:151], v[172:175], v[108:111]
	v_mfma_f32_16x16x32_bf16 v[116:119], v[148:151], v[180:183], v[116:119]
	v_mfma_f32_16x16x32_bf16 v[116:119], v[152:155], v[184:187], v[116:119]
	v_mfma_f32_16x16x32_bf16 v[120:123], v[160:163], v[184:187], v[120:123]
	v_mfma_f32_16x16x32_bf16 v[120:123], v[156:159], v[180:183], v[120:123]
	v_mfma_f32_16x16x32_bf16 v[128:131], v[156:159], v[194:197], v[128:131]
	v_mfma_f32_16x16x32_bf16 v[128:131], v[160:163], v[198:201], v[128:131]
	v_mfma_f32_16x16x32_bf16 v[124:127], v[152:155], v[198:201], v[124:127]
	v_mfma_f32_16x16x32_bf16 v[124:127], v[148:151], v[194:197], v[124:127]
	s_setprio 0
	s_barrier
	s_add_i32 s28, s28, 2
	s_add_u32 s14, s14, 0x100
	s_addc_u32 s15, s15, 0
	s_add_u32 s26, s26, 0x100
	s_addc_u32 s27, s27, 0
	s_cmp_gt_u32 s28, 13
	s_cbranch_scc0 .LBB0_2273
	s_and_b64 vcc, exec, s[48:49]
	s_cbranch_vccz .LBB0_2276
	s_barrier
